# GEMM K-loops: all per-segment s_setprio flips removed (A/B of the role-split priority)
# speedup vs baseline: 1.0049x; 1.0039x over previous
; #define PG8_STAGE(bufoff, gbase, voff) do { _Pragma("unroll") for (int _i = 0; _i < 2; ++_i) \
;         __builtin_amdgcn_global_load_lds((const unsigned*)((const char*)(gbase) + (voff)[_i]), (PG8_LAS unsigned*)(lds + (bufoff) + ldsw + _i * 8192), 16, 0, 0); } while (0)
; #define PG8_LDA(dst, b, h) do { _Pragma("unroll") for (int m = 0; m < 4; ++m) _Pragma("unroll") for (int k = 0; k < 2; ++k) dst[m][k] = *(const PG8_LAS bf16x8*)(lds + PG8_SA(b, h) + aoff + m * 2048 + k * 1024); } while (0)
; #define PG8_LDB(dst, b, h) do { _Pragma("unroll") for (int n = 0; n < 2; ++n) _Pragma("unroll") for (int k = 0; k < 2; ++k) dst[n][k] = *(const PG8_LAS bf16x8*)(lds + PG8_SB(b, h) + boff + n * 2048 + k * 1024); } while (0)
; #define PG8_MMA(ai, bj, At, Bt) do { __builtin_amdgcn_s_setprio(1); _Pragma("unroll") for (int m = 0; m < 4; ++m) _Pragma("unroll") for (int n = 0; n < 2; ++n) _Pragma("unroll") for (int k = 0; k < 2; ++k) \
;         acc[ai][bj][m][n] = __builtin_amdgcn_mfma_f32_16x16x32_bf16(Bt[n][k], At[m][k], acc[ai][bj][m][n], 0, 0, 0); __builtin_amdgcn_s_setprio(0); } while (0)
; #define PG8_WAIT_V(n) asm volatile("s_waitcnt vmcnt(" #n ")" ::: "memory")
; #define PG8_WAIT_L(n) asm volatile("s_waitcnt lgkmcnt(" #n ")" ::: "memory")
; #define PG8_BAR __builtin_amdgcn_s_barrier()
; template <class Epi, class Sched, bool ALIGN_EPI = false, bool SP2 = false>
; __device__ __forceinline__ void gemm_phase(PG8_LAS unsigned char* lds, const Gemm g, const Sched& S, const Epi& E) {
;     ...
;             const char* a1 = cA + (size_t)(t + 1) * kstep;
;             const char* a2 = last ? nA : cA + (size_t)(t + 2) * kstep; const char* b2 = last ? nB : cB + (size_t)(t + 2) * kstep;
;             const char* a3 = a2 + kstep; const char* b3 = b2 + kstep;
;             if (last && has_next) S.a_ready(nxt);
;             if constexpr (SP2) {
;             PG8_LDB(B0, 0, 0); PG8_LDB(B1, 0, 1); PG8_SCHED; PG8_LDA(At, 0, 0); PG8_STAGE(PG8_SA(1, 1), a1 + hstep, voffA);
;             PG8_WAIT_V(8); PG8_WAIT_L(0); PG8_BAR; PG8_MMA(0, 0, At, B0); PG8_MMA(0, 1, At, B1); PG8_BAR; PG8_SCHED;
;             PG8_LDA(At, 0, 1); PG8_STAGE(PG8_SB(0, 0), b2, voffB); PG8_STAGE(PG8_SB(0, 1), b2 + hstep, voffB); PG8_STAGE(PG8_SA(0, 0), a2, voffA);
;             PG8_WAIT_V(8); PG8_WAIT_L(0); PG8_BAR; PG8_MMA(1, 0, At, B0); PG8_MMA(1, 1, At, B1); PG8_BAR; PG8_SCHED;
.LBB0_223:
	s_ashr_i32 s15, s14, 31
	s_lshl_b64 s[16:17], s[14:15], 19
	s_add_u32 s16, s36, s16
	s_addc_u32 s17, s37, s17
	s_and_b64 s[18:19], s[4:5], exec
	s_cselect_b32 s15, s17, s21
	s_cselect_b32 s68, s16, s20
	s_ashr_i32 s13, s12, 31
	s_lshl_b64 s[18:19], s[12:13], 19
	s_add_u32 s18, s53, s18
	s_addc_u32 s19, s54, s19
	s_and_b64 s[46:47], s[4:5], exec
	s_cselect_b32 s13, s19, s43
	s_cselect_b32 s69, s18, s42
	s_add_u32 s20, s20, 0x40080
	s_addc_u32 s21, s21, 0
	s_add_u32 s70, s42, 0x100
	s_addc_u32 s71, s43, 0
	s_mov_b32 s72, -2
	ds_read_b128 v[154:157], v150
	ds_read_b128 v[158:161], v150 offset:1024
	ds_read_b128 v[162:165], v150 offset:2048
	ds_read_b128 v[166:169], v150 offset:3072
	ds_read_b128 v[170:173], v151
	ds_read_b128 v[174:177], v151 offset:1024
	ds_read_b128 v[178:181], v151 offset:2048
	ds_read_b128 v[182:185], v151 offset:3072
	s_add_u32 s42, s20, 0xfffc0080
	s_addc_u32 s43, s21, -1
	s_cmp_eq_u32 s72, 12
	s_cselect_b32 s47, s15, s43
	s_cselect_b32 s46, s68, s42
	s_cselect_b32 s43, s13, s71
	s_cselect_b32 s42, s69, s70
	s_add_i32 m0, s35, 0xc000
	ds_read_b128 v[186:189], v152
	ds_read_b128 v[190:193], v152 offset:1024
	ds_read_b128 v[198:201], v152 offset:2048
	ds_read_b128 v[202:205], v152 offset:3072
	ds_read_b128 v[206:209], v152 offset:4096
	ds_read_b128 v[210:213], v152 offset:5120
	ds_read_b128 v[214:217], v152 offset:6144
	ds_read_b128 v[218:221], v152 offset:7168
	global_load_lds_dwordx4 v136, s[20:21]
	s_add_i32 m0, s35, 0xe000
	s_nop 0
	global_load_lds_dwordx4 v138, s[20:21]
	s_waitcnt vmcnt(8)
	s_waitcnt lgkmcnt(0)
	s_barrier
	s_waitcnt lgkmcnt(0)
	v_mfma_f32_16x16x32_bf16 v[124:127], v[154:157], v[186:189], 0
	v_mfma_f32_16x16x32_bf16 v[116:119], v[162:165], v[186:189], 0
	v_mfma_f32_16x16x32_bf16 v[108:111], v[154:157], v[198:201], 0
	v_mfma_f32_16x16x32_bf16 v[100:103], v[162:165], v[198:201], 0
	v_mfma_f32_16x16x32_bf16 v[92:95], v[154:157], v[206:209], 0
	v_mfma_f32_16x16x32_bf16 v[84:87], v[162:165], v[206:209], 0
	v_mfma_f32_16x16x32_bf16 v[76:79], v[154:157], v[214:217], 0
	v_mfma_f32_16x16x32_bf16 v[68:71], v[162:165], v[214:217], 0
	v_mfma_f32_16x16x32_bf16 v[124:127], v[158:161], v[190:193], v[124:127]
	v_mfma_f32_16x16x32_bf16 v[116:119], v[166:169], v[190:193], v[116:119]
	v_mfma_f32_16x16x32_bf16 v[108:111], v[158:161], v[202:205], v[108:111]
	v_mfma_f32_16x16x32_bf16 v[100:103], v[166:169], v[202:205], v[100:103]
	v_mfma_f32_16x16x32_bf16 v[92:95], v[158:161], v[210:213], v[92:95]
	v_mfma_f32_16x16x32_bf16 v[84:87], v[166:169], v[210:213], v[84:87]
	v_mfma_f32_16x16x32_bf16 v[76:79], v[158:161], v[218:221], v[76:79]
	v_mfma_f32_16x16x32_bf16 v[68:71], v[166:169], v[218:221], v[68:71]
	v_mfma_f32_16x16x32_bf16 v[120:123], v[170:173], v[186:189], 0
	v_mfma_f32_16x16x32_bf16 v[112:115], v[178:181], v[186:189], 0
	v_mfma_f32_16x16x32_bf16 v[104:107], v[170:173], v[198:201], 0
	v_mfma_f32_16x16x32_bf16 v[96:99], v[178:181], v[198:201], 0
	v_mfma_f32_16x16x32_bf16 v[88:91], v[170:173], v[206:209], 0
	v_mfma_f32_16x16x32_bf16 v[80:83], v[178:181], v[206:209], 0
	v_mfma_f32_16x16x32_bf16 v[72:75], v[170:173], v[214:217], 0
	v_mfma_f32_16x16x32_bf16 v[64:67], v[178:181], v[214:217], 0
	v_mfma_f32_16x16x32_bf16 v[120:123], v[174:177], v[190:193], v[120:123]
	v_mfma_f32_16x16x32_bf16 v[112:115], v[182:185], v[190:193], v[112:115]
	v_mfma_f32_16x16x32_bf16 v[104:107], v[174:177], v[202:205], v[104:107]
	v_mfma_f32_16x16x32_bf16 v[96:99], v[182:185], v[202:205], v[96:99]
	v_mfma_f32_16x16x32_bf16 v[88:91], v[174:177], v[210:213], v[88:91]
	v_mfma_f32_16x16x32_bf16 v[80:83], v[182:185], v[210:213], v[80:83]
	v_mfma_f32_16x16x32_bf16 v[72:75], v[174:177], v[218:221], v[72:75]
	v_mfma_f32_16x16x32_bf16 v[64:67], v[182:185], v[218:221], v[64:67]
	s_barrier
	s_add_i32 s73, s63, s55
	s_add_u32 s98, s42, s8
	s_addc_u32 s99, s43, s9
	s_add_u32 s100, s46, s8
	s_addc_u32 s101, s47, s9
	s_mov_b32 m0, s73
	ds_read_b128 v[186:189], v152 offset:16384
	ds_read_b128 v[190:193], v152 offset:17408
	ds_read_b128 v[198:201], v152 offset:18432
	ds_read_b128 v[202:205], v152 offset:19456
	ds_read_b128 v[206:209], v152 offset:20480
	ds_read_b128 v[210:213], v152 offset:21504
	ds_read_b128 v[214:217], v152 offset:22528
	ds_read_b128 v[218:221], v152 offset:23552
	global_load_lds_dwordx4 v132, s[42:43]
	s_add_i32 m0, s73, 0x2000
	s_add_u32 s74, s42, 0x40000
	s_addc_u32 s75, s43, 0
	s_add_i32 s73, s64, s55
	global_load_lds_dwordx4 v128, s[42:43]
	s_mov_b32 m0, s73
	s_nop 0
	global_load_lds_dwordx4 v132, s[74:75]
	s_add_i32 m0, s73, 0x2000
	s_nop 0
	global_load_lds_dwordx4 v128, s[74:75]
	s_mov_b32 m0, s35
	s_nop 0
	global_load_lds_dwordx4 v134, s[46:47]
	s_mov_b32 m0, s57
	s_nop 0
	global_load_lds_dwordx4 v130, s[46:47]
	s_waitcnt vmcnt(8)
	s_waitcnt lgkmcnt(0)
	s_barrier
; #define PG8_STAGE(bufoff, gbase, voff) do { _Pragma("unroll") for (int _i = 0; _i < 2; ++_i) \
;         __builtin_amdgcn_global_load_lds((const unsigned*)((const char*)(gbase) + (voff)[_i]), (PG8_LAS unsigned*)(lds + (bufoff) + ldsw + _i * 8192), 16, 0, 0); } while (0)
; #define PG8_LDA(dst, b, h) do { _Pragma("unroll") for (int m = 0; m < 4; ++m) _Pragma("unroll") for (int k = 0; k < 2; ++k) dst[m][k] = *(const PG8_LAS bf16x8*)(lds + PG8_SA(b, h) + aoff + m * 2048 + k * 1024); } while (0)
; #define PG8_LDB(dst, b, h) do { _Pragma("unroll") for (int n = 0; n < 2; ++n) _Pragma("unroll") for (int k = 0; k < 2; ++k) dst[n][k] = *(const PG8_LAS bf16x8*)(lds + PG8_SB(b, h) + boff + n * 2048 + k * 1024); } while (0)
; #define PG8_MMA(ai, bj, At, Bt) do { __builtin_amdgcn_s_setprio(1); _Pragma("unroll") for (int m = 0; m < 4; ++m) _Pragma("unroll") for (int n = 0; n < 2; ++n) _Pragma("unroll") for (int k = 0; k < 2; ++k) \
;         acc[ai][bj][m][n] = __builtin_amdgcn_mfma_f32_16x16x32_bf16(Bt[n][k], At[m][k], acc[ai][bj][m][n], 0, 0, 0); __builtin_amdgcn_s_setprio(0); } while (0)
; #define PG8_WAIT_V(n) asm volatile("s_waitcnt vmcnt(" #n ")" ::: "memory")
; #define PG8_WAIT_L(n) asm volatile("s_waitcnt lgkmcnt(" #n ")" ::: "memory")
; #define PG8_BAR __builtin_amdgcn_s_barrier()
; #define PG8_SCHED __builtin_amdgcn_sched_barrier(0)
; template <class Epi, class Sched, bool ALIGN_EPI = false, bool SP2 = false>
; __device__ __forceinline__ void gemm_phase(PG8_LAS unsigned char* lds, const Gemm g, const Sched& S, const Epi& E) {
;     ...
;             PG8_WAIT_V(8); PG8_WAIT_L(0); PG8_BAR; PG8_MMA(1, 0, At, B0); PG8_MMA(1, 1, At, B1); PG8_BAR; PG8_SCHED;
;             PG8_LDB(B0, 1, 0); PG8_LDB(B1, 1, 1); PG8_SCHED; PG8_LDA(At, 1, 0); PG8_STAGE(PG8_SA(0, 1), a2 + hstep, voffA);
;             PG8_WAIT_V(8); PG8_WAIT_L(0); PG8_BAR; PG8_MMA(0, 0, At, B0); PG8_MMA(0, 1, At, B1); PG8_BAR; PG8_SCHED;
	s_waitcnt lgkmcnt(0)
	v_mfma_f32_16x16x32_bf16 v[60:63], v[154:157], v[186:189], 0
	v_mfma_f32_16x16x32_bf16 v[52:55], v[162:165], v[186:189], 0
	v_mfma_f32_16x16x32_bf16 v[44:47], v[154:157], v[198:201], 0
	v_mfma_f32_16x16x32_bf16 v[36:39], v[162:165], v[198:201], 0
	v_mfma_f32_16x16x32_bf16 v[28:31], v[154:157], v[206:209], 0
	v_mfma_f32_16x16x32_bf16 v[20:23], v[162:165], v[206:209], 0
	v_mfma_f32_16x16x32_bf16 v[12:15], v[154:157], v[214:217], 0
	v_mfma_f32_16x16x32_bf16 v[4:7], v[162:165], v[214:217], 0
	v_mfma_f32_16x16x32_bf16 v[60:63], v[158:161], v[190:193], v[60:63]
	v_mfma_f32_16x16x32_bf16 v[52:55], v[166:169], v[190:193], v[52:55]
	v_mfma_f32_16x16x32_bf16 v[44:47], v[158:161], v[202:205], v[44:47]
	v_mfma_f32_16x16x32_bf16 v[36:39], v[166:169], v[202:205], v[36:39]
	v_mfma_f32_16x16x32_bf16 v[28:31], v[158:161], v[210:213], v[28:31]
	v_mfma_f32_16x16x32_bf16 v[20:23], v[166:169], v[210:213], v[20:23]
	v_mfma_f32_16x16x32_bf16 v[12:15], v[158:161], v[218:221], v[12:15]
	v_mfma_f32_16x16x32_bf16 v[4:7], v[166:169], v[218:221], v[4:7]
	v_mfma_f32_16x16x32_bf16 v[56:59], v[170:173], v[186:189], 0
	v_mfma_f32_16x16x32_bf16 v[48:51], v[178:181], v[186:189], 0
	v_mfma_f32_16x16x32_bf16 v[40:43], v[170:173], v[198:201], 0
	v_mfma_f32_16x16x32_bf16 v[32:35], v[178:181], v[198:201], 0
	v_mfma_f32_16x16x32_bf16 v[24:27], v[170:173], v[206:209], 0
	v_mfma_f32_16x16x32_bf16 v[16:19], v[178:181], v[206:209], 0
	v_mfma_f32_16x16x32_bf16 v[8:11], v[170:173], v[214:217], 0
	v_mfma_f32_16x16x32_bf16 v[0:3], v[178:181], v[214:217], 0
	v_mfma_f32_16x16x32_bf16 v[56:59], v[174:177], v[190:193], v[56:59]
	v_mfma_f32_16x16x32_bf16 v[48:51], v[182:185], v[190:193], v[48:51]
	v_mfma_f32_16x16x32_bf16 v[40:43], v[174:177], v[202:205], v[40:43]
	v_mfma_f32_16x16x32_bf16 v[32:35], v[182:185], v[202:205], v[32:35]
	v_mfma_f32_16x16x32_bf16 v[24:27], v[174:177], v[210:213], v[24:27]
	v_mfma_f32_16x16x32_bf16 v[16:19], v[182:185], v[210:213], v[16:19]
	v_mfma_f32_16x16x32_bf16 v[8:11], v[174:177], v[218:221], v[8:11]
	v_mfma_f32_16x16x32_bf16 v[0:3], v[182:185], v[218:221], v[0:3]
	s_barrier
	s_add_i32 s73, 0, 0x18000
	v_add_u32_e32 v153, s73, v147
	s_add_i32 s74, 0, 0x1c000
	ds_read_b128 v[154:157], v153
	ds_read_b128 v[158:161], v153 offset:1024
	ds_read_b128 v[162:165], v153 offset:2048
	ds_read_b128 v[166:169], v153 offset:3072
	v_add_u32_e32 v153, s74, v147
	ds_read_b128 v[170:173], v153
	ds_read_b128 v[174:177], v153 offset:1024
	ds_read_b128 v[178:181], v153 offset:2048
	ds_read_b128 v[182:185], v153 offset:3072
	s_add_u32 s46, s46, 0x40000
	s_addc_u32 s47, s47, 0
	s_mov_b32 m0, s58
	ds_read_b128 v[186:189], v152 offset:32768
	ds_read_b128 v[190:193], v152 offset:33792
	ds_read_b128 v[198:201], v152 offset:34816
	ds_read_b128 v[202:205], v152 offset:35840
	ds_read_b128 v[206:209], v152 offset:36864
	ds_read_b128 v[210:213], v152 offset:37888
	ds_read_b128 v[214:217], v152 offset:38912
	ds_read_b128 v[218:221], v152 offset:39936
	global_load_lds_dwordx4 v134, s[46:47]
	s_mov_b32 m0, s59
	s_nop 0
	global_load_lds_dwordx4 v130, s[46:47]
	s_waitcnt vmcnt(8)
	s_waitcnt lgkmcnt(0)
	s_barrier
	s_waitcnt lgkmcnt(0)
	v_mfma_f32_16x16x32_bf16 v[124:127], v[154:157], v[186:189], v[124:127]
	v_mfma_f32_16x16x32_bf16 v[116:119], v[162:165], v[186:189], v[116:119]
	v_mfma_f32_16x16x32_bf16 v[108:111], v[154:157], v[198:201], v[108:111]
	v_mfma_f32_16x16x32_bf16 v[100:103], v[162:165], v[198:201], v[100:103]
	v_mfma_f32_16x16x32_bf16 v[92:95], v[154:157], v[206:209], v[92:95]
	v_mfma_f32_16x16x32_bf16 v[84:87], v[162:165], v[206:209], v[84:87]
	v_mfma_f32_16x16x32_bf16 v[76:79], v[154:157], v[214:217], v[76:79]
	v_mfma_f32_16x16x32_bf16 v[68:71], v[162:165], v[214:217], v[68:71]
	v_mfma_f32_16x16x32_bf16 v[124:127], v[158:161], v[190:193], v[124:127]
	v_mfma_f32_16x16x32_bf16 v[116:119], v[166:169], v[190:193], v[116:119]
	v_mfma_f32_16x16x32_bf16 v[108:111], v[158:161], v[202:205], v[108:111]
	v_mfma_f32_16x16x32_bf16 v[100:103], v[166:169], v[202:205], v[100:103]
	v_mfma_f32_16x16x32_bf16 v[92:95], v[158:161], v[210:213], v[92:95]
	v_mfma_f32_16x16x32_bf16 v[84:87], v[166:169], v[210:213], v[84:87]
	v_mfma_f32_16x16x32_bf16 v[76:79], v[158:161], v[218:221], v[76:79]
	v_mfma_f32_16x16x32_bf16 v[68:71], v[166:169], v[218:221], v[68:71]
	v_mfma_f32_16x16x32_bf16 v[120:123], v[170:173], v[186:189], v[120:123]
	v_mfma_f32_16x16x32_bf16 v[112:115], v[178:181], v[186:189], v[112:115]
	v_mfma_f32_16x16x32_bf16 v[104:107], v[170:173], v[198:201], v[104:107]
	v_mfma_f32_16x16x32_bf16 v[96:99], v[178:181], v[198:201], v[96:99]
	v_mfma_f32_16x16x32_bf16 v[88:91], v[170:173], v[206:209], v[88:91]
	v_mfma_f32_16x16x32_bf16 v[80:83], v[178:181], v[206:209], v[80:83]
	v_mfma_f32_16x16x32_bf16 v[72:75], v[170:173], v[214:217], v[72:75]
	v_mfma_f32_16x16x32_bf16 v[64:67], v[178:181], v[214:217], v[64:67]
	v_mfma_f32_16x16x32_bf16 v[120:123], v[174:177], v[190:193], v[120:123]
	v_mfma_f32_16x16x32_bf16 v[112:115], v[182:185], v[190:193], v[112:115]
	v_mfma_f32_16x16x32_bf16 v[104:107], v[174:177], v[202:205], v[104:107]
	v_mfma_f32_16x16x32_bf16 v[96:99], v[182:185], v[202:205], v[96:99]
	v_mfma_f32_16x16x32_bf16 v[88:91], v[174:177], v[210:213], v[88:91]
	v_mfma_f32_16x16x32_bf16 v[80:83], v[182:185], v[210:213], v[80:83]
	v_mfma_f32_16x16x32_bf16 v[72:75], v[174:177], v[218:221], v[72:75]
	v_mfma_f32_16x16x32_bf16 v[64:67], v[182:185], v[218:221], v[64:67]
	s_barrier
; #define PG8_STAGE(bufoff, gbase, voff) do { _Pragma("unroll") for (int _i = 0; _i < 2; ++_i) \
;         __builtin_amdgcn_global_load_lds((const unsigned*)((const char*)(gbase) + (voff)[_i]), (PG8_LAS unsigned*)(lds + (bufoff) + ldsw + _i * 8192), 16, 0, 0); } while (0)
; #define PG8_LDA(dst, b, h) do { _Pragma("unroll") for (int m = 0; m < 4; ++m) _Pragma("unroll") for (int k = 0; k < 2; ++k) dst[m][k] = *(const PG8_LAS bf16x8*)(lds + PG8_SA(b, h) + aoff + m * 2048 + k * 1024); } while (0)
; #define PG8_LDB(dst, b, h) do { _Pragma("unroll") for (int n = 0; n < 2; ++n) _Pragma("unroll") for (int k = 0; k < 2; ++k) dst[n][k] = *(const PG8_LAS bf16x8*)(lds + PG8_SB(b, h) + boff + n * 2048 + k * 1024); } while (0)
; #define PG8_MMA(ai, bj, At, Bt) do { __builtin_amdgcn_s_setprio(1); _Pragma("unroll") for (int m = 0; m < 4; ++m) _Pragma("unroll") for (int n = 0; n < 2; ++n) _Pragma("unroll") for (int k = 0; k < 2; ++k) \
;         acc[ai][bj][m][n] = __builtin_amdgcn_mfma_f32_16x16x32_bf16(Bt[n][k], At[m][k], acc[ai][bj][m][n], 0, 0, 0); __builtin_amdgcn_s_setprio(0); } while (0)
; #define PG8_WAIT_V(n) asm volatile("s_waitcnt vmcnt(" #n ")" ::: "memory")
; #define PG8_BAR __builtin_amdgcn_s_barrier()
; template <class Epi, class Sched, bool ALIGN_EPI = false, bool SP2 = false>
; __device__ __forceinline__ void gemm_phase(PG8_LAS unsigned char* lds, const Gemm g, const Sched& S, const Epi& E) {
;     ...
;         for (int t = 0; t < nt; t += 2) {
;             const bool last = (t == nt - 2);
;             const char* a1 = cA + (size_t)(t + 1) * kstep;
;             const char* a2 = last ? nA : cA + (size_t)(t + 2) * kstep; const char* b2 = last ? nB : cB + (size_t)(t + 2) * kstep;
;             const char* a3 = a2 + kstep; const char* b3 = b2 + kstep;
;             if (last && has_next) S.a_ready(nxt);
;             if constexpr (SP2) {
;             PG8_LDB(B0, 0, 0); PG8_LDB(B1, 0, 1); PG8_SCHED; PG8_LDA(At, 0, 0); PG8_STAGE(PG8_SA(1, 1), a1 + hstep, voffA);
;             PG8_WAIT_V(8); PG8_WAIT_L(0); PG8_BAR; PG8_MMA(0, 0, At, B0); PG8_MMA(0, 1, At, B1); PG8_BAR; PG8_SCHED;
;     ...
;             PG8_LDA(At, 1, 1); PG8_STAGE(PG8_SB(1, 0), b3, voffB); PG8_STAGE(PG8_SB(1, 1), b3 + hstep, voffB); PG8_STAGE(PG8_SA(1, 0), a3, voffA);
;             PG8_WAIT_V(8); PG8_WAIT_L(0); PG8_BAR; PG8_MMA(1, 0, At, B0); PG8_MMA(1, 1, At, B1); PG8_BAR; PG8_SCHED;
	s_add_i32 s46, s73, s55
	s_mov_b32 m0, s46
	ds_read_b128 v[186:189], v152 offset:49152
	ds_read_b128 v[190:193], v152 offset:50176
	ds_read_b128 v[198:201], v152 offset:51200
	ds_read_b128 v[202:205], v152 offset:52224
	ds_read_b128 v[206:209], v152 offset:53248
	ds_read_b128 v[210:213], v152 offset:54272
	ds_read_b128 v[214:217], v152 offset:55296
	ds_read_b128 v[218:221], v152 offset:56320
	global_load_lds_dwordx4 v132, s[98:99]
	s_add_i32 m0, s46, 0x2000
	s_add_u32 s42, s42, 0x40080
	s_addc_u32 s43, s43, 0
	s_add_i32 s46, s74, s55
	global_load_lds_dwordx4 v128, s[98:99]
	s_mov_b32 m0, s46
	s_nop 0
	global_load_lds_dwordx4 v132, s[42:43]
	s_add_i32 m0, s46, 0x2000
	s_nop 0
	global_load_lds_dwordx4 v128, s[42:43]
	s_mov_b32 m0, s61
	s_nop 0
	global_load_lds_dwordx4 v134, s[100:101]
	s_mov_b32 m0, s62
	s_nop 0
	global_load_lds_dwordx4 v130, s[100:101]
	s_waitcnt vmcnt(8)
	s_waitcnt lgkmcnt(0)
	s_barrier
	s_waitcnt lgkmcnt(0)
	v_mfma_f32_16x16x32_bf16 v[60:63], v[154:157], v[186:189], v[60:63]
	v_mfma_f32_16x16x32_bf16 v[52:55], v[162:165], v[186:189], v[52:55]
	v_mfma_f32_16x16x32_bf16 v[44:47], v[154:157], v[198:201], v[44:47]
	v_mfma_f32_16x16x32_bf16 v[36:39], v[162:165], v[198:201], v[36:39]
	v_mfma_f32_16x16x32_bf16 v[28:31], v[154:157], v[206:209], v[28:31]
	v_mfma_f32_16x16x32_bf16 v[20:23], v[162:165], v[206:209], v[20:23]
	v_mfma_f32_16x16x32_bf16 v[12:15], v[154:157], v[214:217], v[12:15]
	v_mfma_f32_16x16x32_bf16 v[4:7], v[162:165], v[214:217], v[4:7]
	v_mfma_f32_16x16x32_bf16 v[60:63], v[158:161], v[190:193], v[60:63]
	v_mfma_f32_16x16x32_bf16 v[52:55], v[166:169], v[190:193], v[52:55]
	v_mfma_f32_16x16x32_bf16 v[44:47], v[158:161], v[202:205], v[44:47]
	v_mfma_f32_16x16x32_bf16 v[36:39], v[166:169], v[202:205], v[36:39]
	v_mfma_f32_16x16x32_bf16 v[28:31], v[158:161], v[210:213], v[28:31]
	v_mfma_f32_16x16x32_bf16 v[20:23], v[166:169], v[210:213], v[20:23]
	v_mfma_f32_16x16x32_bf16 v[12:15], v[158:161], v[218:221], v[12:15]
	v_mfma_f32_16x16x32_bf16 v[4:7], v[166:169], v[218:221], v[4:7]
	v_mfma_f32_16x16x32_bf16 v[56:59], v[170:173], v[186:189], v[56:59]
	v_mfma_f32_16x16x32_bf16 v[48:51], v[178:181], v[186:189], v[48:51]
	v_mfma_f32_16x16x32_bf16 v[40:43], v[170:173], v[198:201], v[40:43]
	v_mfma_f32_16x16x32_bf16 v[32:35], v[178:181], v[198:201], v[32:35]
	v_mfma_f32_16x16x32_bf16 v[24:27], v[170:173], v[206:209], v[24:27]
	v_mfma_f32_16x16x32_bf16 v[16:19], v[178:181], v[206:209], v[16:19]
	v_mfma_f32_16x16x32_bf16 v[8:11], v[170:173], v[214:217], v[8:11]
	v_mfma_f32_16x16x32_bf16 v[0:3], v[178:181], v[214:217], v[0:3]
	v_mfma_f32_16x16x32_bf16 v[56:59], v[174:177], v[190:193], v[56:59]
	v_mfma_f32_16x16x32_bf16 v[48:51], v[182:185], v[190:193], v[48:51]
	v_mfma_f32_16x16x32_bf16 v[40:43], v[174:177], v[202:205], v[40:43]
	v_mfma_f32_16x16x32_bf16 v[32:35], v[182:185], v[202:205], v[32:35]
	v_mfma_f32_16x16x32_bf16 v[24:27], v[174:177], v[210:213], v[24:27]
	v_mfma_f32_16x16x32_bf16 v[16:19], v[182:185], v[210:213], v[16:19]
	v_mfma_f32_16x16x32_bf16 v[8:11], v[174:177], v[218:221], v[8:11]
	v_mfma_f32_16x16x32_bf16 v[0:3], v[182:185], v[218:221], v[0:3]
	s_barrier
	s_add_i32 s72, s72, 2
	s_add_u32 s20, s20, 0x100
	s_addc_u32 s21, s21, 0
	s_add_u32 s70, s70, 0x100
	s_addc_u32 s71, s71, 0
	s_cmp_gt_u32 s72, 13
.LBB0_224:
	ds_read_b128 v[154:157], v150
	ds_read_b128 v[158:161], v150 offset:1024
	ds_read_b128 v[162:165], v150 offset:2048
	ds_read_b128 v[166:169], v150 offset:3072
	ds_read_b128 v[170:173], v151
	ds_read_b128 v[174:177], v151 offset:1024
	ds_read_b128 v[178:181], v151 offset:2048
	ds_read_b128 v[182:185], v151 offset:3072
	s_add_u32 s42, s20, 0xfffc0080
	s_addc_u32 s43, s21, -1
	s_cmp_eq_u32 s72, 12
	s_cselect_b32 s47, s15, s43
	s_cselect_b32 s46, s68, s42
	s_cselect_b32 s43, s13, s71
	s_cselect_b32 s42, s69, s70
	s_add_i32 m0, s35, 0xc000
	ds_read_b128 v[186:189], v152
	ds_read_b128 v[190:193], v152 offset:1024
	ds_read_b128 v[198:201], v152 offset:2048
	ds_read_b128 v[202:205], v152 offset:3072
	ds_read_b128 v[206:209], v152 offset:4096
	ds_read_b128 v[210:213], v152 offset:5120
	ds_read_b128 v[214:217], v152 offset:6144
	ds_read_b128 v[218:221], v152 offset:7168
	global_load_lds_dwordx4 v136, s[20:21]
	s_add_i32 m0, s35, 0xe000
	s_nop 0
	global_load_lds_dwordx4 v138, s[20:21]
	s_waitcnt vmcnt(8)
	s_waitcnt lgkmcnt(0)
	s_barrier
	s_waitcnt lgkmcnt(0)
	v_mfma_f32_16x16x32_bf16 v[124:127], v[154:157], v[186:189], v[124:127]
	v_mfma_f32_16x16x32_bf16 v[116:119], v[162:165], v[186:189], v[116:119]
	v_mfma_f32_16x16x32_bf16 v[108:111], v[154:157], v[198:201], v[108:111]
	v_mfma_f32_16x16x32_bf16 v[100:103], v[162:165], v[198:201], v[100:103]
	v_mfma_f32_16x16x32_bf16 v[92:95], v[154:157], v[206:209], v[92:95]
	v_mfma_f32_16x16x32_bf16 v[84:87], v[162:165], v[206:209], v[84:87]
	v_mfma_f32_16x16x32_bf16 v[76:79], v[154:157], v[214:217], v[76:79]
	v_mfma_f32_16x16x32_bf16 v[68:71], v[162:165], v[214:217], v[68:71]
	v_mfma_f32_16x16x32_bf16 v[124:127], v[158:161], v[190:193], v[124:127]
	v_mfma_f32_16x16x32_bf16 v[116:119], v[166:169], v[190:193], v[116:119]
	v_mfma_f32_16x16x32_bf16 v[108:111], v[158:161], v[202:205], v[108:111]
	v_mfma_f32_16x16x32_bf16 v[100:103], v[166:169], v[202:205], v[100:103]
	v_mfma_f32_16x16x32_bf16 v[92:95], v[158:161], v[210:213], v[92:95]
	v_mfma_f32_16x16x32_bf16 v[84:87], v[166:169], v[210:213], v[84:87]
	v_mfma_f32_16x16x32_bf16 v[76:79], v[158:161], v[218:221], v[76:79]
	v_mfma_f32_16x16x32_bf16 v[68:71], v[166:169], v[218:221], v[68:71]
	v_mfma_f32_16x16x32_bf16 v[120:123], v[170:173], v[186:189], v[120:123]
	v_mfma_f32_16x16x32_bf16 v[112:115], v[178:181], v[186:189], v[112:115]
	v_mfma_f32_16x16x32_bf16 v[104:107], v[170:173], v[198:201], v[104:107]
	v_mfma_f32_16x16x32_bf16 v[96:99], v[178:181], v[198:201], v[96:99]
	v_mfma_f32_16x16x32_bf16 v[88:91], v[170:173], v[206:209], v[88:91]
	v_mfma_f32_16x16x32_bf16 v[80:83], v[178:181], v[206:209], v[80:83]
	v_mfma_f32_16x16x32_bf16 v[72:75], v[170:173], v[214:217], v[72:75]
	v_mfma_f32_16x16x32_bf16 v[64:67], v[178:181], v[214:217], v[64:67]
	v_mfma_f32_16x16x32_bf16 v[120:123], v[174:177], v[190:193], v[120:123]
	v_mfma_f32_16x16x32_bf16 v[112:115], v[182:185], v[190:193], v[112:115]
	v_mfma_f32_16x16x32_bf16 v[104:107], v[174:177], v[202:205], v[104:107]
	v_mfma_f32_16x16x32_bf16 v[96:99], v[182:185], v[202:205], v[96:99]
	v_mfma_f32_16x16x32_bf16 v[88:91], v[174:177], v[210:213], v[88:91]
	v_mfma_f32_16x16x32_bf16 v[80:83], v[182:185], v[210:213], v[80:83]
	v_mfma_f32_16x16x32_bf16 v[72:75], v[174:177], v[218:221], v[72:75]
	v_mfma_f32_16x16x32_bf16 v[64:67], v[182:185], v[218:221], v[64:67]
	s_barrier
; #define PG8_STAGE(bufoff, gbase, voff) do { _Pragma("unroll") for (int _i = 0; _i < 2; ++_i) \
;         __builtin_amdgcn_global_load_lds((const unsigned*)((const char*)(gbase) + (voff)[_i]), (PG8_LAS unsigned*)(lds + (bufoff) + ldsw + _i * 8192), 16, 0, 0); } while (0)
; #define PG8_LDA(dst, b, h) do { _Pragma("unroll") for (int m = 0; m < 4; ++m) _Pragma("unroll") for (int k = 0; k < 2; ++k) dst[m][k] = *(const PG8_LAS bf16x8*)(lds + PG8_SA(b, h) + aoff + m * 2048 + k * 1024); } while (0)
; #define PG8_LDB(dst, b, h) do { _Pragma("unroll") for (int n = 0; n < 2; ++n) _Pragma("unroll") for (int k = 0; k < 2; ++k) dst[n][k] = *(const PG8_LAS bf16x8*)(lds + PG8_SB(b, h) + boff + n * 2048 + k * 1024); } while (0)
; #define PG8_MMA(ai, bj, At, Bt) do { __builtin_amdgcn_s_setprio(1); _Pragma("unroll") for (int m = 0; m < 4; ++m) _Pragma("unroll") for (int n = 0; n < 2; ++n) _Pragma("unroll") for (int k = 0; k < 2; ++k) \
;         acc[ai][bj][m][n] = __builtin_amdgcn_mfma_f32_16x16x32_bf16(Bt[n][k], At[m][k], acc[ai][bj][m][n], 0, 0, 0); __builtin_amdgcn_s_setprio(0); } while (0)
; #define PG8_WAIT_V(n) asm volatile("s_waitcnt vmcnt(" #n ")" ::: "memory")
; #define PG8_WAIT_L(n) asm volatile("s_waitcnt lgkmcnt(" #n ")" ::: "memory")
; #define PG8_BAR __builtin_amdgcn_s_barrier()
; #define PG8_SCHED __builtin_amdgcn_sched_barrier(0)
; template <class Epi, class Sched, bool ALIGN_EPI = false, bool SP2 = false>
; __device__ __forceinline__ void gemm_phase(PG8_LAS unsigned char* lds, const Gemm g, const Sched& S, const Epi& E) {
;     ...
;             PG8_LDA(At, 0, 1); PG8_STAGE(PG8_SB(0, 0), b2, voffB); PG8_STAGE(PG8_SB(0, 1), b2 + hstep, voffB); PG8_STAGE(PG8_SA(0, 0), a2, voffA);
;             PG8_WAIT_V(8); PG8_WAIT_L(0); PG8_BAR; PG8_MMA(1, 0, At, B0); PG8_MMA(1, 1, At, B1); PG8_BAR; PG8_SCHED;
;             PG8_LDB(B0, 1, 0); PG8_LDB(B1, 1, 1); PG8_SCHED; PG8_LDA(At, 1, 0); PG8_STAGE(PG8_SA(0, 1), a2 + hstep, voffA);
;             PG8_WAIT_V(8); PG8_WAIT_L(0); PG8_BAR; PG8_MMA(0, 0, At, B0); PG8_MMA(0, 1, At, B1); PG8_BAR; PG8_SCHED;
	s_add_i32 s73, s63, s55
	s_add_u32 s98, s42, s8
	s_addc_u32 s99, s43, s9
	s_add_u32 s100, s46, s8
	s_addc_u32 s101, s47, s9
	s_mov_b32 m0, s73
	ds_read_b128 v[186:189], v152 offset:16384
	ds_read_b128 v[190:193], v152 offset:17408
	ds_read_b128 v[198:201], v152 offset:18432
	ds_read_b128 v[202:205], v152 offset:19456
	ds_read_b128 v[206:209], v152 offset:20480
	ds_read_b128 v[210:213], v152 offset:21504
	ds_read_b128 v[214:217], v152 offset:22528
	ds_read_b128 v[218:221], v152 offset:23552
	global_load_lds_dwordx4 v132, s[42:43]
	s_add_i32 m0, s73, 0x2000
	s_add_u32 s74, s42, 0x40000
	s_addc_u32 s75, s43, 0
	s_add_i32 s73, s64, s55
	global_load_lds_dwordx4 v128, s[42:43]
	s_mov_b32 m0, s73
	s_nop 0
	global_load_lds_dwordx4 v132, s[74:75]
	s_add_i32 m0, s73, 0x2000
	s_nop 0
	global_load_lds_dwordx4 v128, s[74:75]
	s_mov_b32 m0, s35
	s_nop 0
	global_load_lds_dwordx4 v134, s[46:47]
	s_mov_b32 m0, s57
	s_nop 0
	global_load_lds_dwordx4 v130, s[46:47]
	s_waitcnt vmcnt(8)
	s_waitcnt lgkmcnt(0)
	s_barrier
	s_waitcnt lgkmcnt(0)
	v_mfma_f32_16x16x32_bf16 v[60:63], v[154:157], v[186:189], v[60:63]
	v_mfma_f32_16x16x32_bf16 v[52:55], v[162:165], v[186:189], v[52:55]
	v_mfma_f32_16x16x32_bf16 v[44:47], v[154:157], v[198:201], v[44:47]
	v_mfma_f32_16x16x32_bf16 v[36:39], v[162:165], v[198:201], v[36:39]
	v_mfma_f32_16x16x32_bf16 v[28:31], v[154:157], v[206:209], v[28:31]
	v_mfma_f32_16x16x32_bf16 v[20:23], v[162:165], v[206:209], v[20:23]
	v_mfma_f32_16x16x32_bf16 v[12:15], v[154:157], v[214:217], v[12:15]
	v_mfma_f32_16x16x32_bf16 v[4:7], v[162:165], v[214:217], v[4:7]
	v_mfma_f32_16x16x32_bf16 v[60:63], v[158:161], v[190:193], v[60:63]
	v_mfma_f32_16x16x32_bf16 v[52:55], v[166:169], v[190:193], v[52:55]
	v_mfma_f32_16x16x32_bf16 v[44:47], v[158:161], v[202:205], v[44:47]
	v_mfma_f32_16x16x32_bf16 v[36:39], v[166:169], v[202:205], v[36:39]
	v_mfma_f32_16x16x32_bf16 v[28:31], v[158:161], v[210:213], v[28:31]
	v_mfma_f32_16x16x32_bf16 v[20:23], v[166:169], v[210:213], v[20:23]
	v_mfma_f32_16x16x32_bf16 v[12:15], v[158:161], v[218:221], v[12:15]
	v_mfma_f32_16x16x32_bf16 v[4:7], v[166:169], v[218:221], v[4:7]
	v_mfma_f32_16x16x32_bf16 v[56:59], v[170:173], v[186:189], v[56:59]
	v_mfma_f32_16x16x32_bf16 v[48:51], v[178:181], v[186:189], v[48:51]
	v_mfma_f32_16x16x32_bf16 v[40:43], v[170:173], v[198:201], v[40:43]
	v_mfma_f32_16x16x32_bf16 v[32:35], v[178:181], v[198:201], v[32:35]
	v_mfma_f32_16x16x32_bf16 v[24:27], v[170:173], v[206:209], v[24:27]
	v_mfma_f32_16x16x32_bf16 v[16:19], v[178:181], v[206:209], v[16:19]
	v_mfma_f32_16x16x32_bf16 v[8:11], v[170:173], v[214:217], v[8:11]
	v_mfma_f32_16x16x32_bf16 v[0:3], v[178:181], v[214:217], v[0:3]
	v_mfma_f32_16x16x32_bf16 v[56:59], v[174:177], v[190:193], v[56:59]
	v_mfma_f32_16x16x32_bf16 v[48:51], v[182:185], v[190:193], v[48:51]
	v_mfma_f32_16x16x32_bf16 v[40:43], v[174:177], v[202:205], v[40:43]
	v_mfma_f32_16x16x32_bf16 v[32:35], v[182:185], v[202:205], v[32:35]
	v_mfma_f32_16x16x32_bf16 v[24:27], v[174:177], v[210:213], v[24:27]
	v_mfma_f32_16x16x32_bf16 v[16:19], v[182:185], v[210:213], v[16:19]
	v_mfma_f32_16x16x32_bf16 v[8:11], v[174:177], v[218:221], v[8:11]
	v_mfma_f32_16x16x32_bf16 v[0:3], v[182:185], v[218:221], v[0:3]
	s_barrier
	s_add_i32 s73, 0, 0x18000
	v_add_u32_e32 v153, s73, v147
	s_add_i32 s74, 0, 0x1c000
	ds_read_b128 v[154:157], v153
	ds_read_b128 v[158:161], v153 offset:1024
	ds_read_b128 v[162:165], v153 offset:2048
	ds_read_b128 v[166:169], v153 offset:3072
	v_add_u32_e32 v153, s74, v147
	ds_read_b128 v[170:173], v153
	ds_read_b128 v[174:177], v153 offset:1024
	ds_read_b128 v[178:181], v153 offset:2048
	ds_read_b128 v[182:185], v153 offset:3072
	s_add_u32 s46, s46, 0x40000
	s_addc_u32 s47, s47, 0
	s_mov_b32 m0, s58
	ds_read_b128 v[186:189], v152 offset:32768
	ds_read_b128 v[190:193], v152 offset:33792
	ds_read_b128 v[198:201], v152 offset:34816
	ds_read_b128 v[202:205], v152 offset:35840
	ds_read_b128 v[206:209], v152 offset:36864
	ds_read_b128 v[210:213], v152 offset:37888
	ds_read_b128 v[214:217], v152 offset:38912
	ds_read_b128 v[218:221], v152 offset:39936
	global_load_lds_dwordx4 v134, s[46:47]
	s_mov_b32 m0, s59
	s_nop 0
	global_load_lds_dwordx4 v130, s[46:47]
	s_waitcnt vmcnt(8)
	s_waitcnt lgkmcnt(0)
	s_barrier
; #define PG8_STAGE(bufoff, gbase, voff) do { _Pragma("unroll") for (int _i = 0; _i < 2; ++_i) \
;         __builtin_amdgcn_global_load_lds((const unsigned*)((const char*)(gbase) + (voff)[_i]), (PG8_LAS unsigned*)(lds + (bufoff) + ldsw + _i * 8192), 16, 0, 0); } while (0)
; #define PG8_LDA(dst, b, h) do { _Pragma("unroll") for (int m = 0; m < 4; ++m) _Pragma("unroll") for (int k = 0; k < 2; ++k) dst[m][k] = *(const PG8_LAS bf16x8*)(lds + PG8_SA(b, h) + aoff + m * 2048 + k * 1024); } while (0)
; #define PG8_MMA(ai, bj, At, Bt) do { __builtin_amdgcn_s_setprio(1); _Pragma("unroll") for (int m = 0; m < 4; ++m) _Pragma("unroll") for (int n = 0; n < 2; ++n) _Pragma("unroll") for (int k = 0; k < 2; ++k) \
;         acc[ai][bj][m][n] = __builtin_amdgcn_mfma_f32_16x16x32_bf16(Bt[n][k], At[m][k], acc[ai][bj][m][n], 0, 0, 0); __builtin_amdgcn_s_setprio(0); } while (0)
; #define PG8_WAIT_V(n) asm volatile("s_waitcnt vmcnt(" #n ")" ::: "memory")
; #define PG8_WAIT_L(n) asm volatile("s_waitcnt lgkmcnt(" #n ")" ::: "memory")
; #define PG8_BAR __builtin_amdgcn_s_barrier()
; #define PG8_SCHED __builtin_amdgcn_sched_barrier(0)
; template <class Epi, class Sched, bool ALIGN_EPI = false, bool SP2 = false>
; __device__ __forceinline__ void gemm_phase(PG8_LAS unsigned char* lds, const Gemm g, const Sched& S, const Epi& E) {
;     ...
;             PG8_WAIT_V(8); PG8_WAIT_L(0); PG8_BAR; PG8_MMA(0, 0, At, B0); PG8_MMA(0, 1, At, B1); PG8_BAR; PG8_SCHED;
;             PG8_LDA(At, 1, 1); PG8_STAGE(PG8_SB(1, 0), b3, voffB); PG8_STAGE(PG8_SB(1, 1), b3 + hstep, voffB); PG8_STAGE(PG8_SA(1, 0), a3, voffA);
;             PG8_WAIT_V(8); PG8_WAIT_L(0); PG8_BAR; PG8_MMA(1, 0, At, B0); PG8_MMA(1, 1, At, B1); PG8_BAR; PG8_SCHED;
;     ...
;         if constexpr (ALIGN_EPI) { if (wr == 0) PG8_BAR; }
	s_waitcnt lgkmcnt(0)
	v_mfma_f32_16x16x32_bf16 v[124:127], v[154:157], v[186:189], v[124:127]
	v_mfma_f32_16x16x32_bf16 v[116:119], v[162:165], v[186:189], v[116:119]
	v_mfma_f32_16x16x32_bf16 v[108:111], v[154:157], v[198:201], v[108:111]
	v_mfma_f32_16x16x32_bf16 v[100:103], v[162:165], v[198:201], v[100:103]
	v_mfma_f32_16x16x32_bf16 v[92:95], v[154:157], v[206:209], v[92:95]
	v_mfma_f32_16x16x32_bf16 v[84:87], v[162:165], v[206:209], v[84:87]
	v_mfma_f32_16x16x32_bf16 v[76:79], v[154:157], v[214:217], v[76:79]
	v_mfma_f32_16x16x32_bf16 v[68:71], v[162:165], v[214:217], v[68:71]
	v_mfma_f32_16x16x32_bf16 v[124:127], v[158:161], v[190:193], v[124:127]
	v_mfma_f32_16x16x32_bf16 v[116:119], v[166:169], v[190:193], v[116:119]
	v_mfma_f32_16x16x32_bf16 v[108:111], v[158:161], v[202:205], v[108:111]
	v_mfma_f32_16x16x32_bf16 v[100:103], v[166:169], v[202:205], v[100:103]
	v_mfma_f32_16x16x32_bf16 v[92:95], v[158:161], v[210:213], v[92:95]
	v_mfma_f32_16x16x32_bf16 v[84:87], v[166:169], v[210:213], v[84:87]
	v_mfma_f32_16x16x32_bf16 v[76:79], v[158:161], v[218:221], v[76:79]
	v_mfma_f32_16x16x32_bf16 v[68:71], v[166:169], v[218:221], v[68:71]
	v_mfma_f32_16x16x32_bf16 v[120:123], v[170:173], v[186:189], v[120:123]
	v_mfma_f32_16x16x32_bf16 v[112:115], v[178:181], v[186:189], v[112:115]
	v_mfma_f32_16x16x32_bf16 v[104:107], v[170:173], v[198:201], v[104:107]
	v_mfma_f32_16x16x32_bf16 v[96:99], v[178:181], v[198:201], v[96:99]
	v_mfma_f32_16x16x32_bf16 v[88:91], v[170:173], v[206:209], v[88:91]
	v_mfma_f32_16x16x32_bf16 v[80:83], v[178:181], v[206:209], v[80:83]
	v_mfma_f32_16x16x32_bf16 v[72:75], v[170:173], v[214:217], v[72:75]
	v_mfma_f32_16x16x32_bf16 v[64:67], v[178:181], v[214:217], v[64:67]
	v_mfma_f32_16x16x32_bf16 v[120:123], v[174:177], v[190:193], v[120:123]
	v_mfma_f32_16x16x32_bf16 v[112:115], v[182:185], v[190:193], v[112:115]
	v_mfma_f32_16x16x32_bf16 v[104:107], v[174:177], v[202:205], v[104:107]
	v_mfma_f32_16x16x32_bf16 v[96:99], v[182:185], v[202:205], v[96:99]
	v_mfma_f32_16x16x32_bf16 v[88:91], v[174:177], v[210:213], v[88:91]
	v_mfma_f32_16x16x32_bf16 v[80:83], v[182:185], v[210:213], v[80:83]
	v_mfma_f32_16x16x32_bf16 v[72:75], v[174:177], v[218:221], v[72:75]
	v_mfma_f32_16x16x32_bf16 v[64:67], v[182:185], v[218:221], v[64:67]
	s_barrier
	s_add_i32 s46, s73, s55
	s_mov_b32 m0, s46
	ds_read_b128 v[186:189], v152 offset:49152
	ds_read_b128 v[190:193], v152 offset:50176
	ds_read_b128 v[198:201], v152 offset:51200
	ds_read_b128 v[202:205], v152 offset:52224
	ds_read_b128 v[206:209], v152 offset:53248
	ds_read_b128 v[210:213], v152 offset:54272
	ds_read_b128 v[214:217], v152 offset:55296
	ds_read_b128 v[218:221], v152 offset:56320
	global_load_lds_dwordx4 v132, s[98:99]
	s_add_i32 m0, s46, 0x2000
	s_add_u32 s42, s42, 0x40080
	s_addc_u32 s43, s43, 0
	s_add_i32 s46, s74, s55
	global_load_lds_dwordx4 v128, s[98:99]
	s_mov_b32 m0, s46
	s_nop 0
	global_load_lds_dwordx4 v132, s[42:43]
	s_add_i32 m0, s46, 0x2000
	s_nop 0
	global_load_lds_dwordx4 v128, s[42:43]
	s_mov_b32 m0, s61
	s_nop 0
	global_load_lds_dwordx4 v134, s[100:101]
	s_mov_b32 m0, s62
	s_nop 0
	global_load_lds_dwordx4 v130, s[100:101]
	s_waitcnt vmcnt(8)
	s_waitcnt lgkmcnt(0)
	s_barrier
	s_waitcnt lgkmcnt(0)
	v_mfma_f32_16x16x32_bf16 v[60:63], v[154:157], v[186:189], v[60:63]
	v_mfma_f32_16x16x32_bf16 v[52:55], v[162:165], v[186:189], v[52:55]
	v_mfma_f32_16x16x32_bf16 v[44:47], v[154:157], v[198:201], v[44:47]
	v_mfma_f32_16x16x32_bf16 v[36:39], v[162:165], v[198:201], v[36:39]
	v_mfma_f32_16x16x32_bf16 v[28:31], v[154:157], v[206:209], v[28:31]
	v_mfma_f32_16x16x32_bf16 v[20:23], v[162:165], v[206:209], v[20:23]
	v_mfma_f32_16x16x32_bf16 v[12:15], v[154:157], v[214:217], v[12:15]
	v_mfma_f32_16x16x32_bf16 v[4:7], v[162:165], v[214:217], v[4:7]
	v_mfma_f32_16x16x32_bf16 v[60:63], v[158:161], v[190:193], v[60:63]
	v_mfma_f32_16x16x32_bf16 v[52:55], v[166:169], v[190:193], v[52:55]
	v_mfma_f32_16x16x32_bf16 v[44:47], v[158:161], v[202:205], v[44:47]
	v_mfma_f32_16x16x32_bf16 v[36:39], v[166:169], v[202:205], v[36:39]
	v_mfma_f32_16x16x32_bf16 v[28:31], v[158:161], v[210:213], v[28:31]
	v_mfma_f32_16x16x32_bf16 v[20:23], v[166:169], v[210:213], v[20:23]
	v_mfma_f32_16x16x32_bf16 v[12:15], v[158:161], v[218:221], v[12:15]
	v_mfma_f32_16x16x32_bf16 v[4:7], v[166:169], v[218:221], v[4:7]
	v_mfma_f32_16x16x32_bf16 v[56:59], v[170:173], v[186:189], v[56:59]
	v_mfma_f32_16x16x32_bf16 v[48:51], v[178:181], v[186:189], v[48:51]
	v_mfma_f32_16x16x32_bf16 v[40:43], v[170:173], v[198:201], v[40:43]
	v_mfma_f32_16x16x32_bf16 v[32:35], v[178:181], v[198:201], v[32:35]
	v_mfma_f32_16x16x32_bf16 v[24:27], v[170:173], v[206:209], v[24:27]
	v_mfma_f32_16x16x32_bf16 v[16:19], v[178:181], v[206:209], v[16:19]
	v_mfma_f32_16x16x32_bf16 v[8:11], v[170:173], v[214:217], v[8:11]
	v_mfma_f32_16x16x32_bf16 v[0:3], v[178:181], v[214:217], v[0:3]
	v_mfma_f32_16x16x32_bf16 v[56:59], v[174:177], v[190:193], v[56:59]
	v_mfma_f32_16x16x32_bf16 v[48:51], v[182:185], v[190:193], v[48:51]
	v_mfma_f32_16x16x32_bf16 v[40:43], v[174:177], v[202:205], v[40:43]
	v_mfma_f32_16x16x32_bf16 v[32:35], v[182:185], v[202:205], v[32:35]
	v_mfma_f32_16x16x32_bf16 v[24:27], v[174:177], v[210:213], v[24:27]
	v_mfma_f32_16x16x32_bf16 v[16:19], v[182:185], v[210:213], v[16:19]
	v_mfma_f32_16x16x32_bf16 v[8:11], v[174:177], v[218:221], v[8:11]
	v_mfma_f32_16x16x32_bf16 v[0:3], v[182:185], v[218:221], v[0:3]
	s_barrier
	s_add_i32 s72, s72, 2
	s_add_u32 s20, s20, 0x100
	s_addc_u32 s21, s21, 0
	s_add_u32 s70, s70, 0x100
	s_addc_u32 s71, s71, 0
	s_cmp_gt_u32 s72, 13
	s_cbranch_scc0 .LBB0_224
	s_and_b64 vcc, exec, s[10:11]
	s_cbranch_vccz .LBB0_227
	s_barrier

; #define PG8_STAGE(bufoff, gbase, voff) do { _Pragma("unroll") for (int _i = 0; _i < 2; ++_i) \
;         __builtin_amdgcn_global_load_lds((const unsigned*)((const char*)(gbase) + (voff)[_i]), (PG8_LAS unsigned*)(lds + (bufoff) + ldsw + _i * 8192), 16, 0, 0); } while (0)
; #define PG8_LDA(dst, b, h) do { _Pragma("unroll") for (int m = 0; m < 4; ++m) _Pragma("unroll") for (int k = 0; k < 2; ++k) dst[m][k] = *(const PG8_LAS bf16x8*)(lds + PG8_SA(b, h) + aoff + m * 2048 + k * 1024); } while (0)
; #define PG8_LDB(dst, b, h) do { _Pragma("unroll") for (int n = 0; n < 2; ++n) _Pragma("unroll") for (int k = 0; k < 2; ++k) dst[n][k] = *(const PG8_LAS bf16x8*)(lds + PG8_SB(b, h) + boff + n * 2048 + k * 1024); } while (0)
; #define PG8_MMA(ai, bj, At, Bt) do { __builtin_amdgcn_s_setprio(1); _Pragma("unroll") for (int m = 0; m < 4; ++m) _Pragma("unroll") for (int n = 0; n < 2; ++n) _Pragma("unroll") for (int k = 0; k < 2; ++k) \
;         acc[ai][bj][m][n] = __builtin_amdgcn_mfma_f32_16x16x32_bf16(Bt[n][k], At[m][k], acc[ai][bj][m][n], 0, 0, 0); __builtin_amdgcn_s_setprio(0); } while (0)
; #define PG8_WAIT_V(n) asm volatile("s_waitcnt vmcnt(" #n ")" ::: "memory")
; #define PG8_BAR __builtin_amdgcn_s_barrier()
; template <class Epi, class Sched, bool ALIGN_EPI = false, bool SP2 = false>
; __device__ __forceinline__ void gemm_phase(PG8_LAS unsigned char* lds, const Gemm g, const Sched& S, const Epi& E) {
;     ...
;         for (int t = 0; t < nt; t += 2) {
;             const bool last = (t == nt - 2);
;             const char* a1 = cA + (size_t)(t + 1) * kstep;
;             const char* a2 = last ? nA : cA + (size_t)(t + 2) * kstep; const char* b2 = last ? nB : cB + (size_t)(t + 2) * kstep;
;             const char* a3 = a2 + kstep; const char* b3 = b2 + kstep;
;             if (last && has_next) S.a_ready(nxt);
;             if constexpr (SP2) {
;             PG8_LDB(B0, 0, 0); PG8_LDB(B1, 0, 1); PG8_SCHED; PG8_LDA(At, 0, 0); PG8_STAGE(PG8_SA(1, 1), a1 + hstep, voffA);
;             PG8_WAIT_V(8); PG8_WAIT_L(0); PG8_BAR; PG8_MMA(0, 0, At, B0); PG8_MMA(0, 1, At, B1); PG8_BAR; PG8_SCHED;
;             PG8_LDA(At, 0, 1); PG8_STAGE(PG8_SB(0, 0), b2, voffB); PG8_STAGE(PG8_SB(0, 1), b2 + hstep, voffB); PG8_STAGE(PG8_SA(0, 0), a2, voffA);
;             PG8_WAIT_V(8); PG8_WAIT_L(0); PG8_BAR; PG8_MMA(1, 0, At, B0); PG8_MMA(1, 1, At, B1); PG8_BAR; PG8_SCHED;
.LBB0_308:
	s_add_u32 s20, s20, 0xb0080
	s_addc_u32 s21, s21, 0
	s_add_u32 s73, s34, 0x100
	s_addc_u32 s74, s35, 0
	s_mov_b32 s75, -2
	s_waitcnt lgkmcnt(0)
	s_waitcnt lgkmcnt(0)
	ds_read_b128 v[96:99], v223
	ds_read_b128 v[108:111], v223 offset:1024
	ds_read_b128 v[120:123], v223 offset:2048
	ds_read_b128 v[128:131], v223 offset:3072
	ds_read_b128 v[144:147], v224
	ds_read_b128 v[148:151], v224 offset:1024
	ds_read_b128 v[152:155], v224 offset:2048
	ds_read_b128 v[156:159], v224 offset:3072
	s_add_u32 s34, s20, 0xfff50080
	s_addc_u32 s35, s21, -1
	s_cmp_eq_u32 s75, 40
	s_cselect_b32 s51, s1, s35
	s_cselect_b32 s50, s0, s34
	s_cselect_b32 s35, s49, s74
	s_cselect_b32 s34, s48, s73
	s_add_i32 m0, s54, 0xc000
	ds_read_b128 v[160:163], v225
	ds_read_b128 v[164:167], v225 offset:1024
	ds_read_b128 v[168:171], v225 offset:2048
	ds_read_b128 v[172:175], v225 offset:3072
	ds_read_b128 v[176:179], v225 offset:4096
	ds_read_b128 v[180:183], v225 offset:5120
	ds_read_b128 v[202:205], v225 offset:6144
	ds_read_b128 v[206:209], v225 offset:7168
	global_load_lds_dwordx4 v192, s[20:21]
	s_add_i32 m0, s54, 0xe000
	s_nop 0
	global_load_lds_dwordx4 v194, s[20:21]
	s_waitcnt vmcnt(8)
	s_waitcnt lgkmcnt(0)
	s_barrier
	s_waitcnt lgkmcnt(0)
	v_mfma_f32_16x16x32_bf16 v[140:143], v[96:99], v[160:163], 0
	v_mfma_f32_16x16x32_bf16 v[136:139], v[120:123], v[160:163], 0
	v_mfma_f32_16x16x32_bf16 v[116:119], v[96:99], v[168:171], 0
	v_mfma_f32_16x16x32_bf16 v[112:115], v[120:123], v[168:171], 0
	v_mfma_f32_16x16x32_bf16 v[92:95], v[96:99], v[176:179], 0
	v_mfma_f32_16x16x32_bf16 v[88:91], v[120:123], v[176:179], 0
	v_mfma_f32_16x16x32_bf16 v[76:79], v[96:99], v[202:205], 0
	v_mfma_f32_16x16x32_bf16 v[72:75], v[120:123], v[202:205], 0
	v_mfma_f32_16x16x32_bf16 v[140:143], v[108:111], v[164:167], v[140:143]
	v_mfma_f32_16x16x32_bf16 v[136:139], v[128:131], v[164:167], v[136:139]
	v_mfma_f32_16x16x32_bf16 v[116:119], v[108:111], v[172:175], v[116:119]
	v_mfma_f32_16x16x32_bf16 v[112:115], v[128:131], v[172:175], v[112:115]
	v_mfma_f32_16x16x32_bf16 v[92:95], v[108:111], v[180:183], v[92:95]
	v_mfma_f32_16x16x32_bf16 v[88:91], v[128:131], v[180:183], v[88:91]
	v_mfma_f32_16x16x32_bf16 v[76:79], v[108:111], v[206:209], v[76:79]
	v_mfma_f32_16x16x32_bf16 v[72:75], v[128:131], v[206:209], v[72:75]
	v_mfma_f32_16x16x32_bf16 v[132:135], v[144:147], v[160:163], 0
	v_mfma_f32_16x16x32_bf16 v[124:127], v[152:155], v[160:163], 0
	v_mfma_f32_16x16x32_bf16 v[104:107], v[144:147], v[168:171], 0
	v_mfma_f32_16x16x32_bf16 v[100:103], v[152:155], v[168:171], 0
	v_mfma_f32_16x16x32_bf16 v[84:87], v[144:147], v[176:179], 0
	v_mfma_f32_16x16x32_bf16 v[80:83], v[152:155], v[176:179], 0
	v_mfma_f32_16x16x32_bf16 v[68:71], v[144:147], v[202:205], 0
	v_mfma_f32_16x16x32_bf16 v[64:67], v[152:155], v[202:205], 0
	v_mfma_f32_16x16x32_bf16 v[132:135], v[148:151], v[164:167], v[132:135]
	v_mfma_f32_16x16x32_bf16 v[124:127], v[156:159], v[164:167], v[124:127]
	v_mfma_f32_16x16x32_bf16 v[104:107], v[148:151], v[172:175], v[104:107]
	v_mfma_f32_16x16x32_bf16 v[100:103], v[156:159], v[172:175], v[100:103]
	v_mfma_f32_16x16x32_bf16 v[84:87], v[148:151], v[180:183], v[84:87]
	v_mfma_f32_16x16x32_bf16 v[80:83], v[156:159], v[180:183], v[80:83]
	v_mfma_f32_16x16x32_bf16 v[68:71], v[148:151], v[206:209], v[68:71]
	v_mfma_f32_16x16x32_bf16 v[64:67], v[156:159], v[206:209], v[64:67]
	s_barrier
	s_add_i32 s76, s67, s53
	s_add_u32 s98, s34, s12
	s_addc_u32 s99, s35, s13
	s_add_u32 s100, s50, s12
	s_addc_u32 s101, s51, s13
	s_mov_b32 m0, s76
	ds_read_b128 v[160:163], v225 offset:16384
	ds_read_b128 v[164:167], v225 offset:17408
	ds_read_b128 v[168:171], v225 offset:18432
	ds_read_b128 v[172:175], v225 offset:19456
	ds_read_b128 v[176:179], v225 offset:20480
	ds_read_b128 v[180:183], v225 offset:21504
	ds_read_b128 v[202:205], v225 offset:22528
	ds_read_b128 v[206:209], v225 offset:23552
	global_load_lds_dwordx4 v186, s[34:35]
	s_add_i32 m0, s76, 0x2000
	s_add_u32 s76, s34, 0xb0000
	s_addc_u32 s77, s35, 0
	s_add_i32 s78, s68, s53
	global_load_lds_dwordx4 v190, s[34:35]
	s_mov_b32 m0, s78
	s_nop 0
	global_load_lds_dwordx4 v186, s[76:77]
	s_add_i32 m0, s78, 0x2000
	s_nop 0
	global_load_lds_dwordx4 v190, s[76:77]
	s_mov_b32 m0, s54
	s_nop 0
	global_load_lds_dwordx4 v184, s[50:51]
	s_mov_b32 m0, s55
	s_nop 0
	global_load_lds_dwordx4 v188, s[50:51]
	s_waitcnt vmcnt(8)
	s_waitcnt lgkmcnt(0)
	s_barrier
	s_waitcnt lgkmcnt(0)
	v_mfma_f32_16x16x32_bf16 v[60:63], v[96:99], v[160:163], 0
	v_mfma_f32_16x16x32_bf16 v[56:59], v[120:123], v[160:163], 0
	v_mfma_f32_16x16x32_bf16 v[44:47], v[96:99], v[168:171], 0
	v_mfma_f32_16x16x32_bf16 v[40:43], v[120:123], v[168:171], 0
	v_mfma_f32_16x16x32_bf16 v[28:31], v[96:99], v[176:179], 0
	v_mfma_f32_16x16x32_bf16 v[24:27], v[120:123], v[176:179], 0
	v_mfma_f32_16x16x32_bf16 v[12:15], v[96:99], v[202:205], 0
	v_mfma_f32_16x16x32_bf16 v[8:11], v[120:123], v[202:205], 0
	v_mfma_f32_16x16x32_bf16 v[60:63], v[108:111], v[164:167], v[60:63]
	v_mfma_f32_16x16x32_bf16 v[56:59], v[128:131], v[164:167], v[56:59]
	v_mfma_f32_16x16x32_bf16 v[44:47], v[108:111], v[172:175], v[44:47]
	v_mfma_f32_16x16x32_bf16 v[40:43], v[128:131], v[172:175], v[40:43]
	v_mfma_f32_16x16x32_bf16 v[28:31], v[108:111], v[180:183], v[28:31]
	v_mfma_f32_16x16x32_bf16 v[24:27], v[128:131], v[180:183], v[24:27]
	v_mfma_f32_16x16x32_bf16 v[12:15], v[108:111], v[206:209], v[12:15]
	v_mfma_f32_16x16x32_bf16 v[8:11], v[128:131], v[206:209], v[8:11]
	v_mfma_f32_16x16x32_bf16 v[52:55], v[144:147], v[160:163], 0
	v_mfma_f32_16x16x32_bf16 v[48:51], v[152:155], v[160:163], 0
	v_mfma_f32_16x16x32_bf16 v[36:39], v[144:147], v[168:171], 0
	v_mfma_f32_16x16x32_bf16 v[32:35], v[152:155], v[168:171], 0
	v_mfma_f32_16x16x32_bf16 v[20:23], v[144:147], v[176:179], 0
	v_mfma_f32_16x16x32_bf16 v[16:19], v[152:155], v[176:179], 0
	v_mfma_f32_16x16x32_bf16 v[4:7], v[144:147], v[202:205], 0
	v_mfma_f32_16x16x32_bf16 v[0:3], v[152:155], v[202:205], 0
	v_mfma_f32_16x16x32_bf16 v[52:55], v[148:151], v[164:167], v[52:55]
	v_mfma_f32_16x16x32_bf16 v[48:51], v[156:159], v[164:167], v[48:51]
	v_mfma_f32_16x16x32_bf16 v[36:39], v[148:151], v[172:175], v[36:39]
	v_mfma_f32_16x16x32_bf16 v[32:35], v[156:159], v[172:175], v[32:35]
	v_mfma_f32_16x16x32_bf16 v[20:23], v[148:151], v[180:183], v[20:23]
	v_mfma_f32_16x16x32_bf16 v[16:19], v[156:159], v[180:183], v[16:19]
	v_mfma_f32_16x16x32_bf16 v[4:7], v[148:151], v[206:209], v[4:7]
	v_mfma_f32_16x16x32_bf16 v[0:3], v[156:159], v[206:209], v[0:3]
	s_barrier
; #define PG8_STAGE(bufoff, gbase, voff) do { _Pragma("unroll") for (int _i = 0; _i < 2; ++_i) \
;         __builtin_amdgcn_global_load_lds((const unsigned*)((const char*)(gbase) + (voff)[_i]), (PG8_LAS unsigned*)(lds + (bufoff) + ldsw + _i * 8192), 16, 0, 0); } while (0)
; #define PG8_LDA(dst, b, h) do { _Pragma("unroll") for (int m = 0; m < 4; ++m) _Pragma("unroll") for (int k = 0; k < 2; ++k) dst[m][k] = *(const PG8_LAS bf16x8*)(lds + PG8_SA(b, h) + aoff + m * 2048 + k * 1024); } while (0)
; #define PG8_LDB(dst, b, h) do { _Pragma("unroll") for (int n = 0; n < 2; ++n) _Pragma("unroll") for (int k = 0; k < 2; ++k) dst[n][k] = *(const PG8_LAS bf16x8*)(lds + PG8_SB(b, h) + boff + n * 2048 + k * 1024); } while (0)
; #define PG8_MMA(ai, bj, At, Bt) do { __builtin_amdgcn_s_setprio(1); _Pragma("unroll") for (int m = 0; m < 4; ++m) _Pragma("unroll") for (int n = 0; n < 2; ++n) _Pragma("unroll") for (int k = 0; k < 2; ++k) \
;         acc[ai][bj][m][n] = __builtin_amdgcn_mfma_f32_16x16x32_bf16(Bt[n][k], At[m][k], acc[ai][bj][m][n], 0, 0, 0); __builtin_amdgcn_s_setprio(0); } while (0)
; #define PG8_WAIT_V(n) asm volatile("s_waitcnt vmcnt(" #n ")" ::: "memory")
; #define PG8_WAIT_L(n) asm volatile("s_waitcnt lgkmcnt(" #n ")" ::: "memory")
; #define PG8_BAR __builtin_amdgcn_s_barrier()
; #define PG8_SCHED __builtin_amdgcn_sched_barrier(0)
; template <class Epi, class Sched, bool ALIGN_EPI = false, bool SP2 = false>
; __device__ __forceinline__ void gemm_phase(PG8_LAS unsigned char* lds, const Gemm g, const Sched& S, const Epi& E) {
;     ...
;             PG8_LDB(B0, 1, 0); PG8_LDB(B1, 1, 1); PG8_SCHED; PG8_LDA(At, 1, 0); PG8_STAGE(PG8_SA(0, 1), a2 + hstep, voffA);
;             PG8_WAIT_V(8); PG8_WAIT_L(0); PG8_BAR; PG8_MMA(0, 0, At, B0); PG8_MMA(0, 1, At, B1); PG8_BAR; PG8_SCHED;
;             PG8_LDA(At, 1, 1); PG8_STAGE(PG8_SB(1, 0), b3, voffB); PG8_STAGE(PG8_SB(1, 1), b3 + hstep, voffB); PG8_STAGE(PG8_SA(1, 0), a3, voffA);
;             PG8_WAIT_V(8); PG8_WAIT_L(0); PG8_BAR; PG8_MMA(1, 0, At, B0); PG8_MMA(1, 1, At, B1); PG8_BAR; PG8_SCHED;
	s_add_i32 s76, 0, 0x18000
	s_add_i32 s77, 0, 0x1c000
	v_add_u32_e32 v128, s76, v221
	v_add_u32_e32 v156, s77, v221
	ds_read_b128 v[96:99], v128
	ds_read_b128 v[108:111], v128 offset:1024
	ds_read_b128 v[120:123], v128 offset:2048
	ds_read_b128 v[128:131], v128 offset:3072
	ds_read_b128 v[144:147], v156
	ds_read_b128 v[148:151], v156 offset:1024
	ds_read_b128 v[152:155], v156 offset:2048
	ds_read_b128 v[156:159], v156 offset:3072
	s_add_u32 s50, s50, 0xb0000
	s_addc_u32 s51, s51, 0
	s_mov_b32 m0, s56
	ds_read_b128 v[160:163], v225 offset:32768
	ds_read_b128 v[164:167], v225 offset:33792
	ds_read_b128 v[168:171], v225 offset:34816
	ds_read_b128 v[172:175], v225 offset:35840
	ds_read_b128 v[176:179], v225 offset:36864
	ds_read_b128 v[180:183], v225 offset:37888
	ds_read_b128 v[202:205], v225 offset:38912
	ds_read_b128 v[206:209], v225 offset:39936
	global_load_lds_dwordx4 v184, s[50:51]
	s_mov_b32 m0, s57
	s_nop 0
	global_load_lds_dwordx4 v188, s[50:51]
	s_waitcnt vmcnt(8)
	s_waitcnt lgkmcnt(0)
	s_barrier
	s_waitcnt lgkmcnt(0)
	v_mfma_f32_16x16x32_bf16 v[140:143], v[96:99], v[160:163], v[140:143]
	v_mfma_f32_16x16x32_bf16 v[136:139], v[120:123], v[160:163], v[136:139]
	v_mfma_f32_16x16x32_bf16 v[116:119], v[96:99], v[168:171], v[116:119]
	v_mfma_f32_16x16x32_bf16 v[112:115], v[120:123], v[168:171], v[112:115]
	v_mfma_f32_16x16x32_bf16 v[92:95], v[96:99], v[176:179], v[92:95]
	v_mfma_f32_16x16x32_bf16 v[88:91], v[120:123], v[176:179], v[88:91]
	v_mfma_f32_16x16x32_bf16 v[76:79], v[96:99], v[202:205], v[76:79]
	v_mfma_f32_16x16x32_bf16 v[72:75], v[120:123], v[202:205], v[72:75]
	v_mfma_f32_16x16x32_bf16 v[140:143], v[108:111], v[164:167], v[140:143]
	v_mfma_f32_16x16x32_bf16 v[136:139], v[128:131], v[164:167], v[136:139]
	v_mfma_f32_16x16x32_bf16 v[116:119], v[108:111], v[172:175], v[116:119]
	v_mfma_f32_16x16x32_bf16 v[112:115], v[128:131], v[172:175], v[112:115]
	v_mfma_f32_16x16x32_bf16 v[92:95], v[108:111], v[180:183], v[92:95]
	v_mfma_f32_16x16x32_bf16 v[88:91], v[128:131], v[180:183], v[88:91]
	v_mfma_f32_16x16x32_bf16 v[76:79], v[108:111], v[206:209], v[76:79]
	v_mfma_f32_16x16x32_bf16 v[72:75], v[128:131], v[206:209], v[72:75]
	v_mfma_f32_16x16x32_bf16 v[132:135], v[144:147], v[160:163], v[132:135]
	v_mfma_f32_16x16x32_bf16 v[124:127], v[152:155], v[160:163], v[124:127]
	v_mfma_f32_16x16x32_bf16 v[104:107], v[144:147], v[168:171], v[104:107]
	v_mfma_f32_16x16x32_bf16 v[100:103], v[152:155], v[168:171], v[100:103]
	v_mfma_f32_16x16x32_bf16 v[84:87], v[144:147], v[176:179], v[84:87]
	v_mfma_f32_16x16x32_bf16 v[80:83], v[152:155], v[176:179], v[80:83]
	v_mfma_f32_16x16x32_bf16 v[68:71], v[144:147], v[202:205], v[68:71]
	v_mfma_f32_16x16x32_bf16 v[64:67], v[152:155], v[202:205], v[64:67]
	v_mfma_f32_16x16x32_bf16 v[132:135], v[148:151], v[164:167], v[132:135]
	v_mfma_f32_16x16x32_bf16 v[124:127], v[156:159], v[164:167], v[124:127]
	v_mfma_f32_16x16x32_bf16 v[104:107], v[148:151], v[172:175], v[104:107]
	v_mfma_f32_16x16x32_bf16 v[100:103], v[156:159], v[172:175], v[100:103]
	v_mfma_f32_16x16x32_bf16 v[84:87], v[148:151], v[180:183], v[84:87]
	v_mfma_f32_16x16x32_bf16 v[80:83], v[156:159], v[180:183], v[80:83]
	v_mfma_f32_16x16x32_bf16 v[68:71], v[148:151], v[206:209], v[68:71]
	v_mfma_f32_16x16x32_bf16 v[64:67], v[156:159], v[206:209], v[64:67]
	s_barrier
	s_add_i32 s50, s76, s53
	s_mov_b32 m0, s50
	ds_read_b128 v[160:163], v225 offset:49152
	ds_read_b128 v[164:167], v225 offset:50176
	ds_read_b128 v[168:171], v225 offset:51200
	ds_read_b128 v[172:175], v225 offset:52224
	ds_read_b128 v[176:179], v225 offset:53248
	ds_read_b128 v[180:183], v225 offset:54272
	ds_read_b128 v[202:205], v225 offset:55296
	ds_read_b128 v[206:209], v225 offset:56320
	global_load_lds_dwordx4 v186, s[98:99]
	s_add_i32 m0, s50, 0x2000
	s_add_u32 s34, s34, 0xb0080
	s_addc_u32 s35, s35, 0
	s_add_i32 s50, s77, s53
	global_load_lds_dwordx4 v190, s[98:99]
	s_mov_b32 m0, s50
	s_nop 0
	global_load_lds_dwordx4 v186, s[34:35]
	s_add_i32 m0, s50, 0x2000
	s_nop 0
	global_load_lds_dwordx4 v190, s[34:35]
	s_mov_b32 m0, s62
	s_nop 0
	global_load_lds_dwordx4 v184, s[100:101]
	s_mov_b32 m0, s63
	s_nop 0
	global_load_lds_dwordx4 v188, s[100:101]
	s_waitcnt vmcnt(8)
	s_waitcnt lgkmcnt(0)
	s_barrier
	s_waitcnt lgkmcnt(0)
	v_mfma_f32_16x16x32_bf16 v[60:63], v[96:99], v[160:163], v[60:63]
	v_mfma_f32_16x16x32_bf16 v[56:59], v[120:123], v[160:163], v[56:59]
	v_mfma_f32_16x16x32_bf16 v[44:47], v[96:99], v[168:171], v[44:47]
	v_mfma_f32_16x16x32_bf16 v[40:43], v[120:123], v[168:171], v[40:43]
	v_mfma_f32_16x16x32_bf16 v[28:31], v[96:99], v[176:179], v[28:31]
	v_mfma_f32_16x16x32_bf16 v[24:27], v[120:123], v[176:179], v[24:27]
	v_mfma_f32_16x16x32_bf16 v[12:15], v[96:99], v[202:205], v[12:15]
	v_mfma_f32_16x16x32_bf16 v[8:11], v[120:123], v[202:205], v[8:11]
	v_mfma_f32_16x16x32_bf16 v[60:63], v[108:111], v[164:167], v[60:63]
	v_mfma_f32_16x16x32_bf16 v[56:59], v[128:131], v[164:167], v[56:59]
	v_mfma_f32_16x16x32_bf16 v[44:47], v[108:111], v[172:175], v[44:47]
	v_mfma_f32_16x16x32_bf16 v[40:43], v[128:131], v[172:175], v[40:43]
	v_mfma_f32_16x16x32_bf16 v[28:31], v[108:111], v[180:183], v[28:31]
	v_mfma_f32_16x16x32_bf16 v[24:27], v[128:131], v[180:183], v[24:27]
	v_mfma_f32_16x16x32_bf16 v[12:15], v[108:111], v[206:209], v[12:15]
	v_mfma_f32_16x16x32_bf16 v[8:11], v[128:131], v[206:209], v[8:11]
	v_mfma_f32_16x16x32_bf16 v[52:55], v[144:147], v[160:163], v[52:55]
	v_mfma_f32_16x16x32_bf16 v[48:51], v[152:155], v[160:163], v[48:51]
	v_mfma_f32_16x16x32_bf16 v[36:39], v[144:147], v[168:171], v[36:39]
	v_mfma_f32_16x16x32_bf16 v[32:35], v[152:155], v[168:171], v[32:35]
	v_mfma_f32_16x16x32_bf16 v[20:23], v[144:147], v[176:179], v[20:23]
	v_mfma_f32_16x16x32_bf16 v[16:19], v[152:155], v[176:179], v[16:19]
	v_mfma_f32_16x16x32_bf16 v[4:7], v[144:147], v[202:205], v[4:7]
	v_mfma_f32_16x16x32_bf16 v[0:3], v[152:155], v[202:205], v[0:3]
	v_mfma_f32_16x16x32_bf16 v[52:55], v[148:151], v[164:167], v[52:55]
	v_mfma_f32_16x16x32_bf16 v[48:51], v[156:159], v[164:167], v[48:51]
	v_mfma_f32_16x16x32_bf16 v[36:39], v[148:151], v[172:175], v[36:39]
	v_mfma_f32_16x16x32_bf16 v[32:35], v[156:159], v[172:175], v[32:35]
	v_mfma_f32_16x16x32_bf16 v[20:23], v[148:151], v[180:183], v[20:23]
	v_mfma_f32_16x16x32_bf16 v[16:19], v[156:159], v[180:183], v[16:19]
	v_mfma_f32_16x16x32_bf16 v[4:7], v[148:151], v[206:209], v[4:7]
	v_mfma_f32_16x16x32_bf16 v[0:3], v[156:159], v[206:209], v[0:3]
	s_barrier
	s_add_i32 s75, s75, 2
	s_add_u32 s20, s20, 0x100
	s_addc_u32 s21, s21, 0
	s_add_u32 s73, s73, 0x100
	s_addc_u32 s74, s74, 0
	s_cmp_gt_u32 s75, 41
; #define PG8_STAGE(bufoff, gbase, voff) do { _Pragma("unroll") for (int _i = 0; _i < 2; ++_i) \
;         __builtin_amdgcn_global_load_lds((const unsigned*)((const char*)(gbase) + (voff)[_i]), (PG8_LAS unsigned*)(lds + (bufoff) + ldsw + _i * 8192), 16, 0, 0); } while (0)
; #define PG8_LDA(dst, b, h) do { _Pragma("unroll") for (int m = 0; m < 4; ++m) _Pragma("unroll") for (int k = 0; k < 2; ++k) dst[m][k] = *(const PG8_LAS bf16x8*)(lds + PG8_SA(b, h) + aoff + m * 2048 + k * 1024); } while (0)
; #define PG8_LDB(dst, b, h) do { _Pragma("unroll") for (int n = 0; n < 2; ++n) _Pragma("unroll") for (int k = 0; k < 2; ++k) dst[n][k] = *(const PG8_LAS bf16x8*)(lds + PG8_SB(b, h) + boff + n * 2048 + k * 1024); } while (0)
; #define PG8_MMA(ai, bj, At, Bt) do { __builtin_amdgcn_s_setprio(1); _Pragma("unroll") for (int m = 0; m < 4; ++m) _Pragma("unroll") for (int n = 0; n < 2; ++n) _Pragma("unroll") for (int k = 0; k < 2; ++k) \
;         acc[ai][bj][m][n] = __builtin_amdgcn_mfma_f32_16x16x32_bf16(Bt[n][k], At[m][k], acc[ai][bj][m][n], 0, 0, 0); __builtin_amdgcn_s_setprio(0); } while (0)
; #define PG8_WAIT_V(n) asm volatile("s_waitcnt vmcnt(" #n ")" ::: "memory")
; #define PG8_WAIT_L(n) asm volatile("s_waitcnt lgkmcnt(" #n ")" ::: "memory")
; #define PG8_BAR __builtin_amdgcn_s_barrier()
; #define PG8_SCHED __builtin_amdgcn_sched_barrier(0)
; template <class Epi, class Sched, bool ALIGN_EPI = false, bool SP2 = false>
; __device__ __forceinline__ void gemm_phase(PG8_LAS unsigned char* lds, const Gemm g, const Sched& S, const Epi& E) {
;     ...
;             PG8_LDB(B0, 0, 0); PG8_LDB(B1, 0, 1); PG8_SCHED; PG8_LDA(At, 0, 0); PG8_STAGE(PG8_SA(1, 1), a1 + hstep, voffA);
;             PG8_WAIT_V(8); PG8_WAIT_L(0); PG8_BAR; PG8_MMA(0, 0, At, B0); PG8_MMA(0, 1, At, B1); PG8_BAR; PG8_SCHED;
;             PG8_LDA(At, 0, 1); PG8_STAGE(PG8_SB(0, 0), b2, voffB); PG8_STAGE(PG8_SB(0, 1), b2 + hstep, voffB); PG8_STAGE(PG8_SA(0, 0), a2, voffA);
;             PG8_WAIT_V(8); PG8_WAIT_L(0); PG8_BAR; PG8_MMA(1, 0, At, B0); PG8_MMA(1, 1, At, B1); PG8_BAR; PG8_SCHED;
.LBB0_309:
	ds_read_b128 v[96:99], v223
	ds_read_b128 v[108:111], v223 offset:1024
	ds_read_b128 v[120:123], v223 offset:2048
	ds_read_b128 v[128:131], v223 offset:3072
	ds_read_b128 v[144:147], v224
	ds_read_b128 v[148:151], v224 offset:1024
	ds_read_b128 v[152:155], v224 offset:2048
	ds_read_b128 v[156:159], v224 offset:3072
	s_add_u32 s34, s20, 0xfff50080
	s_addc_u32 s35, s21, -1
	s_cmp_eq_u32 s75, 40
	s_cselect_b32 s51, s1, s35
	s_cselect_b32 s50, s0, s34
	s_cselect_b32 s35, s49, s74
	s_cselect_b32 s34, s48, s73
	s_add_i32 m0, s54, 0xc000
	ds_read_b128 v[160:163], v225
	ds_read_b128 v[164:167], v225 offset:1024
	ds_read_b128 v[168:171], v225 offset:2048
	ds_read_b128 v[172:175], v225 offset:3072
	ds_read_b128 v[176:179], v225 offset:4096
	ds_read_b128 v[180:183], v225 offset:5120
	ds_read_b128 v[202:205], v225 offset:6144
	ds_read_b128 v[206:209], v225 offset:7168
	global_load_lds_dwordx4 v192, s[20:21]
	s_add_i32 m0, s54, 0xe000
	s_nop 0
	global_load_lds_dwordx4 v194, s[20:21]
	s_waitcnt vmcnt(8)
	s_waitcnt lgkmcnt(0)
	s_barrier
	s_waitcnt lgkmcnt(0)
	v_mfma_f32_16x16x32_bf16 v[140:143], v[96:99], v[160:163], v[140:143]
	v_mfma_f32_16x16x32_bf16 v[136:139], v[120:123], v[160:163], v[136:139]
	v_mfma_f32_16x16x32_bf16 v[116:119], v[96:99], v[168:171], v[116:119]
	v_mfma_f32_16x16x32_bf16 v[112:115], v[120:123], v[168:171], v[112:115]
	v_mfma_f32_16x16x32_bf16 v[92:95], v[96:99], v[176:179], v[92:95]
	v_mfma_f32_16x16x32_bf16 v[88:91], v[120:123], v[176:179], v[88:91]
	v_mfma_f32_16x16x32_bf16 v[76:79], v[96:99], v[202:205], v[76:79]
	v_mfma_f32_16x16x32_bf16 v[72:75], v[120:123], v[202:205], v[72:75]
	v_mfma_f32_16x16x32_bf16 v[140:143], v[108:111], v[164:167], v[140:143]
	v_mfma_f32_16x16x32_bf16 v[136:139], v[128:131], v[164:167], v[136:139]
	v_mfma_f32_16x16x32_bf16 v[116:119], v[108:111], v[172:175], v[116:119]
	v_mfma_f32_16x16x32_bf16 v[112:115], v[128:131], v[172:175], v[112:115]
	v_mfma_f32_16x16x32_bf16 v[92:95], v[108:111], v[180:183], v[92:95]
	v_mfma_f32_16x16x32_bf16 v[88:91], v[128:131], v[180:183], v[88:91]
	v_mfma_f32_16x16x32_bf16 v[76:79], v[108:111], v[206:209], v[76:79]
	v_mfma_f32_16x16x32_bf16 v[72:75], v[128:131], v[206:209], v[72:75]
	v_mfma_f32_16x16x32_bf16 v[132:135], v[144:147], v[160:163], v[132:135]
	v_mfma_f32_16x16x32_bf16 v[124:127], v[152:155], v[160:163], v[124:127]
	v_mfma_f32_16x16x32_bf16 v[104:107], v[144:147], v[168:171], v[104:107]
	v_mfma_f32_16x16x32_bf16 v[100:103], v[152:155], v[168:171], v[100:103]
	v_mfma_f32_16x16x32_bf16 v[84:87], v[144:147], v[176:179], v[84:87]
	v_mfma_f32_16x16x32_bf16 v[80:83], v[152:155], v[176:179], v[80:83]
	v_mfma_f32_16x16x32_bf16 v[68:71], v[144:147], v[202:205], v[68:71]
	v_mfma_f32_16x16x32_bf16 v[64:67], v[152:155], v[202:205], v[64:67]
	v_mfma_f32_16x16x32_bf16 v[132:135], v[148:151], v[164:167], v[132:135]
	v_mfma_f32_16x16x32_bf16 v[124:127], v[156:159], v[164:167], v[124:127]
	v_mfma_f32_16x16x32_bf16 v[104:107], v[148:151], v[172:175], v[104:107]
	v_mfma_f32_16x16x32_bf16 v[100:103], v[156:159], v[172:175], v[100:103]
	v_mfma_f32_16x16x32_bf16 v[84:87], v[148:151], v[180:183], v[84:87]
	v_mfma_f32_16x16x32_bf16 v[80:83], v[156:159], v[180:183], v[80:83]
	v_mfma_f32_16x16x32_bf16 v[68:71], v[148:151], v[206:209], v[68:71]
	v_mfma_f32_16x16x32_bf16 v[64:67], v[156:159], v[206:209], v[64:67]
	s_barrier
	s_add_i32 s76, s67, s53
	s_add_u32 s98, s34, s12
	s_addc_u32 s99, s35, s13
	s_add_u32 s100, s50, s12
	s_addc_u32 s101, s51, s13
	s_mov_b32 m0, s76
	ds_read_b128 v[160:163], v225 offset:16384
	ds_read_b128 v[164:167], v225 offset:17408
	ds_read_b128 v[168:171], v225 offset:18432
	ds_read_b128 v[172:175], v225 offset:19456
	ds_read_b128 v[176:179], v225 offset:20480
	ds_read_b128 v[180:183], v225 offset:21504
	ds_read_b128 v[202:205], v225 offset:22528
	ds_read_b128 v[206:209], v225 offset:23552
	global_load_lds_dwordx4 v186, s[34:35]
	s_add_i32 m0, s76, 0x2000
	s_add_u32 s76, s34, 0xb0000
	s_addc_u32 s77, s35, 0
	s_add_i32 s78, s68, s53
	global_load_lds_dwordx4 v190, s[34:35]
	s_mov_b32 m0, s78
	s_nop 0
	global_load_lds_dwordx4 v186, s[76:77]
	s_add_i32 m0, s78, 0x2000
	s_nop 0
	global_load_lds_dwordx4 v190, s[76:77]
	s_mov_b32 m0, s54
	s_nop 0
	global_load_lds_dwordx4 v184, s[50:51]
	s_mov_b32 m0, s55
	s_nop 0
	global_load_lds_dwordx4 v188, s[50:51]
	s_waitcnt vmcnt(8)
	s_waitcnt lgkmcnt(0)
	s_barrier
	s_waitcnt lgkmcnt(0)
	v_mfma_f32_16x16x32_bf16 v[60:63], v[96:99], v[160:163], v[60:63]
	v_mfma_f32_16x16x32_bf16 v[56:59], v[120:123], v[160:163], v[56:59]
	v_mfma_f32_16x16x32_bf16 v[44:47], v[96:99], v[168:171], v[44:47]
	v_mfma_f32_16x16x32_bf16 v[40:43], v[120:123], v[168:171], v[40:43]
	v_mfma_f32_16x16x32_bf16 v[28:31], v[96:99], v[176:179], v[28:31]
	v_mfma_f32_16x16x32_bf16 v[24:27], v[120:123], v[176:179], v[24:27]
	v_mfma_f32_16x16x32_bf16 v[12:15], v[96:99], v[202:205], v[12:15]
	v_mfma_f32_16x16x32_bf16 v[8:11], v[120:123], v[202:205], v[8:11]
	v_mfma_f32_16x16x32_bf16 v[60:63], v[108:111], v[164:167], v[60:63]
	v_mfma_f32_16x16x32_bf16 v[56:59], v[128:131], v[164:167], v[56:59]
	v_mfma_f32_16x16x32_bf16 v[44:47], v[108:111], v[172:175], v[44:47]
	v_mfma_f32_16x16x32_bf16 v[40:43], v[128:131], v[172:175], v[40:43]
	v_mfma_f32_16x16x32_bf16 v[28:31], v[108:111], v[180:183], v[28:31]
	v_mfma_f32_16x16x32_bf16 v[24:27], v[128:131], v[180:183], v[24:27]
	v_mfma_f32_16x16x32_bf16 v[12:15], v[108:111], v[206:209], v[12:15]
	v_mfma_f32_16x16x32_bf16 v[8:11], v[128:131], v[206:209], v[8:11]
	v_mfma_f32_16x16x32_bf16 v[52:55], v[144:147], v[160:163], v[52:55]
	v_mfma_f32_16x16x32_bf16 v[48:51], v[152:155], v[160:163], v[48:51]
	v_mfma_f32_16x16x32_bf16 v[36:39], v[144:147], v[168:171], v[36:39]
	v_mfma_f32_16x16x32_bf16 v[32:35], v[152:155], v[168:171], v[32:35]
	v_mfma_f32_16x16x32_bf16 v[20:23], v[144:147], v[176:179], v[20:23]
	v_mfma_f32_16x16x32_bf16 v[16:19], v[152:155], v[176:179], v[16:19]
	v_mfma_f32_16x16x32_bf16 v[4:7], v[144:147], v[202:205], v[4:7]
	v_mfma_f32_16x16x32_bf16 v[0:3], v[152:155], v[202:205], v[0:3]
	v_mfma_f32_16x16x32_bf16 v[52:55], v[148:151], v[164:167], v[52:55]
	v_mfma_f32_16x16x32_bf16 v[48:51], v[156:159], v[164:167], v[48:51]
	v_mfma_f32_16x16x32_bf16 v[36:39], v[148:151], v[172:175], v[36:39]
	v_mfma_f32_16x16x32_bf16 v[32:35], v[156:159], v[172:175], v[32:35]
	v_mfma_f32_16x16x32_bf16 v[20:23], v[148:151], v[180:183], v[20:23]
	v_mfma_f32_16x16x32_bf16 v[16:19], v[156:159], v[180:183], v[16:19]
	v_mfma_f32_16x16x32_bf16 v[4:7], v[148:151], v[206:209], v[4:7]
	v_mfma_f32_16x16x32_bf16 v[0:3], v[156:159], v[206:209], v[0:3]
	s_barrier
; #define PG8_STAGE(bufoff, gbase, voff) do { _Pragma("unroll") for (int _i = 0; _i < 2; ++_i) \
;         __builtin_amdgcn_global_load_lds((const unsigned*)((const char*)(gbase) + (voff)[_i]), (PG8_LAS unsigned*)(lds + (bufoff) + ldsw + _i * 8192), 16, 0, 0); } while (0)
; #define PG8_LDA(dst, b, h) do { _Pragma("unroll") for (int m = 0; m < 4; ++m) _Pragma("unroll") for (int k = 0; k < 2; ++k) dst[m][k] = *(const PG8_LAS bf16x8*)(lds + PG8_SA(b, h) + aoff + m * 2048 + k * 1024); } while (0)
; #define PG8_LDB(dst, b, h) do { _Pragma("unroll") for (int n = 0; n < 2; ++n) _Pragma("unroll") for (int k = 0; k < 2; ++k) dst[n][k] = *(const PG8_LAS bf16x8*)(lds + PG8_SB(b, h) + boff + n * 2048 + k * 1024); } while (0)
; #define PG8_MMA(ai, bj, At, Bt) do { __builtin_amdgcn_s_setprio(1); _Pragma("unroll") for (int m = 0; m < 4; ++m) _Pragma("unroll") for (int n = 0; n < 2; ++n) _Pragma("unroll") for (int k = 0; k < 2; ++k) \
;         acc[ai][bj][m][n] = __builtin_amdgcn_mfma_f32_16x16x32_bf16(Bt[n][k], At[m][k], acc[ai][bj][m][n], 0, 0, 0); __builtin_amdgcn_s_setprio(0); } while (0)
; #define PG8_WAIT_V(n) asm volatile("s_waitcnt vmcnt(" #n ")" ::: "memory")
; #define PG8_WAIT_L(n) asm volatile("s_waitcnt lgkmcnt(" #n ")" ::: "memory")
; #define PG8_BAR __builtin_amdgcn_s_barrier()
; #define PG8_SCHED __builtin_amdgcn_sched_barrier(0)
; template <class Epi, class Sched, bool ALIGN_EPI = false, bool SP2 = false>
; __device__ __forceinline__ void gemm_phase(PG8_LAS unsigned char* lds, const Gemm g, const Sched& S, const Epi& E) {
;     ...
;             PG8_LDB(B0, 1, 0); PG8_LDB(B1, 1, 1); PG8_SCHED; PG8_LDA(At, 1, 0); PG8_STAGE(PG8_SA(0, 1), a2 + hstep, voffA);
;             PG8_WAIT_V(8); PG8_WAIT_L(0); PG8_BAR; PG8_MMA(0, 0, At, B0); PG8_MMA(0, 1, At, B1); PG8_BAR; PG8_SCHED;
;             PG8_LDA(At, 1, 1); PG8_STAGE(PG8_SB(1, 0), b3, voffB); PG8_STAGE(PG8_SB(1, 1), b3 + hstep, voffB); PG8_STAGE(PG8_SA(1, 0), a3, voffA);
;             PG8_WAIT_V(8); PG8_WAIT_L(0); PG8_BAR; PG8_MMA(1, 0, At, B0); PG8_MMA(1, 1, At, B1); PG8_BAR; PG8_SCHED;
;     ...
;         if constexpr (ALIGN_EPI) { if (wr == 0) PG8_BAR; }
	s_add_i32 s76, 0, 0x18000
	s_add_i32 s77, 0, 0x1c000
	v_add_u32_e32 v128, s76, v221
	v_add_u32_e32 v156, s77, v221
	ds_read_b128 v[96:99], v128
	ds_read_b128 v[108:111], v128 offset:1024
	ds_read_b128 v[120:123], v128 offset:2048
	ds_read_b128 v[128:131], v128 offset:3072
	ds_read_b128 v[144:147], v156
	ds_read_b128 v[148:151], v156 offset:1024
	ds_read_b128 v[152:155], v156 offset:2048
	ds_read_b128 v[156:159], v156 offset:3072
	s_add_u32 s50, s50, 0xb0000
	s_addc_u32 s51, s51, 0
	s_mov_b32 m0, s56
	ds_read_b128 v[160:163], v225 offset:32768
	ds_read_b128 v[164:167], v225 offset:33792
	ds_read_b128 v[168:171], v225 offset:34816
	ds_read_b128 v[172:175], v225 offset:35840
	ds_read_b128 v[176:179], v225 offset:36864
	ds_read_b128 v[180:183], v225 offset:37888
	ds_read_b128 v[202:205], v225 offset:38912
	ds_read_b128 v[206:209], v225 offset:39936
	global_load_lds_dwordx4 v184, s[50:51]
	s_mov_b32 m0, s57
	s_nop 0
	global_load_lds_dwordx4 v188, s[50:51]
	s_waitcnt vmcnt(8)
	s_waitcnt lgkmcnt(0)
	s_barrier
	s_waitcnt lgkmcnt(0)
	v_mfma_f32_16x16x32_bf16 v[140:143], v[96:99], v[160:163], v[140:143]
	v_mfma_f32_16x16x32_bf16 v[136:139], v[120:123], v[160:163], v[136:139]
	v_mfma_f32_16x16x32_bf16 v[116:119], v[96:99], v[168:171], v[116:119]
	v_mfma_f32_16x16x32_bf16 v[112:115], v[120:123], v[168:171], v[112:115]
	v_mfma_f32_16x16x32_bf16 v[92:95], v[96:99], v[176:179], v[92:95]
	v_mfma_f32_16x16x32_bf16 v[88:91], v[120:123], v[176:179], v[88:91]
	v_mfma_f32_16x16x32_bf16 v[76:79], v[96:99], v[202:205], v[76:79]
	v_mfma_f32_16x16x32_bf16 v[72:75], v[120:123], v[202:205], v[72:75]
	v_mfma_f32_16x16x32_bf16 v[140:143], v[108:111], v[164:167], v[140:143]
	v_mfma_f32_16x16x32_bf16 v[136:139], v[128:131], v[164:167], v[136:139]
	v_mfma_f32_16x16x32_bf16 v[116:119], v[108:111], v[172:175], v[116:119]
	v_mfma_f32_16x16x32_bf16 v[112:115], v[128:131], v[172:175], v[112:115]
	v_mfma_f32_16x16x32_bf16 v[92:95], v[108:111], v[180:183], v[92:95]
	v_mfma_f32_16x16x32_bf16 v[88:91], v[128:131], v[180:183], v[88:91]
	v_mfma_f32_16x16x32_bf16 v[76:79], v[108:111], v[206:209], v[76:79]
	v_mfma_f32_16x16x32_bf16 v[72:75], v[128:131], v[206:209], v[72:75]
	v_mfma_f32_16x16x32_bf16 v[132:135], v[144:147], v[160:163], v[132:135]
	v_mfma_f32_16x16x32_bf16 v[124:127], v[152:155], v[160:163], v[124:127]
	v_mfma_f32_16x16x32_bf16 v[104:107], v[144:147], v[168:171], v[104:107]
	v_mfma_f32_16x16x32_bf16 v[100:103], v[152:155], v[168:171], v[100:103]
	v_mfma_f32_16x16x32_bf16 v[84:87], v[144:147], v[176:179], v[84:87]
	v_mfma_f32_16x16x32_bf16 v[80:83], v[152:155], v[176:179], v[80:83]
	v_mfma_f32_16x16x32_bf16 v[68:71], v[144:147], v[202:205], v[68:71]
	v_mfma_f32_16x16x32_bf16 v[64:67], v[152:155], v[202:205], v[64:67]
	v_mfma_f32_16x16x32_bf16 v[132:135], v[148:151], v[164:167], v[132:135]
	v_mfma_f32_16x16x32_bf16 v[124:127], v[156:159], v[164:167], v[124:127]
	v_mfma_f32_16x16x32_bf16 v[104:107], v[148:151], v[172:175], v[104:107]
	v_mfma_f32_16x16x32_bf16 v[100:103], v[156:159], v[172:175], v[100:103]
	v_mfma_f32_16x16x32_bf16 v[84:87], v[148:151], v[180:183], v[84:87]
	v_mfma_f32_16x16x32_bf16 v[80:83], v[156:159], v[180:183], v[80:83]
	v_mfma_f32_16x16x32_bf16 v[68:71], v[148:151], v[206:209], v[68:71]
	v_mfma_f32_16x16x32_bf16 v[64:67], v[156:159], v[206:209], v[64:67]
	s_barrier
	s_add_i32 s50, s76, s53
	s_mov_b32 m0, s50
	ds_read_b128 v[160:163], v225 offset:49152
	ds_read_b128 v[164:167], v225 offset:50176
	ds_read_b128 v[168:171], v225 offset:51200
	ds_read_b128 v[172:175], v225 offset:52224
	ds_read_b128 v[176:179], v225 offset:53248
	ds_read_b128 v[180:183], v225 offset:54272
	ds_read_b128 v[202:205], v225 offset:55296
	ds_read_b128 v[206:209], v225 offset:56320
	global_load_lds_dwordx4 v186, s[98:99]
	s_add_i32 m0, s50, 0x2000
	s_add_u32 s34, s34, 0xb0080
	s_addc_u32 s35, s35, 0
	s_add_i32 s50, s77, s53
	global_load_lds_dwordx4 v190, s[98:99]
	s_mov_b32 m0, s50
	s_nop 0
	global_load_lds_dwordx4 v186, s[34:35]
	s_add_i32 m0, s50, 0x2000
	s_nop 0
	global_load_lds_dwordx4 v190, s[34:35]
	s_mov_b32 m0, s62
	s_nop 0
	global_load_lds_dwordx4 v184, s[100:101]
	s_mov_b32 m0, s63
	s_nop 0
	global_load_lds_dwordx4 v188, s[100:101]
	s_waitcnt vmcnt(8)
	s_waitcnt lgkmcnt(0)
	s_barrier
	s_waitcnt lgkmcnt(0)
	v_mfma_f32_16x16x32_bf16 v[60:63], v[96:99], v[160:163], v[60:63]
	v_mfma_f32_16x16x32_bf16 v[56:59], v[120:123], v[160:163], v[56:59]
	v_mfma_f32_16x16x32_bf16 v[44:47], v[96:99], v[168:171], v[44:47]
	v_mfma_f32_16x16x32_bf16 v[40:43], v[120:123], v[168:171], v[40:43]
	v_mfma_f32_16x16x32_bf16 v[28:31], v[96:99], v[176:179], v[28:31]
	v_mfma_f32_16x16x32_bf16 v[24:27], v[120:123], v[176:179], v[24:27]
	v_mfma_f32_16x16x32_bf16 v[12:15], v[96:99], v[202:205], v[12:15]
	v_mfma_f32_16x16x32_bf16 v[8:11], v[120:123], v[202:205], v[8:11]
	v_mfma_f32_16x16x32_bf16 v[60:63], v[108:111], v[164:167], v[60:63]
	v_mfma_f32_16x16x32_bf16 v[56:59], v[128:131], v[164:167], v[56:59]
	v_mfma_f32_16x16x32_bf16 v[44:47], v[108:111], v[172:175], v[44:47]
	v_mfma_f32_16x16x32_bf16 v[40:43], v[128:131], v[172:175], v[40:43]
	v_mfma_f32_16x16x32_bf16 v[28:31], v[108:111], v[180:183], v[28:31]
	v_mfma_f32_16x16x32_bf16 v[24:27], v[128:131], v[180:183], v[24:27]
	v_mfma_f32_16x16x32_bf16 v[12:15], v[108:111], v[206:209], v[12:15]
	v_mfma_f32_16x16x32_bf16 v[8:11], v[128:131], v[206:209], v[8:11]
	v_mfma_f32_16x16x32_bf16 v[52:55], v[144:147], v[160:163], v[52:55]
	v_mfma_f32_16x16x32_bf16 v[48:51], v[152:155], v[160:163], v[48:51]
	v_mfma_f32_16x16x32_bf16 v[36:39], v[144:147], v[168:171], v[36:39]
	v_mfma_f32_16x16x32_bf16 v[32:35], v[152:155], v[168:171], v[32:35]
	v_mfma_f32_16x16x32_bf16 v[20:23], v[144:147], v[176:179], v[20:23]
	v_mfma_f32_16x16x32_bf16 v[16:19], v[152:155], v[176:179], v[16:19]
	v_mfma_f32_16x16x32_bf16 v[4:7], v[144:147], v[202:205], v[4:7]
	v_mfma_f32_16x16x32_bf16 v[0:3], v[152:155], v[202:205], v[0:3]
	v_mfma_f32_16x16x32_bf16 v[52:55], v[148:151], v[164:167], v[52:55]
	v_mfma_f32_16x16x32_bf16 v[48:51], v[156:159], v[164:167], v[48:51]
	v_mfma_f32_16x16x32_bf16 v[36:39], v[148:151], v[172:175], v[36:39]
	v_mfma_f32_16x16x32_bf16 v[32:35], v[156:159], v[172:175], v[32:35]
	v_mfma_f32_16x16x32_bf16 v[20:23], v[148:151], v[180:183], v[20:23]
	v_mfma_f32_16x16x32_bf16 v[16:19], v[156:159], v[180:183], v[16:19]
	v_mfma_f32_16x16x32_bf16 v[4:7], v[148:151], v[206:209], v[4:7]
	v_mfma_f32_16x16x32_bf16 v[0:3], v[156:159], v[206:209], v[0:3]
	s_barrier
	s_add_i32 s75, s75, 2
	s_add_u32 s20, s20, 0x100
	s_addc_u32 s21, s21, 0
	s_add_u32 s73, s73, 0x100
	s_addc_u32 s74, s74, 0
	s_cmp_gt_u32 s75, 41
	s_cbranch_scc0 .LBB0_309
	s_and_b64 vcc, exec, s[14:15]
	s_cbranch_vccz .LBB0_312
	s_barrier

; #define PG8_STAGE(bufoff, gbase, voff) do { _Pragma("unroll") for (int _i = 0; _i < 2; ++_i) \
;         __builtin_amdgcn_global_load_lds((const unsigned*)((const char*)(gbase) + (voff)[_i]), (PG8_LAS unsigned*)(lds + (bufoff) + ldsw + _i * 8192), 16, 0, 0); } while (0)
; #define PG8_LDA(dst, b, h) do { _Pragma("unroll") for (int m = 0; m < 4; ++m) _Pragma("unroll") for (int k = 0; k < 2; ++k) dst[m][k] = *(const PG8_LAS bf16x8*)(lds + PG8_SA(b, h) + aoff + m * 2048 + k * 1024); } while (0)
; #define PG8_LDB(dst, b, h) do { _Pragma("unroll") for (int n = 0; n < 2; ++n) _Pragma("unroll") for (int k = 0; k < 2; ++k) dst[n][k] = *(const PG8_LAS bf16x8*)(lds + PG8_SB(b, h) + boff + n * 2048 + k * 1024); } while (0)
; #define PG8_MMA(ai, bj, At, Bt) do { __builtin_amdgcn_s_setprio(1); _Pragma("unroll") for (int m = 0; m < 4; ++m) _Pragma("unroll") for (int n = 0; n < 2; ++n) _Pragma("unroll") for (int k = 0; k < 2; ++k) \
;         acc[ai][bj][m][n] = __builtin_amdgcn_mfma_f32_16x16x32_bf16(Bt[n][k], At[m][k], acc[ai][bj][m][n], 0, 0, 0); __builtin_amdgcn_s_setprio(0); } while (0)
; #define PG8_BAR __builtin_amdgcn_s_barrier()
; template <class Epi, class Sched, bool ALIGN_EPI = false, bool SP2 = false>
; __device__ __forceinline__ void gemm_phase(PG8_LAS unsigned char* lds, const Gemm g, const Sched& S, const Epi& E) {
;     ...
;         const bool has_next = S.next(ui + 1, nxt);
;         const char* nA = has_next ? (const char*)g.A + (size_t)nxt.pm * tstep : cA; const char* nB = has_next ? (const char*)g.Bt + (size_t)nxt.pn * tstep : cB;
;         for (int t = 0; t < nt; t += 2) {
;             const bool last = (t == nt - 2);
;             const char* a1 = cA + (size_t)(t + 1) * kstep;
;             const char* a2 = last ? nA : cA + (size_t)(t + 2) * kstep; const char* b2 = last ? nB : cB + (size_t)(t + 2) * kstep;
;             const char* a3 = a2 + kstep; const char* b3 = b2 + kstep;
;             if (last && has_next) S.a_ready(nxt);
;             if constexpr (SP2) {
;             PG8_LDB(B0, 0, 0); PG8_LDB(B1, 0, 1); PG8_SCHED; PG8_LDA(At, 0, 0); PG8_STAGE(PG8_SA(1, 1), a1 + hstep, voffA);
;             PG8_WAIT_V(8); PG8_WAIT_L(0); PG8_BAR; PG8_MMA(0, 0, At, B0); PG8_MMA(0, 1, At, B1); PG8_BAR; PG8_SCHED;
;             PG8_LDA(At, 0, 1); PG8_STAGE(PG8_SB(0, 0), b2, voffB); PG8_STAGE(PG8_SB(0, 1), b2 + hstep, voffB); PG8_STAGE(PG8_SA(0, 0), a2, voffA);
.LBB0_413:
	s_ashr_i32 s43, s42, 31
	s_lshl_b64 s[48:49], s[42:43], 19
	s_add_u32 s48, s36, s48
	s_addc_u32 s49, s37, s49
	s_and_b64 s[50:51], s[4:5], exec
	s_cselect_b32 s43, s49, s21
	s_cselect_b32 s78, s48, s20
	s_ashr_i32 s19, s18, 31
	s_lshl_b64 s[50:51], s[18:19], 19
	s_add_u32 s50, s61, s50
	s_addc_u32 s51, s62, s51
	s_and_b64 s[54:55], s[4:5], exec
	s_cselect_b32 s19, s51, s53
	s_cselect_b32 s79, s50, s52
	s_add_u32 s20, s20, 0x40080
	s_addc_u32 s21, s21, 0
	s_add_u32 s80, s52, 0x100
	s_addc_u32 s81, s53, 0
	s_mov_b32 s84, -2
	ds_read_b128 v[146:149], v165
	ds_read_b128 v[150:153], v165 offset:1024
	ds_read_b128 v[154:157], v165 offset:2048
	ds_read_b128 v[168:171], v165 offset:3072
	ds_read_b128 v[172:175], v166
	ds_read_b128 v[176:179], v166 offset:1024
	ds_read_b128 v[180:183], v166 offset:2048
	ds_read_b128 v[184:187], v166 offset:3072
	s_add_u32 s52, s20, 0xfffc0080
	s_addc_u32 s53, s21, -1
	s_cmp_eq_u32 s84, 12
	s_cselect_b32 s55, s43, s53
	s_cselect_b32 s54, s78, s52
	s_cselect_b32 s53, s19, s81
	s_cselect_b32 s52, s79, s80
	s_add_i32 m0, s35, 0xc000
	ds_read_b128 v[188:191], v167
	ds_read_b128 v[192:195], v167 offset:1024
	ds_read_b128 v[198:201], v167 offset:2048
	ds_read_b128 v[202:205], v167 offset:3072
	ds_read_b128 v[206:209], v167 offset:4096
	ds_read_b128 v[210:213], v167 offset:5120
	ds_read_b128 v[214:217], v167 offset:6144
	ds_read_b128 v[218:221], v167 offset:7168
	global_load_lds_dwordx4 v138, s[20:21]
	s_add_i32 m0, s35, 0xe000
	s_nop 0
	global_load_lds_dwordx4 v140, s[20:21]
	s_waitcnt vmcnt(8)
	s_waitcnt lgkmcnt(0)
	s_barrier
	s_waitcnt lgkmcnt(0)
	v_mfma_f32_16x16x32_bf16 v[124:127], v[146:149], v[188:191], 0
	v_mfma_f32_16x16x32_bf16 v[120:123], v[154:157], v[188:191], 0
	v_mfma_f32_16x16x32_bf16 v[108:111], v[146:149], v[198:201], 0
	v_mfma_f32_16x16x32_bf16 v[104:107], v[154:157], v[198:201], 0
	v_mfma_f32_16x16x32_bf16 v[92:95], v[146:149], v[206:209], 0
	v_mfma_f32_16x16x32_bf16 v[88:91], v[154:157], v[206:209], 0
	v_mfma_f32_16x16x32_bf16 v[76:79], v[146:149], v[214:217], 0
	v_mfma_f32_16x16x32_bf16 v[72:75], v[154:157], v[214:217], 0
	v_mfma_f32_16x16x32_bf16 v[124:127], v[150:153], v[192:195], v[124:127]
	v_mfma_f32_16x16x32_bf16 v[120:123], v[168:171], v[192:195], v[120:123]
	v_mfma_f32_16x16x32_bf16 v[108:111], v[150:153], v[202:205], v[108:111]
	v_mfma_f32_16x16x32_bf16 v[104:107], v[168:171], v[202:205], v[104:107]
	v_mfma_f32_16x16x32_bf16 v[92:95], v[150:153], v[210:213], v[92:95]
	v_mfma_f32_16x16x32_bf16 v[88:91], v[168:171], v[210:213], v[88:91]
	v_mfma_f32_16x16x32_bf16 v[76:79], v[150:153], v[218:221], v[76:79]
	v_mfma_f32_16x16x32_bf16 v[72:75], v[168:171], v[218:221], v[72:75]
	v_mfma_f32_16x16x32_bf16 v[116:119], v[172:175], v[188:191], 0
	v_mfma_f32_16x16x32_bf16 v[112:115], v[180:183], v[188:191], 0
	v_mfma_f32_16x16x32_bf16 v[100:103], v[172:175], v[198:201], 0
	v_mfma_f32_16x16x32_bf16 v[96:99], v[180:183], v[198:201], 0
	v_mfma_f32_16x16x32_bf16 v[84:87], v[172:175], v[206:209], 0
	v_mfma_f32_16x16x32_bf16 v[80:83], v[180:183], v[206:209], 0
	v_mfma_f32_16x16x32_bf16 v[68:71], v[172:175], v[214:217], 0
	v_mfma_f32_16x16x32_bf16 v[64:67], v[180:183], v[214:217], 0
	v_mfma_f32_16x16x32_bf16 v[116:119], v[176:179], v[192:195], v[116:119]
	v_mfma_f32_16x16x32_bf16 v[112:115], v[184:187], v[192:195], v[112:115]
	v_mfma_f32_16x16x32_bf16 v[100:103], v[176:179], v[202:205], v[100:103]
	v_mfma_f32_16x16x32_bf16 v[96:99], v[184:187], v[202:205], v[96:99]
	v_mfma_f32_16x16x32_bf16 v[84:87], v[176:179], v[210:213], v[84:87]
	v_mfma_f32_16x16x32_bf16 v[80:83], v[184:187], v[210:213], v[80:83]
	v_mfma_f32_16x16x32_bf16 v[68:71], v[176:179], v[218:221], v[68:71]
	v_mfma_f32_16x16x32_bf16 v[64:67], v[184:187], v[218:221], v[64:67]
	s_barrier
	s_add_i32 s85, s72, s63
	s_add_u32 s98, s52, s8
	s_addc_u32 s99, s53, s9
	s_add_u32 s100, s54, s8
	s_addc_u32 s101, s55, s9
	s_mov_b32 m0, s85
	ds_read_b128 v[188:191], v167 offset:16384
	ds_read_b128 v[192:195], v167 offset:17408
	ds_read_b128 v[198:201], v167 offset:18432
	ds_read_b128 v[202:205], v167 offset:19456
	ds_read_b128 v[206:209], v167 offset:20480
	ds_read_b128 v[210:213], v167 offset:21504
	ds_read_b128 v[214:217], v167 offset:22528
	ds_read_b128 v[218:221], v167 offset:23552
	global_load_lds_dwordx4 v132, s[52:53]
	s_add_i32 m0, s85, 0x2000
	s_add_u32 s86, s52, 0x40000
	s_addc_u32 s87, s53, 0
	s_add_i32 s85, s73, s63
	global_load_lds_dwordx4 v128, s[52:53]
	s_mov_b32 m0, s85
	s_nop 0
	global_load_lds_dwordx4 v132, s[86:87]
	s_add_i32 m0, s85, 0x2000
	s_nop 0
	global_load_lds_dwordx4 v128, s[86:87]
	s_mov_b32 m0, s35
	s_nop 0
	global_load_lds_dwordx4 v134, s[54:55]
	s_mov_b32 m0, s65
	s_nop 0
	global_load_lds_dwordx4 v130, s[54:55]
	s_waitcnt vmcnt(8)
	s_waitcnt lgkmcnt(0)
	s_barrier
; #define PG8_STAGE(bufoff, gbase, voff) do { _Pragma("unroll") for (int _i = 0; _i < 2; ++_i) \
;         __builtin_amdgcn_global_load_lds((const unsigned*)((const char*)(gbase) + (voff)[_i]), (PG8_LAS unsigned*)(lds + (bufoff) + ldsw + _i * 8192), 16, 0, 0); } while (0)
; #define PG8_LDA(dst, b, h) do { _Pragma("unroll") for (int m = 0; m < 4; ++m) _Pragma("unroll") for (int k = 0; k < 2; ++k) dst[m][k] = *(const PG8_LAS bf16x8*)(lds + PG8_SA(b, h) + aoff + m * 2048 + k * 1024); } while (0)
; #define PG8_LDB(dst, b, h) do { _Pragma("unroll") for (int n = 0; n < 2; ++n) _Pragma("unroll") for (int k = 0; k < 2; ++k) dst[n][k] = *(const PG8_LAS bf16x8*)(lds + PG8_SB(b, h) + boff + n * 2048 + k * 1024); } while (0)
; #define PG8_MMA(ai, bj, At, Bt) do { __builtin_amdgcn_s_setprio(1); _Pragma("unroll") for (int m = 0; m < 4; ++m) _Pragma("unroll") for (int n = 0; n < 2; ++n) _Pragma("unroll") for (int k = 0; k < 2; ++k) \
;         acc[ai][bj][m][n] = __builtin_amdgcn_mfma_f32_16x16x32_bf16(Bt[n][k], At[m][k], acc[ai][bj][m][n], 0, 0, 0); __builtin_amdgcn_s_setprio(0); } while (0)
; #define PG8_WAIT_V(n) asm volatile("s_waitcnt vmcnt(" #n ")" ::: "memory")
; #define PG8_WAIT_L(n) asm volatile("s_waitcnt lgkmcnt(" #n ")" ::: "memory")
; #define PG8_BAR __builtin_amdgcn_s_barrier()
; #define PG8_SCHED __builtin_amdgcn_sched_barrier(0)
; template <class Epi, class Sched, bool ALIGN_EPI = false, bool SP2 = false>
; __device__ __forceinline__ void gemm_phase(PG8_LAS unsigned char* lds, const Gemm g, const Sched& S, const Epi& E) {
;     ...
;             PG8_WAIT_V(8); PG8_WAIT_L(0); PG8_BAR; PG8_MMA(1, 0, At, B0); PG8_MMA(1, 1, At, B1); PG8_BAR; PG8_SCHED;
;             PG8_LDB(B0, 1, 0); PG8_LDB(B1, 1, 1); PG8_SCHED; PG8_LDA(At, 1, 0); PG8_STAGE(PG8_SA(0, 1), a2 + hstep, voffA);
;             PG8_WAIT_V(8); PG8_WAIT_L(0); PG8_BAR; PG8_MMA(0, 0, At, B0); PG8_MMA(0, 1, At, B1); PG8_BAR; PG8_SCHED;
	s_waitcnt lgkmcnt(0)
	v_mfma_f32_16x16x32_bf16 v[60:63], v[146:149], v[188:191], 0
	v_mfma_f32_16x16x32_bf16 v[56:59], v[154:157], v[188:191], 0
	v_mfma_f32_16x16x32_bf16 v[44:47], v[146:149], v[198:201], 0
	v_mfma_f32_16x16x32_bf16 v[40:43], v[154:157], v[198:201], 0
	v_mfma_f32_16x16x32_bf16 v[28:31], v[146:149], v[206:209], 0
	v_mfma_f32_16x16x32_bf16 v[24:27], v[154:157], v[206:209], 0
	v_mfma_f32_16x16x32_bf16 v[12:15], v[146:149], v[214:217], 0
	v_mfma_f32_16x16x32_bf16 v[8:11], v[154:157], v[214:217], 0
	v_mfma_f32_16x16x32_bf16 v[60:63], v[150:153], v[192:195], v[60:63]
	v_mfma_f32_16x16x32_bf16 v[56:59], v[168:171], v[192:195], v[56:59]
	v_mfma_f32_16x16x32_bf16 v[44:47], v[150:153], v[202:205], v[44:47]
	v_mfma_f32_16x16x32_bf16 v[40:43], v[168:171], v[202:205], v[40:43]
	v_mfma_f32_16x16x32_bf16 v[28:31], v[150:153], v[210:213], v[28:31]
	v_mfma_f32_16x16x32_bf16 v[24:27], v[168:171], v[210:213], v[24:27]
	v_mfma_f32_16x16x32_bf16 v[12:15], v[150:153], v[218:221], v[12:15]
	v_mfma_f32_16x16x32_bf16 v[8:11], v[168:171], v[218:221], v[8:11]
	v_mfma_f32_16x16x32_bf16 v[52:55], v[172:175], v[188:191], 0
	v_mfma_f32_16x16x32_bf16 v[48:51], v[180:183], v[188:191], 0
	v_mfma_f32_16x16x32_bf16 v[36:39], v[172:175], v[198:201], 0
	v_mfma_f32_16x16x32_bf16 v[32:35], v[180:183], v[198:201], 0
	v_mfma_f32_16x16x32_bf16 v[20:23], v[172:175], v[206:209], 0
	v_mfma_f32_16x16x32_bf16 v[16:19], v[180:183], v[206:209], 0
	v_mfma_f32_16x16x32_bf16 v[4:7], v[172:175], v[214:217], 0
	v_mfma_f32_16x16x32_bf16 v[0:3], v[180:183], v[214:217], 0
	v_mfma_f32_16x16x32_bf16 v[52:55], v[176:179], v[192:195], v[52:55]
	v_mfma_f32_16x16x32_bf16 v[48:51], v[184:187], v[192:195], v[48:51]
	v_mfma_f32_16x16x32_bf16 v[36:39], v[176:179], v[202:205], v[36:39]
	v_mfma_f32_16x16x32_bf16 v[32:35], v[184:187], v[202:205], v[32:35]
	v_mfma_f32_16x16x32_bf16 v[20:23], v[176:179], v[210:213], v[20:23]
	v_mfma_f32_16x16x32_bf16 v[16:19], v[184:187], v[210:213], v[16:19]
	v_mfma_f32_16x16x32_bf16 v[4:7], v[176:179], v[218:221], v[4:7]
	v_mfma_f32_16x16x32_bf16 v[0:3], v[184:187], v[218:221], v[0:3]
	s_barrier
	s_add_i32 s85, 0, 0x18000
	v_add_u32_e32 v136, s85, v161
	s_add_i32 s86, 0, 0x1c000
	ds_read_b128 v[146:149], v136
	ds_read_b128 v[150:153], v136 offset:1024
	ds_read_b128 v[154:157], v136 offset:2048
	ds_read_b128 v[168:171], v136 offset:3072
	v_add_u32_e32 v136, s86, v161
	ds_read_b128 v[172:175], v136
	ds_read_b128 v[176:179], v136 offset:1024
	ds_read_b128 v[180:183], v136 offset:2048
	ds_read_b128 v[184:187], v136 offset:3072
	s_add_u32 s54, s54, 0x40000
	s_addc_u32 s55, s55, 0
	s_mov_b32 m0, s66
	ds_read_b128 v[188:191], v167 offset:32768
	ds_read_b128 v[192:195], v167 offset:33792
	ds_read_b128 v[198:201], v167 offset:34816
	ds_read_b128 v[202:205], v167 offset:35840
	ds_read_b128 v[206:209], v167 offset:36864
	ds_read_b128 v[210:213], v167 offset:37888
	ds_read_b128 v[214:217], v167 offset:38912
	ds_read_b128 v[218:221], v167 offset:39936
	global_load_lds_dwordx4 v134, s[54:55]
	s_mov_b32 m0, s67
	s_nop 0
	global_load_lds_dwordx4 v130, s[54:55]
	s_waitcnt vmcnt(8)
	s_waitcnt lgkmcnt(0)
	s_barrier
	s_waitcnt lgkmcnt(0)
	v_mfma_f32_16x16x32_bf16 v[124:127], v[146:149], v[188:191], v[124:127]
	v_mfma_f32_16x16x32_bf16 v[120:123], v[154:157], v[188:191], v[120:123]
	v_mfma_f32_16x16x32_bf16 v[108:111], v[146:149], v[198:201], v[108:111]
	v_mfma_f32_16x16x32_bf16 v[104:107], v[154:157], v[198:201], v[104:107]
	v_mfma_f32_16x16x32_bf16 v[92:95], v[146:149], v[206:209], v[92:95]
	v_mfma_f32_16x16x32_bf16 v[88:91], v[154:157], v[206:209], v[88:91]
	v_mfma_f32_16x16x32_bf16 v[76:79], v[146:149], v[214:217], v[76:79]
	v_mfma_f32_16x16x32_bf16 v[72:75], v[154:157], v[214:217], v[72:75]
	v_mfma_f32_16x16x32_bf16 v[124:127], v[150:153], v[192:195], v[124:127]
	v_mfma_f32_16x16x32_bf16 v[120:123], v[168:171], v[192:195], v[120:123]
	v_mfma_f32_16x16x32_bf16 v[108:111], v[150:153], v[202:205], v[108:111]
	v_mfma_f32_16x16x32_bf16 v[104:107], v[168:171], v[202:205], v[104:107]
	v_mfma_f32_16x16x32_bf16 v[92:95], v[150:153], v[210:213], v[92:95]
	v_mfma_f32_16x16x32_bf16 v[88:91], v[168:171], v[210:213], v[88:91]
	v_mfma_f32_16x16x32_bf16 v[76:79], v[150:153], v[218:221], v[76:79]
	v_mfma_f32_16x16x32_bf16 v[72:75], v[168:171], v[218:221], v[72:75]
	v_mfma_f32_16x16x32_bf16 v[116:119], v[172:175], v[188:191], v[116:119]
	v_mfma_f32_16x16x32_bf16 v[112:115], v[180:183], v[188:191], v[112:115]
	v_mfma_f32_16x16x32_bf16 v[100:103], v[172:175], v[198:201], v[100:103]
	v_mfma_f32_16x16x32_bf16 v[96:99], v[180:183], v[198:201], v[96:99]
	v_mfma_f32_16x16x32_bf16 v[84:87], v[172:175], v[206:209], v[84:87]
	v_mfma_f32_16x16x32_bf16 v[80:83], v[180:183], v[206:209], v[80:83]
	v_mfma_f32_16x16x32_bf16 v[68:71], v[172:175], v[214:217], v[68:71]
	v_mfma_f32_16x16x32_bf16 v[64:67], v[180:183], v[214:217], v[64:67]
	v_mfma_f32_16x16x32_bf16 v[116:119], v[176:179], v[192:195], v[116:119]
	v_mfma_f32_16x16x32_bf16 v[112:115], v[184:187], v[192:195], v[112:115]
	v_mfma_f32_16x16x32_bf16 v[100:103], v[176:179], v[202:205], v[100:103]
	v_mfma_f32_16x16x32_bf16 v[96:99], v[184:187], v[202:205], v[96:99]
	v_mfma_f32_16x16x32_bf16 v[84:87], v[176:179], v[210:213], v[84:87]
	v_mfma_f32_16x16x32_bf16 v[80:83], v[184:187], v[210:213], v[80:83]
	v_mfma_f32_16x16x32_bf16 v[68:71], v[176:179], v[218:221], v[68:71]
	v_mfma_f32_16x16x32_bf16 v[64:67], v[184:187], v[218:221], v[64:67]
	s_barrier
; #define PG8_STAGE(bufoff, gbase, voff) do { _Pragma("unroll") for (int _i = 0; _i < 2; ++_i) \
;         __builtin_amdgcn_global_load_lds((const unsigned*)((const char*)(gbase) + (voff)[_i]), (PG8_LAS unsigned*)(lds + (bufoff) + ldsw + _i * 8192), 16, 0, 0); } while (0)
; #define PG8_LDA(dst, b, h) do { _Pragma("unroll") for (int m = 0; m < 4; ++m) _Pragma("unroll") for (int k = 0; k < 2; ++k) dst[m][k] = *(const PG8_LAS bf16x8*)(lds + PG8_SA(b, h) + aoff + m * 2048 + k * 1024); } while (0)
; #define PG8_LDB(dst, b, h) do { _Pragma("unroll") for (int n = 0; n < 2; ++n) _Pragma("unroll") for (int k = 0; k < 2; ++k) dst[n][k] = *(const PG8_LAS bf16x8*)(lds + PG8_SB(b, h) + boff + n * 2048 + k * 1024); } while (0)
; #define PG8_MMA(ai, bj, At, Bt) do { __builtin_amdgcn_s_setprio(1); _Pragma("unroll") for (int m = 0; m < 4; ++m) _Pragma("unroll") for (int n = 0; n < 2; ++n) _Pragma("unroll") for (int k = 0; k < 2; ++k) \
;         acc[ai][bj][m][n] = __builtin_amdgcn_mfma_f32_16x16x32_bf16(Bt[n][k], At[m][k], acc[ai][bj][m][n], 0, 0, 0); __builtin_amdgcn_s_setprio(0); } while (0)
; #define PG8_WAIT_V(n) asm volatile("s_waitcnt vmcnt(" #n ")" ::: "memory")
; #define PG8_BAR __builtin_amdgcn_s_barrier()
; template <class Epi, class Sched, bool ALIGN_EPI = false, bool SP2 = false>
; __device__ __forceinline__ void gemm_phase(PG8_LAS unsigned char* lds, const Gemm g, const Sched& S, const Epi& E) {
;     ...
;         for (int t = 0; t < nt; t += 2) {
;             const bool last = (t == nt - 2);
;             const char* a1 = cA + (size_t)(t + 1) * kstep;
;             const char* a2 = last ? nA : cA + (size_t)(t + 2) * kstep; const char* b2 = last ? nB : cB + (size_t)(t + 2) * kstep;
;             const char* a3 = a2 + kstep; const char* b3 = b2 + kstep;
;             if (last && has_next) S.a_ready(nxt);
;             if constexpr (SP2) {
;             PG8_LDB(B0, 0, 0); PG8_LDB(B1, 0, 1); PG8_SCHED; PG8_LDA(At, 0, 0); PG8_STAGE(PG8_SA(1, 1), a1 + hstep, voffA);
;             PG8_WAIT_V(8); PG8_WAIT_L(0); PG8_BAR; PG8_MMA(0, 0, At, B0); PG8_MMA(0, 1, At, B1); PG8_BAR; PG8_SCHED;
;     ...
;             PG8_LDA(At, 1, 1); PG8_STAGE(PG8_SB(1, 0), b3, voffB); PG8_STAGE(PG8_SB(1, 1), b3 + hstep, voffB); PG8_STAGE(PG8_SA(1, 0), a3, voffA);
;             PG8_WAIT_V(8); PG8_WAIT_L(0); PG8_BAR; PG8_MMA(1, 0, At, B0); PG8_MMA(1, 1, At, B1); PG8_BAR; PG8_SCHED;
	s_add_i32 s54, s85, s63
	s_mov_b32 m0, s54
	ds_read_b128 v[188:191], v167 offset:49152
	ds_read_b128 v[192:195], v167 offset:50176
	ds_read_b128 v[198:201], v167 offset:51200
	ds_read_b128 v[202:205], v167 offset:52224
	ds_read_b128 v[206:209], v167 offset:53248
	ds_read_b128 v[210:213], v167 offset:54272
	ds_read_b128 v[214:217], v167 offset:55296
	ds_read_b128 v[218:221], v167 offset:56320
	global_load_lds_dwordx4 v132, s[98:99]
	s_add_i32 m0, s54, 0x2000
	s_add_u32 s52, s52, 0x40080
	s_addc_u32 s53, s53, 0
	s_add_i32 s54, s86, s63
	global_load_lds_dwordx4 v128, s[98:99]
	s_mov_b32 m0, s54
	s_nop 0
	global_load_lds_dwordx4 v132, s[52:53]
	s_add_i32 m0, s54, 0x2000
	s_nop 0
	global_load_lds_dwordx4 v128, s[52:53]
	s_mov_b32 m0, s69
	s_nop 0
	global_load_lds_dwordx4 v134, s[100:101]
	s_mov_b32 m0, s70
	s_nop 0
	global_load_lds_dwordx4 v130, s[100:101]
	s_waitcnt vmcnt(8)
	s_waitcnt lgkmcnt(0)
	s_barrier
	s_waitcnt lgkmcnt(0)
	v_mfma_f32_16x16x32_bf16 v[60:63], v[146:149], v[188:191], v[60:63]
	v_mfma_f32_16x16x32_bf16 v[56:59], v[154:157], v[188:191], v[56:59]
	v_mfma_f32_16x16x32_bf16 v[44:47], v[146:149], v[198:201], v[44:47]
	v_mfma_f32_16x16x32_bf16 v[40:43], v[154:157], v[198:201], v[40:43]
	v_mfma_f32_16x16x32_bf16 v[28:31], v[146:149], v[206:209], v[28:31]
	v_mfma_f32_16x16x32_bf16 v[24:27], v[154:157], v[206:209], v[24:27]
	v_mfma_f32_16x16x32_bf16 v[12:15], v[146:149], v[214:217], v[12:15]
	v_mfma_f32_16x16x32_bf16 v[8:11], v[154:157], v[214:217], v[8:11]
	v_mfma_f32_16x16x32_bf16 v[60:63], v[150:153], v[192:195], v[60:63]
	v_mfma_f32_16x16x32_bf16 v[56:59], v[168:171], v[192:195], v[56:59]
	v_mfma_f32_16x16x32_bf16 v[44:47], v[150:153], v[202:205], v[44:47]
	v_mfma_f32_16x16x32_bf16 v[40:43], v[168:171], v[202:205], v[40:43]
	v_mfma_f32_16x16x32_bf16 v[28:31], v[150:153], v[210:213], v[28:31]
	v_mfma_f32_16x16x32_bf16 v[24:27], v[168:171], v[210:213], v[24:27]
	v_mfma_f32_16x16x32_bf16 v[12:15], v[150:153], v[218:221], v[12:15]
	v_mfma_f32_16x16x32_bf16 v[8:11], v[168:171], v[218:221], v[8:11]
	v_mfma_f32_16x16x32_bf16 v[52:55], v[172:175], v[188:191], v[52:55]
	v_mfma_f32_16x16x32_bf16 v[48:51], v[180:183], v[188:191], v[48:51]
	v_mfma_f32_16x16x32_bf16 v[36:39], v[172:175], v[198:201], v[36:39]
	v_mfma_f32_16x16x32_bf16 v[32:35], v[180:183], v[198:201], v[32:35]
	v_mfma_f32_16x16x32_bf16 v[20:23], v[172:175], v[206:209], v[20:23]
	v_mfma_f32_16x16x32_bf16 v[16:19], v[180:183], v[206:209], v[16:19]
	v_mfma_f32_16x16x32_bf16 v[4:7], v[172:175], v[214:217], v[4:7]
	v_mfma_f32_16x16x32_bf16 v[0:3], v[180:183], v[214:217], v[0:3]
	v_mfma_f32_16x16x32_bf16 v[52:55], v[176:179], v[192:195], v[52:55]
	v_mfma_f32_16x16x32_bf16 v[48:51], v[184:187], v[192:195], v[48:51]
	v_mfma_f32_16x16x32_bf16 v[36:39], v[176:179], v[202:205], v[36:39]
	v_mfma_f32_16x16x32_bf16 v[32:35], v[184:187], v[202:205], v[32:35]
	v_mfma_f32_16x16x32_bf16 v[20:23], v[176:179], v[210:213], v[20:23]
	v_mfma_f32_16x16x32_bf16 v[16:19], v[184:187], v[210:213], v[16:19]
	v_mfma_f32_16x16x32_bf16 v[4:7], v[176:179], v[218:221], v[4:7]
	v_mfma_f32_16x16x32_bf16 v[0:3], v[184:187], v[218:221], v[0:3]
	s_barrier
	s_add_i32 s84, s84, 2
	s_add_u32 s20, s20, 0x100
	s_addc_u32 s21, s21, 0
	s_add_u32 s80, s80, 0x100
	s_addc_u32 s81, s81, 0
	s_cmp_gt_u32 s84, 13
.LBB0_414:
	ds_read_b128 v[146:149], v165
	ds_read_b128 v[150:153], v165 offset:1024
	ds_read_b128 v[154:157], v165 offset:2048
	ds_read_b128 v[168:171], v165 offset:3072
	ds_read_b128 v[172:175], v166
	ds_read_b128 v[176:179], v166 offset:1024
	ds_read_b128 v[180:183], v166 offset:2048
	ds_read_b128 v[184:187], v166 offset:3072
	s_add_u32 s52, s20, 0xfffc0080
	s_addc_u32 s53, s21, -1
	s_cmp_eq_u32 s84, 12
	s_cselect_b32 s55, s43, s53
	s_cselect_b32 s54, s78, s52
	s_cselect_b32 s53, s19, s81
	s_cselect_b32 s52, s79, s80
	s_add_i32 m0, s35, 0xc000
	ds_read_b128 v[188:191], v167
	ds_read_b128 v[192:195], v167 offset:1024
	ds_read_b128 v[198:201], v167 offset:2048
	ds_read_b128 v[202:205], v167 offset:3072
	ds_read_b128 v[206:209], v167 offset:4096
	ds_read_b128 v[210:213], v167 offset:5120
	ds_read_b128 v[214:217], v167 offset:6144
	ds_read_b128 v[218:221], v167 offset:7168
	global_load_lds_dwordx4 v138, s[20:21]
	s_add_i32 m0, s35, 0xe000
	s_nop 0
	global_load_lds_dwordx4 v140, s[20:21]
	s_waitcnt vmcnt(8)
	s_waitcnt lgkmcnt(0)
	s_barrier
	s_waitcnt lgkmcnt(0)
	v_mfma_f32_16x16x32_bf16 v[124:127], v[146:149], v[188:191], v[124:127]
	v_mfma_f32_16x16x32_bf16 v[120:123], v[154:157], v[188:191], v[120:123]
	v_mfma_f32_16x16x32_bf16 v[108:111], v[146:149], v[198:201], v[108:111]
	v_mfma_f32_16x16x32_bf16 v[104:107], v[154:157], v[198:201], v[104:107]
	v_mfma_f32_16x16x32_bf16 v[92:95], v[146:149], v[206:209], v[92:95]
	v_mfma_f32_16x16x32_bf16 v[88:91], v[154:157], v[206:209], v[88:91]
	v_mfma_f32_16x16x32_bf16 v[76:79], v[146:149], v[214:217], v[76:79]
	v_mfma_f32_16x16x32_bf16 v[72:75], v[154:157], v[214:217], v[72:75]
	v_mfma_f32_16x16x32_bf16 v[124:127], v[150:153], v[192:195], v[124:127]
	v_mfma_f32_16x16x32_bf16 v[120:123], v[168:171], v[192:195], v[120:123]
	v_mfma_f32_16x16x32_bf16 v[108:111], v[150:153], v[202:205], v[108:111]
	v_mfma_f32_16x16x32_bf16 v[104:107], v[168:171], v[202:205], v[104:107]
	v_mfma_f32_16x16x32_bf16 v[92:95], v[150:153], v[210:213], v[92:95]
	v_mfma_f32_16x16x32_bf16 v[88:91], v[168:171], v[210:213], v[88:91]
	v_mfma_f32_16x16x32_bf16 v[76:79], v[150:153], v[218:221], v[76:79]
	v_mfma_f32_16x16x32_bf16 v[72:75], v[168:171], v[218:221], v[72:75]
	v_mfma_f32_16x16x32_bf16 v[116:119], v[172:175], v[188:191], v[116:119]
	v_mfma_f32_16x16x32_bf16 v[112:115], v[180:183], v[188:191], v[112:115]
	v_mfma_f32_16x16x32_bf16 v[100:103], v[172:175], v[198:201], v[100:103]
	v_mfma_f32_16x16x32_bf16 v[96:99], v[180:183], v[198:201], v[96:99]
	v_mfma_f32_16x16x32_bf16 v[84:87], v[172:175], v[206:209], v[84:87]
	v_mfma_f32_16x16x32_bf16 v[80:83], v[180:183], v[206:209], v[80:83]
	v_mfma_f32_16x16x32_bf16 v[68:71], v[172:175], v[214:217], v[68:71]
	v_mfma_f32_16x16x32_bf16 v[64:67], v[180:183], v[214:217], v[64:67]
	v_mfma_f32_16x16x32_bf16 v[116:119], v[176:179], v[192:195], v[116:119]
	v_mfma_f32_16x16x32_bf16 v[112:115], v[184:187], v[192:195], v[112:115]
	v_mfma_f32_16x16x32_bf16 v[100:103], v[176:179], v[202:205], v[100:103]
	v_mfma_f32_16x16x32_bf16 v[96:99], v[184:187], v[202:205], v[96:99]
	v_mfma_f32_16x16x32_bf16 v[84:87], v[176:179], v[210:213], v[84:87]
	v_mfma_f32_16x16x32_bf16 v[80:83], v[184:187], v[210:213], v[80:83]
	v_mfma_f32_16x16x32_bf16 v[68:71], v[176:179], v[218:221], v[68:71]
	v_mfma_f32_16x16x32_bf16 v[64:67], v[184:187], v[218:221], v[64:67]
	s_barrier
; #define PG8_STAGE(bufoff, gbase, voff) do { _Pragma("unroll") for (int _i = 0; _i < 2; ++_i) \
;         __builtin_amdgcn_global_load_lds((const unsigned*)((const char*)(gbase) + (voff)[_i]), (PG8_LAS unsigned*)(lds + (bufoff) + ldsw + _i * 8192), 16, 0, 0); } while (0)
; #define PG8_LDA(dst, b, h) do { _Pragma("unroll") for (int m = 0; m < 4; ++m) _Pragma("unroll") for (int k = 0; k < 2; ++k) dst[m][k] = *(const PG8_LAS bf16x8*)(lds + PG8_SA(b, h) + aoff + m * 2048 + k * 1024); } while (0)
; #define PG8_LDB(dst, b, h) do { _Pragma("unroll") for (int n = 0; n < 2; ++n) _Pragma("unroll") for (int k = 0; k < 2; ++k) dst[n][k] = *(const PG8_LAS bf16x8*)(lds + PG8_SB(b, h) + boff + n * 2048 + k * 1024); } while (0)
; #define PG8_MMA(ai, bj, At, Bt) do { __builtin_amdgcn_s_setprio(1); _Pragma("unroll") for (int m = 0; m < 4; ++m) _Pragma("unroll") for (int n = 0; n < 2; ++n) _Pragma("unroll") for (int k = 0; k < 2; ++k) \
;         acc[ai][bj][m][n] = __builtin_amdgcn_mfma_f32_16x16x32_bf16(Bt[n][k], At[m][k], acc[ai][bj][m][n], 0, 0, 0); __builtin_amdgcn_s_setprio(0); } while (0)
; #define PG8_WAIT_V(n) asm volatile("s_waitcnt vmcnt(" #n ")" ::: "memory")
; #define PG8_WAIT_L(n) asm volatile("s_waitcnt lgkmcnt(" #n ")" ::: "memory")
; #define PG8_BAR __builtin_amdgcn_s_barrier()
; #define PG8_SCHED __builtin_amdgcn_sched_barrier(0)
; template <class Epi, class Sched, bool ALIGN_EPI = false, bool SP2 = false>
; __device__ __forceinline__ void gemm_phase(PG8_LAS unsigned char* lds, const Gemm g, const Sched& S, const Epi& E) {
;     ...
;             PG8_LDA(At, 0, 1); PG8_STAGE(PG8_SB(0, 0), b2, voffB); PG8_STAGE(PG8_SB(0, 1), b2 + hstep, voffB); PG8_STAGE(PG8_SA(0, 0), a2, voffA);
;             PG8_WAIT_V(8); PG8_WAIT_L(0); PG8_BAR; PG8_MMA(1, 0, At, B0); PG8_MMA(1, 1, At, B1); PG8_BAR; PG8_SCHED;
;             PG8_LDB(B0, 1, 0); PG8_LDB(B1, 1, 1); PG8_SCHED; PG8_LDA(At, 1, 0); PG8_STAGE(PG8_SA(0, 1), a2 + hstep, voffA);
;             PG8_WAIT_V(8); PG8_WAIT_L(0); PG8_BAR; PG8_MMA(0, 0, At, B0); PG8_MMA(0, 1, At, B1); PG8_BAR; PG8_SCHED;
	s_add_i32 s85, s72, s63
	s_add_u32 s98, s52, s8
	s_addc_u32 s99, s53, s9
	s_add_u32 s100, s54, s8
	s_addc_u32 s101, s55, s9
	s_mov_b32 m0, s85
	ds_read_b128 v[188:191], v167 offset:16384
	ds_read_b128 v[192:195], v167 offset:17408
	ds_read_b128 v[198:201], v167 offset:18432
	ds_read_b128 v[202:205], v167 offset:19456
	ds_read_b128 v[206:209], v167 offset:20480
	ds_read_b128 v[210:213], v167 offset:21504
	ds_read_b128 v[214:217], v167 offset:22528
	ds_read_b128 v[218:221], v167 offset:23552
	global_load_lds_dwordx4 v132, s[52:53]
	s_add_i32 m0, s85, 0x2000
	s_add_u32 s86, s52, 0x40000
	s_addc_u32 s87, s53, 0
	s_add_i32 s85, s73, s63
	global_load_lds_dwordx4 v128, s[52:53]
	s_mov_b32 m0, s85
	s_nop 0
	global_load_lds_dwordx4 v132, s[86:87]
	s_add_i32 m0, s85, 0x2000
	s_nop 0
	global_load_lds_dwordx4 v128, s[86:87]
	s_mov_b32 m0, s35
	s_nop 0
	global_load_lds_dwordx4 v134, s[54:55]
	s_mov_b32 m0, s65
	s_nop 0
	global_load_lds_dwordx4 v130, s[54:55]
	s_waitcnt vmcnt(8)
	s_waitcnt lgkmcnt(0)
	s_barrier
	s_waitcnt lgkmcnt(0)
	v_mfma_f32_16x16x32_bf16 v[60:63], v[146:149], v[188:191], v[60:63]
	v_mfma_f32_16x16x32_bf16 v[56:59], v[154:157], v[188:191], v[56:59]
	v_mfma_f32_16x16x32_bf16 v[44:47], v[146:149], v[198:201], v[44:47]
	v_mfma_f32_16x16x32_bf16 v[40:43], v[154:157], v[198:201], v[40:43]
	v_mfma_f32_16x16x32_bf16 v[28:31], v[146:149], v[206:209], v[28:31]
	v_mfma_f32_16x16x32_bf16 v[24:27], v[154:157], v[206:209], v[24:27]
	v_mfma_f32_16x16x32_bf16 v[12:15], v[146:149], v[214:217], v[12:15]
	v_mfma_f32_16x16x32_bf16 v[8:11], v[154:157], v[214:217], v[8:11]
	v_mfma_f32_16x16x32_bf16 v[60:63], v[150:153], v[192:195], v[60:63]
	v_mfma_f32_16x16x32_bf16 v[56:59], v[168:171], v[192:195], v[56:59]
	v_mfma_f32_16x16x32_bf16 v[44:47], v[150:153], v[202:205], v[44:47]
	v_mfma_f32_16x16x32_bf16 v[40:43], v[168:171], v[202:205], v[40:43]
	v_mfma_f32_16x16x32_bf16 v[28:31], v[150:153], v[210:213], v[28:31]
	v_mfma_f32_16x16x32_bf16 v[24:27], v[168:171], v[210:213], v[24:27]
	v_mfma_f32_16x16x32_bf16 v[12:15], v[150:153], v[218:221], v[12:15]
	v_mfma_f32_16x16x32_bf16 v[8:11], v[168:171], v[218:221], v[8:11]
	v_mfma_f32_16x16x32_bf16 v[52:55], v[172:175], v[188:191], v[52:55]
	v_mfma_f32_16x16x32_bf16 v[48:51], v[180:183], v[188:191], v[48:51]
	v_mfma_f32_16x16x32_bf16 v[36:39], v[172:175], v[198:201], v[36:39]
	v_mfma_f32_16x16x32_bf16 v[32:35], v[180:183], v[198:201], v[32:35]
	v_mfma_f32_16x16x32_bf16 v[20:23], v[172:175], v[206:209], v[20:23]
	v_mfma_f32_16x16x32_bf16 v[16:19], v[180:183], v[206:209], v[16:19]
	v_mfma_f32_16x16x32_bf16 v[4:7], v[172:175], v[214:217], v[4:7]
	v_mfma_f32_16x16x32_bf16 v[0:3], v[180:183], v[214:217], v[0:3]
	v_mfma_f32_16x16x32_bf16 v[52:55], v[176:179], v[192:195], v[52:55]
	v_mfma_f32_16x16x32_bf16 v[48:51], v[184:187], v[192:195], v[48:51]
	v_mfma_f32_16x16x32_bf16 v[36:39], v[176:179], v[202:205], v[36:39]
	v_mfma_f32_16x16x32_bf16 v[32:35], v[184:187], v[202:205], v[32:35]
	v_mfma_f32_16x16x32_bf16 v[20:23], v[176:179], v[210:213], v[20:23]
	v_mfma_f32_16x16x32_bf16 v[16:19], v[184:187], v[210:213], v[16:19]
	v_mfma_f32_16x16x32_bf16 v[4:7], v[176:179], v[218:221], v[4:7]
	v_mfma_f32_16x16x32_bf16 v[0:3], v[184:187], v[218:221], v[0:3]
	s_barrier
	s_add_i32 s85, 0, 0x18000
	v_add_u32_e32 v136, s85, v161
	s_add_i32 s86, 0, 0x1c000
	ds_read_b128 v[146:149], v136
	ds_read_b128 v[150:153], v136 offset:1024
	ds_read_b128 v[154:157], v136 offset:2048
	ds_read_b128 v[168:171], v136 offset:3072
	v_add_u32_e32 v136, s86, v161
	ds_read_b128 v[172:175], v136
	ds_read_b128 v[176:179], v136 offset:1024
	ds_read_b128 v[180:183], v136 offset:2048
	ds_read_b128 v[184:187], v136 offset:3072
	s_add_u32 s54, s54, 0x40000
	s_addc_u32 s55, s55, 0
	s_mov_b32 m0, s66
	ds_read_b128 v[188:191], v167 offset:32768
	ds_read_b128 v[192:195], v167 offset:33792
	ds_read_b128 v[198:201], v167 offset:34816
	ds_read_b128 v[202:205], v167 offset:35840
	ds_read_b128 v[206:209], v167 offset:36864
	ds_read_b128 v[210:213], v167 offset:37888
	ds_read_b128 v[214:217], v167 offset:38912
	ds_read_b128 v[218:221], v167 offset:39936
	global_load_lds_dwordx4 v134, s[54:55]
	s_mov_b32 m0, s67
	s_nop 0
	global_load_lds_dwordx4 v130, s[54:55]
	s_waitcnt vmcnt(8)
	s_waitcnt lgkmcnt(0)
	s_barrier
; #define PG8_STAGE(bufoff, gbase, voff) do { _Pragma("unroll") for (int _i = 0; _i < 2; ++_i) \
;         __builtin_amdgcn_global_load_lds((const unsigned*)((const char*)(gbase) + (voff)[_i]), (PG8_LAS unsigned*)(lds + (bufoff) + ldsw + _i * 8192), 16, 0, 0); } while (0)
; #define PG8_LDA(dst, b, h) do { _Pragma("unroll") for (int m = 0; m < 4; ++m) _Pragma("unroll") for (int k = 0; k < 2; ++k) dst[m][k] = *(const PG8_LAS bf16x8*)(lds + PG8_SA(b, h) + aoff + m * 2048 + k * 1024); } while (0)
; #define PG8_MMA(ai, bj, At, Bt) do { __builtin_amdgcn_s_setprio(1); _Pragma("unroll") for (int m = 0; m < 4; ++m) _Pragma("unroll") for (int n = 0; n < 2; ++n) _Pragma("unroll") for (int k = 0; k < 2; ++k) \
;         acc[ai][bj][m][n] = __builtin_amdgcn_mfma_f32_16x16x32_bf16(Bt[n][k], At[m][k], acc[ai][bj][m][n], 0, 0, 0); __builtin_amdgcn_s_setprio(0); } while (0)
; #define PG8_WAIT_V(n) asm volatile("s_waitcnt vmcnt(" #n ")" ::: "memory")
; #define PG8_WAIT_L(n) asm volatile("s_waitcnt lgkmcnt(" #n ")" ::: "memory")
; #define PG8_BAR __builtin_amdgcn_s_barrier()
; #define PG8_SCHED __builtin_amdgcn_sched_barrier(0)
; template <class Epi, class Sched, bool ALIGN_EPI = false, bool SP2 = false>
; __device__ __forceinline__ void gemm_phase(PG8_LAS unsigned char* lds, const Gemm g, const Sched& S, const Epi& E) {
;     ...
;             PG8_WAIT_V(8); PG8_WAIT_L(0); PG8_BAR; PG8_MMA(0, 0, At, B0); PG8_MMA(0, 1, At, B1); PG8_BAR; PG8_SCHED;
;             PG8_LDA(At, 1, 1); PG8_STAGE(PG8_SB(1, 0), b3, voffB); PG8_STAGE(PG8_SB(1, 1), b3 + hstep, voffB); PG8_STAGE(PG8_SA(1, 0), a3, voffA);
;             PG8_WAIT_V(8); PG8_WAIT_L(0); PG8_BAR; PG8_MMA(1, 0, At, B0); PG8_MMA(1, 1, At, B1); PG8_BAR; PG8_SCHED;
;     ...
;         if constexpr (ALIGN_EPI) { if (wr == 0) PG8_BAR; }
	s_waitcnt lgkmcnt(0)
	v_mfma_f32_16x16x32_bf16 v[124:127], v[146:149], v[188:191], v[124:127]
	v_mfma_f32_16x16x32_bf16 v[120:123], v[154:157], v[188:191], v[120:123]
	v_mfma_f32_16x16x32_bf16 v[108:111], v[146:149], v[198:201], v[108:111]
	v_mfma_f32_16x16x32_bf16 v[104:107], v[154:157], v[198:201], v[104:107]
	v_mfma_f32_16x16x32_bf16 v[92:95], v[146:149], v[206:209], v[92:95]
	v_mfma_f32_16x16x32_bf16 v[88:91], v[154:157], v[206:209], v[88:91]
	v_mfma_f32_16x16x32_bf16 v[76:79], v[146:149], v[214:217], v[76:79]
	v_mfma_f32_16x16x32_bf16 v[72:75], v[154:157], v[214:217], v[72:75]
	v_mfma_f32_16x16x32_bf16 v[124:127], v[150:153], v[192:195], v[124:127]
	v_mfma_f32_16x16x32_bf16 v[120:123], v[168:171], v[192:195], v[120:123]
	v_mfma_f32_16x16x32_bf16 v[108:111], v[150:153], v[202:205], v[108:111]
	v_mfma_f32_16x16x32_bf16 v[104:107], v[168:171], v[202:205], v[104:107]
	v_mfma_f32_16x16x32_bf16 v[92:95], v[150:153], v[210:213], v[92:95]
	v_mfma_f32_16x16x32_bf16 v[88:91], v[168:171], v[210:213], v[88:91]
	v_mfma_f32_16x16x32_bf16 v[76:79], v[150:153], v[218:221], v[76:79]
	v_mfma_f32_16x16x32_bf16 v[72:75], v[168:171], v[218:221], v[72:75]
	v_mfma_f32_16x16x32_bf16 v[116:119], v[172:175], v[188:191], v[116:119]
	v_mfma_f32_16x16x32_bf16 v[112:115], v[180:183], v[188:191], v[112:115]
	v_mfma_f32_16x16x32_bf16 v[100:103], v[172:175], v[198:201], v[100:103]
	v_mfma_f32_16x16x32_bf16 v[96:99], v[180:183], v[198:201], v[96:99]
	v_mfma_f32_16x16x32_bf16 v[84:87], v[172:175], v[206:209], v[84:87]
	v_mfma_f32_16x16x32_bf16 v[80:83], v[180:183], v[206:209], v[80:83]
	v_mfma_f32_16x16x32_bf16 v[68:71], v[172:175], v[214:217], v[68:71]
	v_mfma_f32_16x16x32_bf16 v[64:67], v[180:183], v[214:217], v[64:67]
	v_mfma_f32_16x16x32_bf16 v[116:119], v[176:179], v[192:195], v[116:119]
	v_mfma_f32_16x16x32_bf16 v[112:115], v[184:187], v[192:195], v[112:115]
	v_mfma_f32_16x16x32_bf16 v[100:103], v[176:179], v[202:205], v[100:103]
	v_mfma_f32_16x16x32_bf16 v[96:99], v[184:187], v[202:205], v[96:99]
	v_mfma_f32_16x16x32_bf16 v[84:87], v[176:179], v[210:213], v[84:87]
	v_mfma_f32_16x16x32_bf16 v[80:83], v[184:187], v[210:213], v[80:83]
	v_mfma_f32_16x16x32_bf16 v[68:71], v[176:179], v[218:221], v[68:71]
	v_mfma_f32_16x16x32_bf16 v[64:67], v[184:187], v[218:221], v[64:67]
	s_barrier
	s_add_i32 s54, s85, s63
	s_mov_b32 m0, s54
	ds_read_b128 v[188:191], v167 offset:49152
	ds_read_b128 v[192:195], v167 offset:50176
	ds_read_b128 v[198:201], v167 offset:51200
	ds_read_b128 v[202:205], v167 offset:52224
	ds_read_b128 v[206:209], v167 offset:53248
	ds_read_b128 v[210:213], v167 offset:54272
	ds_read_b128 v[214:217], v167 offset:55296
	ds_read_b128 v[218:221], v167 offset:56320
	global_load_lds_dwordx4 v132, s[98:99]
	s_add_i32 m0, s54, 0x2000
	s_add_u32 s52, s52, 0x40080
	s_addc_u32 s53, s53, 0
	s_add_i32 s54, s86, s63
	global_load_lds_dwordx4 v128, s[98:99]
	s_mov_b32 m0, s54
	s_nop 0
	global_load_lds_dwordx4 v132, s[52:53]
	s_add_i32 m0, s54, 0x2000
	s_nop 0
	global_load_lds_dwordx4 v128, s[52:53]
	s_mov_b32 m0, s69
	s_nop 0
	global_load_lds_dwordx4 v134, s[100:101]
	s_mov_b32 m0, s70
	s_nop 0
	global_load_lds_dwordx4 v130, s[100:101]
	s_waitcnt vmcnt(8)
	s_waitcnt lgkmcnt(0)
	s_barrier
	s_waitcnt lgkmcnt(0)
	v_mfma_f32_16x16x32_bf16 v[60:63], v[146:149], v[188:191], v[60:63]
	v_mfma_f32_16x16x32_bf16 v[56:59], v[154:157], v[188:191], v[56:59]
	v_mfma_f32_16x16x32_bf16 v[44:47], v[146:149], v[198:201], v[44:47]
	v_mfma_f32_16x16x32_bf16 v[40:43], v[154:157], v[198:201], v[40:43]
	v_mfma_f32_16x16x32_bf16 v[28:31], v[146:149], v[206:209], v[28:31]
	v_mfma_f32_16x16x32_bf16 v[24:27], v[154:157], v[206:209], v[24:27]
	v_mfma_f32_16x16x32_bf16 v[12:15], v[146:149], v[214:217], v[12:15]
	v_mfma_f32_16x16x32_bf16 v[8:11], v[154:157], v[214:217], v[8:11]
	v_mfma_f32_16x16x32_bf16 v[60:63], v[150:153], v[192:195], v[60:63]
	v_mfma_f32_16x16x32_bf16 v[56:59], v[168:171], v[192:195], v[56:59]
	v_mfma_f32_16x16x32_bf16 v[44:47], v[150:153], v[202:205], v[44:47]
	v_mfma_f32_16x16x32_bf16 v[40:43], v[168:171], v[202:205], v[40:43]
	v_mfma_f32_16x16x32_bf16 v[28:31], v[150:153], v[210:213], v[28:31]
	v_mfma_f32_16x16x32_bf16 v[24:27], v[168:171], v[210:213], v[24:27]
	v_mfma_f32_16x16x32_bf16 v[12:15], v[150:153], v[218:221], v[12:15]
	v_mfma_f32_16x16x32_bf16 v[8:11], v[168:171], v[218:221], v[8:11]
	v_mfma_f32_16x16x32_bf16 v[52:55], v[172:175], v[188:191], v[52:55]
	v_mfma_f32_16x16x32_bf16 v[48:51], v[180:183], v[188:191], v[48:51]
	v_mfma_f32_16x16x32_bf16 v[36:39], v[172:175], v[198:201], v[36:39]
	v_mfma_f32_16x16x32_bf16 v[32:35], v[180:183], v[198:201], v[32:35]
	v_mfma_f32_16x16x32_bf16 v[20:23], v[172:175], v[206:209], v[20:23]
	v_mfma_f32_16x16x32_bf16 v[16:19], v[180:183], v[206:209], v[16:19]
	v_mfma_f32_16x16x32_bf16 v[4:7], v[172:175], v[214:217], v[4:7]
	v_mfma_f32_16x16x32_bf16 v[0:3], v[180:183], v[214:217], v[0:3]
	v_mfma_f32_16x16x32_bf16 v[52:55], v[176:179], v[192:195], v[52:55]
	v_mfma_f32_16x16x32_bf16 v[48:51], v[184:187], v[192:195], v[48:51]
	v_mfma_f32_16x16x32_bf16 v[36:39], v[176:179], v[202:205], v[36:39]
	v_mfma_f32_16x16x32_bf16 v[32:35], v[184:187], v[202:205], v[32:35]
	v_mfma_f32_16x16x32_bf16 v[20:23], v[176:179], v[210:213], v[20:23]
	v_mfma_f32_16x16x32_bf16 v[16:19], v[184:187], v[210:213], v[16:19]
	v_mfma_f32_16x16x32_bf16 v[4:7], v[176:179], v[218:221], v[4:7]
	v_mfma_f32_16x16x32_bf16 v[0:3], v[184:187], v[218:221], v[0:3]
	s_barrier
	s_add_i32 s84, s84, 2
	s_add_u32 s20, s20, 0x100
	s_addc_u32 s21, s21, 0
	s_add_u32 s80, s80, 0x100
	s_addc_u32 s81, s81, 0
	s_cmp_gt_u32 s84, 13
	s_cbranch_scc0 .LBB0_414
	s_and_b64 vcc, exec, s[10:11]
	s_cbranch_vccz .LBB0_417
	s_barrier

; #define PG8_STAGE(bufoff, gbase, voff) do { _Pragma("unroll") for (int _i = 0; _i < 2; ++_i) \
;         __builtin_amdgcn_global_load_lds((const unsigned*)((const char*)(gbase) + (voff)[_i]), (PG8_LAS unsigned*)(lds + (bufoff) + ldsw + _i * 8192), 16, 0, 0); } while (0)
; #define PG8_LDA(dst, b, h) do { _Pragma("unroll") for (int m = 0; m < 4; ++m) _Pragma("unroll") for (int k = 0; k < 2; ++k) dst[m][k] = *(const PG8_LAS bf16x8*)(lds + PG8_SA(b, h) + aoff + m * 2048 + k * 1024); } while (0)
; #define PG8_LDB(dst, b, h) do { _Pragma("unroll") for (int n = 0; n < 2; ++n) _Pragma("unroll") for (int k = 0; k < 2; ++k) dst[n][k] = *(const PG8_LAS bf16x8*)(lds + PG8_SB(b, h) + boff + n * 2048 + k * 1024); } while (0)
; #define PG8_MMA(ai, bj, At, Bt) do { __builtin_amdgcn_s_setprio(1); _Pragma("unroll") for (int m = 0; m < 4; ++m) _Pragma("unroll") for (int n = 0; n < 2; ++n) _Pragma("unroll") for (int k = 0; k < 2; ++k) \
;         acc[ai][bj][m][n] = __builtin_amdgcn_mfma_f32_16x16x32_bf16(Bt[n][k], At[m][k], acc[ai][bj][m][n], 0, 0, 0); __builtin_amdgcn_s_setprio(0); } while (0)
; #define PG8_BAR __builtin_amdgcn_s_barrier()
; template <class Epi, class Sched, bool ALIGN_EPI = false, bool SP2 = false>
; __device__ __forceinline__ void gemm_phase(PG8_LAS unsigned char* lds, const Gemm g, const Sched& S, const Epi& E) {
;     ...
;         const bool has_next = S.next(ui + 1, nxt);
;         const char* nA = has_next ? (const char*)g.A + (size_t)nxt.pm * tstep : cA; const char* nB = has_next ? (const char*)g.Bt + (size_t)nxt.pn * tstep : cB;
;         for (int t = 0; t < nt; t += 2) {
;             const bool last = (t == nt - 2);
;             const char* a1 = cA + (size_t)(t + 1) * kstep;
;             const char* a2 = last ? nA : cA + (size_t)(t + 2) * kstep; const char* b2 = last ? nB : cB + (size_t)(t + 2) * kstep;
;             const char* a3 = a2 + kstep; const char* b3 = b2 + kstep;
;             if (last && has_next) S.a_ready(nxt);
;             if constexpr (SP2) {
;             PG8_LDB(B0, 0, 0); PG8_LDB(B1, 0, 1); PG8_SCHED; PG8_LDA(At, 0, 0); PG8_STAGE(PG8_SA(1, 1), a1 + hstep, voffA);
;             PG8_WAIT_V(8); PG8_WAIT_L(0); PG8_BAR; PG8_MMA(0, 0, At, B0); PG8_MMA(0, 1, At, B1); PG8_BAR; PG8_SCHED;
;             PG8_LDA(At, 0, 1); PG8_STAGE(PG8_SB(0, 0), b2, voffB); PG8_STAGE(PG8_SB(0, 1), b2 + hstep, voffB); PG8_STAGE(PG8_SA(0, 0), a2, voffA);
.LBB0_623:
	s_ashr_i32 s17, s16, 31
	s_lshl_b64 s[18:19], s[16:17], 18
	s_add_u32 s18, s0, s18
	s_addc_u32 s19, s1, s19
	s_and_b64 s[38:39], s[4:5], exec
	s_cselect_b32 s17, s19, s21
	s_cselect_b32 s63, s18, s20
	s_ashr_i32 s15, s14, 31
	s_lshl_b64 s[38:39], s[14:15], 18
	s_add_u32 s38, s33, s38
	s_addc_u32 s39, s50, s39
	s_and_b64 s[48:49], s[4:5], exec
	s_cselect_b32 s15, s39, s47
	s_cselect_b32 s64, s38, s46
	s_add_u32 s20, s20, 0x20080
	s_addc_u32 s21, s21, 0
	s_add_u32 s65, s46, 0x100
	s_addc_u32 s66, s47, 0
	s_mov_b32 s67, -2
	ds_read_b128 v[112:115], v167
	ds_read_b128 v[116:119], v167 offset:1024
	ds_read_b128 v[152:155], v167 offset:2048
	ds_read_b128 v[156:159], v167 offset:3072
	ds_read_b128 v[160:163], v168
	ds_read_b128 v[170:173], v168 offset:1024
	ds_read_b128 v[174:177], v168 offset:2048
	ds_read_b128 v[178:181], v168 offset:3072
	s_add_u32 s46, s20, 0xfffe0080
	s_addc_u32 s47, s21, -1
	s_cmp_eq_u32 s67, 4
	s_cselect_b32 s49, s17, s47
	s_cselect_b32 s48, s63, s46
	s_cselect_b32 s47, s15, s66
	s_cselect_b32 s46, s64, s65
	s_add_i32 m0, s35, 0xc000
	ds_read_b128 v[182:185], v169
	ds_read_b128 v[186:189], v169 offset:1024
	ds_read_b128 v[190:193], v169 offset:2048
	ds_read_b128 v[198:201], v169 offset:3072
	ds_read_b128 v[202:205], v169 offset:4096
	ds_read_b128 v[206:209], v169 offset:5120
	ds_read_b128 v[210:213], v169 offset:6144
	ds_read_b128 v[214:217], v169 offset:7168
	global_load_lds_dwordx4 v144, s[20:21]
	s_add_i32 m0, s35, 0xe000
	s_nop 0
	global_load_lds_dwordx4 v146, s[20:21]
	s_waitcnt vmcnt(8)
	s_waitcnt lgkmcnt(0)
	s_barrier
	s_waitcnt lgkmcnt(0)
	v_mfma_f32_16x16x32_bf16 v[132:135], v[112:115], v[182:185], 0
	v_mfma_f32_16x16x32_bf16 v[128:131], v[152:155], v[182:185], 0
	v_mfma_f32_16x16x32_bf16 v[124:127], v[112:115], v[190:193], 0
	v_mfma_f32_16x16x32_bf16 v[120:123], v[152:155], v[190:193], 0
	v_mfma_f32_16x16x32_bf16 v[108:111], v[112:115], v[202:205], 0
	v_mfma_f32_16x16x32_bf16 v[104:107], v[152:155], v[202:205], 0
	v_mfma_f32_16x16x32_bf16 v[100:103], v[112:115], v[210:213], 0
	v_mfma_f32_16x16x32_bf16 v[96:99], v[152:155], v[210:213], 0
	v_mfma_f32_16x16x32_bf16 v[132:135], v[116:119], v[186:189], v[132:135]
	v_mfma_f32_16x16x32_bf16 v[128:131], v[156:159], v[186:189], v[128:131]
	v_mfma_f32_16x16x32_bf16 v[124:127], v[116:119], v[198:201], v[124:127]
	v_mfma_f32_16x16x32_bf16 v[120:123], v[156:159], v[198:201], v[120:123]
	v_mfma_f32_16x16x32_bf16 v[108:111], v[116:119], v[206:209], v[108:111]
	v_mfma_f32_16x16x32_bf16 v[104:107], v[156:159], v[206:209], v[104:107]
	v_mfma_f32_16x16x32_bf16 v[100:103], v[116:119], v[214:217], v[100:103]
	v_mfma_f32_16x16x32_bf16 v[96:99], v[156:159], v[214:217], v[96:99]
	v_mfma_f32_16x16x32_bf16 v[60:63], v[160:163], v[182:185], 0
	v_mfma_f32_16x16x32_bf16 v[56:59], v[174:177], v[182:185], 0
	v_mfma_f32_16x16x32_bf16 v[52:55], v[160:163], v[190:193], 0
	v_mfma_f32_16x16x32_bf16 v[48:51], v[174:177], v[190:193], 0
	v_mfma_f32_16x16x32_bf16 v[44:47], v[160:163], v[202:205], 0
	v_mfma_f32_16x16x32_bf16 v[40:43], v[174:177], v[202:205], 0
	v_mfma_f32_16x16x32_bf16 v[36:39], v[160:163], v[210:213], 0
	v_mfma_f32_16x16x32_bf16 v[32:35], v[174:177], v[210:213], 0
	v_mfma_f32_16x16x32_bf16 v[60:63], v[170:173], v[186:189], v[60:63]
	v_mfma_f32_16x16x32_bf16 v[56:59], v[178:181], v[186:189], v[56:59]
	v_mfma_f32_16x16x32_bf16 v[52:55], v[170:173], v[198:201], v[52:55]
	v_mfma_f32_16x16x32_bf16 v[48:51], v[178:181], v[198:201], v[48:51]
	v_mfma_f32_16x16x32_bf16 v[44:47], v[170:173], v[206:209], v[44:47]
	v_mfma_f32_16x16x32_bf16 v[40:43], v[178:181], v[206:209], v[40:43]
	v_mfma_f32_16x16x32_bf16 v[36:39], v[170:173], v[214:217], v[36:39]
	v_mfma_f32_16x16x32_bf16 v[32:35], v[178:181], v[214:217], v[32:35]
	s_barrier
	s_add_i32 s68, s60, s51
	s_add_u32 s98, s46, s10
	s_addc_u32 s99, s47, s11
	s_add_u32 s100, s48, s10
	s_addc_u32 s101, s49, s11
	s_mov_b32 m0, s68
	ds_read_b128 v[182:185], v169 offset:16384
	ds_read_b128 v[186:189], v169 offset:17408
	ds_read_b128 v[190:193], v169 offset:18432
	ds_read_b128 v[198:201], v169 offset:19456
	ds_read_b128 v[202:205], v169 offset:20480
	ds_read_b128 v[206:209], v169 offset:21504
	ds_read_b128 v[210:213], v169 offset:22528
	ds_read_b128 v[214:217], v169 offset:23552
	global_load_lds_dwordx4 v138, s[46:47]
	s_add_i32 m0, s68, 0x2000
	s_add_u32 s68, s46, 0x20000
	s_addc_u32 s69, s47, 0
	s_add_i32 s70, s61, s51
	global_load_lds_dwordx4 v142, s[46:47]
	s_mov_b32 m0, s70
	s_nop 0
	global_load_lds_dwordx4 v138, s[68:69]
	s_add_i32 m0, s70, 0x2000
	s_nop 0
	global_load_lds_dwordx4 v142, s[68:69]
	s_mov_b32 m0, s35
	s_nop 0
	global_load_lds_dwordx4 v136, s[48:49]
	s_mov_b32 m0, s52
	s_nop 0
	global_load_lds_dwordx4 v140, s[48:49]
	s_waitcnt vmcnt(8)
	s_waitcnt lgkmcnt(0)
	s_barrier
; #define PG8_STAGE(bufoff, gbase, voff) do { _Pragma("unroll") for (int _i = 0; _i < 2; ++_i) \
;         __builtin_amdgcn_global_load_lds((const unsigned*)((const char*)(gbase) + (voff)[_i]), (PG8_LAS unsigned*)(lds + (bufoff) + ldsw + _i * 8192), 16, 0, 0); } while (0)
; #define PG8_LDA(dst, b, h) do { _Pragma("unroll") for (int m = 0; m < 4; ++m) _Pragma("unroll") for (int k = 0; k < 2; ++k) dst[m][k] = *(const PG8_LAS bf16x8*)(lds + PG8_SA(b, h) + aoff + m * 2048 + k * 1024); } while (0)
; #define PG8_LDB(dst, b, h) do { _Pragma("unroll") for (int n = 0; n < 2; ++n) _Pragma("unroll") for (int k = 0; k < 2; ++k) dst[n][k] = *(const PG8_LAS bf16x8*)(lds + PG8_SB(b, h) + boff + n * 2048 + k * 1024); } while (0)
; #define PG8_MMA(ai, bj, At, Bt) do { __builtin_amdgcn_s_setprio(1); _Pragma("unroll") for (int m = 0; m < 4; ++m) _Pragma("unroll") for (int n = 0; n < 2; ++n) _Pragma("unroll") for (int k = 0; k < 2; ++k) \
;         acc[ai][bj][m][n] = __builtin_amdgcn_mfma_f32_16x16x32_bf16(Bt[n][k], At[m][k], acc[ai][bj][m][n], 0, 0, 0); __builtin_amdgcn_s_setprio(0); } while (0)
; #define PG8_WAIT_V(n) asm volatile("s_waitcnt vmcnt(" #n ")" ::: "memory")
; #define PG8_WAIT_L(n) asm volatile("s_waitcnt lgkmcnt(" #n ")" ::: "memory")
; #define PG8_BAR __builtin_amdgcn_s_barrier()
; #define PG8_SCHED __builtin_amdgcn_sched_barrier(0)
; template <class Epi, class Sched, bool ALIGN_EPI = false, bool SP2 = false>
; __device__ __forceinline__ void gemm_phase(PG8_LAS unsigned char* lds, const Gemm g, const Sched& S, const Epi& E) {
;     ...
;             PG8_WAIT_V(8); PG8_WAIT_L(0); PG8_BAR; PG8_MMA(1, 0, At, B0); PG8_MMA(1, 1, At, B1); PG8_BAR; PG8_SCHED;
;             PG8_LDB(B0, 1, 0); PG8_LDB(B1, 1, 1); PG8_SCHED; PG8_LDA(At, 1, 0); PG8_STAGE(PG8_SA(0, 1), a2 + hstep, voffA);
;             PG8_WAIT_V(8); PG8_WAIT_L(0); PG8_BAR; PG8_MMA(0, 0, At, B0); PG8_MMA(0, 1, At, B1); PG8_BAR; PG8_SCHED;
	s_waitcnt lgkmcnt(0)
	v_mfma_f32_16x16x32_bf16 v[92:95], v[112:115], v[182:185], 0
	v_mfma_f32_16x16x32_bf16 v[88:91], v[152:155], v[182:185], 0
	v_mfma_f32_16x16x32_bf16 v[84:87], v[112:115], v[190:193], 0
	v_mfma_f32_16x16x32_bf16 v[80:83], v[152:155], v[190:193], 0
	v_mfma_f32_16x16x32_bf16 v[76:79], v[112:115], v[202:205], 0
	v_mfma_f32_16x16x32_bf16 v[72:75], v[152:155], v[202:205], 0
	v_mfma_f32_16x16x32_bf16 v[68:71], v[112:115], v[210:213], 0
	v_mfma_f32_16x16x32_bf16 v[64:67], v[152:155], v[210:213], 0
	v_mfma_f32_16x16x32_bf16 v[92:95], v[116:119], v[186:189], v[92:95]
	v_mfma_f32_16x16x32_bf16 v[88:91], v[156:159], v[186:189], v[88:91]
	v_mfma_f32_16x16x32_bf16 v[84:87], v[116:119], v[198:201], v[84:87]
	v_mfma_f32_16x16x32_bf16 v[80:83], v[156:159], v[198:201], v[80:83]
	v_mfma_f32_16x16x32_bf16 v[76:79], v[116:119], v[206:209], v[76:79]
	v_mfma_f32_16x16x32_bf16 v[72:75], v[156:159], v[206:209], v[72:75]
	v_mfma_f32_16x16x32_bf16 v[68:71], v[116:119], v[214:217], v[68:71]
	v_mfma_f32_16x16x32_bf16 v[64:67], v[156:159], v[214:217], v[64:67]
	v_mfma_f32_16x16x32_bf16 v[28:31], v[160:163], v[182:185], 0
	v_mfma_f32_16x16x32_bf16 v[24:27], v[174:177], v[182:185], 0
	v_mfma_f32_16x16x32_bf16 v[20:23], v[160:163], v[190:193], 0
	v_mfma_f32_16x16x32_bf16 v[16:19], v[174:177], v[190:193], 0
	v_mfma_f32_16x16x32_bf16 v[12:15], v[160:163], v[202:205], 0
	v_mfma_f32_16x16x32_bf16 v[8:11], v[174:177], v[202:205], 0
	v_mfma_f32_16x16x32_bf16 v[4:7], v[160:163], v[210:213], 0
	v_mfma_f32_16x16x32_bf16 v[0:3], v[174:177], v[210:213], 0
	v_mfma_f32_16x16x32_bf16 v[28:31], v[170:173], v[186:189], v[28:31]
	v_mfma_f32_16x16x32_bf16 v[24:27], v[178:181], v[186:189], v[24:27]
	v_mfma_f32_16x16x32_bf16 v[20:23], v[170:173], v[198:201], v[20:23]
	v_mfma_f32_16x16x32_bf16 v[16:19], v[178:181], v[198:201], v[16:19]
	v_mfma_f32_16x16x32_bf16 v[12:15], v[170:173], v[206:209], v[12:15]
	v_mfma_f32_16x16x32_bf16 v[8:11], v[178:181], v[206:209], v[8:11]
	v_mfma_f32_16x16x32_bf16 v[4:7], v[170:173], v[214:217], v[4:7]
	v_mfma_f32_16x16x32_bf16 v[0:3], v[178:181], v[214:217], v[0:3]
	s_barrier
	s_add_i32 s68, 0, 0x18000
	s_add_i32 s69, 0, 0x1c000
	v_add_u32_e32 v156, s68, v165
	v_add_u32_e32 v178, s69, v165
	ds_read_b128 v[112:115], v156
	ds_read_b128 v[116:119], v156 offset:1024
	ds_read_b128 v[152:155], v156 offset:2048
	ds_read_b128 v[156:159], v156 offset:3072
	ds_read_b128 v[160:163], v178
	ds_read_b128 v[170:173], v178 offset:1024
	ds_read_b128 v[174:177], v178 offset:2048
	ds_read_b128 v[178:181], v178 offset:3072
	s_add_u32 s48, s48, 0x20000
	s_addc_u32 s49, s49, 0
	s_mov_b32 m0, s53
	ds_read_b128 v[182:185], v169 offset:32768
	ds_read_b128 v[186:189], v169 offset:33792
	ds_read_b128 v[190:193], v169 offset:34816
	ds_read_b128 v[198:201], v169 offset:35840
	ds_read_b128 v[202:205], v169 offset:36864
	ds_read_b128 v[206:209], v169 offset:37888
	ds_read_b128 v[210:213], v169 offset:38912
	ds_read_b128 v[214:217], v169 offset:39936
	global_load_lds_dwordx4 v136, s[48:49]
	s_mov_b32 m0, s54
	s_nop 0
	global_load_lds_dwordx4 v140, s[48:49]
	s_waitcnt vmcnt(8)
	s_waitcnt lgkmcnt(0)
	s_barrier
	s_waitcnt lgkmcnt(0)
	v_mfma_f32_16x16x32_bf16 v[132:135], v[112:115], v[182:185], v[132:135]
	v_mfma_f32_16x16x32_bf16 v[128:131], v[152:155], v[182:185], v[128:131]
	v_mfma_f32_16x16x32_bf16 v[124:127], v[112:115], v[190:193], v[124:127]
	v_mfma_f32_16x16x32_bf16 v[120:123], v[152:155], v[190:193], v[120:123]
	v_mfma_f32_16x16x32_bf16 v[108:111], v[112:115], v[202:205], v[108:111]
	v_mfma_f32_16x16x32_bf16 v[104:107], v[152:155], v[202:205], v[104:107]
	v_mfma_f32_16x16x32_bf16 v[100:103], v[112:115], v[210:213], v[100:103]
	v_mfma_f32_16x16x32_bf16 v[96:99], v[152:155], v[210:213], v[96:99]
	v_mfma_f32_16x16x32_bf16 v[132:135], v[116:119], v[186:189], v[132:135]
	v_mfma_f32_16x16x32_bf16 v[128:131], v[156:159], v[186:189], v[128:131]
	v_mfma_f32_16x16x32_bf16 v[124:127], v[116:119], v[198:201], v[124:127]
	v_mfma_f32_16x16x32_bf16 v[120:123], v[156:159], v[198:201], v[120:123]
	v_mfma_f32_16x16x32_bf16 v[108:111], v[116:119], v[206:209], v[108:111]
	v_mfma_f32_16x16x32_bf16 v[104:107], v[156:159], v[206:209], v[104:107]
	v_mfma_f32_16x16x32_bf16 v[100:103], v[116:119], v[214:217], v[100:103]
	v_mfma_f32_16x16x32_bf16 v[96:99], v[156:159], v[214:217], v[96:99]
	v_mfma_f32_16x16x32_bf16 v[60:63], v[160:163], v[182:185], v[60:63]
	v_mfma_f32_16x16x32_bf16 v[56:59], v[174:177], v[182:185], v[56:59]
	v_mfma_f32_16x16x32_bf16 v[52:55], v[160:163], v[190:193], v[52:55]
	v_mfma_f32_16x16x32_bf16 v[48:51], v[174:177], v[190:193], v[48:51]
	v_mfma_f32_16x16x32_bf16 v[44:47], v[160:163], v[202:205], v[44:47]
	v_mfma_f32_16x16x32_bf16 v[40:43], v[174:177], v[202:205], v[40:43]
	v_mfma_f32_16x16x32_bf16 v[36:39], v[160:163], v[210:213], v[36:39]
	v_mfma_f32_16x16x32_bf16 v[32:35], v[174:177], v[210:213], v[32:35]
	v_mfma_f32_16x16x32_bf16 v[60:63], v[170:173], v[186:189], v[60:63]
	v_mfma_f32_16x16x32_bf16 v[56:59], v[178:181], v[186:189], v[56:59]
	v_mfma_f32_16x16x32_bf16 v[52:55], v[170:173], v[198:201], v[52:55]
	v_mfma_f32_16x16x32_bf16 v[48:51], v[178:181], v[198:201], v[48:51]
	v_mfma_f32_16x16x32_bf16 v[44:47], v[170:173], v[206:209], v[44:47]
	v_mfma_f32_16x16x32_bf16 v[40:43], v[178:181], v[206:209], v[40:43]
	v_mfma_f32_16x16x32_bf16 v[36:39], v[170:173], v[214:217], v[36:39]
	v_mfma_f32_16x16x32_bf16 v[32:35], v[178:181], v[214:217], v[32:35]
	s_barrier
; #define PG8_STAGE(bufoff, gbase, voff) do { _Pragma("unroll") for (int _i = 0; _i < 2; ++_i) \
;         __builtin_amdgcn_global_load_lds((const unsigned*)((const char*)(gbase) + (voff)[_i]), (PG8_LAS unsigned*)(lds + (bufoff) + ldsw + _i * 8192), 16, 0, 0); } while (0)
; #define PG8_LDA(dst, b, h) do { _Pragma("unroll") for (int m = 0; m < 4; ++m) _Pragma("unroll") for (int k = 0; k < 2; ++k) dst[m][k] = *(const PG8_LAS bf16x8*)(lds + PG8_SA(b, h) + aoff + m * 2048 + k * 1024); } while (0)
; #define PG8_LDB(dst, b, h) do { _Pragma("unroll") for (int n = 0; n < 2; ++n) _Pragma("unroll") for (int k = 0; k < 2; ++k) dst[n][k] = *(const PG8_LAS bf16x8*)(lds + PG8_SB(b, h) + boff + n * 2048 + k * 1024); } while (0)
; #define PG8_MMA(ai, bj, At, Bt) do { __builtin_amdgcn_s_setprio(1); _Pragma("unroll") for (int m = 0; m < 4; ++m) _Pragma("unroll") for (int n = 0; n < 2; ++n) _Pragma("unroll") for (int k = 0; k < 2; ++k) \
;         acc[ai][bj][m][n] = __builtin_amdgcn_mfma_f32_16x16x32_bf16(Bt[n][k], At[m][k], acc[ai][bj][m][n], 0, 0, 0); __builtin_amdgcn_s_setprio(0); } while (0)
; #define PG8_WAIT_V(n) asm volatile("s_waitcnt vmcnt(" #n ")" ::: "memory")
; #define PG8_BAR __builtin_amdgcn_s_barrier()
; template <class Epi, class Sched, bool ALIGN_EPI = false, bool SP2 = false>
; __device__ __forceinline__ void gemm_phase(PG8_LAS unsigned char* lds, const Gemm g, const Sched& S, const Epi& E) {
;     ...
;         for (int t = 0; t < nt; t += 2) {
;             const bool last = (t == nt - 2);
;             const char* a1 = cA + (size_t)(t + 1) * kstep;
;             const char* a2 = last ? nA : cA + (size_t)(t + 2) * kstep; const char* b2 = last ? nB : cB + (size_t)(t + 2) * kstep;
;             const char* a3 = a2 + kstep; const char* b3 = b2 + kstep;
;             if (last && has_next) S.a_ready(nxt);
;             if constexpr (SP2) {
;             PG8_LDB(B0, 0, 0); PG8_LDB(B1, 0, 1); PG8_SCHED; PG8_LDA(At, 0, 0); PG8_STAGE(PG8_SA(1, 1), a1 + hstep, voffA);
;             PG8_WAIT_V(8); PG8_WAIT_L(0); PG8_BAR; PG8_MMA(0, 0, At, B0); PG8_MMA(0, 1, At, B1); PG8_BAR; PG8_SCHED;
;     ...
;             PG8_LDA(At, 1, 1); PG8_STAGE(PG8_SB(1, 0), b3, voffB); PG8_STAGE(PG8_SB(1, 1), b3 + hstep, voffB); PG8_STAGE(PG8_SA(1, 0), a3, voffA);
;             PG8_WAIT_V(8); PG8_WAIT_L(0); PG8_BAR; PG8_MMA(1, 0, At, B0); PG8_MMA(1, 1, At, B1); PG8_BAR; PG8_SCHED;
	s_add_i32 s48, s68, s51
	s_mov_b32 m0, s48
	ds_read_b128 v[182:185], v169 offset:49152
	ds_read_b128 v[186:189], v169 offset:50176
	ds_read_b128 v[190:193], v169 offset:51200
	ds_read_b128 v[198:201], v169 offset:52224
	ds_read_b128 v[202:205], v169 offset:53248
	ds_read_b128 v[206:209], v169 offset:54272
	ds_read_b128 v[210:213], v169 offset:55296
	ds_read_b128 v[214:217], v169 offset:56320
	global_load_lds_dwordx4 v138, s[98:99]
	s_add_i32 m0, s48, 0x2000
	s_add_u32 s46, s46, 0x20080
	s_addc_u32 s47, s47, 0
	s_add_i32 s48, s69, s51
	global_load_lds_dwordx4 v142, s[98:99]
	s_mov_b32 m0, s48
	s_nop 0
	global_load_lds_dwordx4 v138, s[46:47]
	s_add_i32 m0, s48, 0x2000
	s_nop 0
	global_load_lds_dwordx4 v142, s[46:47]
	s_mov_b32 m0, s56
	s_nop 0
	global_load_lds_dwordx4 v136, s[100:101]
	s_mov_b32 m0, s57
	s_nop 0
	global_load_lds_dwordx4 v140, s[100:101]
	s_waitcnt vmcnt(8)
	s_waitcnt lgkmcnt(0)
	s_barrier
	s_waitcnt lgkmcnt(0)
	v_mfma_f32_16x16x32_bf16 v[92:95], v[112:115], v[182:185], v[92:95]
	v_mfma_f32_16x16x32_bf16 v[88:91], v[152:155], v[182:185], v[88:91]
	v_mfma_f32_16x16x32_bf16 v[84:87], v[112:115], v[190:193], v[84:87]
	v_mfma_f32_16x16x32_bf16 v[80:83], v[152:155], v[190:193], v[80:83]
	v_mfma_f32_16x16x32_bf16 v[76:79], v[112:115], v[202:205], v[76:79]
	v_mfma_f32_16x16x32_bf16 v[72:75], v[152:155], v[202:205], v[72:75]
	v_mfma_f32_16x16x32_bf16 v[68:71], v[112:115], v[210:213], v[68:71]
	v_mfma_f32_16x16x32_bf16 v[64:67], v[152:155], v[210:213], v[64:67]
	v_mfma_f32_16x16x32_bf16 v[92:95], v[116:119], v[186:189], v[92:95]
	v_mfma_f32_16x16x32_bf16 v[88:91], v[156:159], v[186:189], v[88:91]
	v_mfma_f32_16x16x32_bf16 v[84:87], v[116:119], v[198:201], v[84:87]
	v_mfma_f32_16x16x32_bf16 v[80:83], v[156:159], v[198:201], v[80:83]
	v_mfma_f32_16x16x32_bf16 v[76:79], v[116:119], v[206:209], v[76:79]
	v_mfma_f32_16x16x32_bf16 v[72:75], v[156:159], v[206:209], v[72:75]
	v_mfma_f32_16x16x32_bf16 v[68:71], v[116:119], v[214:217], v[68:71]
	v_mfma_f32_16x16x32_bf16 v[64:67], v[156:159], v[214:217], v[64:67]
	v_mfma_f32_16x16x32_bf16 v[28:31], v[160:163], v[182:185], v[28:31]
	v_mfma_f32_16x16x32_bf16 v[24:27], v[174:177], v[182:185], v[24:27]
	v_mfma_f32_16x16x32_bf16 v[20:23], v[160:163], v[190:193], v[20:23]
	v_mfma_f32_16x16x32_bf16 v[16:19], v[174:177], v[190:193], v[16:19]
	v_mfma_f32_16x16x32_bf16 v[12:15], v[160:163], v[202:205], v[12:15]
	v_mfma_f32_16x16x32_bf16 v[8:11], v[174:177], v[202:205], v[8:11]
	v_mfma_f32_16x16x32_bf16 v[4:7], v[160:163], v[210:213], v[4:7]
	v_mfma_f32_16x16x32_bf16 v[0:3], v[174:177], v[210:213], v[0:3]
	v_mfma_f32_16x16x32_bf16 v[28:31], v[170:173], v[186:189], v[28:31]
	v_mfma_f32_16x16x32_bf16 v[24:27], v[178:181], v[186:189], v[24:27]
	v_mfma_f32_16x16x32_bf16 v[20:23], v[170:173], v[198:201], v[20:23]
	v_mfma_f32_16x16x32_bf16 v[16:19], v[178:181], v[198:201], v[16:19]
	v_mfma_f32_16x16x32_bf16 v[12:15], v[170:173], v[206:209], v[12:15]
	v_mfma_f32_16x16x32_bf16 v[8:11], v[178:181], v[206:209], v[8:11]
	v_mfma_f32_16x16x32_bf16 v[4:7], v[170:173], v[214:217], v[4:7]
	v_mfma_f32_16x16x32_bf16 v[0:3], v[178:181], v[214:217], v[0:3]
	s_barrier
	s_add_i32 s67, s67, 2
	s_add_u32 s20, s20, 0x100
	s_addc_u32 s21, s21, 0
	s_add_u32 s65, s65, 0x100
	s_addc_u32 s66, s66, 0
	s_cmp_gt_u32 s67, 5
.LBB0_624:
	ds_read_b128 v[112:115], v167
	ds_read_b128 v[116:119], v167 offset:1024
	ds_read_b128 v[152:155], v167 offset:2048
	ds_read_b128 v[156:159], v167 offset:3072
	ds_read_b128 v[160:163], v168
	ds_read_b128 v[170:173], v168 offset:1024
	ds_read_b128 v[174:177], v168 offset:2048
	ds_read_b128 v[178:181], v168 offset:3072
	s_add_u32 s46, s20, 0xfffe0080
	s_addc_u32 s47, s21, -1
	s_cmp_eq_u32 s67, 4
	s_cselect_b32 s49, s17, s47
	s_cselect_b32 s48, s63, s46
	s_cselect_b32 s47, s15, s66
	s_cselect_b32 s46, s64, s65
	s_add_i32 m0, s35, 0xc000
	ds_read_b128 v[182:185], v169
	ds_read_b128 v[186:189], v169 offset:1024
	ds_read_b128 v[190:193], v169 offset:2048
	ds_read_b128 v[198:201], v169 offset:3072
	ds_read_b128 v[202:205], v169 offset:4096
	ds_read_b128 v[206:209], v169 offset:5120
	ds_read_b128 v[210:213], v169 offset:6144
	ds_read_b128 v[214:217], v169 offset:7168
	global_load_lds_dwordx4 v144, s[20:21]
	s_add_i32 m0, s35, 0xe000
	s_nop 0
	global_load_lds_dwordx4 v146, s[20:21]
	s_waitcnt vmcnt(8)
	s_waitcnt lgkmcnt(0)
	s_barrier
	s_waitcnt lgkmcnt(0)
	v_mfma_f32_16x16x32_bf16 v[132:135], v[112:115], v[182:185], v[132:135]
	v_mfma_f32_16x16x32_bf16 v[128:131], v[152:155], v[182:185], v[128:131]
	v_mfma_f32_16x16x32_bf16 v[124:127], v[112:115], v[190:193], v[124:127]
	v_mfma_f32_16x16x32_bf16 v[120:123], v[152:155], v[190:193], v[120:123]
	v_mfma_f32_16x16x32_bf16 v[108:111], v[112:115], v[202:205], v[108:111]
	v_mfma_f32_16x16x32_bf16 v[104:107], v[152:155], v[202:205], v[104:107]
	v_mfma_f32_16x16x32_bf16 v[100:103], v[112:115], v[210:213], v[100:103]
	v_mfma_f32_16x16x32_bf16 v[96:99], v[152:155], v[210:213], v[96:99]
	v_mfma_f32_16x16x32_bf16 v[132:135], v[116:119], v[186:189], v[132:135]
	v_mfma_f32_16x16x32_bf16 v[128:131], v[156:159], v[186:189], v[128:131]
	v_mfma_f32_16x16x32_bf16 v[124:127], v[116:119], v[198:201], v[124:127]
	v_mfma_f32_16x16x32_bf16 v[120:123], v[156:159], v[198:201], v[120:123]
	v_mfma_f32_16x16x32_bf16 v[108:111], v[116:119], v[206:209], v[108:111]
	v_mfma_f32_16x16x32_bf16 v[104:107], v[156:159], v[206:209], v[104:107]
	v_mfma_f32_16x16x32_bf16 v[100:103], v[116:119], v[214:217], v[100:103]
	v_mfma_f32_16x16x32_bf16 v[96:99], v[156:159], v[214:217], v[96:99]
	v_mfma_f32_16x16x32_bf16 v[60:63], v[160:163], v[182:185], v[60:63]
	v_mfma_f32_16x16x32_bf16 v[56:59], v[174:177], v[182:185], v[56:59]
	v_mfma_f32_16x16x32_bf16 v[52:55], v[160:163], v[190:193], v[52:55]
	v_mfma_f32_16x16x32_bf16 v[48:51], v[174:177], v[190:193], v[48:51]
	v_mfma_f32_16x16x32_bf16 v[44:47], v[160:163], v[202:205], v[44:47]
	v_mfma_f32_16x16x32_bf16 v[40:43], v[174:177], v[202:205], v[40:43]
	v_mfma_f32_16x16x32_bf16 v[36:39], v[160:163], v[210:213], v[36:39]
	v_mfma_f32_16x16x32_bf16 v[32:35], v[174:177], v[210:213], v[32:35]
	v_mfma_f32_16x16x32_bf16 v[60:63], v[170:173], v[186:189], v[60:63]
	v_mfma_f32_16x16x32_bf16 v[56:59], v[178:181], v[186:189], v[56:59]
	v_mfma_f32_16x16x32_bf16 v[52:55], v[170:173], v[198:201], v[52:55]
	v_mfma_f32_16x16x32_bf16 v[48:51], v[178:181], v[198:201], v[48:51]
	v_mfma_f32_16x16x32_bf16 v[44:47], v[170:173], v[206:209], v[44:47]
	v_mfma_f32_16x16x32_bf16 v[40:43], v[178:181], v[206:209], v[40:43]
	v_mfma_f32_16x16x32_bf16 v[36:39], v[170:173], v[214:217], v[36:39]
	v_mfma_f32_16x16x32_bf16 v[32:35], v[178:181], v[214:217], v[32:35]
	s_barrier
; #define PG8_STAGE(bufoff, gbase, voff) do { _Pragma("unroll") for (int _i = 0; _i < 2; ++_i) \
;         __builtin_amdgcn_global_load_lds((const unsigned*)((const char*)(gbase) + (voff)[_i]), (PG8_LAS unsigned*)(lds + (bufoff) + ldsw + _i * 8192), 16, 0, 0); } while (0)
; #define PG8_LDA(dst, b, h) do { _Pragma("unroll") for (int m = 0; m < 4; ++m) _Pragma("unroll") for (int k = 0; k < 2; ++k) dst[m][k] = *(const PG8_LAS bf16x8*)(lds + PG8_SA(b, h) + aoff + m * 2048 + k * 1024); } while (0)
; #define PG8_LDB(dst, b, h) do { _Pragma("unroll") for (int n = 0; n < 2; ++n) _Pragma("unroll") for (int k = 0; k < 2; ++k) dst[n][k] = *(const PG8_LAS bf16x8*)(lds + PG8_SB(b, h) + boff + n * 2048 + k * 1024); } while (0)
; #define PG8_MMA(ai, bj, At, Bt) do { __builtin_amdgcn_s_setprio(1); _Pragma("unroll") for (int m = 0; m < 4; ++m) _Pragma("unroll") for (int n = 0; n < 2; ++n) _Pragma("unroll") for (int k = 0; k < 2; ++k) \
;         acc[ai][bj][m][n] = __builtin_amdgcn_mfma_f32_16x16x32_bf16(Bt[n][k], At[m][k], acc[ai][bj][m][n], 0, 0, 0); __builtin_amdgcn_s_setprio(0); } while (0)
; #define PG8_WAIT_V(n) asm volatile("s_waitcnt vmcnt(" #n ")" ::: "memory")
; #define PG8_WAIT_L(n) asm volatile("s_waitcnt lgkmcnt(" #n ")" ::: "memory")
; #define PG8_BAR __builtin_amdgcn_s_barrier()
; #define PG8_SCHED __builtin_amdgcn_sched_barrier(0)
; template <class Epi, class Sched, bool ALIGN_EPI = false, bool SP2 = false>
; __device__ __forceinline__ void gemm_phase(PG8_LAS unsigned char* lds, const Gemm g, const Sched& S, const Epi& E) {
;     ...
;             PG8_LDA(At, 0, 1); PG8_STAGE(PG8_SB(0, 0), b2, voffB); PG8_STAGE(PG8_SB(0, 1), b2 + hstep, voffB); PG8_STAGE(PG8_SA(0, 0), a2, voffA);
;             PG8_WAIT_V(8); PG8_WAIT_L(0); PG8_BAR; PG8_MMA(1, 0, At, B0); PG8_MMA(1, 1, At, B1); PG8_BAR; PG8_SCHED;
;             PG8_LDB(B0, 1, 0); PG8_LDB(B1, 1, 1); PG8_SCHED; PG8_LDA(At, 1, 0); PG8_STAGE(PG8_SA(0, 1), a2 + hstep, voffA);
;             PG8_WAIT_V(8); PG8_WAIT_L(0); PG8_BAR; PG8_MMA(0, 0, At, B0); PG8_MMA(0, 1, At, B1); PG8_BAR; PG8_SCHED;
	s_add_i32 s68, s60, s51
	s_add_u32 s98, s46, s10
	s_addc_u32 s99, s47, s11
	s_add_u32 s100, s48, s10
	s_addc_u32 s101, s49, s11
	s_mov_b32 m0, s68
	ds_read_b128 v[182:185], v169 offset:16384
	ds_read_b128 v[186:189], v169 offset:17408
	ds_read_b128 v[190:193], v169 offset:18432
	ds_read_b128 v[198:201], v169 offset:19456
	ds_read_b128 v[202:205], v169 offset:20480
	ds_read_b128 v[206:209], v169 offset:21504
	ds_read_b128 v[210:213], v169 offset:22528
	ds_read_b128 v[214:217], v169 offset:23552
	global_load_lds_dwordx4 v138, s[46:47]
	s_add_i32 m0, s68, 0x2000
	s_add_u32 s68, s46, 0x20000
	s_addc_u32 s69, s47, 0
	s_add_i32 s70, s61, s51
	global_load_lds_dwordx4 v142, s[46:47]
	s_mov_b32 m0, s70
	s_nop 0
	global_load_lds_dwordx4 v138, s[68:69]
	s_add_i32 m0, s70, 0x2000
	s_nop 0
	global_load_lds_dwordx4 v142, s[68:69]
	s_mov_b32 m0, s35
	s_nop 0
	global_load_lds_dwordx4 v136, s[48:49]
	s_mov_b32 m0, s52
	s_nop 0
	global_load_lds_dwordx4 v140, s[48:49]
	s_waitcnt vmcnt(8)
	s_waitcnt lgkmcnt(0)
	s_barrier
	s_waitcnt lgkmcnt(0)
	v_mfma_f32_16x16x32_bf16 v[92:95], v[112:115], v[182:185], v[92:95]
	v_mfma_f32_16x16x32_bf16 v[88:91], v[152:155], v[182:185], v[88:91]
	v_mfma_f32_16x16x32_bf16 v[84:87], v[112:115], v[190:193], v[84:87]
	v_mfma_f32_16x16x32_bf16 v[80:83], v[152:155], v[190:193], v[80:83]
	v_mfma_f32_16x16x32_bf16 v[76:79], v[112:115], v[202:205], v[76:79]
	v_mfma_f32_16x16x32_bf16 v[72:75], v[152:155], v[202:205], v[72:75]
	v_mfma_f32_16x16x32_bf16 v[68:71], v[112:115], v[210:213], v[68:71]
	v_mfma_f32_16x16x32_bf16 v[64:67], v[152:155], v[210:213], v[64:67]
	v_mfma_f32_16x16x32_bf16 v[92:95], v[116:119], v[186:189], v[92:95]
	v_mfma_f32_16x16x32_bf16 v[88:91], v[156:159], v[186:189], v[88:91]
	v_mfma_f32_16x16x32_bf16 v[84:87], v[116:119], v[198:201], v[84:87]
	v_mfma_f32_16x16x32_bf16 v[80:83], v[156:159], v[198:201], v[80:83]
	v_mfma_f32_16x16x32_bf16 v[76:79], v[116:119], v[206:209], v[76:79]
	v_mfma_f32_16x16x32_bf16 v[72:75], v[156:159], v[206:209], v[72:75]
	v_mfma_f32_16x16x32_bf16 v[68:71], v[116:119], v[214:217], v[68:71]
	v_mfma_f32_16x16x32_bf16 v[64:67], v[156:159], v[214:217], v[64:67]
	v_mfma_f32_16x16x32_bf16 v[28:31], v[160:163], v[182:185], v[28:31]
	v_mfma_f32_16x16x32_bf16 v[24:27], v[174:177], v[182:185], v[24:27]
	v_mfma_f32_16x16x32_bf16 v[20:23], v[160:163], v[190:193], v[20:23]
	v_mfma_f32_16x16x32_bf16 v[16:19], v[174:177], v[190:193], v[16:19]
	v_mfma_f32_16x16x32_bf16 v[12:15], v[160:163], v[202:205], v[12:15]
	v_mfma_f32_16x16x32_bf16 v[8:11], v[174:177], v[202:205], v[8:11]
	v_mfma_f32_16x16x32_bf16 v[4:7], v[160:163], v[210:213], v[4:7]
	v_mfma_f32_16x16x32_bf16 v[0:3], v[174:177], v[210:213], v[0:3]
	v_mfma_f32_16x16x32_bf16 v[28:31], v[170:173], v[186:189], v[28:31]
	v_mfma_f32_16x16x32_bf16 v[24:27], v[178:181], v[186:189], v[24:27]
	v_mfma_f32_16x16x32_bf16 v[20:23], v[170:173], v[198:201], v[20:23]
	v_mfma_f32_16x16x32_bf16 v[16:19], v[178:181], v[198:201], v[16:19]
	v_mfma_f32_16x16x32_bf16 v[12:15], v[170:173], v[206:209], v[12:15]
	v_mfma_f32_16x16x32_bf16 v[8:11], v[178:181], v[206:209], v[8:11]
	v_mfma_f32_16x16x32_bf16 v[4:7], v[170:173], v[214:217], v[4:7]
	v_mfma_f32_16x16x32_bf16 v[0:3], v[178:181], v[214:217], v[0:3]
	s_barrier
	s_add_i32 s68, 0, 0x18000
	s_add_i32 s69, 0, 0x1c000
	v_add_u32_e32 v156, s68, v165
	v_add_u32_e32 v178, s69, v165
	ds_read_b128 v[112:115], v156
	ds_read_b128 v[116:119], v156 offset:1024
	ds_read_b128 v[152:155], v156 offset:2048
	ds_read_b128 v[156:159], v156 offset:3072
	ds_read_b128 v[160:163], v178
	ds_read_b128 v[170:173], v178 offset:1024
	ds_read_b128 v[174:177], v178 offset:2048
	ds_read_b128 v[178:181], v178 offset:3072
	s_add_u32 s48, s48, 0x20000
	s_addc_u32 s49, s49, 0
	s_mov_b32 m0, s53
	ds_read_b128 v[182:185], v169 offset:32768
	ds_read_b128 v[186:189], v169 offset:33792
	ds_read_b128 v[190:193], v169 offset:34816
	ds_read_b128 v[198:201], v169 offset:35840
	ds_read_b128 v[202:205], v169 offset:36864
	ds_read_b128 v[206:209], v169 offset:37888
	ds_read_b128 v[210:213], v169 offset:38912
	ds_read_b128 v[214:217], v169 offset:39936
	global_load_lds_dwordx4 v136, s[48:49]
	s_mov_b32 m0, s54
	s_nop 0
	global_load_lds_dwordx4 v140, s[48:49]
	s_waitcnt vmcnt(8)
	s_waitcnt lgkmcnt(0)
	s_barrier
; #define PG8_STAGE(bufoff, gbase, voff) do { _Pragma("unroll") for (int _i = 0; _i < 2; ++_i) \
;         __builtin_amdgcn_global_load_lds((const unsigned*)((const char*)(gbase) + (voff)[_i]), (PG8_LAS unsigned*)(lds + (bufoff) + ldsw + _i * 8192), 16, 0, 0); } while (0)
; #define PG8_LDA(dst, b, h) do { _Pragma("unroll") for (int m = 0; m < 4; ++m) _Pragma("unroll") for (int k = 0; k < 2; ++k) dst[m][k] = *(const PG8_LAS bf16x8*)(lds + PG8_SA(b, h) + aoff + m * 2048 + k * 1024); } while (0)
; #define PG8_MMA(ai, bj, At, Bt) do { __builtin_amdgcn_s_setprio(1); _Pragma("unroll") for (int m = 0; m < 4; ++m) _Pragma("unroll") for (int n = 0; n < 2; ++n) _Pragma("unroll") for (int k = 0; k < 2; ++k) \
;         acc[ai][bj][m][n] = __builtin_amdgcn_mfma_f32_16x16x32_bf16(Bt[n][k], At[m][k], acc[ai][bj][m][n], 0, 0, 0); __builtin_amdgcn_s_setprio(0); } while (0)
; #define PG8_WAIT_V(n) asm volatile("s_waitcnt vmcnt(" #n ")" ::: "memory")
; #define PG8_WAIT_L(n) asm volatile("s_waitcnt lgkmcnt(" #n ")" ::: "memory")
; #define PG8_BAR __builtin_amdgcn_s_barrier()
; #define PG8_SCHED __builtin_amdgcn_sched_barrier(0)
; template <class Epi, class Sched, bool ALIGN_EPI = false, bool SP2 = false>
; __device__ __forceinline__ void gemm_phase(PG8_LAS unsigned char* lds, const Gemm g, const Sched& S, const Epi& E) {
;     ...
;             PG8_WAIT_V(8); PG8_WAIT_L(0); PG8_BAR; PG8_MMA(0, 0, At, B0); PG8_MMA(0, 1, At, B1); PG8_BAR; PG8_SCHED;
;             PG8_LDA(At, 1, 1); PG8_STAGE(PG8_SB(1, 0), b3, voffB); PG8_STAGE(PG8_SB(1, 1), b3 + hstep, voffB); PG8_STAGE(PG8_SA(1, 0), a3, voffA);
;             PG8_WAIT_V(8); PG8_WAIT_L(0); PG8_BAR; PG8_MMA(1, 0, At, B0); PG8_MMA(1, 1, At, B1); PG8_BAR; PG8_SCHED;
;     ...
;         if constexpr (ALIGN_EPI) { if (wr == 0) PG8_BAR; }
	s_waitcnt lgkmcnt(0)
	v_mfma_f32_16x16x32_bf16 v[132:135], v[112:115], v[182:185], v[132:135]
	v_mfma_f32_16x16x32_bf16 v[128:131], v[152:155], v[182:185], v[128:131]
	v_mfma_f32_16x16x32_bf16 v[124:127], v[112:115], v[190:193], v[124:127]
	v_mfma_f32_16x16x32_bf16 v[120:123], v[152:155], v[190:193], v[120:123]
	v_mfma_f32_16x16x32_bf16 v[108:111], v[112:115], v[202:205], v[108:111]
	v_mfma_f32_16x16x32_bf16 v[104:107], v[152:155], v[202:205], v[104:107]
	v_mfma_f32_16x16x32_bf16 v[100:103], v[112:115], v[210:213], v[100:103]
	v_mfma_f32_16x16x32_bf16 v[96:99], v[152:155], v[210:213], v[96:99]
	v_mfma_f32_16x16x32_bf16 v[132:135], v[116:119], v[186:189], v[132:135]
	v_mfma_f32_16x16x32_bf16 v[128:131], v[156:159], v[186:189], v[128:131]
	v_mfma_f32_16x16x32_bf16 v[124:127], v[116:119], v[198:201], v[124:127]
	v_mfma_f32_16x16x32_bf16 v[120:123], v[156:159], v[198:201], v[120:123]
	v_mfma_f32_16x16x32_bf16 v[108:111], v[116:119], v[206:209], v[108:111]
	v_mfma_f32_16x16x32_bf16 v[104:107], v[156:159], v[206:209], v[104:107]
	v_mfma_f32_16x16x32_bf16 v[100:103], v[116:119], v[214:217], v[100:103]
	v_mfma_f32_16x16x32_bf16 v[96:99], v[156:159], v[214:217], v[96:99]
	v_mfma_f32_16x16x32_bf16 v[60:63], v[160:163], v[182:185], v[60:63]
	v_mfma_f32_16x16x32_bf16 v[56:59], v[174:177], v[182:185], v[56:59]
	v_mfma_f32_16x16x32_bf16 v[52:55], v[160:163], v[190:193], v[52:55]
	v_mfma_f32_16x16x32_bf16 v[48:51], v[174:177], v[190:193], v[48:51]
	v_mfma_f32_16x16x32_bf16 v[44:47], v[160:163], v[202:205], v[44:47]
	v_mfma_f32_16x16x32_bf16 v[40:43], v[174:177], v[202:205], v[40:43]
	v_mfma_f32_16x16x32_bf16 v[36:39], v[160:163], v[210:213], v[36:39]
	v_mfma_f32_16x16x32_bf16 v[32:35], v[174:177], v[210:213], v[32:35]
	v_mfma_f32_16x16x32_bf16 v[60:63], v[170:173], v[186:189], v[60:63]
	v_mfma_f32_16x16x32_bf16 v[56:59], v[178:181], v[186:189], v[56:59]
	v_mfma_f32_16x16x32_bf16 v[52:55], v[170:173], v[198:201], v[52:55]
	v_mfma_f32_16x16x32_bf16 v[48:51], v[178:181], v[198:201], v[48:51]
	v_mfma_f32_16x16x32_bf16 v[44:47], v[170:173], v[206:209], v[44:47]
	v_mfma_f32_16x16x32_bf16 v[40:43], v[178:181], v[206:209], v[40:43]
	v_mfma_f32_16x16x32_bf16 v[36:39], v[170:173], v[214:217], v[36:39]
	v_mfma_f32_16x16x32_bf16 v[32:35], v[178:181], v[214:217], v[32:35]
	s_barrier
	s_add_i32 s48, s68, s51
	s_mov_b32 m0, s48
	ds_read_b128 v[182:185], v169 offset:49152
	ds_read_b128 v[186:189], v169 offset:50176
	ds_read_b128 v[190:193], v169 offset:51200
	ds_read_b128 v[198:201], v169 offset:52224
	ds_read_b128 v[202:205], v169 offset:53248
	ds_read_b128 v[206:209], v169 offset:54272
	ds_read_b128 v[210:213], v169 offset:55296
	ds_read_b128 v[214:217], v169 offset:56320
	global_load_lds_dwordx4 v138, s[98:99]
	s_add_i32 m0, s48, 0x2000
	s_add_u32 s46, s46, 0x20080
	s_addc_u32 s47, s47, 0
	s_add_i32 s48, s69, s51
	global_load_lds_dwordx4 v142, s[98:99]
	s_mov_b32 m0, s48
	s_nop 0
	global_load_lds_dwordx4 v138, s[46:47]
	s_add_i32 m0, s48, 0x2000
	s_nop 0
	global_load_lds_dwordx4 v142, s[46:47]
	s_mov_b32 m0, s56
	s_nop 0
	global_load_lds_dwordx4 v136, s[100:101]
	s_mov_b32 m0, s57
	s_nop 0
	global_load_lds_dwordx4 v140, s[100:101]
	s_waitcnt vmcnt(8)
	s_waitcnt lgkmcnt(0)
	s_barrier
	s_waitcnt lgkmcnt(0)
	v_mfma_f32_16x16x32_bf16 v[92:95], v[112:115], v[182:185], v[92:95]
	v_mfma_f32_16x16x32_bf16 v[88:91], v[152:155], v[182:185], v[88:91]
	v_mfma_f32_16x16x32_bf16 v[84:87], v[112:115], v[190:193], v[84:87]
	v_mfma_f32_16x16x32_bf16 v[80:83], v[152:155], v[190:193], v[80:83]
	v_mfma_f32_16x16x32_bf16 v[76:79], v[112:115], v[202:205], v[76:79]
	v_mfma_f32_16x16x32_bf16 v[72:75], v[152:155], v[202:205], v[72:75]
	v_mfma_f32_16x16x32_bf16 v[68:71], v[112:115], v[210:213], v[68:71]
	v_mfma_f32_16x16x32_bf16 v[64:67], v[152:155], v[210:213], v[64:67]
	v_mfma_f32_16x16x32_bf16 v[92:95], v[116:119], v[186:189], v[92:95]
	v_mfma_f32_16x16x32_bf16 v[88:91], v[156:159], v[186:189], v[88:91]
	v_mfma_f32_16x16x32_bf16 v[84:87], v[116:119], v[198:201], v[84:87]
	v_mfma_f32_16x16x32_bf16 v[80:83], v[156:159], v[198:201], v[80:83]
	v_mfma_f32_16x16x32_bf16 v[76:79], v[116:119], v[206:209], v[76:79]
	v_mfma_f32_16x16x32_bf16 v[72:75], v[156:159], v[206:209], v[72:75]
	v_mfma_f32_16x16x32_bf16 v[68:71], v[116:119], v[214:217], v[68:71]
	v_mfma_f32_16x16x32_bf16 v[64:67], v[156:159], v[214:217], v[64:67]
	v_mfma_f32_16x16x32_bf16 v[28:31], v[160:163], v[182:185], v[28:31]
	v_mfma_f32_16x16x32_bf16 v[24:27], v[174:177], v[182:185], v[24:27]
	v_mfma_f32_16x16x32_bf16 v[20:23], v[160:163], v[190:193], v[20:23]
	v_mfma_f32_16x16x32_bf16 v[16:19], v[174:177], v[190:193], v[16:19]
	v_mfma_f32_16x16x32_bf16 v[12:15], v[160:163], v[202:205], v[12:15]
	v_mfma_f32_16x16x32_bf16 v[8:11], v[174:177], v[202:205], v[8:11]
	v_mfma_f32_16x16x32_bf16 v[4:7], v[160:163], v[210:213], v[4:7]
	v_mfma_f32_16x16x32_bf16 v[0:3], v[174:177], v[210:213], v[0:3]
	v_mfma_f32_16x16x32_bf16 v[28:31], v[170:173], v[186:189], v[28:31]
	v_mfma_f32_16x16x32_bf16 v[24:27], v[178:181], v[186:189], v[24:27]
	v_mfma_f32_16x16x32_bf16 v[20:23], v[170:173], v[198:201], v[20:23]
	v_mfma_f32_16x16x32_bf16 v[16:19], v[178:181], v[198:201], v[16:19]
	v_mfma_f32_16x16x32_bf16 v[12:15], v[170:173], v[206:209], v[12:15]
	v_mfma_f32_16x16x32_bf16 v[8:11], v[178:181], v[206:209], v[8:11]
	v_mfma_f32_16x16x32_bf16 v[4:7], v[170:173], v[214:217], v[4:7]
	v_mfma_f32_16x16x32_bf16 v[0:3], v[178:181], v[214:217], v[0:3]
	s_barrier
	s_add_i32 s67, s67, 2
	s_add_u32 s20, s20, 0x100
	s_addc_u32 s21, s21, 0
	s_add_u32 s65, s65, 0x100
	s_addc_u32 s66, s66, 0
	s_cmp_gt_u32 s67, 5
	s_cbranch_scc0 .LBB0_624
	s_and_b64 vcc, exec, s[12:13]
	s_cbranch_vccz .LBB0_627
	s_barrier

; #define PG8_STAGE(bufoff, gbase, voff) do { _Pragma("unroll") for (int _i = 0; _i < 2; ++_i) \
;         __builtin_amdgcn_global_load_lds((const unsigned*)((const char*)(gbase) + (voff)[_i]), (PG8_LAS unsigned*)(lds + (bufoff) + ldsw + _i * 8192), 16, 0, 0); } while (0)
; #define PG8_LDA(dst, b, h) do { _Pragma("unroll") for (int m = 0; m < 4; ++m) _Pragma("unroll") for (int k = 0; k < 2; ++k) dst[m][k] = *(const PG8_LAS bf16x8*)(lds + PG8_SA(b, h) + aoff + m * 2048 + k * 1024); } while (0)
; #define PG8_LDB(dst, b, h) do { _Pragma("unroll") for (int n = 0; n < 2; ++n) _Pragma("unroll") for (int k = 0; k < 2; ++k) dst[n][k] = *(const PG8_LAS bf16x8*)(lds + PG8_SB(b, h) + boff + n * 2048 + k * 1024); } while (0)
; #define PG8_MMA(ai, bj, At, Bt) do { __builtin_amdgcn_s_setprio(1); _Pragma("unroll") for (int m = 0; m < 4; ++m) _Pragma("unroll") for (int n = 0; n < 2; ++n) _Pragma("unroll") for (int k = 0; k < 2; ++k) \
;         acc[ai][bj][m][n] = __builtin_amdgcn_mfma_f32_16x16x32_bf16(Bt[n][k], At[m][k], acc[ai][bj][m][n], 0, 0, 0); __builtin_amdgcn_s_setprio(0); } while (0)
; #define PG8_BAR __builtin_amdgcn_s_barrier()
; template <class Epi, class Sched, bool ALIGN_EPI = false, bool SP2 = false>
; __device__ __forceinline__ void gemm_phase(PG8_LAS unsigned char* lds, const Gemm g, const Sched& S, const Epi& E) {
;     ...
;         const bool has_next = S.next(ui + 1, nxt);
;         const char* nA = has_next ? (const char*)g.A + (size_t)nxt.pm * tstep : cA; const char* nB = has_next ? (const char*)g.Bt + (size_t)nxt.pn * tstep : cB;
;         for (int t = 0; t < nt; t += 2) {
;             const bool last = (t == nt - 2);
;             const char* a1 = cA + (size_t)(t + 1) * kstep;
;             const char* a2 = last ? nA : cA + (size_t)(t + 2) * kstep; const char* b2 = last ? nB : cB + (size_t)(t + 2) * kstep;
;             const char* a3 = a2 + kstep; const char* b3 = b2 + kstep;
;             if (last && has_next) S.a_ready(nxt);
;             if constexpr (SP2) {
;             PG8_LDB(B0, 0, 0); PG8_LDB(B1, 0, 1); PG8_SCHED; PG8_LDA(At, 0, 0); PG8_STAGE(PG8_SA(1, 1), a1 + hstep, voffA);
;             PG8_WAIT_V(8); PG8_WAIT_L(0); PG8_BAR; PG8_MMA(0, 0, At, B0); PG8_MMA(0, 1, At, B1); PG8_BAR; PG8_SCHED;
;             PG8_LDA(At, 0, 1); PG8_STAGE(PG8_SB(0, 0), b2, voffB); PG8_STAGE(PG8_SB(0, 1), b2 + hstep, voffB); PG8_STAGE(PG8_SA(0, 0), a2, voffA);
.LBB0_704:
	s_ashr_i32 s47, s46, 31
	s_lshl_b64 s[48:49], s[46:47], 19
	s_add_u32 s48, s42, s48
	s_addc_u32 s49, s43, s49
	s_and_b64 s[50:51], s[6:7], exec
	s_cselect_b32 s35, s49, s21
	s_cselect_b32 s47, s48, s20
	s_ashr_i32 s45, s44, 31
	s_lshl_b64 s[50:51], s[44:45], 19
	s_add_u32 s50, s3, s50
	s_addc_u32 s51, s33, s51
	s_and_b64 s[56:57], s[6:7], exec
	s_cselect_b32 s45, s51, s55
	s_cselect_b32 s73, s50, s54
	s_add_u32 s20, s20, 0x40080
	s_addc_u32 s21, s21, 0
	s_add_u32 s74, s54, 0x100
	s_addc_u32 s75, s55, 0
	s_mov_b32 s76, -2
	s_waitcnt lgkmcnt(0)
	ds_read_b128 v[96:99], v223
	ds_read_b128 v[108:111], v223 offset:1024
	ds_read_b128 v[120:123], v223 offset:2048
	ds_read_b128 v[128:131], v223 offset:3072
	ds_read_b128 v[144:147], v224
	ds_read_b128 v[148:151], v224 offset:1024
	ds_read_b128 v[152:155], v224 offset:2048
	ds_read_b128 v[156:159], v224 offset:3072
	s_add_u32 s54, s20, 0xfffc0080
	s_addc_u32 s55, s21, -1
	s_cmp_eq_u32 s76, 12
	s_cselect_b32 s57, s35, s55
	s_cselect_b32 s56, s47, s54
	s_cselect_b32 s55, s45, s75
	s_cselect_b32 s54, s73, s74
	s_add_i32 m0, s53, 0xc000
	ds_read_b128 v[160:163], v225
	ds_read_b128 v[164:167], v225 offset:1024
	ds_read_b128 v[168:171], v225 offset:2048
	ds_read_b128 v[172:175], v225 offset:3072
	ds_read_b128 v[176:179], v225 offset:4096
	ds_read_b128 v[180:183], v225 offset:5120
	ds_read_b128 v[202:205], v225 offset:6144
	ds_read_b128 v[206:209], v225 offset:7168
	global_load_lds_dwordx4 v192, s[20:21]
	s_add_i32 m0, s53, 0xe000
	s_nop 0
	global_load_lds_dwordx4 v194, s[20:21]
	s_waitcnt vmcnt(8)
	s_waitcnt lgkmcnt(0)
	s_barrier
	s_waitcnt lgkmcnt(0)
	v_mfma_f32_16x16x32_bf16 v[140:143], v[96:99], v[160:163], 0
	v_mfma_f32_16x16x32_bf16 v[136:139], v[120:123], v[160:163], 0
	v_mfma_f32_16x16x32_bf16 v[116:119], v[96:99], v[168:171], 0
	v_mfma_f32_16x16x32_bf16 v[112:115], v[120:123], v[168:171], 0
	v_mfma_f32_16x16x32_bf16 v[92:95], v[96:99], v[176:179], 0
	v_mfma_f32_16x16x32_bf16 v[88:91], v[120:123], v[176:179], 0
	v_mfma_f32_16x16x32_bf16 v[76:79], v[96:99], v[202:205], 0
	v_mfma_f32_16x16x32_bf16 v[72:75], v[120:123], v[202:205], 0
	v_mfma_f32_16x16x32_bf16 v[140:143], v[108:111], v[164:167], v[140:143]
	v_mfma_f32_16x16x32_bf16 v[136:139], v[128:131], v[164:167], v[136:139]
	v_mfma_f32_16x16x32_bf16 v[116:119], v[108:111], v[172:175], v[116:119]
	v_mfma_f32_16x16x32_bf16 v[112:115], v[128:131], v[172:175], v[112:115]
	v_mfma_f32_16x16x32_bf16 v[92:95], v[108:111], v[180:183], v[92:95]
	v_mfma_f32_16x16x32_bf16 v[88:91], v[128:131], v[180:183], v[88:91]
	v_mfma_f32_16x16x32_bf16 v[76:79], v[108:111], v[206:209], v[76:79]
	v_mfma_f32_16x16x32_bf16 v[72:75], v[128:131], v[206:209], v[72:75]
	v_mfma_f32_16x16x32_bf16 v[132:135], v[144:147], v[160:163], 0
	v_mfma_f32_16x16x32_bf16 v[124:127], v[152:155], v[160:163], 0
	v_mfma_f32_16x16x32_bf16 v[104:107], v[144:147], v[168:171], 0
	v_mfma_f32_16x16x32_bf16 v[100:103], v[152:155], v[168:171], 0
	v_mfma_f32_16x16x32_bf16 v[84:87], v[144:147], v[176:179], 0
	v_mfma_f32_16x16x32_bf16 v[80:83], v[152:155], v[176:179], 0
	v_mfma_f32_16x16x32_bf16 v[68:71], v[144:147], v[202:205], 0
	v_mfma_f32_16x16x32_bf16 v[64:67], v[152:155], v[202:205], 0
	v_mfma_f32_16x16x32_bf16 v[132:135], v[148:151], v[164:167], v[132:135]
	v_mfma_f32_16x16x32_bf16 v[124:127], v[156:159], v[164:167], v[124:127]
	v_mfma_f32_16x16x32_bf16 v[104:107], v[148:151], v[172:175], v[104:107]
	v_mfma_f32_16x16x32_bf16 v[100:103], v[156:159], v[172:175], v[100:103]
	v_mfma_f32_16x16x32_bf16 v[84:87], v[148:151], v[180:183], v[84:87]
	v_mfma_f32_16x16x32_bf16 v[80:83], v[156:159], v[180:183], v[80:83]
	v_mfma_f32_16x16x32_bf16 v[68:71], v[148:151], v[206:209], v[68:71]
	v_mfma_f32_16x16x32_bf16 v[64:67], v[156:159], v[206:209], v[64:67]
	s_barrier
	s_add_i32 s77, s71, s58
	s_add_u32 s98, s54, s12
	s_addc_u32 s99, s55, s13
	s_add_u32 s100, s56, s12
	s_addc_u32 s101, s57, s13
	s_mov_b32 m0, s77
	ds_read_b128 v[160:163], v225 offset:16384
	ds_read_b128 v[164:167], v225 offset:17408
	ds_read_b128 v[168:171], v225 offset:18432
	ds_read_b128 v[172:175], v225 offset:19456
	ds_read_b128 v[176:179], v225 offset:20480
	ds_read_b128 v[180:183], v225 offset:21504
	ds_read_b128 v[202:205], v225 offset:22528
	ds_read_b128 v[206:209], v225 offset:23552
	global_load_lds_dwordx4 v186, s[54:55]
	s_add_i32 m0, s77, 0x2000
	s_add_u32 s78, s54, 0x40000
	s_addc_u32 s79, s55, 0
	s_add_i32 s77, s72, s58
	global_load_lds_dwordx4 v190, s[54:55]
	s_mov_b32 m0, s77
	s_nop 0
	global_load_lds_dwordx4 v186, s[78:79]
	s_add_i32 m0, s77, 0x2000
	s_nop 0
	global_load_lds_dwordx4 v190, s[78:79]
	s_mov_b32 m0, s53
	s_nop 0
	global_load_lds_dwordx4 v184, s[56:57]
	s_mov_b32 m0, s59
	s_nop 0
	global_load_lds_dwordx4 v188, s[56:57]
	s_waitcnt vmcnt(8)
	s_waitcnt lgkmcnt(0)
	s_barrier
; #define PG8_STAGE(bufoff, gbase, voff) do { _Pragma("unroll") for (int _i = 0; _i < 2; ++_i) \
;         __builtin_amdgcn_global_load_lds((const unsigned*)((const char*)(gbase) + (voff)[_i]), (PG8_LAS unsigned*)(lds + (bufoff) + ldsw + _i * 8192), 16, 0, 0); } while (0)
; #define PG8_LDA(dst, b, h) do { _Pragma("unroll") for (int m = 0; m < 4; ++m) _Pragma("unroll") for (int k = 0; k < 2; ++k) dst[m][k] = *(const PG8_LAS bf16x8*)(lds + PG8_SA(b, h) + aoff + m * 2048 + k * 1024); } while (0)
; #define PG8_LDB(dst, b, h) do { _Pragma("unroll") for (int n = 0; n < 2; ++n) _Pragma("unroll") for (int k = 0; k < 2; ++k) dst[n][k] = *(const PG8_LAS bf16x8*)(lds + PG8_SB(b, h) + boff + n * 2048 + k * 1024); } while (0)
; #define PG8_MMA(ai, bj, At, Bt) do { __builtin_amdgcn_s_setprio(1); _Pragma("unroll") for (int m = 0; m < 4; ++m) _Pragma("unroll") for (int n = 0; n < 2; ++n) _Pragma("unroll") for (int k = 0; k < 2; ++k) \
;         acc[ai][bj][m][n] = __builtin_amdgcn_mfma_f32_16x16x32_bf16(Bt[n][k], At[m][k], acc[ai][bj][m][n], 0, 0, 0); __builtin_amdgcn_s_setprio(0); } while (0)
; #define PG8_WAIT_V(n) asm volatile("s_waitcnt vmcnt(" #n ")" ::: "memory")
; #define PG8_WAIT_L(n) asm volatile("s_waitcnt lgkmcnt(" #n ")" ::: "memory")
; #define PG8_BAR __builtin_amdgcn_s_barrier()
; #define PG8_SCHED __builtin_amdgcn_sched_barrier(0)
; template <class Epi, class Sched, bool ALIGN_EPI = false, bool SP2 = false>
; __device__ __forceinline__ void gemm_phase(PG8_LAS unsigned char* lds, const Gemm g, const Sched& S, const Epi& E) {
;     ...
;             PG8_WAIT_V(8); PG8_WAIT_L(0); PG8_BAR; PG8_MMA(1, 0, At, B0); PG8_MMA(1, 1, At, B1); PG8_BAR; PG8_SCHED;
;             PG8_LDB(B0, 1, 0); PG8_LDB(B1, 1, 1); PG8_SCHED; PG8_LDA(At, 1, 0); PG8_STAGE(PG8_SA(0, 1), a2 + hstep, voffA);
;             PG8_WAIT_V(8); PG8_WAIT_L(0); PG8_BAR; PG8_MMA(0, 0, At, B0); PG8_MMA(0, 1, At, B1); PG8_BAR; PG8_SCHED;
	s_waitcnt lgkmcnt(0)
	v_mfma_f32_16x16x32_bf16 v[60:63], v[96:99], v[160:163], 0
	v_mfma_f32_16x16x32_bf16 v[56:59], v[120:123], v[160:163], 0
	v_mfma_f32_16x16x32_bf16 v[44:47], v[96:99], v[168:171], 0
	v_mfma_f32_16x16x32_bf16 v[40:43], v[120:123], v[168:171], 0
	v_mfma_f32_16x16x32_bf16 v[28:31], v[96:99], v[176:179], 0
	v_mfma_f32_16x16x32_bf16 v[24:27], v[120:123], v[176:179], 0
	v_mfma_f32_16x16x32_bf16 v[12:15], v[96:99], v[202:205], 0
	v_mfma_f32_16x16x32_bf16 v[8:11], v[120:123], v[202:205], 0
	v_mfma_f32_16x16x32_bf16 v[60:63], v[108:111], v[164:167], v[60:63]
	v_mfma_f32_16x16x32_bf16 v[56:59], v[128:131], v[164:167], v[56:59]
	v_mfma_f32_16x16x32_bf16 v[44:47], v[108:111], v[172:175], v[44:47]
	v_mfma_f32_16x16x32_bf16 v[40:43], v[128:131], v[172:175], v[40:43]
	v_mfma_f32_16x16x32_bf16 v[28:31], v[108:111], v[180:183], v[28:31]
	v_mfma_f32_16x16x32_bf16 v[24:27], v[128:131], v[180:183], v[24:27]
	v_mfma_f32_16x16x32_bf16 v[12:15], v[108:111], v[206:209], v[12:15]
	v_mfma_f32_16x16x32_bf16 v[8:11], v[128:131], v[206:209], v[8:11]
	v_mfma_f32_16x16x32_bf16 v[52:55], v[144:147], v[160:163], 0
	v_mfma_f32_16x16x32_bf16 v[48:51], v[152:155], v[160:163], 0
	v_mfma_f32_16x16x32_bf16 v[36:39], v[144:147], v[168:171], 0
	v_mfma_f32_16x16x32_bf16 v[32:35], v[152:155], v[168:171], 0
	v_mfma_f32_16x16x32_bf16 v[20:23], v[144:147], v[176:179], 0
	v_mfma_f32_16x16x32_bf16 v[16:19], v[152:155], v[176:179], 0
	v_mfma_f32_16x16x32_bf16 v[4:7], v[144:147], v[202:205], 0
	v_mfma_f32_16x16x32_bf16 v[0:3], v[152:155], v[202:205], 0
	v_mfma_f32_16x16x32_bf16 v[52:55], v[148:151], v[164:167], v[52:55]
	v_mfma_f32_16x16x32_bf16 v[48:51], v[156:159], v[164:167], v[48:51]
	v_mfma_f32_16x16x32_bf16 v[36:39], v[148:151], v[172:175], v[36:39]
	v_mfma_f32_16x16x32_bf16 v[32:35], v[156:159], v[172:175], v[32:35]
	v_mfma_f32_16x16x32_bf16 v[20:23], v[148:151], v[180:183], v[20:23]
	v_mfma_f32_16x16x32_bf16 v[16:19], v[156:159], v[180:183], v[16:19]
	v_mfma_f32_16x16x32_bf16 v[4:7], v[148:151], v[206:209], v[4:7]
	v_mfma_f32_16x16x32_bf16 v[0:3], v[156:159], v[206:209], v[0:3]
	s_barrier
	s_add_i32 s77, 0, 0x18000
	s_add_i32 s78, 0, 0x1c000
	v_add_u32_e32 v128, s77, v221
	v_add_u32_e32 v156, s78, v221
	ds_read_b128 v[96:99], v128
	ds_read_b128 v[108:111], v128 offset:1024
	ds_read_b128 v[120:123], v128 offset:2048
	ds_read_b128 v[128:131], v128 offset:3072
	ds_read_b128 v[144:147], v156
	ds_read_b128 v[148:151], v156 offset:1024
	ds_read_b128 v[152:155], v156 offset:2048
	ds_read_b128 v[156:159], v156 offset:3072
	s_add_u32 s56, s56, 0x40000
	s_addc_u32 s57, s57, 0
	s_mov_b32 m0, s60
	ds_read_b128 v[160:163], v225 offset:32768
	ds_read_b128 v[164:167], v225 offset:33792
	ds_read_b128 v[168:171], v225 offset:34816
	ds_read_b128 v[172:175], v225 offset:35840
	ds_read_b128 v[176:179], v225 offset:36864
	ds_read_b128 v[180:183], v225 offset:37888
	ds_read_b128 v[202:205], v225 offset:38912
	ds_read_b128 v[206:209], v225 offset:39936
	global_load_lds_dwordx4 v184, s[56:57]
	s_mov_b32 m0, s61
	s_nop 0
	global_load_lds_dwordx4 v188, s[56:57]
	s_waitcnt vmcnt(8)
	s_waitcnt lgkmcnt(0)
	s_barrier
	s_waitcnt lgkmcnt(0)
	v_mfma_f32_16x16x32_bf16 v[140:143], v[96:99], v[160:163], v[140:143]
	v_mfma_f32_16x16x32_bf16 v[136:139], v[120:123], v[160:163], v[136:139]
	v_mfma_f32_16x16x32_bf16 v[116:119], v[96:99], v[168:171], v[116:119]
	v_mfma_f32_16x16x32_bf16 v[112:115], v[120:123], v[168:171], v[112:115]
	v_mfma_f32_16x16x32_bf16 v[92:95], v[96:99], v[176:179], v[92:95]
	v_mfma_f32_16x16x32_bf16 v[88:91], v[120:123], v[176:179], v[88:91]
	v_mfma_f32_16x16x32_bf16 v[76:79], v[96:99], v[202:205], v[76:79]
	v_mfma_f32_16x16x32_bf16 v[72:75], v[120:123], v[202:205], v[72:75]
	v_mfma_f32_16x16x32_bf16 v[140:143], v[108:111], v[164:167], v[140:143]
	v_mfma_f32_16x16x32_bf16 v[136:139], v[128:131], v[164:167], v[136:139]
	v_mfma_f32_16x16x32_bf16 v[116:119], v[108:111], v[172:175], v[116:119]
	v_mfma_f32_16x16x32_bf16 v[112:115], v[128:131], v[172:175], v[112:115]
	v_mfma_f32_16x16x32_bf16 v[92:95], v[108:111], v[180:183], v[92:95]
	v_mfma_f32_16x16x32_bf16 v[88:91], v[128:131], v[180:183], v[88:91]
	v_mfma_f32_16x16x32_bf16 v[76:79], v[108:111], v[206:209], v[76:79]
	v_mfma_f32_16x16x32_bf16 v[72:75], v[128:131], v[206:209], v[72:75]
	v_mfma_f32_16x16x32_bf16 v[132:135], v[144:147], v[160:163], v[132:135]
	v_mfma_f32_16x16x32_bf16 v[124:127], v[152:155], v[160:163], v[124:127]
	v_mfma_f32_16x16x32_bf16 v[104:107], v[144:147], v[168:171], v[104:107]
	v_mfma_f32_16x16x32_bf16 v[100:103], v[152:155], v[168:171], v[100:103]
	v_mfma_f32_16x16x32_bf16 v[84:87], v[144:147], v[176:179], v[84:87]
	v_mfma_f32_16x16x32_bf16 v[80:83], v[152:155], v[176:179], v[80:83]
	v_mfma_f32_16x16x32_bf16 v[68:71], v[144:147], v[202:205], v[68:71]
	v_mfma_f32_16x16x32_bf16 v[64:67], v[152:155], v[202:205], v[64:67]
	v_mfma_f32_16x16x32_bf16 v[132:135], v[148:151], v[164:167], v[132:135]
	v_mfma_f32_16x16x32_bf16 v[124:127], v[156:159], v[164:167], v[124:127]
	v_mfma_f32_16x16x32_bf16 v[104:107], v[148:151], v[172:175], v[104:107]
	v_mfma_f32_16x16x32_bf16 v[100:103], v[156:159], v[172:175], v[100:103]
	v_mfma_f32_16x16x32_bf16 v[84:87], v[148:151], v[180:183], v[84:87]
	v_mfma_f32_16x16x32_bf16 v[80:83], v[156:159], v[180:183], v[80:83]
	v_mfma_f32_16x16x32_bf16 v[68:71], v[148:151], v[206:209], v[68:71]
	v_mfma_f32_16x16x32_bf16 v[64:67], v[156:159], v[206:209], v[64:67]
	s_barrier
; #define PG8_STAGE(bufoff, gbase, voff) do { _Pragma("unroll") for (int _i = 0; _i < 2; ++_i) \
;         __builtin_amdgcn_global_load_lds((const unsigned*)((const char*)(gbase) + (voff)[_i]), (PG8_LAS unsigned*)(lds + (bufoff) + ldsw + _i * 8192), 16, 0, 0); } while (0)
; #define PG8_LDA(dst, b, h) do { _Pragma("unroll") for (int m = 0; m < 4; ++m) _Pragma("unroll") for (int k = 0; k < 2; ++k) dst[m][k] = *(const PG8_LAS bf16x8*)(lds + PG8_SA(b, h) + aoff + m * 2048 + k * 1024); } while (0)
; #define PG8_LDB(dst, b, h) do { _Pragma("unroll") for (int n = 0; n < 2; ++n) _Pragma("unroll") for (int k = 0; k < 2; ++k) dst[n][k] = *(const PG8_LAS bf16x8*)(lds + PG8_SB(b, h) + boff + n * 2048 + k * 1024); } while (0)
; #define PG8_MMA(ai, bj, At, Bt) do { __builtin_amdgcn_s_setprio(1); _Pragma("unroll") for (int m = 0; m < 4; ++m) _Pragma("unroll") for (int n = 0; n < 2; ++n) _Pragma("unroll") for (int k = 0; k < 2; ++k) \
;         acc[ai][bj][m][n] = __builtin_amdgcn_mfma_f32_16x16x32_bf16(Bt[n][k], At[m][k], acc[ai][bj][m][n], 0, 0, 0); __builtin_amdgcn_s_setprio(0); } while (0)
; #define PG8_WAIT_V(n) asm volatile("s_waitcnt vmcnt(" #n ")" ::: "memory")
; #define PG8_BAR __builtin_amdgcn_s_barrier()
; template <class Epi, class Sched, bool ALIGN_EPI = false, bool SP2 = false>
; __device__ __forceinline__ void gemm_phase(PG8_LAS unsigned char* lds, const Gemm g, const Sched& S, const Epi& E) {
;     ...
;         for (int t = 0; t < nt; t += 2) {
;             const bool last = (t == nt - 2);
;             const char* a1 = cA + (size_t)(t + 1) * kstep;
;             const char* a2 = last ? nA : cA + (size_t)(t + 2) * kstep; const char* b2 = last ? nB : cB + (size_t)(t + 2) * kstep;
;             const char* a3 = a2 + kstep; const char* b3 = b2 + kstep;
;             if (last && has_next) S.a_ready(nxt);
;             if constexpr (SP2) {
;             PG8_LDB(B0, 0, 0); PG8_LDB(B1, 0, 1); PG8_SCHED; PG8_LDA(At, 0, 0); PG8_STAGE(PG8_SA(1, 1), a1 + hstep, voffA);
;             PG8_WAIT_V(8); PG8_WAIT_L(0); PG8_BAR; PG8_MMA(0, 0, At, B0); PG8_MMA(0, 1, At, B1); PG8_BAR; PG8_SCHED;
;     ...
;             PG8_LDA(At, 1, 1); PG8_STAGE(PG8_SB(1, 0), b3, voffB); PG8_STAGE(PG8_SB(1, 1), b3 + hstep, voffB); PG8_STAGE(PG8_SA(1, 0), a3, voffA);
;             PG8_WAIT_V(8); PG8_WAIT_L(0); PG8_BAR; PG8_MMA(1, 0, At, B0); PG8_MMA(1, 1, At, B1); PG8_BAR; PG8_SCHED;
	s_add_i32 s56, s77, s58
	s_mov_b32 m0, s56
	ds_read_b128 v[160:163], v225 offset:49152
	ds_read_b128 v[164:167], v225 offset:50176
	ds_read_b128 v[168:171], v225 offset:51200
	ds_read_b128 v[172:175], v225 offset:52224
	ds_read_b128 v[176:179], v225 offset:53248
	ds_read_b128 v[180:183], v225 offset:54272
	ds_read_b128 v[202:205], v225 offset:55296
	ds_read_b128 v[206:209], v225 offset:56320
	global_load_lds_dwordx4 v186, s[98:99]
	s_add_i32 m0, s56, 0x2000
	s_add_u32 s54, s54, 0x40080
	s_addc_u32 s55, s55, 0
	s_add_i32 s56, s78, s58
	global_load_lds_dwordx4 v190, s[98:99]
	s_mov_b32 m0, s56
	s_nop 0
	global_load_lds_dwordx4 v186, s[54:55]
	s_add_i32 m0, s56, 0x2000
	s_nop 0
	global_load_lds_dwordx4 v190, s[54:55]
	s_mov_b32 m0, s66
	s_nop 0
	global_load_lds_dwordx4 v184, s[100:101]
	s_mov_b32 m0, s67
	s_nop 0
	global_load_lds_dwordx4 v188, s[100:101]
	s_waitcnt vmcnt(8)
	s_waitcnt lgkmcnt(0)
	s_barrier
	s_waitcnt lgkmcnt(0)
	v_mfma_f32_16x16x32_bf16 v[60:63], v[96:99], v[160:163], v[60:63]
	v_mfma_f32_16x16x32_bf16 v[56:59], v[120:123], v[160:163], v[56:59]
	v_mfma_f32_16x16x32_bf16 v[44:47], v[96:99], v[168:171], v[44:47]
	v_mfma_f32_16x16x32_bf16 v[40:43], v[120:123], v[168:171], v[40:43]
	v_mfma_f32_16x16x32_bf16 v[28:31], v[96:99], v[176:179], v[28:31]
	v_mfma_f32_16x16x32_bf16 v[24:27], v[120:123], v[176:179], v[24:27]
	v_mfma_f32_16x16x32_bf16 v[12:15], v[96:99], v[202:205], v[12:15]
	v_mfma_f32_16x16x32_bf16 v[8:11], v[120:123], v[202:205], v[8:11]
	v_mfma_f32_16x16x32_bf16 v[60:63], v[108:111], v[164:167], v[60:63]
	v_mfma_f32_16x16x32_bf16 v[56:59], v[128:131], v[164:167], v[56:59]
	v_mfma_f32_16x16x32_bf16 v[44:47], v[108:111], v[172:175], v[44:47]
	v_mfma_f32_16x16x32_bf16 v[40:43], v[128:131], v[172:175], v[40:43]
	v_mfma_f32_16x16x32_bf16 v[28:31], v[108:111], v[180:183], v[28:31]
	v_mfma_f32_16x16x32_bf16 v[24:27], v[128:131], v[180:183], v[24:27]
	v_mfma_f32_16x16x32_bf16 v[12:15], v[108:111], v[206:209], v[12:15]
	v_mfma_f32_16x16x32_bf16 v[8:11], v[128:131], v[206:209], v[8:11]
	v_mfma_f32_16x16x32_bf16 v[52:55], v[144:147], v[160:163], v[52:55]
	v_mfma_f32_16x16x32_bf16 v[48:51], v[152:155], v[160:163], v[48:51]
	v_mfma_f32_16x16x32_bf16 v[36:39], v[144:147], v[168:171], v[36:39]
	v_mfma_f32_16x16x32_bf16 v[32:35], v[152:155], v[168:171], v[32:35]
	v_mfma_f32_16x16x32_bf16 v[20:23], v[144:147], v[176:179], v[20:23]
	v_mfma_f32_16x16x32_bf16 v[16:19], v[152:155], v[176:179], v[16:19]
	v_mfma_f32_16x16x32_bf16 v[4:7], v[144:147], v[202:205], v[4:7]
	v_mfma_f32_16x16x32_bf16 v[0:3], v[152:155], v[202:205], v[0:3]
	v_mfma_f32_16x16x32_bf16 v[52:55], v[148:151], v[164:167], v[52:55]
	v_mfma_f32_16x16x32_bf16 v[48:51], v[156:159], v[164:167], v[48:51]
	v_mfma_f32_16x16x32_bf16 v[36:39], v[148:151], v[172:175], v[36:39]
	v_mfma_f32_16x16x32_bf16 v[32:35], v[156:159], v[172:175], v[32:35]
	v_mfma_f32_16x16x32_bf16 v[20:23], v[148:151], v[180:183], v[20:23]
	v_mfma_f32_16x16x32_bf16 v[16:19], v[156:159], v[180:183], v[16:19]
	v_mfma_f32_16x16x32_bf16 v[4:7], v[148:151], v[206:209], v[4:7]
	v_mfma_f32_16x16x32_bf16 v[0:3], v[156:159], v[206:209], v[0:3]
	s_barrier
	s_add_i32 s76, s76, 2
	s_add_u32 s20, s20, 0x100
	s_addc_u32 s21, s21, 0
	s_add_u32 s74, s74, 0x100
	s_addc_u32 s75, s75, 0
	s_cmp_gt_u32 s76, 13
.LBB0_705:
	ds_read_b128 v[96:99], v223
	ds_read_b128 v[108:111], v223 offset:1024
	ds_read_b128 v[120:123], v223 offset:2048
	ds_read_b128 v[128:131], v223 offset:3072
	ds_read_b128 v[144:147], v224
	ds_read_b128 v[148:151], v224 offset:1024
	ds_read_b128 v[152:155], v224 offset:2048
	ds_read_b128 v[156:159], v224 offset:3072
	s_add_u32 s54, s20, 0xfffc0080
	s_addc_u32 s55, s21, -1
	s_cmp_eq_u32 s76, 12
	s_cselect_b32 s57, s35, s55
	s_cselect_b32 s56, s47, s54
	s_cselect_b32 s55, s45, s75
	s_cselect_b32 s54, s73, s74
	s_add_i32 m0, s53, 0xc000
	ds_read_b128 v[160:163], v225
	ds_read_b128 v[164:167], v225 offset:1024
	ds_read_b128 v[168:171], v225 offset:2048
	ds_read_b128 v[172:175], v225 offset:3072
	ds_read_b128 v[176:179], v225 offset:4096
	ds_read_b128 v[180:183], v225 offset:5120
	ds_read_b128 v[202:205], v225 offset:6144
	ds_read_b128 v[206:209], v225 offset:7168
	global_load_lds_dwordx4 v192, s[20:21]
	s_add_i32 m0, s53, 0xe000
	s_nop 0
	global_load_lds_dwordx4 v194, s[20:21]
	s_waitcnt vmcnt(8)
	s_waitcnt lgkmcnt(0)
	s_barrier
	s_waitcnt lgkmcnt(0)
	v_mfma_f32_16x16x32_bf16 v[140:143], v[96:99], v[160:163], v[140:143]
	v_mfma_f32_16x16x32_bf16 v[136:139], v[120:123], v[160:163], v[136:139]
	v_mfma_f32_16x16x32_bf16 v[116:119], v[96:99], v[168:171], v[116:119]
	v_mfma_f32_16x16x32_bf16 v[112:115], v[120:123], v[168:171], v[112:115]
	v_mfma_f32_16x16x32_bf16 v[92:95], v[96:99], v[176:179], v[92:95]
	v_mfma_f32_16x16x32_bf16 v[88:91], v[120:123], v[176:179], v[88:91]
	v_mfma_f32_16x16x32_bf16 v[76:79], v[96:99], v[202:205], v[76:79]
	v_mfma_f32_16x16x32_bf16 v[72:75], v[120:123], v[202:205], v[72:75]
	v_mfma_f32_16x16x32_bf16 v[140:143], v[108:111], v[164:167], v[140:143]
	v_mfma_f32_16x16x32_bf16 v[136:139], v[128:131], v[164:167], v[136:139]
	v_mfma_f32_16x16x32_bf16 v[116:119], v[108:111], v[172:175], v[116:119]
	v_mfma_f32_16x16x32_bf16 v[112:115], v[128:131], v[172:175], v[112:115]
	v_mfma_f32_16x16x32_bf16 v[92:95], v[108:111], v[180:183], v[92:95]
	v_mfma_f32_16x16x32_bf16 v[88:91], v[128:131], v[180:183], v[88:91]
	v_mfma_f32_16x16x32_bf16 v[76:79], v[108:111], v[206:209], v[76:79]
	v_mfma_f32_16x16x32_bf16 v[72:75], v[128:131], v[206:209], v[72:75]
	v_mfma_f32_16x16x32_bf16 v[132:135], v[144:147], v[160:163], v[132:135]
	v_mfma_f32_16x16x32_bf16 v[124:127], v[152:155], v[160:163], v[124:127]
	v_mfma_f32_16x16x32_bf16 v[104:107], v[144:147], v[168:171], v[104:107]
	v_mfma_f32_16x16x32_bf16 v[100:103], v[152:155], v[168:171], v[100:103]
	v_mfma_f32_16x16x32_bf16 v[84:87], v[144:147], v[176:179], v[84:87]
	v_mfma_f32_16x16x32_bf16 v[80:83], v[152:155], v[176:179], v[80:83]
	v_mfma_f32_16x16x32_bf16 v[68:71], v[144:147], v[202:205], v[68:71]
	v_mfma_f32_16x16x32_bf16 v[64:67], v[152:155], v[202:205], v[64:67]
	v_mfma_f32_16x16x32_bf16 v[132:135], v[148:151], v[164:167], v[132:135]
	v_mfma_f32_16x16x32_bf16 v[124:127], v[156:159], v[164:167], v[124:127]
	v_mfma_f32_16x16x32_bf16 v[104:107], v[148:151], v[172:175], v[104:107]
	v_mfma_f32_16x16x32_bf16 v[100:103], v[156:159], v[172:175], v[100:103]
	v_mfma_f32_16x16x32_bf16 v[84:87], v[148:151], v[180:183], v[84:87]
	v_mfma_f32_16x16x32_bf16 v[80:83], v[156:159], v[180:183], v[80:83]
	v_mfma_f32_16x16x32_bf16 v[68:71], v[148:151], v[206:209], v[68:71]
	v_mfma_f32_16x16x32_bf16 v[64:67], v[156:159], v[206:209], v[64:67]
	s_barrier
; #define PG8_STAGE(bufoff, gbase, voff) do { _Pragma("unroll") for (int _i = 0; _i < 2; ++_i) \
;         __builtin_amdgcn_global_load_lds((const unsigned*)((const char*)(gbase) + (voff)[_i]), (PG8_LAS unsigned*)(lds + (bufoff) + ldsw + _i * 8192), 16, 0, 0); } while (0)
; #define PG8_LDA(dst, b, h) do { _Pragma("unroll") for (int m = 0; m < 4; ++m) _Pragma("unroll") for (int k = 0; k < 2; ++k) dst[m][k] = *(const PG8_LAS bf16x8*)(lds + PG8_SA(b, h) + aoff + m * 2048 + k * 1024); } while (0)
; #define PG8_LDB(dst, b, h) do { _Pragma("unroll") for (int n = 0; n < 2; ++n) _Pragma("unroll") for (int k = 0; k < 2; ++k) dst[n][k] = *(const PG8_LAS bf16x8*)(lds + PG8_SB(b, h) + boff + n * 2048 + k * 1024); } while (0)
; #define PG8_MMA(ai, bj, At, Bt) do { __builtin_amdgcn_s_setprio(1); _Pragma("unroll") for (int m = 0; m < 4; ++m) _Pragma("unroll") for (int n = 0; n < 2; ++n) _Pragma("unroll") for (int k = 0; k < 2; ++k) \
;         acc[ai][bj][m][n] = __builtin_amdgcn_mfma_f32_16x16x32_bf16(Bt[n][k], At[m][k], acc[ai][bj][m][n], 0, 0, 0); __builtin_amdgcn_s_setprio(0); } while (0)
; #define PG8_WAIT_V(n) asm volatile("s_waitcnt vmcnt(" #n ")" ::: "memory")
; #define PG8_WAIT_L(n) asm volatile("s_waitcnt lgkmcnt(" #n ")" ::: "memory")
; #define PG8_BAR __builtin_amdgcn_s_barrier()
; #define PG8_SCHED __builtin_amdgcn_sched_barrier(0)
; template <class Epi, class Sched, bool ALIGN_EPI = false, bool SP2 = false>
; __device__ __forceinline__ void gemm_phase(PG8_LAS unsigned char* lds, const Gemm g, const Sched& S, const Epi& E) {
;     ...
;             PG8_LDA(At, 0, 1); PG8_STAGE(PG8_SB(0, 0), b2, voffB); PG8_STAGE(PG8_SB(0, 1), b2 + hstep, voffB); PG8_STAGE(PG8_SA(0, 0), a2, voffA);
;             PG8_WAIT_V(8); PG8_WAIT_L(0); PG8_BAR; PG8_MMA(1, 0, At, B0); PG8_MMA(1, 1, At, B1); PG8_BAR; PG8_SCHED;
;             PG8_LDB(B0, 1, 0); PG8_LDB(B1, 1, 1); PG8_SCHED; PG8_LDA(At, 1, 0); PG8_STAGE(PG8_SA(0, 1), a2 + hstep, voffA);
;             PG8_WAIT_V(8); PG8_WAIT_L(0); PG8_BAR; PG8_MMA(0, 0, At, B0); PG8_MMA(0, 1, At, B1); PG8_BAR; PG8_SCHED;
	s_add_i32 s77, s71, s58
	s_add_u32 s98, s54, s12
	s_addc_u32 s99, s55, s13
	s_add_u32 s100, s56, s12
	s_addc_u32 s101, s57, s13
	s_mov_b32 m0, s77
	ds_read_b128 v[160:163], v225 offset:16384
	ds_read_b128 v[164:167], v225 offset:17408
	ds_read_b128 v[168:171], v225 offset:18432
	ds_read_b128 v[172:175], v225 offset:19456
	ds_read_b128 v[176:179], v225 offset:20480
	ds_read_b128 v[180:183], v225 offset:21504
	ds_read_b128 v[202:205], v225 offset:22528
	ds_read_b128 v[206:209], v225 offset:23552
	global_load_lds_dwordx4 v186, s[54:55]
	s_add_i32 m0, s77, 0x2000
	s_add_u32 s78, s54, 0x40000
	s_addc_u32 s79, s55, 0
	s_add_i32 s77, s72, s58
	global_load_lds_dwordx4 v190, s[54:55]
	s_mov_b32 m0, s77
	s_nop 0
	global_load_lds_dwordx4 v186, s[78:79]
	s_add_i32 m0, s77, 0x2000
	s_nop 0
	global_load_lds_dwordx4 v190, s[78:79]
	s_mov_b32 m0, s53
	s_nop 0
	global_load_lds_dwordx4 v184, s[56:57]
	s_mov_b32 m0, s59
	s_nop 0
	global_load_lds_dwordx4 v188, s[56:57]
	s_waitcnt vmcnt(8)
	s_waitcnt lgkmcnt(0)
	s_barrier
	s_waitcnt lgkmcnt(0)
	v_mfma_f32_16x16x32_bf16 v[60:63], v[96:99], v[160:163], v[60:63]
	v_mfma_f32_16x16x32_bf16 v[56:59], v[120:123], v[160:163], v[56:59]
	v_mfma_f32_16x16x32_bf16 v[44:47], v[96:99], v[168:171], v[44:47]
	v_mfma_f32_16x16x32_bf16 v[40:43], v[120:123], v[168:171], v[40:43]
	v_mfma_f32_16x16x32_bf16 v[28:31], v[96:99], v[176:179], v[28:31]
	v_mfma_f32_16x16x32_bf16 v[24:27], v[120:123], v[176:179], v[24:27]
	v_mfma_f32_16x16x32_bf16 v[12:15], v[96:99], v[202:205], v[12:15]
	v_mfma_f32_16x16x32_bf16 v[8:11], v[120:123], v[202:205], v[8:11]
	v_mfma_f32_16x16x32_bf16 v[60:63], v[108:111], v[164:167], v[60:63]
	v_mfma_f32_16x16x32_bf16 v[56:59], v[128:131], v[164:167], v[56:59]
	v_mfma_f32_16x16x32_bf16 v[44:47], v[108:111], v[172:175], v[44:47]
	v_mfma_f32_16x16x32_bf16 v[40:43], v[128:131], v[172:175], v[40:43]
	v_mfma_f32_16x16x32_bf16 v[28:31], v[108:111], v[180:183], v[28:31]
	v_mfma_f32_16x16x32_bf16 v[24:27], v[128:131], v[180:183], v[24:27]
	v_mfma_f32_16x16x32_bf16 v[12:15], v[108:111], v[206:209], v[12:15]
	v_mfma_f32_16x16x32_bf16 v[8:11], v[128:131], v[206:209], v[8:11]
	v_mfma_f32_16x16x32_bf16 v[52:55], v[144:147], v[160:163], v[52:55]
	v_mfma_f32_16x16x32_bf16 v[48:51], v[152:155], v[160:163], v[48:51]
	v_mfma_f32_16x16x32_bf16 v[36:39], v[144:147], v[168:171], v[36:39]
	v_mfma_f32_16x16x32_bf16 v[32:35], v[152:155], v[168:171], v[32:35]
	v_mfma_f32_16x16x32_bf16 v[20:23], v[144:147], v[176:179], v[20:23]
	v_mfma_f32_16x16x32_bf16 v[16:19], v[152:155], v[176:179], v[16:19]
	v_mfma_f32_16x16x32_bf16 v[4:7], v[144:147], v[202:205], v[4:7]
	v_mfma_f32_16x16x32_bf16 v[0:3], v[152:155], v[202:205], v[0:3]
	v_mfma_f32_16x16x32_bf16 v[52:55], v[148:151], v[164:167], v[52:55]
	v_mfma_f32_16x16x32_bf16 v[48:51], v[156:159], v[164:167], v[48:51]
	v_mfma_f32_16x16x32_bf16 v[36:39], v[148:151], v[172:175], v[36:39]
	v_mfma_f32_16x16x32_bf16 v[32:35], v[156:159], v[172:175], v[32:35]
	v_mfma_f32_16x16x32_bf16 v[20:23], v[148:151], v[180:183], v[20:23]
	v_mfma_f32_16x16x32_bf16 v[16:19], v[156:159], v[180:183], v[16:19]
	v_mfma_f32_16x16x32_bf16 v[4:7], v[148:151], v[206:209], v[4:7]
	v_mfma_f32_16x16x32_bf16 v[0:3], v[156:159], v[206:209], v[0:3]
	s_barrier
	s_add_i32 s77, 0, 0x18000
	s_add_i32 s78, 0, 0x1c000
	v_add_u32_e32 v128, s77, v221
	v_add_u32_e32 v156, s78, v221
	ds_read_b128 v[96:99], v128
	ds_read_b128 v[108:111], v128 offset:1024
	ds_read_b128 v[120:123], v128 offset:2048
	ds_read_b128 v[128:131], v128 offset:3072
	ds_read_b128 v[144:147], v156
	ds_read_b128 v[148:151], v156 offset:1024
	ds_read_b128 v[152:155], v156 offset:2048
	ds_read_b128 v[156:159], v156 offset:3072
	s_add_u32 s56, s56, 0x40000
	s_addc_u32 s57, s57, 0
	s_mov_b32 m0, s60
	ds_read_b128 v[160:163], v225 offset:32768
	ds_read_b128 v[164:167], v225 offset:33792
	ds_read_b128 v[168:171], v225 offset:34816
	ds_read_b128 v[172:175], v225 offset:35840
	ds_read_b128 v[176:179], v225 offset:36864
	ds_read_b128 v[180:183], v225 offset:37888
	ds_read_b128 v[202:205], v225 offset:38912
	ds_read_b128 v[206:209], v225 offset:39936
	global_load_lds_dwordx4 v184, s[56:57]
	s_mov_b32 m0, s61
	s_nop 0
	global_load_lds_dwordx4 v188, s[56:57]
	s_waitcnt vmcnt(8)
	s_waitcnt lgkmcnt(0)
	s_barrier
; #define PG8_STAGE(bufoff, gbase, voff) do { _Pragma("unroll") for (int _i = 0; _i < 2; ++_i) \
;         __builtin_amdgcn_global_load_lds((const unsigned*)((const char*)(gbase) + (voff)[_i]), (PG8_LAS unsigned*)(lds + (bufoff) + ldsw + _i * 8192), 16, 0, 0); } while (0)
; #define PG8_LDA(dst, b, h) do { _Pragma("unroll") for (int m = 0; m < 4; ++m) _Pragma("unroll") for (int k = 0; k < 2; ++k) dst[m][k] = *(const PG8_LAS bf16x8*)(lds + PG8_SA(b, h) + aoff + m * 2048 + k * 1024); } while (0)
; #define PG8_LDB(dst, b, h) do { _Pragma("unroll") for (int n = 0; n < 2; ++n) _Pragma("unroll") for (int k = 0; k < 2; ++k) dst[n][k] = *(const PG8_LAS bf16x8*)(lds + PG8_SB(b, h) + boff + n * 2048 + k * 1024); } while (0)
; #define PG8_MMA(ai, bj, At, Bt) do { __builtin_amdgcn_s_setprio(1); _Pragma("unroll") for (int m = 0; m < 4; ++m) _Pragma("unroll") for (int n = 0; n < 2; ++n) _Pragma("unroll") for (int k = 0; k < 2; ++k) \
;         acc[ai][bj][m][n] = __builtin_amdgcn_mfma_f32_16x16x32_bf16(Bt[n][k], At[m][k], acc[ai][bj][m][n], 0, 0, 0); __builtin_amdgcn_s_setprio(0); } while (0)
; #define PG8_WAIT_V(n) asm volatile("s_waitcnt vmcnt(" #n ")" ::: "memory")
; #define PG8_WAIT_L(n) asm volatile("s_waitcnt lgkmcnt(" #n ")" ::: "memory")
; #define PG8_BAR __builtin_amdgcn_s_barrier()
; #define PG8_SCHED __builtin_amdgcn_sched_barrier(0)
; template <class Epi, class Sched, bool ALIGN_EPI = false, bool SP2 = false>
; __device__ __forceinline__ void gemm_phase(PG8_LAS unsigned char* lds, const Gemm g, const Sched& S, const Epi& E) {
;     ...
;             PG8_LDB(B0, 1, 0); PG8_LDB(B1, 1, 1); PG8_SCHED; PG8_LDA(At, 1, 0); PG8_STAGE(PG8_SA(0, 1), a2 + hstep, voffA);
;             PG8_WAIT_V(8); PG8_WAIT_L(0); PG8_BAR; PG8_MMA(0, 0, At, B0); PG8_MMA(0, 1, At, B1); PG8_BAR; PG8_SCHED;
;             PG8_LDA(At, 1, 1); PG8_STAGE(PG8_SB(1, 0), b3, voffB); PG8_STAGE(PG8_SB(1, 1), b3 + hstep, voffB); PG8_STAGE(PG8_SA(1, 0), a3, voffA);
;             PG8_WAIT_V(8); PG8_WAIT_L(0); PG8_BAR; PG8_MMA(1, 0, At, B0); PG8_MMA(1, 1, At, B1); PG8_BAR; PG8_SCHED;
	s_waitcnt lgkmcnt(0)
	v_mfma_f32_16x16x32_bf16 v[140:143], v[96:99], v[160:163], v[140:143]
	v_mfma_f32_16x16x32_bf16 v[136:139], v[120:123], v[160:163], v[136:139]
	v_mfma_f32_16x16x32_bf16 v[116:119], v[96:99], v[168:171], v[116:119]
	v_mfma_f32_16x16x32_bf16 v[112:115], v[120:123], v[168:171], v[112:115]
	v_mfma_f32_16x16x32_bf16 v[92:95], v[96:99], v[176:179], v[92:95]
	v_mfma_f32_16x16x32_bf16 v[88:91], v[120:123], v[176:179], v[88:91]
	v_mfma_f32_16x16x32_bf16 v[76:79], v[96:99], v[202:205], v[76:79]
	v_mfma_f32_16x16x32_bf16 v[72:75], v[120:123], v[202:205], v[72:75]
	v_mfma_f32_16x16x32_bf16 v[140:143], v[108:111], v[164:167], v[140:143]
	v_mfma_f32_16x16x32_bf16 v[136:139], v[128:131], v[164:167], v[136:139]
	v_mfma_f32_16x16x32_bf16 v[116:119], v[108:111], v[172:175], v[116:119]
	v_mfma_f32_16x16x32_bf16 v[112:115], v[128:131], v[172:175], v[112:115]
	v_mfma_f32_16x16x32_bf16 v[92:95], v[108:111], v[180:183], v[92:95]
	v_mfma_f32_16x16x32_bf16 v[88:91], v[128:131], v[180:183], v[88:91]
	v_mfma_f32_16x16x32_bf16 v[76:79], v[108:111], v[206:209], v[76:79]
	v_mfma_f32_16x16x32_bf16 v[72:75], v[128:131], v[206:209], v[72:75]
	v_mfma_f32_16x16x32_bf16 v[132:135], v[144:147], v[160:163], v[132:135]
	v_mfma_f32_16x16x32_bf16 v[124:127], v[152:155], v[160:163], v[124:127]
	v_mfma_f32_16x16x32_bf16 v[104:107], v[144:147], v[168:171], v[104:107]
	v_mfma_f32_16x16x32_bf16 v[100:103], v[152:155], v[168:171], v[100:103]
	v_mfma_f32_16x16x32_bf16 v[84:87], v[144:147], v[176:179], v[84:87]
	v_mfma_f32_16x16x32_bf16 v[80:83], v[152:155], v[176:179], v[80:83]
	v_mfma_f32_16x16x32_bf16 v[68:71], v[144:147], v[202:205], v[68:71]
	v_mfma_f32_16x16x32_bf16 v[64:67], v[152:155], v[202:205], v[64:67]
	v_mfma_f32_16x16x32_bf16 v[132:135], v[148:151], v[164:167], v[132:135]
	v_mfma_f32_16x16x32_bf16 v[124:127], v[156:159], v[164:167], v[124:127]
	v_mfma_f32_16x16x32_bf16 v[104:107], v[148:151], v[172:175], v[104:107]
	v_mfma_f32_16x16x32_bf16 v[100:103], v[156:159], v[172:175], v[100:103]
	v_mfma_f32_16x16x32_bf16 v[84:87], v[148:151], v[180:183], v[84:87]
	v_mfma_f32_16x16x32_bf16 v[80:83], v[156:159], v[180:183], v[80:83]
	v_mfma_f32_16x16x32_bf16 v[68:71], v[148:151], v[206:209], v[68:71]
	v_mfma_f32_16x16x32_bf16 v[64:67], v[156:159], v[206:209], v[64:67]
	s_barrier
	s_add_i32 s56, s77, s58
	s_mov_b32 m0, s56
	ds_read_b128 v[160:163], v225 offset:49152
	ds_read_b128 v[164:167], v225 offset:50176
	ds_read_b128 v[168:171], v225 offset:51200
	ds_read_b128 v[172:175], v225 offset:52224
	ds_read_b128 v[176:179], v225 offset:53248
	ds_read_b128 v[180:183], v225 offset:54272
	ds_read_b128 v[202:205], v225 offset:55296
	ds_read_b128 v[206:209], v225 offset:56320
	global_load_lds_dwordx4 v186, s[98:99]
	s_add_i32 m0, s56, 0x2000
	s_add_u32 s54, s54, 0x40080
	s_addc_u32 s55, s55, 0
	s_add_i32 s56, s78, s58
	global_load_lds_dwordx4 v190, s[98:99]
	s_mov_b32 m0, s56
	s_nop 0
	global_load_lds_dwordx4 v186, s[54:55]
	s_add_i32 m0, s56, 0x2000
	s_nop 0
	global_load_lds_dwordx4 v190, s[54:55]
	s_mov_b32 m0, s66
	s_nop 0
	global_load_lds_dwordx4 v184, s[100:101]
	s_mov_b32 m0, s67
	s_nop 0
	global_load_lds_dwordx4 v188, s[100:101]
	s_waitcnt vmcnt(8)
	s_waitcnt lgkmcnt(0)
	s_barrier
	s_waitcnt lgkmcnt(0)
	v_mfma_f32_16x16x32_bf16 v[60:63], v[96:99], v[160:163], v[60:63]
	v_mfma_f32_16x16x32_bf16 v[56:59], v[120:123], v[160:163], v[56:59]
	v_mfma_f32_16x16x32_bf16 v[44:47], v[96:99], v[168:171], v[44:47]
	v_mfma_f32_16x16x32_bf16 v[40:43], v[120:123], v[168:171], v[40:43]
	v_mfma_f32_16x16x32_bf16 v[28:31], v[96:99], v[176:179], v[28:31]
	v_mfma_f32_16x16x32_bf16 v[24:27], v[120:123], v[176:179], v[24:27]
	v_mfma_f32_16x16x32_bf16 v[12:15], v[96:99], v[202:205], v[12:15]
	v_mfma_f32_16x16x32_bf16 v[8:11], v[120:123], v[202:205], v[8:11]
	v_mfma_f32_16x16x32_bf16 v[60:63], v[108:111], v[164:167], v[60:63]
	v_mfma_f32_16x16x32_bf16 v[56:59], v[128:131], v[164:167], v[56:59]
	v_mfma_f32_16x16x32_bf16 v[44:47], v[108:111], v[172:175], v[44:47]
	v_mfma_f32_16x16x32_bf16 v[40:43], v[128:131], v[172:175], v[40:43]
	v_mfma_f32_16x16x32_bf16 v[28:31], v[108:111], v[180:183], v[28:31]
	v_mfma_f32_16x16x32_bf16 v[24:27], v[128:131], v[180:183], v[24:27]
	v_mfma_f32_16x16x32_bf16 v[12:15], v[108:111], v[206:209], v[12:15]
	v_mfma_f32_16x16x32_bf16 v[8:11], v[128:131], v[206:209], v[8:11]
	v_mfma_f32_16x16x32_bf16 v[52:55], v[144:147], v[160:163], v[52:55]
	v_mfma_f32_16x16x32_bf16 v[48:51], v[152:155], v[160:163], v[48:51]
	v_mfma_f32_16x16x32_bf16 v[36:39], v[144:147], v[168:171], v[36:39]
	v_mfma_f32_16x16x32_bf16 v[32:35], v[152:155], v[168:171], v[32:35]
	v_mfma_f32_16x16x32_bf16 v[20:23], v[144:147], v[176:179], v[20:23]
	v_mfma_f32_16x16x32_bf16 v[16:19], v[152:155], v[176:179], v[16:19]
	v_mfma_f32_16x16x32_bf16 v[4:7], v[144:147], v[202:205], v[4:7]
	v_mfma_f32_16x16x32_bf16 v[0:3], v[152:155], v[202:205], v[0:3]
	v_mfma_f32_16x16x32_bf16 v[52:55], v[148:151], v[164:167], v[52:55]
	v_mfma_f32_16x16x32_bf16 v[48:51], v[156:159], v[164:167], v[48:51]
	v_mfma_f32_16x16x32_bf16 v[36:39], v[148:151], v[172:175], v[36:39]
	v_mfma_f32_16x16x32_bf16 v[32:35], v[156:159], v[172:175], v[32:35]
	v_mfma_f32_16x16x32_bf16 v[20:23], v[148:151], v[180:183], v[20:23]
	v_mfma_f32_16x16x32_bf16 v[16:19], v[156:159], v[180:183], v[16:19]
	v_mfma_f32_16x16x32_bf16 v[4:7], v[148:151], v[206:209], v[4:7]
	v_mfma_f32_16x16x32_bf16 v[0:3], v[156:159], v[206:209], v[0:3]
	s_barrier
	s_add_i32 s76, s76, 2
	s_add_u32 s20, s20, 0x100
	s_addc_u32 s21, s21, 0
	s_add_u32 s74, s74, 0x100
	s_addc_u32 s75, s75, 0
	s_cmp_gt_u32 s76, 13
	s_cbranch_scc0 .LBB0_705
	s_and_b64 vcc, exec, s[14:15]
	s_cbranch_vccz .LBB0_708
	s_barrier

; #define PG8_STAGE(bufoff, gbase, voff) do { _Pragma("unroll") for (int _i = 0; _i < 2; ++_i) \
;         __builtin_amdgcn_global_load_lds((const unsigned*)((const char*)(gbase) + (voff)[_i]), (PG8_LAS unsigned*)(lds + (bufoff) + ldsw + _i * 8192), 16, 0, 0); } while (0)
; #define PG8_LDA(dst, b, h) do { _Pragma("unroll") for (int m = 0; m < 4; ++m) _Pragma("unroll") for (int k = 0; k < 2; ++k) dst[m][k] = *(const PG8_LAS bf16x8*)(lds + PG8_SA(b, h) + aoff + m * 2048 + k * 1024); } while (0)
; #define PG8_LDB(dst, b, h) do { _Pragma("unroll") for (int n = 0; n < 2; ++n) _Pragma("unroll") for (int k = 0; k < 2; ++k) dst[n][k] = *(const PG8_LAS bf16x8*)(lds + PG8_SB(b, h) + boff + n * 2048 + k * 1024); } while (0)
; #define PG8_MMA(ai, bj, At, Bt) do { __builtin_amdgcn_s_setprio(1); _Pragma("unroll") for (int m = 0; m < 4; ++m) _Pragma("unroll") for (int n = 0; n < 2; ++n) _Pragma("unroll") for (int k = 0; k < 2; ++k) \
;         acc[ai][bj][m][n] = __builtin_amdgcn_mfma_f32_16x16x32_bf16(Bt[n][k], At[m][k], acc[ai][bj][m][n], 0, 0, 0); __builtin_amdgcn_s_setprio(0); } while (0)
; #define PG8_BAR __builtin_amdgcn_s_barrier()
; template <class Epi, class Sched, bool ALIGN_EPI = false, bool SP2 = false>
; __device__ __forceinline__ void gemm_phase(PG8_LAS unsigned char* lds, const Gemm g, const Sched& S, const Epi& E) {
;     ...
;         const bool has_next = S.next(ui + 1, nxt);
;         const char* nA = has_next ? (const char*)g.A + (size_t)nxt.pm * tstep : cA; const char* nB = has_next ? (const char*)g.Bt + (size_t)nxt.pn * tstep : cB;
;         for (int t = 0; t < nt; t += 2) {
;             const bool last = (t == nt - 2);
;             const char* a1 = cA + (size_t)(t + 1) * kstep;
;             const char* a2 = last ? nA : cA + (size_t)(t + 2) * kstep; const char* b2 = last ? nB : cB + (size_t)(t + 2) * kstep;
;             const char* a3 = a2 + kstep; const char* b3 = b2 + kstep;
;             if (last && has_next) S.a_ready(nxt);
;             if constexpr (SP2) {
;             PG8_LDB(B0, 0, 0); PG8_LDB(B1, 0, 1); PG8_SCHED; PG8_LDA(At, 0, 0); PG8_STAGE(PG8_SA(1, 1), a1 + hstep, voffA);
;             PG8_WAIT_V(8); PG8_WAIT_L(0); PG8_BAR; PG8_MMA(0, 0, At, B0); PG8_MMA(0, 1, At, B1); PG8_BAR; PG8_SCHED;
;             PG8_LDA(At, 0, 1); PG8_STAGE(PG8_SB(0, 0), b2, voffB); PG8_STAGE(PG8_SB(0, 1), b2 + hstep, voffB); PG8_STAGE(PG8_SA(0, 0), a2, voffA);
.LBB0_809:
	s_ashr_i32 s15, s14, 31
	s_lshl_b64 s[16:17], s[14:15], 19
	s_add_u32 s16, s36, s16
	s_addc_u32 s17, s37, s17
	s_and_b64 s[18:19], s[4:5], exec
	s_cselect_b32 s15, s17, s21
	s_cselect_b32 s65, s16, s20
	s_ashr_i32 s13, s12, 31
	s_lshl_b64 s[18:19], s[12:13], 19
	s_add_u32 s18, s50, s18
	s_addc_u32 s19, s51, s19
	s_and_b64 s[44:45], s[4:5], exec
	s_cselect_b32 s13, s19, s39
	s_cselect_b32 s66, s18, s38
	s_add_u32 s20, s20, 0x40080
	s_addc_u32 s21, s21, 0
	s_add_u32 s67, s38, 0x100
	s_addc_u32 s68, s39, 0
	s_mov_b32 s69, -2
	ds_read_b128 v[154:157], v150
	ds_read_b128 v[158:161], v150 offset:1024
	ds_read_b128 v[162:165], v150 offset:2048
	ds_read_b128 v[166:169], v150 offset:3072
	ds_read_b128 v[170:173], v151
	ds_read_b128 v[174:177], v151 offset:1024
	ds_read_b128 v[178:181], v151 offset:2048
	ds_read_b128 v[182:185], v151 offset:3072
	s_add_u32 s38, s20, 0xfffc0080
	s_addc_u32 s39, s21, -1
	s_cmp_eq_u32 s69, 12
	s_cselect_b32 s45, s15, s39
	s_cselect_b32 s44, s65, s38
	s_cselect_b32 s39, s13, s68
	s_cselect_b32 s38, s66, s67
	s_add_i32 m0, s35, 0xc000
	ds_read_b128 v[186:189], v152
	ds_read_b128 v[190:193], v152 offset:1024
	ds_read_b128 v[198:201], v152 offset:2048
	ds_read_b128 v[202:205], v152 offset:3072
	ds_read_b128 v[206:209], v152 offset:4096
	ds_read_b128 v[210:213], v152 offset:5120
	ds_read_b128 v[214:217], v152 offset:6144
	ds_read_b128 v[218:221], v152 offset:7168
	global_load_lds_dwordx4 v136, s[20:21]
	s_add_i32 m0, s35, 0xe000
	s_nop 0
	global_load_lds_dwordx4 v138, s[20:21]
	s_waitcnt vmcnt(8)
	s_waitcnt lgkmcnt(0)
	s_barrier
	s_waitcnt lgkmcnt(0)
	v_mfma_f32_16x16x32_bf16 v[124:127], v[154:157], v[186:189], 0
	v_mfma_f32_16x16x32_bf16 v[116:119], v[162:165], v[186:189], 0
	v_mfma_f32_16x16x32_bf16 v[108:111], v[154:157], v[198:201], 0
	v_mfma_f32_16x16x32_bf16 v[100:103], v[162:165], v[198:201], 0
	v_mfma_f32_16x16x32_bf16 v[92:95], v[154:157], v[206:209], 0
	v_mfma_f32_16x16x32_bf16 v[84:87], v[162:165], v[206:209], 0
	v_mfma_f32_16x16x32_bf16 v[76:79], v[154:157], v[214:217], 0
	v_mfma_f32_16x16x32_bf16 v[68:71], v[162:165], v[214:217], 0
	v_mfma_f32_16x16x32_bf16 v[124:127], v[158:161], v[190:193], v[124:127]
	v_mfma_f32_16x16x32_bf16 v[116:119], v[166:169], v[190:193], v[116:119]
	v_mfma_f32_16x16x32_bf16 v[108:111], v[158:161], v[202:205], v[108:111]
	v_mfma_f32_16x16x32_bf16 v[100:103], v[166:169], v[202:205], v[100:103]
	v_mfma_f32_16x16x32_bf16 v[92:95], v[158:161], v[210:213], v[92:95]
	v_mfma_f32_16x16x32_bf16 v[84:87], v[166:169], v[210:213], v[84:87]
	v_mfma_f32_16x16x32_bf16 v[76:79], v[158:161], v[218:221], v[76:79]
	v_mfma_f32_16x16x32_bf16 v[68:71], v[166:169], v[218:221], v[68:71]
	v_mfma_f32_16x16x32_bf16 v[120:123], v[170:173], v[186:189], 0
	v_mfma_f32_16x16x32_bf16 v[112:115], v[178:181], v[186:189], 0
	v_mfma_f32_16x16x32_bf16 v[104:107], v[170:173], v[198:201], 0
	v_mfma_f32_16x16x32_bf16 v[96:99], v[178:181], v[198:201], 0
	v_mfma_f32_16x16x32_bf16 v[88:91], v[170:173], v[206:209], 0
	v_mfma_f32_16x16x32_bf16 v[80:83], v[178:181], v[206:209], 0
	v_mfma_f32_16x16x32_bf16 v[72:75], v[170:173], v[214:217], 0
	v_mfma_f32_16x16x32_bf16 v[64:67], v[178:181], v[214:217], 0
	v_mfma_f32_16x16x32_bf16 v[120:123], v[174:177], v[190:193], v[120:123]
	v_mfma_f32_16x16x32_bf16 v[112:115], v[182:185], v[190:193], v[112:115]
	v_mfma_f32_16x16x32_bf16 v[104:107], v[174:177], v[202:205], v[104:107]
	v_mfma_f32_16x16x32_bf16 v[96:99], v[182:185], v[202:205], v[96:99]
	v_mfma_f32_16x16x32_bf16 v[88:91], v[174:177], v[210:213], v[88:91]
	v_mfma_f32_16x16x32_bf16 v[80:83], v[182:185], v[210:213], v[80:83]
	v_mfma_f32_16x16x32_bf16 v[72:75], v[174:177], v[218:221], v[72:75]
	v_mfma_f32_16x16x32_bf16 v[64:67], v[182:185], v[218:221], v[64:67]
	s_barrier
	s_add_i32 s70, s60, s52
	s_add_u32 s98, s38, s8
	s_addc_u32 s99, s39, s9
	s_add_u32 s100, s44, s8
	s_addc_u32 s101, s45, s9
	s_mov_b32 m0, s70
	ds_read_b128 v[186:189], v152 offset:16384
	ds_read_b128 v[190:193], v152 offset:17408
	ds_read_b128 v[198:201], v152 offset:18432
	ds_read_b128 v[202:205], v152 offset:19456
	ds_read_b128 v[206:209], v152 offset:20480
	ds_read_b128 v[210:213], v152 offset:21504
	ds_read_b128 v[214:217], v152 offset:22528
	ds_read_b128 v[218:221], v152 offset:23552
	global_load_lds_dwordx4 v132, s[38:39]
	s_add_i32 m0, s70, 0x2000
	s_add_u32 s70, s38, 0x40000
	s_addc_u32 s71, s39, 0
	s_add_i32 s72, s61, s52
	global_load_lds_dwordx4 v128, s[38:39]
	s_mov_b32 m0, s72
	s_nop 0
	global_load_lds_dwordx4 v132, s[70:71]
	s_add_i32 m0, s72, 0x2000
	s_nop 0
	global_load_lds_dwordx4 v128, s[70:71]
	s_mov_b32 m0, s35
	s_nop 0
	global_load_lds_dwordx4 v134, s[44:45]
	s_mov_b32 m0, s54
	s_nop 0
	global_load_lds_dwordx4 v130, s[44:45]
	s_waitcnt vmcnt(8)
	s_waitcnt lgkmcnt(0)
	s_barrier
; #define PG8_STAGE(bufoff, gbase, voff) do { _Pragma("unroll") for (int _i = 0; _i < 2; ++_i) \
;         __builtin_amdgcn_global_load_lds((const unsigned*)((const char*)(gbase) + (voff)[_i]), (PG8_LAS unsigned*)(lds + (bufoff) + ldsw + _i * 8192), 16, 0, 0); } while (0)
; #define PG8_LDA(dst, b, h) do { _Pragma("unroll") for (int m = 0; m < 4; ++m) _Pragma("unroll") for (int k = 0; k < 2; ++k) dst[m][k] = *(const PG8_LAS bf16x8*)(lds + PG8_SA(b, h) + aoff + m * 2048 + k * 1024); } while (0)
; #define PG8_LDB(dst, b, h) do { _Pragma("unroll") for (int n = 0; n < 2; ++n) _Pragma("unroll") for (int k = 0; k < 2; ++k) dst[n][k] = *(const PG8_LAS bf16x8*)(lds + PG8_SB(b, h) + boff + n * 2048 + k * 1024); } while (0)
; #define PG8_MMA(ai, bj, At, Bt) do { __builtin_amdgcn_s_setprio(1); _Pragma("unroll") for (int m = 0; m < 4; ++m) _Pragma("unroll") for (int n = 0; n < 2; ++n) _Pragma("unroll") for (int k = 0; k < 2; ++k) \
;         acc[ai][bj][m][n] = __builtin_amdgcn_mfma_f32_16x16x32_bf16(Bt[n][k], At[m][k], acc[ai][bj][m][n], 0, 0, 0); __builtin_amdgcn_s_setprio(0); } while (0)
; #define PG8_WAIT_V(n) asm volatile("s_waitcnt vmcnt(" #n ")" ::: "memory")
; #define PG8_WAIT_L(n) asm volatile("s_waitcnt lgkmcnt(" #n ")" ::: "memory")
; #define PG8_BAR __builtin_amdgcn_s_barrier()
; #define PG8_SCHED __builtin_amdgcn_sched_barrier(0)
; template <class Epi, class Sched, bool ALIGN_EPI = false, bool SP2 = false>
; __device__ __forceinline__ void gemm_phase(PG8_LAS unsigned char* lds, const Gemm g, const Sched& S, const Epi& E) {
;     ...
;             PG8_LDA(At, 0, 1); PG8_STAGE(PG8_SB(0, 0), b2, voffB); PG8_STAGE(PG8_SB(0, 1), b2 + hstep, voffB); PG8_STAGE(PG8_SA(0, 0), a2, voffA);
;             PG8_WAIT_V(8); PG8_WAIT_L(0); PG8_BAR; PG8_MMA(1, 0, At, B0); PG8_MMA(1, 1, At, B1); PG8_BAR; PG8_SCHED;
;             PG8_LDB(B0, 1, 0); PG8_LDB(B1, 1, 1); PG8_SCHED; PG8_LDA(At, 1, 0); PG8_STAGE(PG8_SA(0, 1), a2 + hstep, voffA);
;             PG8_WAIT_V(8); PG8_WAIT_L(0); PG8_BAR; PG8_MMA(0, 0, At, B0); PG8_MMA(0, 1, At, B1); PG8_BAR; PG8_SCHED;
	s_waitcnt lgkmcnt(0)
	v_mfma_f32_16x16x32_bf16 v[60:63], v[154:157], v[186:189], 0
	v_mfma_f32_16x16x32_bf16 v[52:55], v[162:165], v[186:189], 0
	v_mfma_f32_16x16x32_bf16 v[44:47], v[154:157], v[198:201], 0
	v_mfma_f32_16x16x32_bf16 v[36:39], v[162:165], v[198:201], 0
	v_mfma_f32_16x16x32_bf16 v[28:31], v[154:157], v[206:209], 0
	v_mfma_f32_16x16x32_bf16 v[20:23], v[162:165], v[206:209], 0
	v_mfma_f32_16x16x32_bf16 v[12:15], v[154:157], v[214:217], 0
	v_mfma_f32_16x16x32_bf16 v[4:7], v[162:165], v[214:217], 0
	v_mfma_f32_16x16x32_bf16 v[60:63], v[158:161], v[190:193], v[60:63]
	v_mfma_f32_16x16x32_bf16 v[52:55], v[166:169], v[190:193], v[52:55]
	v_mfma_f32_16x16x32_bf16 v[44:47], v[158:161], v[202:205], v[44:47]
	v_mfma_f32_16x16x32_bf16 v[36:39], v[166:169], v[202:205], v[36:39]
	v_mfma_f32_16x16x32_bf16 v[28:31], v[158:161], v[210:213], v[28:31]
	v_mfma_f32_16x16x32_bf16 v[20:23], v[166:169], v[210:213], v[20:23]
	v_mfma_f32_16x16x32_bf16 v[12:15], v[158:161], v[218:221], v[12:15]
	v_mfma_f32_16x16x32_bf16 v[4:7], v[166:169], v[218:221], v[4:7]
	v_mfma_f32_16x16x32_bf16 v[56:59], v[170:173], v[186:189], 0
	v_mfma_f32_16x16x32_bf16 v[48:51], v[178:181], v[186:189], 0
	v_mfma_f32_16x16x32_bf16 v[40:43], v[170:173], v[198:201], 0
	v_mfma_f32_16x16x32_bf16 v[32:35], v[178:181], v[198:201], 0
	v_mfma_f32_16x16x32_bf16 v[24:27], v[170:173], v[206:209], 0
	v_mfma_f32_16x16x32_bf16 v[16:19], v[178:181], v[206:209], 0
	v_mfma_f32_16x16x32_bf16 v[8:11], v[170:173], v[214:217], 0
	v_mfma_f32_16x16x32_bf16 v[0:3], v[178:181], v[214:217], 0
	v_mfma_f32_16x16x32_bf16 v[56:59], v[174:177], v[190:193], v[56:59]
	v_mfma_f32_16x16x32_bf16 v[48:51], v[182:185], v[190:193], v[48:51]
	v_mfma_f32_16x16x32_bf16 v[40:43], v[174:177], v[202:205], v[40:43]
	v_mfma_f32_16x16x32_bf16 v[32:35], v[182:185], v[202:205], v[32:35]
	v_mfma_f32_16x16x32_bf16 v[24:27], v[174:177], v[210:213], v[24:27]
	v_mfma_f32_16x16x32_bf16 v[16:19], v[182:185], v[210:213], v[16:19]
	v_mfma_f32_16x16x32_bf16 v[8:11], v[174:177], v[218:221], v[8:11]
	v_mfma_f32_16x16x32_bf16 v[0:3], v[182:185], v[218:221], v[0:3]
	s_barrier
	s_add_i32 s70, 0, 0x18000
	v_add_u32_e32 v153, s70, v147
	s_add_i32 s71, 0, 0x1c000
	ds_read_b128 v[154:157], v153
	ds_read_b128 v[158:161], v153 offset:1024
	ds_read_b128 v[162:165], v153 offset:2048
	ds_read_b128 v[166:169], v153 offset:3072
	v_add_u32_e32 v153, s71, v147
	ds_read_b128 v[170:173], v153
	ds_read_b128 v[174:177], v153 offset:1024
	ds_read_b128 v[178:181], v153 offset:2048
	ds_read_b128 v[182:185], v153 offset:3072
	s_add_u32 s44, s44, 0x40000
	s_addc_u32 s45, s45, 0
	s_mov_b32 m0, s55
	ds_read_b128 v[186:189], v152 offset:32768
	ds_read_b128 v[190:193], v152 offset:33792
	ds_read_b128 v[198:201], v152 offset:34816
	ds_read_b128 v[202:205], v152 offset:35840
	ds_read_b128 v[206:209], v152 offset:36864
	ds_read_b128 v[210:213], v152 offset:37888
	ds_read_b128 v[214:217], v152 offset:38912
	ds_read_b128 v[218:221], v152 offset:39936
	global_load_lds_dwordx4 v134, s[44:45]
	s_mov_b32 m0, s56
	s_nop 0
	global_load_lds_dwordx4 v130, s[44:45]
	s_waitcnt vmcnt(8)
	s_waitcnt lgkmcnt(0)
	s_barrier
	s_waitcnt lgkmcnt(0)
	v_mfma_f32_16x16x32_bf16 v[124:127], v[154:157], v[186:189], v[124:127]
	v_mfma_f32_16x16x32_bf16 v[116:119], v[162:165], v[186:189], v[116:119]
	v_mfma_f32_16x16x32_bf16 v[108:111], v[154:157], v[198:201], v[108:111]
	v_mfma_f32_16x16x32_bf16 v[100:103], v[162:165], v[198:201], v[100:103]
	v_mfma_f32_16x16x32_bf16 v[92:95], v[154:157], v[206:209], v[92:95]
	v_mfma_f32_16x16x32_bf16 v[84:87], v[162:165], v[206:209], v[84:87]
	v_mfma_f32_16x16x32_bf16 v[76:79], v[154:157], v[214:217], v[76:79]
	v_mfma_f32_16x16x32_bf16 v[68:71], v[162:165], v[214:217], v[68:71]
	v_mfma_f32_16x16x32_bf16 v[124:127], v[158:161], v[190:193], v[124:127]
	v_mfma_f32_16x16x32_bf16 v[116:119], v[166:169], v[190:193], v[116:119]
	v_mfma_f32_16x16x32_bf16 v[108:111], v[158:161], v[202:205], v[108:111]
	v_mfma_f32_16x16x32_bf16 v[100:103], v[166:169], v[202:205], v[100:103]
	v_mfma_f32_16x16x32_bf16 v[92:95], v[158:161], v[210:213], v[92:95]
	v_mfma_f32_16x16x32_bf16 v[84:87], v[166:169], v[210:213], v[84:87]
	v_mfma_f32_16x16x32_bf16 v[76:79], v[158:161], v[218:221], v[76:79]
	v_mfma_f32_16x16x32_bf16 v[68:71], v[166:169], v[218:221], v[68:71]
	v_mfma_f32_16x16x32_bf16 v[120:123], v[170:173], v[186:189], v[120:123]
	v_mfma_f32_16x16x32_bf16 v[112:115], v[178:181], v[186:189], v[112:115]
	v_mfma_f32_16x16x32_bf16 v[104:107], v[170:173], v[198:201], v[104:107]
	v_mfma_f32_16x16x32_bf16 v[96:99], v[178:181], v[198:201], v[96:99]
	v_mfma_f32_16x16x32_bf16 v[88:91], v[170:173], v[206:209], v[88:91]
	v_mfma_f32_16x16x32_bf16 v[80:83], v[178:181], v[206:209], v[80:83]
	v_mfma_f32_16x16x32_bf16 v[72:75], v[170:173], v[214:217], v[72:75]
	v_mfma_f32_16x16x32_bf16 v[64:67], v[178:181], v[214:217], v[64:67]
	v_mfma_f32_16x16x32_bf16 v[120:123], v[174:177], v[190:193], v[120:123]
	v_mfma_f32_16x16x32_bf16 v[112:115], v[182:185], v[190:193], v[112:115]
	v_mfma_f32_16x16x32_bf16 v[104:107], v[174:177], v[202:205], v[104:107]
	v_mfma_f32_16x16x32_bf16 v[96:99], v[182:185], v[202:205], v[96:99]
	v_mfma_f32_16x16x32_bf16 v[88:91], v[174:177], v[210:213], v[88:91]
	v_mfma_f32_16x16x32_bf16 v[80:83], v[182:185], v[210:213], v[80:83]
	v_mfma_f32_16x16x32_bf16 v[72:75], v[174:177], v[218:221], v[72:75]
	v_mfma_f32_16x16x32_bf16 v[64:67], v[182:185], v[218:221], v[64:67]
	s_barrier
; #define PG8_STAGE(bufoff, gbase, voff) do { _Pragma("unroll") for (int _i = 0; _i < 2; ++_i) \
;         __builtin_amdgcn_global_load_lds((const unsigned*)((const char*)(gbase) + (voff)[_i]), (PG8_LAS unsigned*)(lds + (bufoff) + ldsw + _i * 8192), 16, 0, 0); } while (0)
; #define PG8_LDA(dst, b, h) do { _Pragma("unroll") for (int m = 0; m < 4; ++m) _Pragma("unroll") for (int k = 0; k < 2; ++k) dst[m][k] = *(const PG8_LAS bf16x8*)(lds + PG8_SA(b, h) + aoff + m * 2048 + k * 1024); } while (0)
; #define PG8_LDB(dst, b, h) do { _Pragma("unroll") for (int n = 0; n < 2; ++n) _Pragma("unroll") for (int k = 0; k < 2; ++k) dst[n][k] = *(const PG8_LAS bf16x8*)(lds + PG8_SB(b, h) + boff + n * 2048 + k * 1024); } while (0)
; #define PG8_MMA(ai, bj, At, Bt) do { __builtin_amdgcn_s_setprio(1); _Pragma("unroll") for (int m = 0; m < 4; ++m) _Pragma("unroll") for (int n = 0; n < 2; ++n) _Pragma("unroll") for (int k = 0; k < 2; ++k) \
;         acc[ai][bj][m][n] = __builtin_amdgcn_mfma_f32_16x16x32_bf16(Bt[n][k], At[m][k], acc[ai][bj][m][n], 0, 0, 0); __builtin_amdgcn_s_setprio(0); } while (0)
; #define PG8_WAIT_V(n) asm volatile("s_waitcnt vmcnt(" #n ")" ::: "memory")
; template <class Epi, class Sched, bool ALIGN_EPI = false, bool SP2 = false>
; __device__ __forceinline__ void gemm_phase(PG8_LAS unsigned char* lds, const Gemm g, const Sched& S, const Epi& E) {
;     ...
;             PG8_LDB(B0, 0, 0); PG8_LDB(B1, 0, 1); PG8_SCHED; PG8_LDA(At, 0, 0); PG8_STAGE(PG8_SA(1, 1), a1 + hstep, voffA);
;             PG8_WAIT_V(8); PG8_WAIT_L(0); PG8_BAR; PG8_MMA(0, 0, At, B0); PG8_MMA(0, 1, At, B1); PG8_BAR; PG8_SCHED;
;             PG8_LDA(At, 0, 1); PG8_STAGE(PG8_SB(0, 0), b2, voffB); PG8_STAGE(PG8_SB(0, 1), b2 + hstep, voffB); PG8_STAGE(PG8_SA(0, 0), a2, voffA);
;             PG8_WAIT_V(8); PG8_WAIT_L(0); PG8_BAR; PG8_MMA(1, 0, At, B0); PG8_MMA(1, 1, At, B1); PG8_BAR; PG8_SCHED;
;             PG8_LDB(B0, 1, 0); PG8_LDB(B1, 1, 1); PG8_SCHED; PG8_LDA(At, 1, 0); PG8_STAGE(PG8_SA(0, 1), a2 + hstep, voffA);
;             PG8_WAIT_V(8); PG8_WAIT_L(0); PG8_BAR; PG8_MMA(0, 0, At, B0); PG8_MMA(0, 1, At, B1); PG8_BAR; PG8_SCHED;
;             PG8_LDA(At, 1, 1); PG8_STAGE(PG8_SB(1, 0), b3, voffB); PG8_STAGE(PG8_SB(1, 1), b3 + hstep, voffB); PG8_STAGE(PG8_SA(1, 0), a3, voffA);
;             PG8_WAIT_V(8); PG8_WAIT_L(0); PG8_BAR; PG8_MMA(1, 0, At, B0); PG8_MMA(1, 1, At, B1); PG8_BAR; PG8_SCHED;
	s_add_i32 s44, s70, s52
	s_mov_b32 m0, s44
	ds_read_b128 v[186:189], v152 offset:49152
	ds_read_b128 v[190:193], v152 offset:50176
	ds_read_b128 v[198:201], v152 offset:51200
	ds_read_b128 v[202:205], v152 offset:52224
	ds_read_b128 v[206:209], v152 offset:53248
	ds_read_b128 v[210:213], v152 offset:54272
	ds_read_b128 v[214:217], v152 offset:55296
	ds_read_b128 v[218:221], v152 offset:56320
	global_load_lds_dwordx4 v132, s[98:99]
	s_add_i32 m0, s44, 0x2000
	s_add_u32 s38, s38, 0x40080
	s_addc_u32 s39, s39, 0
	s_add_i32 s44, s71, s52
	global_load_lds_dwordx4 v128, s[98:99]
	s_mov_b32 m0, s44
	s_nop 0
	global_load_lds_dwordx4 v132, s[38:39]
	s_add_i32 m0, s44, 0x2000
	s_nop 0
	global_load_lds_dwordx4 v128, s[38:39]
	s_mov_b32 m0, s58
	s_nop 0
	global_load_lds_dwordx4 v134, s[100:101]
	s_mov_b32 m0, s59
	s_nop 0
	global_load_lds_dwordx4 v130, s[100:101]
	s_waitcnt vmcnt(8)
	s_waitcnt lgkmcnt(0)
	s_barrier
	s_waitcnt lgkmcnt(0)
	v_mfma_f32_16x16x32_bf16 v[60:63], v[154:157], v[186:189], v[60:63]
	v_mfma_f32_16x16x32_bf16 v[52:55], v[162:165], v[186:189], v[52:55]
	v_mfma_f32_16x16x32_bf16 v[44:47], v[154:157], v[198:201], v[44:47]
	v_mfma_f32_16x16x32_bf16 v[36:39], v[162:165], v[198:201], v[36:39]
	v_mfma_f32_16x16x32_bf16 v[28:31], v[154:157], v[206:209], v[28:31]
	v_mfma_f32_16x16x32_bf16 v[20:23], v[162:165], v[206:209], v[20:23]
	v_mfma_f32_16x16x32_bf16 v[12:15], v[154:157], v[214:217], v[12:15]
	v_mfma_f32_16x16x32_bf16 v[4:7], v[162:165], v[214:217], v[4:7]
	v_mfma_f32_16x16x32_bf16 v[60:63], v[158:161], v[190:193], v[60:63]
	v_mfma_f32_16x16x32_bf16 v[52:55], v[166:169], v[190:193], v[52:55]
	v_mfma_f32_16x16x32_bf16 v[44:47], v[158:161], v[202:205], v[44:47]
	v_mfma_f32_16x16x32_bf16 v[36:39], v[166:169], v[202:205], v[36:39]
	v_mfma_f32_16x16x32_bf16 v[28:31], v[158:161], v[210:213], v[28:31]
	v_mfma_f32_16x16x32_bf16 v[20:23], v[166:169], v[210:213], v[20:23]
	v_mfma_f32_16x16x32_bf16 v[12:15], v[158:161], v[218:221], v[12:15]
	v_mfma_f32_16x16x32_bf16 v[4:7], v[166:169], v[218:221], v[4:7]
	v_mfma_f32_16x16x32_bf16 v[56:59], v[170:173], v[186:189], v[56:59]
	v_mfma_f32_16x16x32_bf16 v[48:51], v[178:181], v[186:189], v[48:51]
	v_mfma_f32_16x16x32_bf16 v[40:43], v[170:173], v[198:201], v[40:43]
	v_mfma_f32_16x16x32_bf16 v[32:35], v[178:181], v[198:201], v[32:35]
	v_mfma_f32_16x16x32_bf16 v[24:27], v[170:173], v[206:209], v[24:27]
	v_mfma_f32_16x16x32_bf16 v[16:19], v[178:181], v[206:209], v[16:19]
	v_mfma_f32_16x16x32_bf16 v[8:11], v[170:173], v[214:217], v[8:11]
	v_mfma_f32_16x16x32_bf16 v[0:3], v[178:181], v[214:217], v[0:3]
	v_mfma_f32_16x16x32_bf16 v[56:59], v[174:177], v[190:193], v[56:59]
	v_mfma_f32_16x16x32_bf16 v[48:51], v[182:185], v[190:193], v[48:51]
	v_mfma_f32_16x16x32_bf16 v[40:43], v[174:177], v[202:205], v[40:43]
	v_mfma_f32_16x16x32_bf16 v[32:35], v[182:185], v[202:205], v[32:35]
	v_mfma_f32_16x16x32_bf16 v[24:27], v[174:177], v[210:213], v[24:27]
	v_mfma_f32_16x16x32_bf16 v[16:19], v[182:185], v[210:213], v[16:19]
	v_mfma_f32_16x16x32_bf16 v[8:11], v[174:177], v[218:221], v[8:11]
	v_mfma_f32_16x16x32_bf16 v[0:3], v[182:185], v[218:221], v[0:3]
	s_barrier
	s_add_i32 s69, s69, 2
	s_add_u32 s20, s20, 0x100
	s_addc_u32 s21, s21, 0
	s_add_u32 s67, s67, 0x100
	s_addc_u32 s68, s68, 0
	s_cmp_gt_u32 s69, 13
.LBB0_810:
	ds_read_b128 v[154:157], v150
	ds_read_b128 v[158:161], v150 offset:1024
	ds_read_b128 v[162:165], v150 offset:2048
	ds_read_b128 v[166:169], v150 offset:3072
	ds_read_b128 v[170:173], v151
	ds_read_b128 v[174:177], v151 offset:1024
	ds_read_b128 v[178:181], v151 offset:2048
	ds_read_b128 v[182:185], v151 offset:3072
	s_add_u32 s38, s20, 0xfffc0080
	s_addc_u32 s39, s21, -1
	s_cmp_eq_u32 s69, 12
	s_cselect_b32 s45, s15, s39
	s_cselect_b32 s44, s65, s38
	s_cselect_b32 s39, s13, s68
	s_cselect_b32 s38, s66, s67
	s_add_i32 m0, s35, 0xc000
	ds_read_b128 v[186:189], v152
	ds_read_b128 v[190:193], v152 offset:1024
	ds_read_b128 v[198:201], v152 offset:2048
	ds_read_b128 v[202:205], v152 offset:3072
	ds_read_b128 v[206:209], v152 offset:4096
	ds_read_b128 v[210:213], v152 offset:5120
	ds_read_b128 v[214:217], v152 offset:6144
	ds_read_b128 v[218:221], v152 offset:7168
	global_load_lds_dwordx4 v136, s[20:21]
	s_add_i32 m0, s35, 0xe000
	s_nop 0
	global_load_lds_dwordx4 v138, s[20:21]
	s_waitcnt vmcnt(8)
	s_waitcnt lgkmcnt(0)
	s_barrier
	s_waitcnt lgkmcnt(0)
	v_mfma_f32_16x16x32_bf16 v[124:127], v[154:157], v[186:189], v[124:127]
	v_mfma_f32_16x16x32_bf16 v[116:119], v[162:165], v[186:189], v[116:119]
	v_mfma_f32_16x16x32_bf16 v[108:111], v[154:157], v[198:201], v[108:111]
	v_mfma_f32_16x16x32_bf16 v[100:103], v[162:165], v[198:201], v[100:103]
	v_mfma_f32_16x16x32_bf16 v[92:95], v[154:157], v[206:209], v[92:95]
	v_mfma_f32_16x16x32_bf16 v[84:87], v[162:165], v[206:209], v[84:87]
	v_mfma_f32_16x16x32_bf16 v[76:79], v[154:157], v[214:217], v[76:79]
	v_mfma_f32_16x16x32_bf16 v[68:71], v[162:165], v[214:217], v[68:71]
	v_mfma_f32_16x16x32_bf16 v[124:127], v[158:161], v[190:193], v[124:127]
	v_mfma_f32_16x16x32_bf16 v[116:119], v[166:169], v[190:193], v[116:119]
	v_mfma_f32_16x16x32_bf16 v[108:111], v[158:161], v[202:205], v[108:111]
	v_mfma_f32_16x16x32_bf16 v[100:103], v[166:169], v[202:205], v[100:103]
	v_mfma_f32_16x16x32_bf16 v[92:95], v[158:161], v[210:213], v[92:95]
	v_mfma_f32_16x16x32_bf16 v[84:87], v[166:169], v[210:213], v[84:87]
	v_mfma_f32_16x16x32_bf16 v[76:79], v[158:161], v[218:221], v[76:79]
	v_mfma_f32_16x16x32_bf16 v[68:71], v[166:169], v[218:221], v[68:71]
	v_mfma_f32_16x16x32_bf16 v[120:123], v[170:173], v[186:189], v[120:123]
	v_mfma_f32_16x16x32_bf16 v[112:115], v[178:181], v[186:189], v[112:115]
	v_mfma_f32_16x16x32_bf16 v[104:107], v[170:173], v[198:201], v[104:107]
	v_mfma_f32_16x16x32_bf16 v[96:99], v[178:181], v[198:201], v[96:99]
	v_mfma_f32_16x16x32_bf16 v[88:91], v[170:173], v[206:209], v[88:91]
	v_mfma_f32_16x16x32_bf16 v[80:83], v[178:181], v[206:209], v[80:83]
	v_mfma_f32_16x16x32_bf16 v[72:75], v[170:173], v[214:217], v[72:75]
	v_mfma_f32_16x16x32_bf16 v[64:67], v[178:181], v[214:217], v[64:67]
	v_mfma_f32_16x16x32_bf16 v[120:123], v[174:177], v[190:193], v[120:123]
	v_mfma_f32_16x16x32_bf16 v[112:115], v[182:185], v[190:193], v[112:115]
	v_mfma_f32_16x16x32_bf16 v[104:107], v[174:177], v[202:205], v[104:107]
	v_mfma_f32_16x16x32_bf16 v[96:99], v[182:185], v[202:205], v[96:99]
	v_mfma_f32_16x16x32_bf16 v[88:91], v[174:177], v[210:213], v[88:91]
	v_mfma_f32_16x16x32_bf16 v[80:83], v[182:185], v[210:213], v[80:83]
	v_mfma_f32_16x16x32_bf16 v[72:75], v[174:177], v[218:221], v[72:75]
	v_mfma_f32_16x16x32_bf16 v[64:67], v[182:185], v[218:221], v[64:67]
	s_barrier
; #define PG8_STAGE(bufoff, gbase, voff) do { _Pragma("unroll") for (int _i = 0; _i < 2; ++_i) \
;         __builtin_amdgcn_global_load_lds((const unsigned*)((const char*)(gbase) + (voff)[_i]), (PG8_LAS unsigned*)(lds + (bufoff) + ldsw + _i * 8192), 16, 0, 0); } while (0)
; #define PG8_LDA(dst, b, h) do { _Pragma("unroll") for (int m = 0; m < 4; ++m) _Pragma("unroll") for (int k = 0; k < 2; ++k) dst[m][k] = *(const PG8_LAS bf16x8*)(lds + PG8_SA(b, h) + aoff + m * 2048 + k * 1024); } while (0)
; #define PG8_LDB(dst, b, h) do { _Pragma("unroll") for (int n = 0; n < 2; ++n) _Pragma("unroll") for (int k = 0; k < 2; ++k) dst[n][k] = *(const PG8_LAS bf16x8*)(lds + PG8_SB(b, h) + boff + n * 2048 + k * 1024); } while (0)
; #define PG8_MMA(ai, bj, At, Bt) do { __builtin_amdgcn_s_setprio(1); _Pragma("unroll") for (int m = 0; m < 4; ++m) _Pragma("unroll") for (int n = 0; n < 2; ++n) _Pragma("unroll") for (int k = 0; k < 2; ++k) \
;         acc[ai][bj][m][n] = __builtin_amdgcn_mfma_f32_16x16x32_bf16(Bt[n][k], At[m][k], acc[ai][bj][m][n], 0, 0, 0); __builtin_amdgcn_s_setprio(0); } while (0)
; #define PG8_WAIT_V(n) asm volatile("s_waitcnt vmcnt(" #n ")" ::: "memory")
; #define PG8_WAIT_L(n) asm volatile("s_waitcnt lgkmcnt(" #n ")" ::: "memory")
; #define PG8_BAR __builtin_amdgcn_s_barrier()
; #define PG8_SCHED __builtin_amdgcn_sched_barrier(0)
; template <class Epi, class Sched, bool ALIGN_EPI = false, bool SP2 = false>
; __device__ __forceinline__ void gemm_phase(PG8_LAS unsigned char* lds, const Gemm g, const Sched& S, const Epi& E) {
;     ...
;             PG8_LDA(At, 0, 1); PG8_STAGE(PG8_SB(0, 0), b2, voffB); PG8_STAGE(PG8_SB(0, 1), b2 + hstep, voffB); PG8_STAGE(PG8_SA(0, 0), a2, voffA);
;             PG8_WAIT_V(8); PG8_WAIT_L(0); PG8_BAR; PG8_MMA(1, 0, At, B0); PG8_MMA(1, 1, At, B1); PG8_BAR; PG8_SCHED;
;             PG8_LDB(B0, 1, 0); PG8_LDB(B1, 1, 1); PG8_SCHED; PG8_LDA(At, 1, 0); PG8_STAGE(PG8_SA(0, 1), a2 + hstep, voffA);
;             PG8_WAIT_V(8); PG8_WAIT_L(0); PG8_BAR; PG8_MMA(0, 0, At, B0); PG8_MMA(0, 1, At, B1); PG8_BAR; PG8_SCHED;
	s_add_i32 s70, s60, s52
	s_add_u32 s98, s38, s8
	s_addc_u32 s99, s39, s9
	s_add_u32 s100, s44, s8
	s_addc_u32 s101, s45, s9
	s_mov_b32 m0, s70
	ds_read_b128 v[186:189], v152 offset:16384
	ds_read_b128 v[190:193], v152 offset:17408
	ds_read_b128 v[198:201], v152 offset:18432
	ds_read_b128 v[202:205], v152 offset:19456
	ds_read_b128 v[206:209], v152 offset:20480
	ds_read_b128 v[210:213], v152 offset:21504
	ds_read_b128 v[214:217], v152 offset:22528
	ds_read_b128 v[218:221], v152 offset:23552
	global_load_lds_dwordx4 v132, s[38:39]
	s_add_i32 m0, s70, 0x2000
	s_add_u32 s70, s38, 0x40000
	s_addc_u32 s71, s39, 0
	s_add_i32 s72, s61, s52
	global_load_lds_dwordx4 v128, s[38:39]
	s_mov_b32 m0, s72
	s_nop 0
	global_load_lds_dwordx4 v132, s[70:71]
	s_add_i32 m0, s72, 0x2000
	s_nop 0
	global_load_lds_dwordx4 v128, s[70:71]
	s_mov_b32 m0, s35
	s_nop 0
	global_load_lds_dwordx4 v134, s[44:45]
	s_mov_b32 m0, s54
	s_nop 0
	global_load_lds_dwordx4 v130, s[44:45]
	s_waitcnt vmcnt(8)
	s_waitcnt lgkmcnt(0)
	s_barrier
	s_waitcnt lgkmcnt(0)
	v_mfma_f32_16x16x32_bf16 v[60:63], v[154:157], v[186:189], v[60:63]
	v_mfma_f32_16x16x32_bf16 v[52:55], v[162:165], v[186:189], v[52:55]
	v_mfma_f32_16x16x32_bf16 v[44:47], v[154:157], v[198:201], v[44:47]
	v_mfma_f32_16x16x32_bf16 v[36:39], v[162:165], v[198:201], v[36:39]
	v_mfma_f32_16x16x32_bf16 v[28:31], v[154:157], v[206:209], v[28:31]
	v_mfma_f32_16x16x32_bf16 v[20:23], v[162:165], v[206:209], v[20:23]
	v_mfma_f32_16x16x32_bf16 v[12:15], v[154:157], v[214:217], v[12:15]
	v_mfma_f32_16x16x32_bf16 v[4:7], v[162:165], v[214:217], v[4:7]
	v_mfma_f32_16x16x32_bf16 v[60:63], v[158:161], v[190:193], v[60:63]
	v_mfma_f32_16x16x32_bf16 v[52:55], v[166:169], v[190:193], v[52:55]
	v_mfma_f32_16x16x32_bf16 v[44:47], v[158:161], v[202:205], v[44:47]
	v_mfma_f32_16x16x32_bf16 v[36:39], v[166:169], v[202:205], v[36:39]
	v_mfma_f32_16x16x32_bf16 v[28:31], v[158:161], v[210:213], v[28:31]
	v_mfma_f32_16x16x32_bf16 v[20:23], v[166:169], v[210:213], v[20:23]
	v_mfma_f32_16x16x32_bf16 v[12:15], v[158:161], v[218:221], v[12:15]
	v_mfma_f32_16x16x32_bf16 v[4:7], v[166:169], v[218:221], v[4:7]
	v_mfma_f32_16x16x32_bf16 v[56:59], v[170:173], v[186:189], v[56:59]
	v_mfma_f32_16x16x32_bf16 v[48:51], v[178:181], v[186:189], v[48:51]
	v_mfma_f32_16x16x32_bf16 v[40:43], v[170:173], v[198:201], v[40:43]
	v_mfma_f32_16x16x32_bf16 v[32:35], v[178:181], v[198:201], v[32:35]
	v_mfma_f32_16x16x32_bf16 v[24:27], v[170:173], v[206:209], v[24:27]
	v_mfma_f32_16x16x32_bf16 v[16:19], v[178:181], v[206:209], v[16:19]
	v_mfma_f32_16x16x32_bf16 v[8:11], v[170:173], v[214:217], v[8:11]
	v_mfma_f32_16x16x32_bf16 v[0:3], v[178:181], v[214:217], v[0:3]
	v_mfma_f32_16x16x32_bf16 v[56:59], v[174:177], v[190:193], v[56:59]
	v_mfma_f32_16x16x32_bf16 v[48:51], v[182:185], v[190:193], v[48:51]
	v_mfma_f32_16x16x32_bf16 v[40:43], v[174:177], v[202:205], v[40:43]
	v_mfma_f32_16x16x32_bf16 v[32:35], v[182:185], v[202:205], v[32:35]
	v_mfma_f32_16x16x32_bf16 v[24:27], v[174:177], v[210:213], v[24:27]
	v_mfma_f32_16x16x32_bf16 v[16:19], v[182:185], v[210:213], v[16:19]
	v_mfma_f32_16x16x32_bf16 v[8:11], v[174:177], v[218:221], v[8:11]
	v_mfma_f32_16x16x32_bf16 v[0:3], v[182:185], v[218:221], v[0:3]
	s_barrier
	s_add_i32 s70, 0, 0x18000
	v_add_u32_e32 v153, s70, v147
	s_add_i32 s71, 0, 0x1c000
	ds_read_b128 v[154:157], v153
	ds_read_b128 v[158:161], v153 offset:1024
	ds_read_b128 v[162:165], v153 offset:2048
	ds_read_b128 v[166:169], v153 offset:3072
	v_add_u32_e32 v153, s71, v147
	ds_read_b128 v[170:173], v153
	ds_read_b128 v[174:177], v153 offset:1024
	ds_read_b128 v[178:181], v153 offset:2048
	ds_read_b128 v[182:185], v153 offset:3072
	s_add_u32 s44, s44, 0x40000
	s_addc_u32 s45, s45, 0
	s_mov_b32 m0, s55
	ds_read_b128 v[186:189], v152 offset:32768
	ds_read_b128 v[190:193], v152 offset:33792
	ds_read_b128 v[198:201], v152 offset:34816
	ds_read_b128 v[202:205], v152 offset:35840
	ds_read_b128 v[206:209], v152 offset:36864
	ds_read_b128 v[210:213], v152 offset:37888
	ds_read_b128 v[214:217], v152 offset:38912
	ds_read_b128 v[218:221], v152 offset:39936
	global_load_lds_dwordx4 v134, s[44:45]
	s_mov_b32 m0, s56
	s_nop 0
	global_load_lds_dwordx4 v130, s[44:45]
	s_waitcnt vmcnt(8)
	s_waitcnt lgkmcnt(0)
	s_barrier
; #define PG8_STAGE(bufoff, gbase, voff) do { _Pragma("unroll") for (int _i = 0; _i < 2; ++_i) \
;         __builtin_amdgcn_global_load_lds((const unsigned*)((const char*)(gbase) + (voff)[_i]), (PG8_LAS unsigned*)(lds + (bufoff) + ldsw + _i * 8192), 16, 0, 0); } while (0)
; #define PG8_LDA(dst, b, h) do { _Pragma("unroll") for (int m = 0; m < 4; ++m) _Pragma("unroll") for (int k = 0; k < 2; ++k) dst[m][k] = *(const PG8_LAS bf16x8*)(lds + PG8_SA(b, h) + aoff + m * 2048 + k * 1024); } while (0)
; #define PG8_MMA(ai, bj, At, Bt) do { __builtin_amdgcn_s_setprio(1); _Pragma("unroll") for (int m = 0; m < 4; ++m) _Pragma("unroll") for (int n = 0; n < 2; ++n) _Pragma("unroll") for (int k = 0; k < 2; ++k) \
;         acc[ai][bj][m][n] = __builtin_amdgcn_mfma_f32_16x16x32_bf16(Bt[n][k], At[m][k], acc[ai][bj][m][n], 0, 0, 0); __builtin_amdgcn_s_setprio(0); } while (0)
; #define PG8_WAIT_V(n) asm volatile("s_waitcnt vmcnt(" #n ")" ::: "memory")
; #define PG8_WAIT_L(n) asm volatile("s_waitcnt lgkmcnt(" #n ")" ::: "memory")
; #define PG8_BAR __builtin_amdgcn_s_barrier()
; #define PG8_SCHED __builtin_amdgcn_sched_barrier(0)
; template <class Epi, class Sched, bool ALIGN_EPI = false, bool SP2 = false>
; __device__ __forceinline__ void gemm_phase(PG8_LAS unsigned char* lds, const Gemm g, const Sched& S, const Epi& E) {
;     ...
;             PG8_WAIT_V(8); PG8_WAIT_L(0); PG8_BAR; PG8_MMA(0, 0, At, B0); PG8_MMA(0, 1, At, B1); PG8_BAR; PG8_SCHED;
;             PG8_LDA(At, 1, 1); PG8_STAGE(PG8_SB(1, 0), b3, voffB); PG8_STAGE(PG8_SB(1, 1), b3 + hstep, voffB); PG8_STAGE(PG8_SA(1, 0), a3, voffA);
;             PG8_WAIT_V(8); PG8_WAIT_L(0); PG8_BAR; PG8_MMA(1, 0, At, B0); PG8_MMA(1, 1, At, B1); PG8_BAR; PG8_SCHED;
	s_waitcnt lgkmcnt(0)
	v_mfma_f32_16x16x32_bf16 v[124:127], v[154:157], v[186:189], v[124:127]
	v_mfma_f32_16x16x32_bf16 v[116:119], v[162:165], v[186:189], v[116:119]
	v_mfma_f32_16x16x32_bf16 v[108:111], v[154:157], v[198:201], v[108:111]
	v_mfma_f32_16x16x32_bf16 v[100:103], v[162:165], v[198:201], v[100:103]
	v_mfma_f32_16x16x32_bf16 v[92:95], v[154:157], v[206:209], v[92:95]
	v_mfma_f32_16x16x32_bf16 v[84:87], v[162:165], v[206:209], v[84:87]
	v_mfma_f32_16x16x32_bf16 v[76:79], v[154:157], v[214:217], v[76:79]
	v_mfma_f32_16x16x32_bf16 v[68:71], v[162:165], v[214:217], v[68:71]
	v_mfma_f32_16x16x32_bf16 v[124:127], v[158:161], v[190:193], v[124:127]
	v_mfma_f32_16x16x32_bf16 v[116:119], v[166:169], v[190:193], v[116:119]
	v_mfma_f32_16x16x32_bf16 v[108:111], v[158:161], v[202:205], v[108:111]
	v_mfma_f32_16x16x32_bf16 v[100:103], v[166:169], v[202:205], v[100:103]
	v_mfma_f32_16x16x32_bf16 v[92:95], v[158:161], v[210:213], v[92:95]
	v_mfma_f32_16x16x32_bf16 v[84:87], v[166:169], v[210:213], v[84:87]
	v_mfma_f32_16x16x32_bf16 v[76:79], v[158:161], v[218:221], v[76:79]
	v_mfma_f32_16x16x32_bf16 v[68:71], v[166:169], v[218:221], v[68:71]
	v_mfma_f32_16x16x32_bf16 v[120:123], v[170:173], v[186:189], v[120:123]
	v_mfma_f32_16x16x32_bf16 v[112:115], v[178:181], v[186:189], v[112:115]
	v_mfma_f32_16x16x32_bf16 v[104:107], v[170:173], v[198:201], v[104:107]
	v_mfma_f32_16x16x32_bf16 v[96:99], v[178:181], v[198:201], v[96:99]
	v_mfma_f32_16x16x32_bf16 v[88:91], v[170:173], v[206:209], v[88:91]
	v_mfma_f32_16x16x32_bf16 v[80:83], v[178:181], v[206:209], v[80:83]
	v_mfma_f32_16x16x32_bf16 v[72:75], v[170:173], v[214:217], v[72:75]
	v_mfma_f32_16x16x32_bf16 v[64:67], v[178:181], v[214:217], v[64:67]
	v_mfma_f32_16x16x32_bf16 v[120:123], v[174:177], v[190:193], v[120:123]
	v_mfma_f32_16x16x32_bf16 v[112:115], v[182:185], v[190:193], v[112:115]
	v_mfma_f32_16x16x32_bf16 v[104:107], v[174:177], v[202:205], v[104:107]
	v_mfma_f32_16x16x32_bf16 v[96:99], v[182:185], v[202:205], v[96:99]
	v_mfma_f32_16x16x32_bf16 v[88:91], v[174:177], v[210:213], v[88:91]
	v_mfma_f32_16x16x32_bf16 v[80:83], v[182:185], v[210:213], v[80:83]
	v_mfma_f32_16x16x32_bf16 v[72:75], v[174:177], v[218:221], v[72:75]
	v_mfma_f32_16x16x32_bf16 v[64:67], v[182:185], v[218:221], v[64:67]
	s_barrier
	s_add_i32 s44, s70, s52
	s_mov_b32 m0, s44
	ds_read_b128 v[186:189], v152 offset:49152
	ds_read_b128 v[190:193], v152 offset:50176
	ds_read_b128 v[198:201], v152 offset:51200
	ds_read_b128 v[202:205], v152 offset:52224
	ds_read_b128 v[206:209], v152 offset:53248
	ds_read_b128 v[210:213], v152 offset:54272
	ds_read_b128 v[214:217], v152 offset:55296
	ds_read_b128 v[218:221], v152 offset:56320
	global_load_lds_dwordx4 v132, s[98:99]
	s_add_i32 m0, s44, 0x2000
	s_add_u32 s38, s38, 0x40080
	s_addc_u32 s39, s39, 0
	s_add_i32 s44, s71, s52
	global_load_lds_dwordx4 v128, s[98:99]
	s_mov_b32 m0, s44
	s_nop 0
	global_load_lds_dwordx4 v132, s[38:39]
	s_add_i32 m0, s44, 0x2000
	s_nop 0
	global_load_lds_dwordx4 v128, s[38:39]
	s_mov_b32 m0, s58
	s_nop 0
	global_load_lds_dwordx4 v134, s[100:101]
	s_mov_b32 m0, s59
	s_nop 0
	global_load_lds_dwordx4 v130, s[100:101]
	s_waitcnt vmcnt(8)
	s_waitcnt lgkmcnt(0)
	s_barrier
	s_waitcnt lgkmcnt(0)
	v_mfma_f32_16x16x32_bf16 v[60:63], v[154:157], v[186:189], v[60:63]
	v_mfma_f32_16x16x32_bf16 v[52:55], v[162:165], v[186:189], v[52:55]
	v_mfma_f32_16x16x32_bf16 v[44:47], v[154:157], v[198:201], v[44:47]
	v_mfma_f32_16x16x32_bf16 v[36:39], v[162:165], v[198:201], v[36:39]
	v_mfma_f32_16x16x32_bf16 v[28:31], v[154:157], v[206:209], v[28:31]
	v_mfma_f32_16x16x32_bf16 v[20:23], v[162:165], v[206:209], v[20:23]
	v_mfma_f32_16x16x32_bf16 v[12:15], v[154:157], v[214:217], v[12:15]
	v_mfma_f32_16x16x32_bf16 v[4:7], v[162:165], v[214:217], v[4:7]
	v_mfma_f32_16x16x32_bf16 v[60:63], v[158:161], v[190:193], v[60:63]
	v_mfma_f32_16x16x32_bf16 v[52:55], v[166:169], v[190:193], v[52:55]
	v_mfma_f32_16x16x32_bf16 v[44:47], v[158:161], v[202:205], v[44:47]
	v_mfma_f32_16x16x32_bf16 v[36:39], v[166:169], v[202:205], v[36:39]
	v_mfma_f32_16x16x32_bf16 v[28:31], v[158:161], v[210:213], v[28:31]
	v_mfma_f32_16x16x32_bf16 v[20:23], v[166:169], v[210:213], v[20:23]
	v_mfma_f32_16x16x32_bf16 v[12:15], v[158:161], v[218:221], v[12:15]
	v_mfma_f32_16x16x32_bf16 v[4:7], v[166:169], v[218:221], v[4:7]
	v_mfma_f32_16x16x32_bf16 v[56:59], v[170:173], v[186:189], v[56:59]
	v_mfma_f32_16x16x32_bf16 v[48:51], v[178:181], v[186:189], v[48:51]
	v_mfma_f32_16x16x32_bf16 v[40:43], v[170:173], v[198:201], v[40:43]
	v_mfma_f32_16x16x32_bf16 v[32:35], v[178:181], v[198:201], v[32:35]
	v_mfma_f32_16x16x32_bf16 v[24:27], v[170:173], v[206:209], v[24:27]
	v_mfma_f32_16x16x32_bf16 v[16:19], v[178:181], v[206:209], v[16:19]
	v_mfma_f32_16x16x32_bf16 v[8:11], v[170:173], v[214:217], v[8:11]
	v_mfma_f32_16x16x32_bf16 v[0:3], v[178:181], v[214:217], v[0:3]
	v_mfma_f32_16x16x32_bf16 v[56:59], v[174:177], v[190:193], v[56:59]
	v_mfma_f32_16x16x32_bf16 v[48:51], v[182:185], v[190:193], v[48:51]
	v_mfma_f32_16x16x32_bf16 v[40:43], v[174:177], v[202:205], v[40:43]
	v_mfma_f32_16x16x32_bf16 v[32:35], v[182:185], v[202:205], v[32:35]
	v_mfma_f32_16x16x32_bf16 v[24:27], v[174:177], v[210:213], v[24:27]
	v_mfma_f32_16x16x32_bf16 v[16:19], v[182:185], v[210:213], v[16:19]
	v_mfma_f32_16x16x32_bf16 v[8:11], v[174:177], v[218:221], v[8:11]
	v_mfma_f32_16x16x32_bf16 v[0:3], v[182:185], v[218:221], v[0:3]
	s_barrier
	s_add_i32 s69, s69, 2
	s_add_u32 s20, s20, 0x100
	s_addc_u32 s21, s21, 0
	s_add_u32 s67, s67, 0x100
	s_addc_u32 s68, s68, 0
	s_cmp_gt_u32 s69, 13
	s_cbranch_scc0 .LBB0_810
	s_and_b64 vcc, exec, s[10:11]
	s_cbranch_vccz .LBB0_813
	s_barrier

; #define PG8_STAGE(bufoff, gbase, voff) do { _Pragma("unroll") for (int _i = 0; _i < 2; ++_i) \
;         __builtin_amdgcn_global_load_lds((const unsigned*)((const char*)(gbase) + (voff)[_i]), (PG8_LAS unsigned*)(lds + (bufoff) + ldsw + _i * 8192), 16, 0, 0); } while (0)
; #define PG8_LDA(dst, b, h) do { _Pragma("unroll") for (int m = 0; m < 4; ++m) _Pragma("unroll") for (int k = 0; k < 2; ++k) dst[m][k] = *(const PG8_LAS bf16x8*)(lds + PG8_SA(b, h) + aoff + m * 2048 + k * 1024); } while (0)
; #define PG8_LDB(dst, b, h) do { _Pragma("unroll") for (int n = 0; n < 2; ++n) _Pragma("unroll") for (int k = 0; k < 2; ++k) dst[n][k] = *(const PG8_LAS bf16x8*)(lds + PG8_SB(b, h) + boff + n * 2048 + k * 1024); } while (0)
; #define PG8_MMA(ai, bj, At, Bt) do { __builtin_amdgcn_s_setprio(1); _Pragma("unroll") for (int m = 0; m < 4; ++m) _Pragma("unroll") for (int n = 0; n < 2; ++n) _Pragma("unroll") for (int k = 0; k < 2; ++k) \
;         acc[ai][bj][m][n] = __builtin_amdgcn_mfma_f32_16x16x32_bf16(Bt[n][k], At[m][k], acc[ai][bj][m][n], 0, 0, 0); __builtin_amdgcn_s_setprio(0); } while (0)
; #define PG8_WAIT_V(n) asm volatile("s_waitcnt vmcnt(" #n ")" ::: "memory")
; #define PG8_BAR __builtin_amdgcn_s_barrier()
; template <class Epi, class Sched, bool ALIGN_EPI = false, bool SP2 = false>
; __device__ __forceinline__ void gemm_phase(PG8_LAS unsigned char* lds, const Gemm g, const Sched& S, const Epi& E) {
;     ...
;         for (int t = 0; t < nt; t += 2) {
;             const bool last = (t == nt - 2);
;             const char* a1 = cA + (size_t)(t + 1) * kstep;
;             const char* a2 = last ? nA : cA + (size_t)(t + 2) * kstep; const char* b2 = last ? nB : cB + (size_t)(t + 2) * kstep;
;             const char* a3 = a2 + kstep; const char* b3 = b2 + kstep;
;             if (last && has_next) S.a_ready(nxt);
;             if constexpr (SP2) {
;             PG8_LDB(B0, 0, 0); PG8_LDB(B1, 0, 1); PG8_SCHED; PG8_LDA(At, 0, 0); PG8_STAGE(PG8_SA(1, 1), a1 + hstep, voffA);
;             PG8_WAIT_V(8); PG8_WAIT_L(0); PG8_BAR; PG8_MMA(0, 0, At, B0); PG8_MMA(0, 1, At, B1); PG8_BAR; PG8_SCHED;
;             PG8_LDA(At, 0, 1); PG8_STAGE(PG8_SB(0, 0), b2, voffB); PG8_STAGE(PG8_SB(0, 1), b2 + hstep, voffB); PG8_STAGE(PG8_SA(0, 0), a2, voffA);
;             PG8_WAIT_V(8); PG8_WAIT_L(0); PG8_BAR; PG8_MMA(1, 0, At, B0); PG8_MMA(1, 1, At, B1); PG8_BAR; PG8_SCHED;
.LBB0_894:
	s_add_u32 s20, s20, 0xb0080
	s_addc_u32 s21, s21, 0
	s_add_u32 s70, s34, 0x100
	s_addc_u32 s71, s35, 0
	s_mov_b32 s72, -2
	s_waitcnt lgkmcnt(0)
	ds_read_b128 v[96:99], v223
	ds_read_b128 v[108:111], v223 offset:1024
	ds_read_b128 v[120:123], v223 offset:2048
	ds_read_b128 v[128:131], v223 offset:3072
	ds_read_b128 v[144:147], v224
	ds_read_b128 v[148:151], v224 offset:1024
	ds_read_b128 v[152:155], v224 offset:2048
	ds_read_b128 v[156:159], v224 offset:3072
	s_add_u32 s34, s20, 0xfff50080
	s_addc_u32 s35, s21, -1
	s_cmp_eq_u32 s72, 40
	s_cselect_b32 s49, s1, s35
	s_cselect_b32 s48, s0, s34
	s_cselect_b32 s35, s47, s71
	s_cselect_b32 s34, s46, s70
	s_add_i32 m0, s51, 0xc000
	ds_read_b128 v[160:163], v225
	ds_read_b128 v[164:167], v225 offset:1024
	ds_read_b128 v[168:171], v225 offset:2048
	ds_read_b128 v[172:175], v225 offset:3072
	ds_read_b128 v[176:179], v225 offset:4096
	ds_read_b128 v[180:183], v225 offset:5120
	ds_read_b128 v[202:205], v225 offset:6144
	ds_read_b128 v[206:209], v225 offset:7168
	global_load_lds_dwordx4 v192, s[20:21]
	s_add_i32 m0, s51, 0xe000
	s_nop 0
	global_load_lds_dwordx4 v194, s[20:21]
	s_waitcnt vmcnt(8)
	s_waitcnt lgkmcnt(0)
	s_barrier
	s_waitcnt lgkmcnt(0)
	v_mfma_f32_16x16x32_bf16 v[140:143], v[96:99], v[160:163], 0
	v_mfma_f32_16x16x32_bf16 v[136:139], v[120:123], v[160:163], 0
	v_mfma_f32_16x16x32_bf16 v[116:119], v[96:99], v[168:171], 0
	v_mfma_f32_16x16x32_bf16 v[112:115], v[120:123], v[168:171], 0
	v_mfma_f32_16x16x32_bf16 v[92:95], v[96:99], v[176:179], 0
	v_mfma_f32_16x16x32_bf16 v[88:91], v[120:123], v[176:179], 0
	v_mfma_f32_16x16x32_bf16 v[76:79], v[96:99], v[202:205], 0
	v_mfma_f32_16x16x32_bf16 v[72:75], v[120:123], v[202:205], 0
	v_mfma_f32_16x16x32_bf16 v[140:143], v[108:111], v[164:167], v[140:143]
	v_mfma_f32_16x16x32_bf16 v[136:139], v[128:131], v[164:167], v[136:139]
	v_mfma_f32_16x16x32_bf16 v[116:119], v[108:111], v[172:175], v[116:119]
	v_mfma_f32_16x16x32_bf16 v[112:115], v[128:131], v[172:175], v[112:115]
	v_mfma_f32_16x16x32_bf16 v[92:95], v[108:111], v[180:183], v[92:95]
	v_mfma_f32_16x16x32_bf16 v[88:91], v[128:131], v[180:183], v[88:91]
	v_mfma_f32_16x16x32_bf16 v[76:79], v[108:111], v[206:209], v[76:79]
	v_mfma_f32_16x16x32_bf16 v[72:75], v[128:131], v[206:209], v[72:75]
	v_mfma_f32_16x16x32_bf16 v[132:135], v[144:147], v[160:163], 0
	v_mfma_f32_16x16x32_bf16 v[124:127], v[152:155], v[160:163], 0
	v_mfma_f32_16x16x32_bf16 v[104:107], v[144:147], v[168:171], 0
	v_mfma_f32_16x16x32_bf16 v[100:103], v[152:155], v[168:171], 0
	v_mfma_f32_16x16x32_bf16 v[84:87], v[144:147], v[176:179], 0
	v_mfma_f32_16x16x32_bf16 v[80:83], v[152:155], v[176:179], 0
	v_mfma_f32_16x16x32_bf16 v[68:71], v[144:147], v[202:205], 0
	v_mfma_f32_16x16x32_bf16 v[64:67], v[152:155], v[202:205], 0
	v_mfma_f32_16x16x32_bf16 v[132:135], v[148:151], v[164:167], v[132:135]
	v_mfma_f32_16x16x32_bf16 v[124:127], v[156:159], v[164:167], v[124:127]
	v_mfma_f32_16x16x32_bf16 v[104:107], v[148:151], v[172:175], v[104:107]
	v_mfma_f32_16x16x32_bf16 v[100:103], v[156:159], v[172:175], v[100:103]
	v_mfma_f32_16x16x32_bf16 v[84:87], v[148:151], v[180:183], v[84:87]
	v_mfma_f32_16x16x32_bf16 v[80:83], v[156:159], v[180:183], v[80:83]
	v_mfma_f32_16x16x32_bf16 v[68:71], v[148:151], v[206:209], v[68:71]
	v_mfma_f32_16x16x32_bf16 v[64:67], v[156:159], v[206:209], v[64:67]
	s_barrier
	s_add_i32 s73, s64, s50
	s_add_u32 s98, s34, s12
	s_addc_u32 s99, s35, s13
	s_add_u32 s100, s48, s12
	s_addc_u32 s101, s49, s13
	s_mov_b32 m0, s73
	ds_read_b128 v[160:163], v225 offset:16384
	ds_read_b128 v[164:167], v225 offset:17408
	ds_read_b128 v[168:171], v225 offset:18432
	ds_read_b128 v[172:175], v225 offset:19456
	ds_read_b128 v[176:179], v225 offset:20480
	ds_read_b128 v[180:183], v225 offset:21504
	ds_read_b128 v[202:205], v225 offset:22528
	ds_read_b128 v[206:209], v225 offset:23552
	global_load_lds_dwordx4 v186, s[34:35]
	s_add_i32 m0, s73, 0x2000
	s_add_u32 s74, s34, 0xb0000
	s_addc_u32 s75, s35, 0
	s_add_i32 s73, s65, s50
	global_load_lds_dwordx4 v190, s[34:35]
	s_mov_b32 m0, s73
	s_nop 0
	global_load_lds_dwordx4 v186, s[74:75]
	s_add_i32 m0, s73, 0x2000
	s_nop 0
	global_load_lds_dwordx4 v190, s[74:75]
	s_mov_b32 m0, s51
	s_nop 0
	global_load_lds_dwordx4 v184, s[48:49]
	s_mov_b32 m0, s52
	s_nop 0
	global_load_lds_dwordx4 v188, s[48:49]
	s_waitcnt vmcnt(8)
	s_waitcnt lgkmcnt(0)
	s_barrier
	s_waitcnt lgkmcnt(0)
	v_mfma_f32_16x16x32_bf16 v[60:63], v[96:99], v[160:163], 0
	v_mfma_f32_16x16x32_bf16 v[56:59], v[120:123], v[160:163], 0
	v_mfma_f32_16x16x32_bf16 v[44:47], v[96:99], v[168:171], 0
	v_mfma_f32_16x16x32_bf16 v[40:43], v[120:123], v[168:171], 0
	v_mfma_f32_16x16x32_bf16 v[28:31], v[96:99], v[176:179], 0
	v_mfma_f32_16x16x32_bf16 v[24:27], v[120:123], v[176:179], 0
	v_mfma_f32_16x16x32_bf16 v[12:15], v[96:99], v[202:205], 0
	v_mfma_f32_16x16x32_bf16 v[8:11], v[120:123], v[202:205], 0
	v_mfma_f32_16x16x32_bf16 v[60:63], v[108:111], v[164:167], v[60:63]
	v_mfma_f32_16x16x32_bf16 v[56:59], v[128:131], v[164:167], v[56:59]
	v_mfma_f32_16x16x32_bf16 v[44:47], v[108:111], v[172:175], v[44:47]
	v_mfma_f32_16x16x32_bf16 v[40:43], v[128:131], v[172:175], v[40:43]
	v_mfma_f32_16x16x32_bf16 v[28:31], v[108:111], v[180:183], v[28:31]
	v_mfma_f32_16x16x32_bf16 v[24:27], v[128:131], v[180:183], v[24:27]
	v_mfma_f32_16x16x32_bf16 v[12:15], v[108:111], v[206:209], v[12:15]
	v_mfma_f32_16x16x32_bf16 v[8:11], v[128:131], v[206:209], v[8:11]
	v_mfma_f32_16x16x32_bf16 v[52:55], v[144:147], v[160:163], 0
	v_mfma_f32_16x16x32_bf16 v[48:51], v[152:155], v[160:163], 0
	v_mfma_f32_16x16x32_bf16 v[36:39], v[144:147], v[168:171], 0
	v_mfma_f32_16x16x32_bf16 v[32:35], v[152:155], v[168:171], 0
	v_mfma_f32_16x16x32_bf16 v[20:23], v[144:147], v[176:179], 0
	v_mfma_f32_16x16x32_bf16 v[16:19], v[152:155], v[176:179], 0
	v_mfma_f32_16x16x32_bf16 v[4:7], v[144:147], v[202:205], 0
	v_mfma_f32_16x16x32_bf16 v[0:3], v[152:155], v[202:205], 0
	v_mfma_f32_16x16x32_bf16 v[52:55], v[148:151], v[164:167], v[52:55]
	v_mfma_f32_16x16x32_bf16 v[48:51], v[156:159], v[164:167], v[48:51]
	v_mfma_f32_16x16x32_bf16 v[36:39], v[148:151], v[172:175], v[36:39]
	v_mfma_f32_16x16x32_bf16 v[32:35], v[156:159], v[172:175], v[32:35]
	v_mfma_f32_16x16x32_bf16 v[20:23], v[148:151], v[180:183], v[20:23]
	v_mfma_f32_16x16x32_bf16 v[16:19], v[156:159], v[180:183], v[16:19]
	v_mfma_f32_16x16x32_bf16 v[4:7], v[148:151], v[206:209], v[4:7]
	v_mfma_f32_16x16x32_bf16 v[0:3], v[156:159], v[206:209], v[0:3]
	s_barrier
; #define PG8_STAGE(bufoff, gbase, voff) do { _Pragma("unroll") for (int _i = 0; _i < 2; ++_i) \
;         __builtin_amdgcn_global_load_lds((const unsigned*)((const char*)(gbase) + (voff)[_i]), (PG8_LAS unsigned*)(lds + (bufoff) + ldsw + _i * 8192), 16, 0, 0); } while (0)
; #define PG8_LDA(dst, b, h) do { _Pragma("unroll") for (int m = 0; m < 4; ++m) _Pragma("unroll") for (int k = 0; k < 2; ++k) dst[m][k] = *(const PG8_LAS bf16x8*)(lds + PG8_SA(b, h) + aoff + m * 2048 + k * 1024); } while (0)
; #define PG8_LDB(dst, b, h) do { _Pragma("unroll") for (int n = 0; n < 2; ++n) _Pragma("unroll") for (int k = 0; k < 2; ++k) dst[n][k] = *(const PG8_LAS bf16x8*)(lds + PG8_SB(b, h) + boff + n * 2048 + k * 1024); } while (0)
; #define PG8_MMA(ai, bj, At, Bt) do { __builtin_amdgcn_s_setprio(1); _Pragma("unroll") for (int m = 0; m < 4; ++m) _Pragma("unroll") for (int n = 0; n < 2; ++n) _Pragma("unroll") for (int k = 0; k < 2; ++k) \
;         acc[ai][bj][m][n] = __builtin_amdgcn_mfma_f32_16x16x32_bf16(Bt[n][k], At[m][k], acc[ai][bj][m][n], 0, 0, 0); __builtin_amdgcn_s_setprio(0); } while (0)
; #define PG8_WAIT_V(n) asm volatile("s_waitcnt vmcnt(" #n ")" ::: "memory")
; #define PG8_WAIT_L(n) asm volatile("s_waitcnt lgkmcnt(" #n ")" ::: "memory")
; #define PG8_BAR __builtin_amdgcn_s_barrier()
; #define PG8_SCHED __builtin_amdgcn_sched_barrier(0)
; template <class Epi, class Sched, bool ALIGN_EPI = false, bool SP2 = false>
; __device__ __forceinline__ void gemm_phase(PG8_LAS unsigned char* lds, const Gemm g, const Sched& S, const Epi& E) {
;     ...
;             PG8_LDB(B0, 1, 0); PG8_LDB(B1, 1, 1); PG8_SCHED; PG8_LDA(At, 1, 0); PG8_STAGE(PG8_SA(0, 1), a2 + hstep, voffA);
;             PG8_WAIT_V(8); PG8_WAIT_L(0); PG8_BAR; PG8_MMA(0, 0, At, B0); PG8_MMA(0, 1, At, B1); PG8_BAR; PG8_SCHED;
;             PG8_LDA(At, 1, 1); PG8_STAGE(PG8_SB(1, 0), b3, voffB); PG8_STAGE(PG8_SB(1, 1), b3 + hstep, voffB); PG8_STAGE(PG8_SA(1, 0), a3, voffA);
;             PG8_WAIT_V(8); PG8_WAIT_L(0); PG8_BAR; PG8_MMA(1, 0, At, B0); PG8_MMA(1, 1, At, B1); PG8_BAR; PG8_SCHED;
	s_add_i32 s73, 0, 0x18000
	s_add_i32 s74, 0, 0x1c000
	v_add_u32_e32 v128, s73, v221
	v_add_u32_e32 v156, s74, v221
	ds_read_b128 v[96:99], v128
	ds_read_b128 v[108:111], v128 offset:1024
	ds_read_b128 v[120:123], v128 offset:2048
	ds_read_b128 v[128:131], v128 offset:3072
	ds_read_b128 v[144:147], v156
	ds_read_b128 v[148:151], v156 offset:1024
	ds_read_b128 v[152:155], v156 offset:2048
	ds_read_b128 v[156:159], v156 offset:3072
	s_add_u32 s48, s48, 0xb0000
	s_addc_u32 s49, s49, 0
	s_mov_b32 m0, s53
	ds_read_b128 v[160:163], v225 offset:32768
	ds_read_b128 v[164:167], v225 offset:33792
	ds_read_b128 v[168:171], v225 offset:34816
	ds_read_b128 v[172:175], v225 offset:35840
	ds_read_b128 v[176:179], v225 offset:36864
	ds_read_b128 v[180:183], v225 offset:37888
	ds_read_b128 v[202:205], v225 offset:38912
	ds_read_b128 v[206:209], v225 offset:39936
	global_load_lds_dwordx4 v184, s[48:49]
	s_mov_b32 m0, s54
	s_nop 0
	global_load_lds_dwordx4 v188, s[48:49]
	s_waitcnt vmcnt(8)
	s_waitcnt lgkmcnt(0)
	s_barrier
	s_waitcnt lgkmcnt(0)
	v_mfma_f32_16x16x32_bf16 v[140:143], v[96:99], v[160:163], v[140:143]
	v_mfma_f32_16x16x32_bf16 v[136:139], v[120:123], v[160:163], v[136:139]
	v_mfma_f32_16x16x32_bf16 v[116:119], v[96:99], v[168:171], v[116:119]
	v_mfma_f32_16x16x32_bf16 v[112:115], v[120:123], v[168:171], v[112:115]
	v_mfma_f32_16x16x32_bf16 v[92:95], v[96:99], v[176:179], v[92:95]
	v_mfma_f32_16x16x32_bf16 v[88:91], v[120:123], v[176:179], v[88:91]
	v_mfma_f32_16x16x32_bf16 v[76:79], v[96:99], v[202:205], v[76:79]
	v_mfma_f32_16x16x32_bf16 v[72:75], v[120:123], v[202:205], v[72:75]
	v_mfma_f32_16x16x32_bf16 v[140:143], v[108:111], v[164:167], v[140:143]
	v_mfma_f32_16x16x32_bf16 v[136:139], v[128:131], v[164:167], v[136:139]
	v_mfma_f32_16x16x32_bf16 v[116:119], v[108:111], v[172:175], v[116:119]
	v_mfma_f32_16x16x32_bf16 v[112:115], v[128:131], v[172:175], v[112:115]
	v_mfma_f32_16x16x32_bf16 v[92:95], v[108:111], v[180:183], v[92:95]
	v_mfma_f32_16x16x32_bf16 v[88:91], v[128:131], v[180:183], v[88:91]
	v_mfma_f32_16x16x32_bf16 v[76:79], v[108:111], v[206:209], v[76:79]
	v_mfma_f32_16x16x32_bf16 v[72:75], v[128:131], v[206:209], v[72:75]
	v_mfma_f32_16x16x32_bf16 v[132:135], v[144:147], v[160:163], v[132:135]
	v_mfma_f32_16x16x32_bf16 v[124:127], v[152:155], v[160:163], v[124:127]
	v_mfma_f32_16x16x32_bf16 v[104:107], v[144:147], v[168:171], v[104:107]
	v_mfma_f32_16x16x32_bf16 v[100:103], v[152:155], v[168:171], v[100:103]
	v_mfma_f32_16x16x32_bf16 v[84:87], v[144:147], v[176:179], v[84:87]
	v_mfma_f32_16x16x32_bf16 v[80:83], v[152:155], v[176:179], v[80:83]
	v_mfma_f32_16x16x32_bf16 v[68:71], v[144:147], v[202:205], v[68:71]
	v_mfma_f32_16x16x32_bf16 v[64:67], v[152:155], v[202:205], v[64:67]
	v_mfma_f32_16x16x32_bf16 v[132:135], v[148:151], v[164:167], v[132:135]
	v_mfma_f32_16x16x32_bf16 v[124:127], v[156:159], v[164:167], v[124:127]
	v_mfma_f32_16x16x32_bf16 v[104:107], v[148:151], v[172:175], v[104:107]
	v_mfma_f32_16x16x32_bf16 v[100:103], v[156:159], v[172:175], v[100:103]
	v_mfma_f32_16x16x32_bf16 v[84:87], v[148:151], v[180:183], v[84:87]
	v_mfma_f32_16x16x32_bf16 v[80:83], v[156:159], v[180:183], v[80:83]
	v_mfma_f32_16x16x32_bf16 v[68:71], v[148:151], v[206:209], v[68:71]
	v_mfma_f32_16x16x32_bf16 v[64:67], v[156:159], v[206:209], v[64:67]
	s_barrier
	s_add_i32 s48, s73, s50
	s_mov_b32 m0, s48
	ds_read_b128 v[160:163], v225 offset:49152
	ds_read_b128 v[164:167], v225 offset:50176
	ds_read_b128 v[168:171], v225 offset:51200
	ds_read_b128 v[172:175], v225 offset:52224
	ds_read_b128 v[176:179], v225 offset:53248
	ds_read_b128 v[180:183], v225 offset:54272
	ds_read_b128 v[202:205], v225 offset:55296
	ds_read_b128 v[206:209], v225 offset:56320
	global_load_lds_dwordx4 v186, s[98:99]
	s_add_i32 m0, s48, 0x2000
	s_add_u32 s34, s34, 0xb0080
	s_addc_u32 s35, s35, 0
	s_add_i32 s48, s74, s50
	global_load_lds_dwordx4 v190, s[98:99]
	s_mov_b32 m0, s48
	s_nop 0
	global_load_lds_dwordx4 v186, s[34:35]
	s_add_i32 m0, s48, 0x2000
	s_nop 0
	global_load_lds_dwordx4 v190, s[34:35]
	s_mov_b32 m0, s59
	s_nop 0
	global_load_lds_dwordx4 v184, s[100:101]
	s_mov_b32 m0, s60
	s_nop 0
	global_load_lds_dwordx4 v188, s[100:101]
	s_waitcnt vmcnt(8)
	s_waitcnt lgkmcnt(0)
	s_barrier
	s_waitcnt lgkmcnt(0)
	v_mfma_f32_16x16x32_bf16 v[60:63], v[96:99], v[160:163], v[60:63]
	v_mfma_f32_16x16x32_bf16 v[56:59], v[120:123], v[160:163], v[56:59]
	v_mfma_f32_16x16x32_bf16 v[44:47], v[96:99], v[168:171], v[44:47]
	v_mfma_f32_16x16x32_bf16 v[40:43], v[120:123], v[168:171], v[40:43]
	v_mfma_f32_16x16x32_bf16 v[28:31], v[96:99], v[176:179], v[28:31]
	v_mfma_f32_16x16x32_bf16 v[24:27], v[120:123], v[176:179], v[24:27]
	v_mfma_f32_16x16x32_bf16 v[12:15], v[96:99], v[202:205], v[12:15]
	v_mfma_f32_16x16x32_bf16 v[8:11], v[120:123], v[202:205], v[8:11]
	v_mfma_f32_16x16x32_bf16 v[60:63], v[108:111], v[164:167], v[60:63]
	v_mfma_f32_16x16x32_bf16 v[56:59], v[128:131], v[164:167], v[56:59]
	v_mfma_f32_16x16x32_bf16 v[44:47], v[108:111], v[172:175], v[44:47]
	v_mfma_f32_16x16x32_bf16 v[40:43], v[128:131], v[172:175], v[40:43]
	v_mfma_f32_16x16x32_bf16 v[28:31], v[108:111], v[180:183], v[28:31]
	v_mfma_f32_16x16x32_bf16 v[24:27], v[128:131], v[180:183], v[24:27]
	v_mfma_f32_16x16x32_bf16 v[12:15], v[108:111], v[206:209], v[12:15]
	v_mfma_f32_16x16x32_bf16 v[8:11], v[128:131], v[206:209], v[8:11]
	v_mfma_f32_16x16x32_bf16 v[52:55], v[144:147], v[160:163], v[52:55]
	v_mfma_f32_16x16x32_bf16 v[48:51], v[152:155], v[160:163], v[48:51]
	v_mfma_f32_16x16x32_bf16 v[36:39], v[144:147], v[168:171], v[36:39]
	v_mfma_f32_16x16x32_bf16 v[32:35], v[152:155], v[168:171], v[32:35]
	v_mfma_f32_16x16x32_bf16 v[20:23], v[144:147], v[176:179], v[20:23]
	v_mfma_f32_16x16x32_bf16 v[16:19], v[152:155], v[176:179], v[16:19]
	v_mfma_f32_16x16x32_bf16 v[4:7], v[144:147], v[202:205], v[4:7]
	v_mfma_f32_16x16x32_bf16 v[0:3], v[152:155], v[202:205], v[0:3]
	v_mfma_f32_16x16x32_bf16 v[52:55], v[148:151], v[164:167], v[52:55]
	v_mfma_f32_16x16x32_bf16 v[48:51], v[156:159], v[164:167], v[48:51]
	v_mfma_f32_16x16x32_bf16 v[36:39], v[148:151], v[172:175], v[36:39]
	v_mfma_f32_16x16x32_bf16 v[32:35], v[156:159], v[172:175], v[32:35]
	v_mfma_f32_16x16x32_bf16 v[20:23], v[148:151], v[180:183], v[20:23]
	v_mfma_f32_16x16x32_bf16 v[16:19], v[156:159], v[180:183], v[16:19]
	v_mfma_f32_16x16x32_bf16 v[4:7], v[148:151], v[206:209], v[4:7]
	v_mfma_f32_16x16x32_bf16 v[0:3], v[156:159], v[206:209], v[0:3]
	s_barrier
	s_add_i32 s72, s72, 2
	s_add_u32 s20, s20, 0x100
	s_addc_u32 s21, s21, 0
	s_add_u32 s70, s70, 0x100
	s_addc_u32 s71, s71, 0
	s_cmp_gt_u32 s72, 41
; #define PG8_STAGE(bufoff, gbase, voff) do { _Pragma("unroll") for (int _i = 0; _i < 2; ++_i) \
;         __builtin_amdgcn_global_load_lds((const unsigned*)((const char*)(gbase) + (voff)[_i]), (PG8_LAS unsigned*)(lds + (bufoff) + ldsw + _i * 8192), 16, 0, 0); } while (0)
; #define PG8_LDA(dst, b, h) do { _Pragma("unroll") for (int m = 0; m < 4; ++m) _Pragma("unroll") for (int k = 0; k < 2; ++k) dst[m][k] = *(const PG8_LAS bf16x8*)(lds + PG8_SA(b, h) + aoff + m * 2048 + k * 1024); } while (0)
; #define PG8_LDB(dst, b, h) do { _Pragma("unroll") for (int n = 0; n < 2; ++n) _Pragma("unroll") for (int k = 0; k < 2; ++k) dst[n][k] = *(const PG8_LAS bf16x8*)(lds + PG8_SB(b, h) + boff + n * 2048 + k * 1024); } while (0)
; #define PG8_MMA(ai, bj, At, Bt) do { __builtin_amdgcn_s_setprio(1); _Pragma("unroll") for (int m = 0; m < 4; ++m) _Pragma("unroll") for (int n = 0; n < 2; ++n) _Pragma("unroll") for (int k = 0; k < 2; ++k) \
;         acc[ai][bj][m][n] = __builtin_amdgcn_mfma_f32_16x16x32_bf16(Bt[n][k], At[m][k], acc[ai][bj][m][n], 0, 0, 0); __builtin_amdgcn_s_setprio(0); } while (0)
; #define PG8_WAIT_V(n) asm volatile("s_waitcnt vmcnt(" #n ")" ::: "memory")
; #define PG8_WAIT_L(n) asm volatile("s_waitcnt lgkmcnt(" #n ")" ::: "memory")
; #define PG8_BAR __builtin_amdgcn_s_barrier()
; #define PG8_SCHED __builtin_amdgcn_sched_barrier(0)
; template <class Epi, class Sched, bool ALIGN_EPI = false, bool SP2 = false>
; __device__ __forceinline__ void gemm_phase(PG8_LAS unsigned char* lds, const Gemm g, const Sched& S, const Epi& E) {
;     ...
;             PG8_LDB(B0, 0, 0); PG8_LDB(B1, 0, 1); PG8_SCHED; PG8_LDA(At, 0, 0); PG8_STAGE(PG8_SA(1, 1), a1 + hstep, voffA);
;             PG8_WAIT_V(8); PG8_WAIT_L(0); PG8_BAR; PG8_MMA(0, 0, At, B0); PG8_MMA(0, 1, At, B1); PG8_BAR; PG8_SCHED;
;             PG8_LDA(At, 0, 1); PG8_STAGE(PG8_SB(0, 0), b2, voffB); PG8_STAGE(PG8_SB(0, 1), b2 + hstep, voffB); PG8_STAGE(PG8_SA(0, 0), a2, voffA);
;             PG8_WAIT_V(8); PG8_WAIT_L(0); PG8_BAR; PG8_MMA(1, 0, At, B0); PG8_MMA(1, 1, At, B1); PG8_BAR; PG8_SCHED;
.LBB0_895:
	ds_read_b128 v[96:99], v223
	ds_read_b128 v[108:111], v223 offset:1024
	ds_read_b128 v[120:123], v223 offset:2048
	ds_read_b128 v[128:131], v223 offset:3072
	ds_read_b128 v[144:147], v224
	ds_read_b128 v[148:151], v224 offset:1024
	ds_read_b128 v[152:155], v224 offset:2048
	ds_read_b128 v[156:159], v224 offset:3072
	s_add_u32 s34, s20, 0xfff50080
	s_addc_u32 s35, s21, -1
	s_cmp_eq_u32 s72, 40
	s_cselect_b32 s49, s1, s35
	s_cselect_b32 s48, s0, s34
	s_cselect_b32 s35, s47, s71
	s_cselect_b32 s34, s46, s70
	s_add_i32 m0, s51, 0xc000
	ds_read_b128 v[160:163], v225
	ds_read_b128 v[164:167], v225 offset:1024
	ds_read_b128 v[168:171], v225 offset:2048
	ds_read_b128 v[172:175], v225 offset:3072
	ds_read_b128 v[176:179], v225 offset:4096
	ds_read_b128 v[180:183], v225 offset:5120
	ds_read_b128 v[202:205], v225 offset:6144
	ds_read_b128 v[206:209], v225 offset:7168
	global_load_lds_dwordx4 v192, s[20:21]
	s_add_i32 m0, s51, 0xe000
	s_nop 0
	global_load_lds_dwordx4 v194, s[20:21]
	s_waitcnt vmcnt(8)
	s_waitcnt lgkmcnt(0)
	s_barrier
	s_waitcnt lgkmcnt(0)
	v_mfma_f32_16x16x32_bf16 v[140:143], v[96:99], v[160:163], v[140:143]
	v_mfma_f32_16x16x32_bf16 v[136:139], v[120:123], v[160:163], v[136:139]
	v_mfma_f32_16x16x32_bf16 v[116:119], v[96:99], v[168:171], v[116:119]
	v_mfma_f32_16x16x32_bf16 v[112:115], v[120:123], v[168:171], v[112:115]
	v_mfma_f32_16x16x32_bf16 v[92:95], v[96:99], v[176:179], v[92:95]
	v_mfma_f32_16x16x32_bf16 v[88:91], v[120:123], v[176:179], v[88:91]
	v_mfma_f32_16x16x32_bf16 v[76:79], v[96:99], v[202:205], v[76:79]
	v_mfma_f32_16x16x32_bf16 v[72:75], v[120:123], v[202:205], v[72:75]
	v_mfma_f32_16x16x32_bf16 v[140:143], v[108:111], v[164:167], v[140:143]
	v_mfma_f32_16x16x32_bf16 v[136:139], v[128:131], v[164:167], v[136:139]
	v_mfma_f32_16x16x32_bf16 v[116:119], v[108:111], v[172:175], v[116:119]
	v_mfma_f32_16x16x32_bf16 v[112:115], v[128:131], v[172:175], v[112:115]
	v_mfma_f32_16x16x32_bf16 v[92:95], v[108:111], v[180:183], v[92:95]
	v_mfma_f32_16x16x32_bf16 v[88:91], v[128:131], v[180:183], v[88:91]
	v_mfma_f32_16x16x32_bf16 v[76:79], v[108:111], v[206:209], v[76:79]
	v_mfma_f32_16x16x32_bf16 v[72:75], v[128:131], v[206:209], v[72:75]
	v_mfma_f32_16x16x32_bf16 v[132:135], v[144:147], v[160:163], v[132:135]
	v_mfma_f32_16x16x32_bf16 v[124:127], v[152:155], v[160:163], v[124:127]
	v_mfma_f32_16x16x32_bf16 v[104:107], v[144:147], v[168:171], v[104:107]
	v_mfma_f32_16x16x32_bf16 v[100:103], v[152:155], v[168:171], v[100:103]
	v_mfma_f32_16x16x32_bf16 v[84:87], v[144:147], v[176:179], v[84:87]
	v_mfma_f32_16x16x32_bf16 v[80:83], v[152:155], v[176:179], v[80:83]
	v_mfma_f32_16x16x32_bf16 v[68:71], v[144:147], v[202:205], v[68:71]
	v_mfma_f32_16x16x32_bf16 v[64:67], v[152:155], v[202:205], v[64:67]
	v_mfma_f32_16x16x32_bf16 v[132:135], v[148:151], v[164:167], v[132:135]
	v_mfma_f32_16x16x32_bf16 v[124:127], v[156:159], v[164:167], v[124:127]
	v_mfma_f32_16x16x32_bf16 v[104:107], v[148:151], v[172:175], v[104:107]
	v_mfma_f32_16x16x32_bf16 v[100:103], v[156:159], v[172:175], v[100:103]
	v_mfma_f32_16x16x32_bf16 v[84:87], v[148:151], v[180:183], v[84:87]
	v_mfma_f32_16x16x32_bf16 v[80:83], v[156:159], v[180:183], v[80:83]
	v_mfma_f32_16x16x32_bf16 v[68:71], v[148:151], v[206:209], v[68:71]
	v_mfma_f32_16x16x32_bf16 v[64:67], v[156:159], v[206:209], v[64:67]
	s_barrier
	s_add_i32 s73, s64, s50
	s_add_u32 s98, s34, s12
	s_addc_u32 s99, s35, s13
	s_add_u32 s100, s48, s12
	s_addc_u32 s101, s49, s13
	s_mov_b32 m0, s73
	ds_read_b128 v[160:163], v225 offset:16384
	ds_read_b128 v[164:167], v225 offset:17408
	ds_read_b128 v[168:171], v225 offset:18432
	ds_read_b128 v[172:175], v225 offset:19456
	ds_read_b128 v[176:179], v225 offset:20480
	ds_read_b128 v[180:183], v225 offset:21504
	ds_read_b128 v[202:205], v225 offset:22528
	ds_read_b128 v[206:209], v225 offset:23552
	global_load_lds_dwordx4 v186, s[34:35]
	s_add_i32 m0, s73, 0x2000
	s_add_u32 s74, s34, 0xb0000
	s_addc_u32 s75, s35, 0
	s_add_i32 s73, s65, s50
	global_load_lds_dwordx4 v190, s[34:35]
	s_mov_b32 m0, s73
	s_nop 0
	global_load_lds_dwordx4 v186, s[74:75]
	s_add_i32 m0, s73, 0x2000
	s_nop 0
	global_load_lds_dwordx4 v190, s[74:75]
	s_mov_b32 m0, s51
	s_nop 0
	global_load_lds_dwordx4 v184, s[48:49]
	s_mov_b32 m0, s52
	s_nop 0
	global_load_lds_dwordx4 v188, s[48:49]
	s_waitcnt vmcnt(8)
	s_waitcnt lgkmcnt(0)
	s_barrier
	s_waitcnt lgkmcnt(0)
	v_mfma_f32_16x16x32_bf16 v[60:63], v[96:99], v[160:163], v[60:63]
	v_mfma_f32_16x16x32_bf16 v[56:59], v[120:123], v[160:163], v[56:59]
	v_mfma_f32_16x16x32_bf16 v[44:47], v[96:99], v[168:171], v[44:47]
	v_mfma_f32_16x16x32_bf16 v[40:43], v[120:123], v[168:171], v[40:43]
	v_mfma_f32_16x16x32_bf16 v[28:31], v[96:99], v[176:179], v[28:31]
	v_mfma_f32_16x16x32_bf16 v[24:27], v[120:123], v[176:179], v[24:27]
	v_mfma_f32_16x16x32_bf16 v[12:15], v[96:99], v[202:205], v[12:15]
	v_mfma_f32_16x16x32_bf16 v[8:11], v[120:123], v[202:205], v[8:11]
	v_mfma_f32_16x16x32_bf16 v[60:63], v[108:111], v[164:167], v[60:63]
	v_mfma_f32_16x16x32_bf16 v[56:59], v[128:131], v[164:167], v[56:59]
	v_mfma_f32_16x16x32_bf16 v[44:47], v[108:111], v[172:175], v[44:47]
	v_mfma_f32_16x16x32_bf16 v[40:43], v[128:131], v[172:175], v[40:43]
	v_mfma_f32_16x16x32_bf16 v[28:31], v[108:111], v[180:183], v[28:31]
	v_mfma_f32_16x16x32_bf16 v[24:27], v[128:131], v[180:183], v[24:27]
	v_mfma_f32_16x16x32_bf16 v[12:15], v[108:111], v[206:209], v[12:15]
	v_mfma_f32_16x16x32_bf16 v[8:11], v[128:131], v[206:209], v[8:11]
	v_mfma_f32_16x16x32_bf16 v[52:55], v[144:147], v[160:163], v[52:55]
	v_mfma_f32_16x16x32_bf16 v[48:51], v[152:155], v[160:163], v[48:51]
	v_mfma_f32_16x16x32_bf16 v[36:39], v[144:147], v[168:171], v[36:39]
	v_mfma_f32_16x16x32_bf16 v[32:35], v[152:155], v[168:171], v[32:35]
	v_mfma_f32_16x16x32_bf16 v[20:23], v[144:147], v[176:179], v[20:23]
	v_mfma_f32_16x16x32_bf16 v[16:19], v[152:155], v[176:179], v[16:19]
	v_mfma_f32_16x16x32_bf16 v[4:7], v[144:147], v[202:205], v[4:7]
	v_mfma_f32_16x16x32_bf16 v[0:3], v[152:155], v[202:205], v[0:3]
	v_mfma_f32_16x16x32_bf16 v[52:55], v[148:151], v[164:167], v[52:55]
	v_mfma_f32_16x16x32_bf16 v[48:51], v[156:159], v[164:167], v[48:51]
	v_mfma_f32_16x16x32_bf16 v[36:39], v[148:151], v[172:175], v[36:39]
	v_mfma_f32_16x16x32_bf16 v[32:35], v[156:159], v[172:175], v[32:35]
	v_mfma_f32_16x16x32_bf16 v[20:23], v[148:151], v[180:183], v[20:23]
	v_mfma_f32_16x16x32_bf16 v[16:19], v[156:159], v[180:183], v[16:19]
	v_mfma_f32_16x16x32_bf16 v[4:7], v[148:151], v[206:209], v[4:7]
	v_mfma_f32_16x16x32_bf16 v[0:3], v[156:159], v[206:209], v[0:3]
	s_barrier
; #define PG8_STAGE(bufoff, gbase, voff) do { _Pragma("unroll") for (int _i = 0; _i < 2; ++_i) \
;         __builtin_amdgcn_global_load_lds((const unsigned*)((const char*)(gbase) + (voff)[_i]), (PG8_LAS unsigned*)(lds + (bufoff) + ldsw + _i * 8192), 16, 0, 0); } while (0)
; #define PG8_LDA(dst, b, h) do { _Pragma("unroll") for (int m = 0; m < 4; ++m) _Pragma("unroll") for (int k = 0; k < 2; ++k) dst[m][k] = *(const PG8_LAS bf16x8*)(lds + PG8_SA(b, h) + aoff + m * 2048 + k * 1024); } while (0)
; #define PG8_LDB(dst, b, h) do { _Pragma("unroll") for (int n = 0; n < 2; ++n) _Pragma("unroll") for (int k = 0; k < 2; ++k) dst[n][k] = *(const PG8_LAS bf16x8*)(lds + PG8_SB(b, h) + boff + n * 2048 + k * 1024); } while (0)
; #define PG8_MMA(ai, bj, At, Bt) do { __builtin_amdgcn_s_setprio(1); _Pragma("unroll") for (int m = 0; m < 4; ++m) _Pragma("unroll") for (int n = 0; n < 2; ++n) _Pragma("unroll") for (int k = 0; k < 2; ++k) \
;         acc[ai][bj][m][n] = __builtin_amdgcn_mfma_f32_16x16x32_bf16(Bt[n][k], At[m][k], acc[ai][bj][m][n], 0, 0, 0); __builtin_amdgcn_s_setprio(0); } while (0)
; #define PG8_WAIT_V(n) asm volatile("s_waitcnt vmcnt(" #n ")" ::: "memory")
; #define PG8_WAIT_L(n) asm volatile("s_waitcnt lgkmcnt(" #n ")" ::: "memory")
; #define PG8_BAR __builtin_amdgcn_s_barrier()
; #define PG8_SCHED __builtin_amdgcn_sched_barrier(0)
; template <class Epi, class Sched, bool ALIGN_EPI = false, bool SP2 = false>
; __device__ __forceinline__ void gemm_phase(PG8_LAS unsigned char* lds, const Gemm g, const Sched& S, const Epi& E) {
;     ...
;             PG8_LDB(B0, 1, 0); PG8_LDB(B1, 1, 1); PG8_SCHED; PG8_LDA(At, 1, 0); PG8_STAGE(PG8_SA(0, 1), a2 + hstep, voffA);
;             PG8_WAIT_V(8); PG8_WAIT_L(0); PG8_BAR; PG8_MMA(0, 0, At, B0); PG8_MMA(0, 1, At, B1); PG8_BAR; PG8_SCHED;
;             PG8_LDA(At, 1, 1); PG8_STAGE(PG8_SB(1, 0), b3, voffB); PG8_STAGE(PG8_SB(1, 1), b3 + hstep, voffB); PG8_STAGE(PG8_SA(1, 0), a3, voffA);
;             PG8_WAIT_V(8); PG8_WAIT_L(0); PG8_BAR; PG8_MMA(1, 0, At, B0); PG8_MMA(1, 1, At, B1); PG8_BAR; PG8_SCHED;
	s_add_i32 s73, 0, 0x18000
	s_add_i32 s74, 0, 0x1c000
	v_add_u32_e32 v128, s73, v221
	v_add_u32_e32 v156, s74, v221
	ds_read_b128 v[96:99], v128
	ds_read_b128 v[108:111], v128 offset:1024
	ds_read_b128 v[120:123], v128 offset:2048
	ds_read_b128 v[128:131], v128 offset:3072
	ds_read_b128 v[144:147], v156
	ds_read_b128 v[148:151], v156 offset:1024
	ds_read_b128 v[152:155], v156 offset:2048
	ds_read_b128 v[156:159], v156 offset:3072
	s_add_u32 s48, s48, 0xb0000
	s_addc_u32 s49, s49, 0
	s_mov_b32 m0, s53
	ds_read_b128 v[160:163], v225 offset:32768
	ds_read_b128 v[164:167], v225 offset:33792
	ds_read_b128 v[168:171], v225 offset:34816
	ds_read_b128 v[172:175], v225 offset:35840
	ds_read_b128 v[176:179], v225 offset:36864
	ds_read_b128 v[180:183], v225 offset:37888
	ds_read_b128 v[202:205], v225 offset:38912
	ds_read_b128 v[206:209], v225 offset:39936
	global_load_lds_dwordx4 v184, s[48:49]
	s_mov_b32 m0, s54
	s_nop 0
	global_load_lds_dwordx4 v188, s[48:49]
	s_waitcnt vmcnt(8)
	s_waitcnt lgkmcnt(0)
	s_barrier
	s_waitcnt lgkmcnt(0)
	v_mfma_f32_16x16x32_bf16 v[140:143], v[96:99], v[160:163], v[140:143]
	v_mfma_f32_16x16x32_bf16 v[136:139], v[120:123], v[160:163], v[136:139]
	v_mfma_f32_16x16x32_bf16 v[116:119], v[96:99], v[168:171], v[116:119]
	v_mfma_f32_16x16x32_bf16 v[112:115], v[120:123], v[168:171], v[112:115]
	v_mfma_f32_16x16x32_bf16 v[92:95], v[96:99], v[176:179], v[92:95]
	v_mfma_f32_16x16x32_bf16 v[88:91], v[120:123], v[176:179], v[88:91]
	v_mfma_f32_16x16x32_bf16 v[76:79], v[96:99], v[202:205], v[76:79]
	v_mfma_f32_16x16x32_bf16 v[72:75], v[120:123], v[202:205], v[72:75]
	v_mfma_f32_16x16x32_bf16 v[140:143], v[108:111], v[164:167], v[140:143]
	v_mfma_f32_16x16x32_bf16 v[136:139], v[128:131], v[164:167], v[136:139]
	v_mfma_f32_16x16x32_bf16 v[116:119], v[108:111], v[172:175], v[116:119]
	v_mfma_f32_16x16x32_bf16 v[112:115], v[128:131], v[172:175], v[112:115]
	v_mfma_f32_16x16x32_bf16 v[92:95], v[108:111], v[180:183], v[92:95]
	v_mfma_f32_16x16x32_bf16 v[88:91], v[128:131], v[180:183], v[88:91]
	v_mfma_f32_16x16x32_bf16 v[76:79], v[108:111], v[206:209], v[76:79]
	v_mfma_f32_16x16x32_bf16 v[72:75], v[128:131], v[206:209], v[72:75]
	v_mfma_f32_16x16x32_bf16 v[132:135], v[144:147], v[160:163], v[132:135]
	v_mfma_f32_16x16x32_bf16 v[124:127], v[152:155], v[160:163], v[124:127]
	v_mfma_f32_16x16x32_bf16 v[104:107], v[144:147], v[168:171], v[104:107]
	v_mfma_f32_16x16x32_bf16 v[100:103], v[152:155], v[168:171], v[100:103]
	v_mfma_f32_16x16x32_bf16 v[84:87], v[144:147], v[176:179], v[84:87]
	v_mfma_f32_16x16x32_bf16 v[80:83], v[152:155], v[176:179], v[80:83]
	v_mfma_f32_16x16x32_bf16 v[68:71], v[144:147], v[202:205], v[68:71]
	v_mfma_f32_16x16x32_bf16 v[64:67], v[152:155], v[202:205], v[64:67]
	v_mfma_f32_16x16x32_bf16 v[132:135], v[148:151], v[164:167], v[132:135]
	v_mfma_f32_16x16x32_bf16 v[124:127], v[156:159], v[164:167], v[124:127]
	v_mfma_f32_16x16x32_bf16 v[104:107], v[148:151], v[172:175], v[104:107]
	v_mfma_f32_16x16x32_bf16 v[100:103], v[156:159], v[172:175], v[100:103]
	v_mfma_f32_16x16x32_bf16 v[84:87], v[148:151], v[180:183], v[84:87]
	v_mfma_f32_16x16x32_bf16 v[80:83], v[156:159], v[180:183], v[80:83]
	v_mfma_f32_16x16x32_bf16 v[68:71], v[148:151], v[206:209], v[68:71]
	v_mfma_f32_16x16x32_bf16 v[64:67], v[156:159], v[206:209], v[64:67]
	s_barrier
	s_add_i32 s48, s73, s50
	s_mov_b32 m0, s48
	ds_read_b128 v[160:163], v225 offset:49152
	ds_read_b128 v[164:167], v225 offset:50176
	ds_read_b128 v[168:171], v225 offset:51200
	ds_read_b128 v[172:175], v225 offset:52224
	ds_read_b128 v[176:179], v225 offset:53248
	ds_read_b128 v[180:183], v225 offset:54272
	ds_read_b128 v[202:205], v225 offset:55296
	ds_read_b128 v[206:209], v225 offset:56320
	global_load_lds_dwordx4 v186, s[98:99]
	s_add_i32 m0, s48, 0x2000
	s_add_u32 s34, s34, 0xb0080
	s_addc_u32 s35, s35, 0
	s_add_i32 s48, s74, s50
	global_load_lds_dwordx4 v190, s[98:99]
	s_mov_b32 m0, s48
	s_nop 0
	global_load_lds_dwordx4 v186, s[34:35]
	s_add_i32 m0, s48, 0x2000
	s_nop 0
	global_load_lds_dwordx4 v190, s[34:35]
	s_mov_b32 m0, s59
	s_nop 0
	global_load_lds_dwordx4 v184, s[100:101]
	s_mov_b32 m0, s60
	s_nop 0
	global_load_lds_dwordx4 v188, s[100:101]
	s_waitcnt vmcnt(8)
	s_waitcnt lgkmcnt(0)
	s_barrier
	s_waitcnt lgkmcnt(0)
	v_mfma_f32_16x16x32_bf16 v[60:63], v[96:99], v[160:163], v[60:63]
	v_mfma_f32_16x16x32_bf16 v[56:59], v[120:123], v[160:163], v[56:59]
	v_mfma_f32_16x16x32_bf16 v[44:47], v[96:99], v[168:171], v[44:47]
	v_mfma_f32_16x16x32_bf16 v[40:43], v[120:123], v[168:171], v[40:43]
	v_mfma_f32_16x16x32_bf16 v[28:31], v[96:99], v[176:179], v[28:31]
	v_mfma_f32_16x16x32_bf16 v[24:27], v[120:123], v[176:179], v[24:27]
	v_mfma_f32_16x16x32_bf16 v[12:15], v[96:99], v[202:205], v[12:15]
	v_mfma_f32_16x16x32_bf16 v[8:11], v[120:123], v[202:205], v[8:11]
	v_mfma_f32_16x16x32_bf16 v[60:63], v[108:111], v[164:167], v[60:63]
	v_mfma_f32_16x16x32_bf16 v[56:59], v[128:131], v[164:167], v[56:59]
	v_mfma_f32_16x16x32_bf16 v[44:47], v[108:111], v[172:175], v[44:47]
	v_mfma_f32_16x16x32_bf16 v[40:43], v[128:131], v[172:175], v[40:43]
	v_mfma_f32_16x16x32_bf16 v[28:31], v[108:111], v[180:183], v[28:31]
	v_mfma_f32_16x16x32_bf16 v[24:27], v[128:131], v[180:183], v[24:27]
	v_mfma_f32_16x16x32_bf16 v[12:15], v[108:111], v[206:209], v[12:15]
	v_mfma_f32_16x16x32_bf16 v[8:11], v[128:131], v[206:209], v[8:11]
	v_mfma_f32_16x16x32_bf16 v[52:55], v[144:147], v[160:163], v[52:55]
	v_mfma_f32_16x16x32_bf16 v[48:51], v[152:155], v[160:163], v[48:51]
	v_mfma_f32_16x16x32_bf16 v[36:39], v[144:147], v[168:171], v[36:39]
	v_mfma_f32_16x16x32_bf16 v[32:35], v[152:155], v[168:171], v[32:35]
	v_mfma_f32_16x16x32_bf16 v[20:23], v[144:147], v[176:179], v[20:23]
	v_mfma_f32_16x16x32_bf16 v[16:19], v[152:155], v[176:179], v[16:19]
	v_mfma_f32_16x16x32_bf16 v[4:7], v[144:147], v[202:205], v[4:7]
	v_mfma_f32_16x16x32_bf16 v[0:3], v[152:155], v[202:205], v[0:3]
	v_mfma_f32_16x16x32_bf16 v[52:55], v[148:151], v[164:167], v[52:55]
	v_mfma_f32_16x16x32_bf16 v[48:51], v[156:159], v[164:167], v[48:51]
	v_mfma_f32_16x16x32_bf16 v[36:39], v[148:151], v[172:175], v[36:39]
	v_mfma_f32_16x16x32_bf16 v[32:35], v[156:159], v[172:175], v[32:35]
	v_mfma_f32_16x16x32_bf16 v[20:23], v[148:151], v[180:183], v[20:23]
	v_mfma_f32_16x16x32_bf16 v[16:19], v[156:159], v[180:183], v[16:19]
	v_mfma_f32_16x16x32_bf16 v[4:7], v[148:151], v[206:209], v[4:7]
	v_mfma_f32_16x16x32_bf16 v[0:3], v[156:159], v[206:209], v[0:3]
	s_barrier
	s_add_i32 s72, s72, 2
	s_add_u32 s20, s20, 0x100
	s_addc_u32 s21, s21, 0
	s_add_u32 s70, s70, 0x100
	s_addc_u32 s71, s71, 0
	s_cmp_gt_u32 s72, 41
	s_cbranch_scc0 .LBB0_895
	s_and_b64 vcc, exec, s[14:15]
	s_cbranch_vccz .LBB0_898
	s_barrier

; #define PG8_STAGE(bufoff, gbase, voff) do { _Pragma("unroll") for (int _i = 0; _i < 2; ++_i) \
;         __builtin_amdgcn_global_load_lds((const unsigned*)((const char*)(gbase) + (voff)[_i]), (PG8_LAS unsigned*)(lds + (bufoff) + ldsw + _i * 8192), 16, 0, 0); } while (0)
; #define PG8_LDA(dst, b, h) do { _Pragma("unroll") for (int m = 0; m < 4; ++m) _Pragma("unroll") for (int k = 0; k < 2; ++k) dst[m][k] = *(const PG8_LAS bf16x8*)(lds + PG8_SA(b, h) + aoff + m * 2048 + k * 1024); } while (0)
; #define PG8_LDB(dst, b, h) do { _Pragma("unroll") for (int n = 0; n < 2; ++n) _Pragma("unroll") for (int k = 0; k < 2; ++k) dst[n][k] = *(const PG8_LAS bf16x8*)(lds + PG8_SB(b, h) + boff + n * 2048 + k * 1024); } while (0)
; #define PG8_MMA(ai, bj, At, Bt) do { __builtin_amdgcn_s_setprio(1); _Pragma("unroll") for (int m = 0; m < 4; ++m) _Pragma("unroll") for (int n = 0; n < 2; ++n) _Pragma("unroll") for (int k = 0; k < 2; ++k) \
;         acc[ai][bj][m][n] = __builtin_amdgcn_mfma_f32_16x16x32_bf16(Bt[n][k], At[m][k], acc[ai][bj][m][n], 0, 0, 0); __builtin_amdgcn_s_setprio(0); } while (0)
; #define PG8_BAR __builtin_amdgcn_s_barrier()
; template <class Epi, class Sched, bool ALIGN_EPI = false, bool SP2 = false>
; __device__ __forceinline__ void gemm_phase(PG8_LAS unsigned char* lds, const Gemm g, const Sched& S, const Epi& E) {
;     ...
;         const bool has_next = S.next(ui + 1, nxt);
;         const char* nA = has_next ? (const char*)g.A + (size_t)nxt.pm * tstep : cA; const char* nB = has_next ? (const char*)g.Bt + (size_t)nxt.pn * tstep : cB;
;         for (int t = 0; t < nt; t += 2) {
;             const bool last = (t == nt - 2);
;             const char* a1 = cA + (size_t)(t + 1) * kstep;
;             const char* a2 = last ? nA : cA + (size_t)(t + 2) * kstep; const char* b2 = last ? nB : cB + (size_t)(t + 2) * kstep;
;             const char* a3 = a2 + kstep; const char* b3 = b2 + kstep;
;             if (last && has_next) S.a_ready(nxt);
;             if constexpr (SP2) {
;             PG8_LDB(B0, 0, 0); PG8_LDB(B1, 0, 1); PG8_SCHED; PG8_LDA(At, 0, 0); PG8_STAGE(PG8_SA(1, 1), a1 + hstep, voffA);
;             PG8_WAIT_V(8); PG8_WAIT_L(0); PG8_BAR; PG8_MMA(0, 0, At, B0); PG8_MMA(0, 1, At, B1); PG8_BAR; PG8_SCHED;
;             PG8_LDA(At, 0, 1); PG8_STAGE(PG8_SB(0, 0), b2, voffB); PG8_STAGE(PG8_SB(0, 1), b2 + hstep, voffB); PG8_STAGE(PG8_SA(0, 0), a2, voffA);
.LBB0_1199:
	s_ashr_i32 s57, s56, 31
	s_lshl_b64 s[58:59], s[56:57], 19
	s_add_u32 s58, s36, s58
	s_addc_u32 s59, s37, s59
	s_and_b64 s[60:61], s[8:9], exec
	s_cselect_b32 s1, s59, s21
	s_cselect_b32 s57, s58, s20
	s_ashr_i32 s55, s54, 31
	s_lshl_b64 s[60:61], s[54:55], 19
	s_add_u32 s60, s68, s60
	s_addc_u32 s61, s69, s61
	s_and_b64 s[62:63], s[8:9], exec
	s_cselect_b32 s55, s61, s35
	s_cselect_b32 s85, s60, s34
	s_add_u32 s20, s20, 0x40080
	s_addc_u32 s21, s21, 0
	s_add_u32 s86, s34, 0x100
	s_addc_u32 s87, s35, 0
	s_mov_b32 s88, -2
	s_waitcnt lgkmcnt(0)
	ds_read_b128 v[140:143], v163
	ds_read_b128 v[168:171], v163 offset:1024
	ds_read_b128 v[172:175], v163 offset:2048
	ds_read_b128 v[176:179], v163 offset:3072
	ds_read_b128 v[180:183], v164
	ds_read_b128 v[184:187], v164 offset:1024
	ds_read_b128 v[188:191], v164 offset:2048
	ds_read_b128 v[192:195], v164 offset:3072
	s_add_u32 s34, s20, 0xfffc0080
	s_addc_u32 s35, s21, -1
	s_cmp_eq_u32 s88, 12
	s_cselect_b32 s63, s1, s35
	s_cselect_b32 s62, s57, s34
	s_cselect_b32 s35, s55, s87
	s_cselect_b32 s34, s85, s86
	s_add_i32 m0, s71, 0xc000
	ds_read_b128 v[198:201], v165
	ds_read_b128 v[202:205], v165 offset:1024
	ds_read_b128 v[206:209], v165 offset:2048
	ds_read_b128 v[210:213], v165 offset:3072
	ds_read_b128 v[214:217], v165 offset:4096
	ds_read_b128 v[218:221], v165 offset:5120
	ds_read_b128 v[222:225], v165 offset:6144
	ds_read_b128 v[226:229], v165 offset:7168
	global_load_lds_dwordx4 v132, s[20:21]
	s_add_i32 m0, s71, 0xe000
	s_nop 0
	global_load_lds_dwordx4 v134, s[20:21]
	s_waitcnt vmcnt(8)
	s_waitcnt lgkmcnt(0)
	s_barrier
	s_waitcnt lgkmcnt(0)
	v_mfma_f32_16x16x32_bf16 v[124:127], v[140:143], v[198:201], 0
	v_mfma_f32_16x16x32_bf16 v[120:123], v[172:175], v[198:201], 0
	v_mfma_f32_16x16x32_bf16 v[108:111], v[140:143], v[206:209], 0
	v_mfma_f32_16x16x32_bf16 v[104:107], v[172:175], v[206:209], 0
	v_mfma_f32_16x16x32_bf16 v[92:95], v[140:143], v[214:217], 0
	v_mfma_f32_16x16x32_bf16 v[88:91], v[172:175], v[214:217], 0
	v_mfma_f32_16x16x32_bf16 v[76:79], v[140:143], v[222:225], 0
	v_mfma_f32_16x16x32_bf16 v[72:75], v[172:175], v[222:225], 0
	v_mfma_f32_16x16x32_bf16 v[124:127], v[168:171], v[202:205], v[124:127]
	v_mfma_f32_16x16x32_bf16 v[120:123], v[176:179], v[202:205], v[120:123]
	v_mfma_f32_16x16x32_bf16 v[108:111], v[168:171], v[210:213], v[108:111]
	v_mfma_f32_16x16x32_bf16 v[104:107], v[176:179], v[210:213], v[104:107]
	v_mfma_f32_16x16x32_bf16 v[92:95], v[168:171], v[218:221], v[92:95]
	v_mfma_f32_16x16x32_bf16 v[88:91], v[176:179], v[218:221], v[88:91]
	v_mfma_f32_16x16x32_bf16 v[76:79], v[168:171], v[226:229], v[76:79]
	v_mfma_f32_16x16x32_bf16 v[72:75], v[176:179], v[226:229], v[72:75]
	v_mfma_f32_16x16x32_bf16 v[116:119], v[180:183], v[198:201], 0
	v_mfma_f32_16x16x32_bf16 v[112:115], v[188:191], v[198:201], 0
	v_mfma_f32_16x16x32_bf16 v[100:103], v[180:183], v[206:209], 0
	v_mfma_f32_16x16x32_bf16 v[96:99], v[188:191], v[206:209], 0
	v_mfma_f32_16x16x32_bf16 v[84:87], v[180:183], v[214:217], 0
	v_mfma_f32_16x16x32_bf16 v[80:83], v[188:191], v[214:217], 0
	v_mfma_f32_16x16x32_bf16 v[68:71], v[180:183], v[222:225], 0
	v_mfma_f32_16x16x32_bf16 v[64:67], v[188:191], v[222:225], 0
	v_mfma_f32_16x16x32_bf16 v[116:119], v[184:187], v[202:205], v[116:119]
	v_mfma_f32_16x16x32_bf16 v[112:115], v[192:195], v[202:205], v[112:115]
	v_mfma_f32_16x16x32_bf16 v[100:103], v[184:187], v[210:213], v[100:103]
	v_mfma_f32_16x16x32_bf16 v[96:99], v[192:195], v[210:213], v[96:99]
	v_mfma_f32_16x16x32_bf16 v[84:87], v[184:187], v[218:221], v[84:87]
	v_mfma_f32_16x16x32_bf16 v[80:83], v[192:195], v[218:221], v[80:83]
	v_mfma_f32_16x16x32_bf16 v[68:71], v[184:187], v[226:229], v[68:71]
	v_mfma_f32_16x16x32_bf16 v[64:67], v[192:195], v[226:229], v[64:67]
	s_barrier
	s_add_i32 s89, s77, s70
	s_add_u32 s98, s34, s18
	s_addc_u32 s99, s35, s19
	s_add_u32 s100, s62, s18
	s_addc_u32 s101, s63, s19
	s_mov_b32 m0, s89
	ds_read_b128 v[198:201], v165 offset:16384
	ds_read_b128 v[202:205], v165 offset:17408
	ds_read_b128 v[206:209], v165 offset:18432
	ds_read_b128 v[210:213], v165 offset:19456
	ds_read_b128 v[214:217], v165 offset:20480
	ds_read_b128 v[218:221], v165 offset:21504
	ds_read_b128 v[222:225], v165 offset:22528
	ds_read_b128 v[226:229], v165 offset:23552
	global_load_lds_dwordx4 v146, s[34:35]
	s_add_i32 m0, s89, 0x2000
	s_add_u32 s90, s34, 0x40000
	s_addc_u32 s91, s35, 0
	s_add_i32 s89, s78, s70
	global_load_lds_dwordx4 v150, s[34:35]
	s_mov_b32 m0, s89
	s_nop 0
	global_load_lds_dwordx4 v146, s[90:91]
	s_add_i32 m0, s89, 0x2000
	s_nop 0
	global_load_lds_dwordx4 v150, s[90:91]
	s_mov_b32 m0, s71
	s_nop 0
	global_load_lds_dwordx4 v144, s[62:63]
	s_mov_b32 m0, s72
	s_nop 0
	global_load_lds_dwordx4 v148, s[62:63]
	s_waitcnt vmcnt(8)
	s_waitcnt lgkmcnt(0)
	s_barrier
; #define PG8_STAGE(bufoff, gbase, voff) do { _Pragma("unroll") for (int _i = 0; _i < 2; ++_i) \
;         __builtin_amdgcn_global_load_lds((const unsigned*)((const char*)(gbase) + (voff)[_i]), (PG8_LAS unsigned*)(lds + (bufoff) + ldsw + _i * 8192), 16, 0, 0); } while (0)
; #define PG8_LDA(dst, b, h) do { _Pragma("unroll") for (int m = 0; m < 4; ++m) _Pragma("unroll") for (int k = 0; k < 2; ++k) dst[m][k] = *(const PG8_LAS bf16x8*)(lds + PG8_SA(b, h) + aoff + m * 2048 + k * 1024); } while (0)
; #define PG8_LDB(dst, b, h) do { _Pragma("unroll") for (int n = 0; n < 2; ++n) _Pragma("unroll") for (int k = 0; k < 2; ++k) dst[n][k] = *(const PG8_LAS bf16x8*)(lds + PG8_SB(b, h) + boff + n * 2048 + k * 1024); } while (0)
; #define PG8_MMA(ai, bj, At, Bt) do { __builtin_amdgcn_s_setprio(1); _Pragma("unroll") for (int m = 0; m < 4; ++m) _Pragma("unroll") for (int n = 0; n < 2; ++n) _Pragma("unroll") for (int k = 0; k < 2; ++k) \
;         acc[ai][bj][m][n] = __builtin_amdgcn_mfma_f32_16x16x32_bf16(Bt[n][k], At[m][k], acc[ai][bj][m][n], 0, 0, 0); __builtin_amdgcn_s_setprio(0); } while (0)
; #define PG8_WAIT_V(n) asm volatile("s_waitcnt vmcnt(" #n ")" ::: "memory")
; #define PG8_WAIT_L(n) asm volatile("s_waitcnt lgkmcnt(" #n ")" ::: "memory")
; #define PG8_BAR __builtin_amdgcn_s_barrier()
; #define PG8_SCHED __builtin_amdgcn_sched_barrier(0)
; template <class Epi, class Sched, bool ALIGN_EPI = false, bool SP2 = false>
; __device__ __forceinline__ void gemm_phase(PG8_LAS unsigned char* lds, const Gemm g, const Sched& S, const Epi& E) {
;     ...
;             PG8_WAIT_V(8); PG8_WAIT_L(0); PG8_BAR; PG8_MMA(1, 0, At, B0); PG8_MMA(1, 1, At, B1); PG8_BAR; PG8_SCHED;
;             PG8_LDB(B0, 1, 0); PG8_LDB(B1, 1, 1); PG8_SCHED; PG8_LDA(At, 1, 0); PG8_STAGE(PG8_SA(0, 1), a2 + hstep, voffA);
;             PG8_WAIT_V(8); PG8_WAIT_L(0); PG8_BAR; PG8_MMA(0, 0, At, B0); PG8_MMA(0, 1, At, B1); PG8_BAR; PG8_SCHED;
	s_waitcnt lgkmcnt(0)
	v_mfma_f32_16x16x32_bf16 v[60:63], v[140:143], v[198:201], 0
	v_mfma_f32_16x16x32_bf16 v[56:59], v[172:175], v[198:201], 0
	v_mfma_f32_16x16x32_bf16 v[48:51], v[140:143], v[206:209], 0
	v_mfma_f32_16x16x32_bf16 v[40:43], v[172:175], v[206:209], 0
	v_mfma_f32_16x16x32_bf16 v[32:35], v[140:143], v[214:217], 0
	v_mfma_f32_16x16x32_bf16 v[24:27], v[172:175], v[214:217], 0
	v_mfma_f32_16x16x32_bf16 v[16:19], v[140:143], v[222:225], 0
	v_mfma_f32_16x16x32_bf16 v[8:11], v[172:175], v[222:225], 0
	v_mfma_f32_16x16x32_bf16 v[60:63], v[168:171], v[202:205], v[60:63]
	v_mfma_f32_16x16x32_bf16 v[56:59], v[176:179], v[202:205], v[56:59]
	v_mfma_f32_16x16x32_bf16 v[48:51], v[168:171], v[210:213], v[48:51]
	v_mfma_f32_16x16x32_bf16 v[40:43], v[176:179], v[210:213], v[40:43]
	v_mfma_f32_16x16x32_bf16 v[32:35], v[168:171], v[218:221], v[32:35]
	v_mfma_f32_16x16x32_bf16 v[24:27], v[176:179], v[218:221], v[24:27]
	v_mfma_f32_16x16x32_bf16 v[16:19], v[168:171], v[226:229], v[16:19]
	v_mfma_f32_16x16x32_bf16 v[8:11], v[176:179], v[226:229], v[8:11]
	v_mfma_f32_16x16x32_bf16 v[52:55], v[180:183], v[198:201], 0
	v_mfma_f32_16x16x32_bf16 v[44:47], v[188:191], v[198:201], 0
	v_mfma_f32_16x16x32_bf16 v[36:39], v[180:183], v[206:209], 0
	v_mfma_f32_16x16x32_bf16 v[28:31], v[188:191], v[206:209], 0
	v_mfma_f32_16x16x32_bf16 v[20:23], v[180:183], v[214:217], 0
	v_mfma_f32_16x16x32_bf16 v[12:15], v[188:191], v[214:217], 0
	v_mfma_f32_16x16x32_bf16 v[4:7], v[180:183], v[222:225], 0
	v_mfma_f32_16x16x32_bf16 v[0:3], v[188:191], v[222:225], 0
	v_mfma_f32_16x16x32_bf16 v[52:55], v[184:187], v[202:205], v[52:55]
	v_mfma_f32_16x16x32_bf16 v[44:47], v[192:195], v[202:205], v[44:47]
	v_mfma_f32_16x16x32_bf16 v[36:39], v[184:187], v[210:213], v[36:39]
	v_mfma_f32_16x16x32_bf16 v[28:31], v[192:195], v[210:213], v[28:31]
	v_mfma_f32_16x16x32_bf16 v[20:23], v[184:187], v[218:221], v[20:23]
	v_mfma_f32_16x16x32_bf16 v[12:15], v[192:195], v[218:221], v[12:15]
	v_mfma_f32_16x16x32_bf16 v[4:7], v[184:187], v[226:229], v[4:7]
	v_mfma_f32_16x16x32_bf16 v[0:3], v[192:195], v[226:229], v[0:3]
	s_barrier
	s_add_i32 s89, 0, 0x18000
	v_add_u32_e32 v128, s89, v161
	s_add_i32 s90, 0, 0x1c000
	ds_read_b128 v[140:143], v128
	ds_read_b128 v[168:171], v128 offset:1024
	ds_read_b128 v[172:175], v128 offset:2048
	ds_read_b128 v[176:179], v128 offset:3072
	v_add_u32_e32 v128, s90, v161
	ds_read_b128 v[180:183], v128
	ds_read_b128 v[184:187], v128 offset:1024
	ds_read_b128 v[188:191], v128 offset:2048
	ds_read_b128 v[192:195], v128 offset:3072
	s_add_u32 s62, s62, 0x40000
	s_addc_u32 s63, s63, 0
	s_mov_b32 m0, s73
	ds_read_b128 v[198:201], v165 offset:32768
	ds_read_b128 v[202:205], v165 offset:33792
	ds_read_b128 v[206:209], v165 offset:34816
	ds_read_b128 v[210:213], v165 offset:35840
	ds_read_b128 v[214:217], v165 offset:36864
	ds_read_b128 v[218:221], v165 offset:37888
	ds_read_b128 v[222:225], v165 offset:38912
	ds_read_b128 v[226:229], v165 offset:39936
	global_load_lds_dwordx4 v144, s[62:63]
	s_mov_b32 m0, s74
	s_nop 0
	global_load_lds_dwordx4 v148, s[62:63]
	s_waitcnt vmcnt(8)
	s_waitcnt lgkmcnt(0)
	s_barrier
	s_waitcnt lgkmcnt(0)
	v_mfma_f32_16x16x32_bf16 v[124:127], v[140:143], v[198:201], v[124:127]
	v_mfma_f32_16x16x32_bf16 v[120:123], v[172:175], v[198:201], v[120:123]
	v_mfma_f32_16x16x32_bf16 v[108:111], v[140:143], v[206:209], v[108:111]
	v_mfma_f32_16x16x32_bf16 v[104:107], v[172:175], v[206:209], v[104:107]
	v_mfma_f32_16x16x32_bf16 v[92:95], v[140:143], v[214:217], v[92:95]
	v_mfma_f32_16x16x32_bf16 v[88:91], v[172:175], v[214:217], v[88:91]
	v_mfma_f32_16x16x32_bf16 v[76:79], v[140:143], v[222:225], v[76:79]
	v_mfma_f32_16x16x32_bf16 v[72:75], v[172:175], v[222:225], v[72:75]
	v_mfma_f32_16x16x32_bf16 v[124:127], v[168:171], v[202:205], v[124:127]
	v_mfma_f32_16x16x32_bf16 v[120:123], v[176:179], v[202:205], v[120:123]
	v_mfma_f32_16x16x32_bf16 v[108:111], v[168:171], v[210:213], v[108:111]
	v_mfma_f32_16x16x32_bf16 v[104:107], v[176:179], v[210:213], v[104:107]
	v_mfma_f32_16x16x32_bf16 v[92:95], v[168:171], v[218:221], v[92:95]
	v_mfma_f32_16x16x32_bf16 v[88:91], v[176:179], v[218:221], v[88:91]
	v_mfma_f32_16x16x32_bf16 v[76:79], v[168:171], v[226:229], v[76:79]
	v_mfma_f32_16x16x32_bf16 v[72:75], v[176:179], v[226:229], v[72:75]
	v_mfma_f32_16x16x32_bf16 v[116:119], v[180:183], v[198:201], v[116:119]
	v_mfma_f32_16x16x32_bf16 v[112:115], v[188:191], v[198:201], v[112:115]
	v_mfma_f32_16x16x32_bf16 v[100:103], v[180:183], v[206:209], v[100:103]
	v_mfma_f32_16x16x32_bf16 v[96:99], v[188:191], v[206:209], v[96:99]
	v_mfma_f32_16x16x32_bf16 v[84:87], v[180:183], v[214:217], v[84:87]
	v_mfma_f32_16x16x32_bf16 v[80:83], v[188:191], v[214:217], v[80:83]
	v_mfma_f32_16x16x32_bf16 v[68:71], v[180:183], v[222:225], v[68:71]
	v_mfma_f32_16x16x32_bf16 v[64:67], v[188:191], v[222:225], v[64:67]
	v_mfma_f32_16x16x32_bf16 v[116:119], v[184:187], v[202:205], v[116:119]
	v_mfma_f32_16x16x32_bf16 v[112:115], v[192:195], v[202:205], v[112:115]
	v_mfma_f32_16x16x32_bf16 v[100:103], v[184:187], v[210:213], v[100:103]
	v_mfma_f32_16x16x32_bf16 v[96:99], v[192:195], v[210:213], v[96:99]
	v_mfma_f32_16x16x32_bf16 v[84:87], v[184:187], v[218:221], v[84:87]
	v_mfma_f32_16x16x32_bf16 v[80:83], v[192:195], v[218:221], v[80:83]
	v_mfma_f32_16x16x32_bf16 v[68:71], v[184:187], v[226:229], v[68:71]
	v_mfma_f32_16x16x32_bf16 v[64:67], v[192:195], v[226:229], v[64:67]
	s_barrier
; #define PG8_STAGE(bufoff, gbase, voff) do { _Pragma("unroll") for (int _i = 0; _i < 2; ++_i) \
;         __builtin_amdgcn_global_load_lds((const unsigned*)((const char*)(gbase) + (voff)[_i]), (PG8_LAS unsigned*)(lds + (bufoff) + ldsw + _i * 8192), 16, 0, 0); } while (0)
; #define PG8_LDA(dst, b, h) do { _Pragma("unroll") for (int m = 0; m < 4; ++m) _Pragma("unroll") for (int k = 0; k < 2; ++k) dst[m][k] = *(const PG8_LAS bf16x8*)(lds + PG8_SA(b, h) + aoff + m * 2048 + k * 1024); } while (0)
; #define PG8_LDB(dst, b, h) do { _Pragma("unroll") for (int n = 0; n < 2; ++n) _Pragma("unroll") for (int k = 0; k < 2; ++k) dst[n][k] = *(const PG8_LAS bf16x8*)(lds + PG8_SB(b, h) + boff + n * 2048 + k * 1024); } while (0)
; #define PG8_MMA(ai, bj, At, Bt) do { __builtin_amdgcn_s_setprio(1); _Pragma("unroll") for (int m = 0; m < 4; ++m) _Pragma("unroll") for (int n = 0; n < 2; ++n) _Pragma("unroll") for (int k = 0; k < 2; ++k) \
;         acc[ai][bj][m][n] = __builtin_amdgcn_mfma_f32_16x16x32_bf16(Bt[n][k], At[m][k], acc[ai][bj][m][n], 0, 0, 0); __builtin_amdgcn_s_setprio(0); } while (0)
; #define PG8_WAIT_V(n) asm volatile("s_waitcnt vmcnt(" #n ")" ::: "memory")
; template <class Epi, class Sched, bool ALIGN_EPI = false, bool SP2 = false>
; __device__ __forceinline__ void gemm_phase(PG8_LAS unsigned char* lds, const Gemm g, const Sched& S, const Epi& E) {
;     ...
;             PG8_LDB(B0, 0, 0); PG8_LDB(B1, 0, 1); PG8_SCHED; PG8_LDA(At, 0, 0); PG8_STAGE(PG8_SA(1, 1), a1 + hstep, voffA);
;             PG8_WAIT_V(8); PG8_WAIT_L(0); PG8_BAR; PG8_MMA(0, 0, At, B0); PG8_MMA(0, 1, At, B1); PG8_BAR; PG8_SCHED;
;             PG8_LDA(At, 0, 1); PG8_STAGE(PG8_SB(0, 0), b2, voffB); PG8_STAGE(PG8_SB(0, 1), b2 + hstep, voffB); PG8_STAGE(PG8_SA(0, 0), a2, voffA);
;             PG8_WAIT_V(8); PG8_WAIT_L(0); PG8_BAR; PG8_MMA(1, 0, At, B0); PG8_MMA(1, 1, At, B1); PG8_BAR; PG8_SCHED;
;             PG8_LDB(B0, 1, 0); PG8_LDB(B1, 1, 1); PG8_SCHED; PG8_LDA(At, 1, 0); PG8_STAGE(PG8_SA(0, 1), a2 + hstep, voffA);
;             PG8_WAIT_V(8); PG8_WAIT_L(0); PG8_BAR; PG8_MMA(0, 0, At, B0); PG8_MMA(0, 1, At, B1); PG8_BAR; PG8_SCHED;
;             PG8_LDA(At, 1, 1); PG8_STAGE(PG8_SB(1, 0), b3, voffB); PG8_STAGE(PG8_SB(1, 1), b3 + hstep, voffB); PG8_STAGE(PG8_SA(1, 0), a3, voffA);
;             PG8_WAIT_V(8); PG8_WAIT_L(0); PG8_BAR; PG8_MMA(1, 0, At, B0); PG8_MMA(1, 1, At, B1); PG8_BAR; PG8_SCHED;
	s_add_i32 s62, s89, s70
	s_mov_b32 m0, s62
	ds_read_b128 v[198:201], v165 offset:49152
	ds_read_b128 v[202:205], v165 offset:50176
	ds_read_b128 v[206:209], v165 offset:51200
	ds_read_b128 v[210:213], v165 offset:52224
	ds_read_b128 v[214:217], v165 offset:53248
	ds_read_b128 v[218:221], v165 offset:54272
	ds_read_b128 v[222:225], v165 offset:55296
	ds_read_b128 v[226:229], v165 offset:56320
	global_load_lds_dwordx4 v146, s[98:99]
	s_add_i32 m0, s62, 0x2000
	s_add_u32 s34, s34, 0x40080
	s_addc_u32 s35, s35, 0
	s_add_i32 s62, s90, s70
	global_load_lds_dwordx4 v150, s[98:99]
	s_mov_b32 m0, s62
	s_nop 0
	global_load_lds_dwordx4 v146, s[34:35]
	s_add_i32 m0, s62, 0x2000
	s_nop 0
	global_load_lds_dwordx4 v150, s[34:35]
	s_mov_b32 m0, s75
	s_nop 0
	global_load_lds_dwordx4 v144, s[100:101]
	s_mov_b32 m0, s76
	s_nop 0
	global_load_lds_dwordx4 v148, s[100:101]
	s_waitcnt vmcnt(8)
	s_waitcnt lgkmcnt(0)
	s_barrier
	s_waitcnt lgkmcnt(0)
	v_mfma_f32_16x16x32_bf16 v[60:63], v[140:143], v[198:201], v[60:63]
	v_mfma_f32_16x16x32_bf16 v[56:59], v[172:175], v[198:201], v[56:59]
	v_mfma_f32_16x16x32_bf16 v[48:51], v[140:143], v[206:209], v[48:51]
	v_mfma_f32_16x16x32_bf16 v[40:43], v[172:175], v[206:209], v[40:43]
	v_mfma_f32_16x16x32_bf16 v[32:35], v[140:143], v[214:217], v[32:35]
	v_mfma_f32_16x16x32_bf16 v[24:27], v[172:175], v[214:217], v[24:27]
	v_mfma_f32_16x16x32_bf16 v[16:19], v[140:143], v[222:225], v[16:19]
	v_mfma_f32_16x16x32_bf16 v[8:11], v[172:175], v[222:225], v[8:11]
	v_mfma_f32_16x16x32_bf16 v[60:63], v[168:171], v[202:205], v[60:63]
	v_mfma_f32_16x16x32_bf16 v[56:59], v[176:179], v[202:205], v[56:59]
	v_mfma_f32_16x16x32_bf16 v[48:51], v[168:171], v[210:213], v[48:51]
	v_mfma_f32_16x16x32_bf16 v[40:43], v[176:179], v[210:213], v[40:43]
	v_mfma_f32_16x16x32_bf16 v[32:35], v[168:171], v[218:221], v[32:35]
	v_mfma_f32_16x16x32_bf16 v[24:27], v[176:179], v[218:221], v[24:27]
	v_mfma_f32_16x16x32_bf16 v[16:19], v[168:171], v[226:229], v[16:19]
	v_mfma_f32_16x16x32_bf16 v[8:11], v[176:179], v[226:229], v[8:11]
	v_mfma_f32_16x16x32_bf16 v[52:55], v[180:183], v[198:201], v[52:55]
	v_mfma_f32_16x16x32_bf16 v[44:47], v[188:191], v[198:201], v[44:47]
	v_mfma_f32_16x16x32_bf16 v[36:39], v[180:183], v[206:209], v[36:39]
	v_mfma_f32_16x16x32_bf16 v[28:31], v[188:191], v[206:209], v[28:31]
	v_mfma_f32_16x16x32_bf16 v[20:23], v[180:183], v[214:217], v[20:23]
	v_mfma_f32_16x16x32_bf16 v[12:15], v[188:191], v[214:217], v[12:15]
	v_mfma_f32_16x16x32_bf16 v[4:7], v[180:183], v[222:225], v[4:7]
	v_mfma_f32_16x16x32_bf16 v[0:3], v[188:191], v[222:225], v[0:3]
	v_mfma_f32_16x16x32_bf16 v[52:55], v[184:187], v[202:205], v[52:55]
	v_mfma_f32_16x16x32_bf16 v[44:47], v[192:195], v[202:205], v[44:47]
	v_mfma_f32_16x16x32_bf16 v[36:39], v[184:187], v[210:213], v[36:39]
	v_mfma_f32_16x16x32_bf16 v[28:31], v[192:195], v[210:213], v[28:31]
	v_mfma_f32_16x16x32_bf16 v[20:23], v[184:187], v[218:221], v[20:23]
	v_mfma_f32_16x16x32_bf16 v[12:15], v[192:195], v[218:221], v[12:15]
	v_mfma_f32_16x16x32_bf16 v[4:7], v[184:187], v[226:229], v[4:7]
	v_mfma_f32_16x16x32_bf16 v[0:3], v[192:195], v[226:229], v[0:3]
	s_barrier
	s_add_i32 s88, s88, 2
	s_add_u32 s20, s20, 0x100
	s_addc_u32 s21, s21, 0
	s_add_u32 s86, s86, 0x100
	s_addc_u32 s87, s87, 0
	s_cmp_gt_u32 s88, 13
.LBB0_1200:
	ds_read_b128 v[140:143], v163
	ds_read_b128 v[168:171], v163 offset:1024
	ds_read_b128 v[172:175], v163 offset:2048
	ds_read_b128 v[176:179], v163 offset:3072
	ds_read_b128 v[180:183], v164
	ds_read_b128 v[184:187], v164 offset:1024
	ds_read_b128 v[188:191], v164 offset:2048
	ds_read_b128 v[192:195], v164 offset:3072
	s_add_u32 s34, s20, 0xfffc0080
	s_addc_u32 s35, s21, -1
	s_cmp_eq_u32 s88, 12
	s_cselect_b32 s63, s1, s35
	s_cselect_b32 s62, s57, s34
	s_cselect_b32 s35, s55, s87
	s_cselect_b32 s34, s85, s86
	s_add_i32 m0, s71, 0xc000
	ds_read_b128 v[198:201], v165
	ds_read_b128 v[202:205], v165 offset:1024
	ds_read_b128 v[206:209], v165 offset:2048
	ds_read_b128 v[210:213], v165 offset:3072
	ds_read_b128 v[214:217], v165 offset:4096
	ds_read_b128 v[218:221], v165 offset:5120
	ds_read_b128 v[222:225], v165 offset:6144
	ds_read_b128 v[226:229], v165 offset:7168
	global_load_lds_dwordx4 v132, s[20:21]
	s_add_i32 m0, s71, 0xe000
	s_nop 0
	global_load_lds_dwordx4 v134, s[20:21]
	s_waitcnt vmcnt(8)
	s_waitcnt lgkmcnt(0)
	s_barrier
	s_waitcnt lgkmcnt(0)
	v_mfma_f32_16x16x32_bf16 v[124:127], v[140:143], v[198:201], v[124:127]
	v_mfma_f32_16x16x32_bf16 v[120:123], v[172:175], v[198:201], v[120:123]
	v_mfma_f32_16x16x32_bf16 v[108:111], v[140:143], v[206:209], v[108:111]
	v_mfma_f32_16x16x32_bf16 v[104:107], v[172:175], v[206:209], v[104:107]
	v_mfma_f32_16x16x32_bf16 v[92:95], v[140:143], v[214:217], v[92:95]
	v_mfma_f32_16x16x32_bf16 v[88:91], v[172:175], v[214:217], v[88:91]
	v_mfma_f32_16x16x32_bf16 v[76:79], v[140:143], v[222:225], v[76:79]
	v_mfma_f32_16x16x32_bf16 v[72:75], v[172:175], v[222:225], v[72:75]
	v_mfma_f32_16x16x32_bf16 v[124:127], v[168:171], v[202:205], v[124:127]
	v_mfma_f32_16x16x32_bf16 v[120:123], v[176:179], v[202:205], v[120:123]
	v_mfma_f32_16x16x32_bf16 v[108:111], v[168:171], v[210:213], v[108:111]
	v_mfma_f32_16x16x32_bf16 v[104:107], v[176:179], v[210:213], v[104:107]
	v_mfma_f32_16x16x32_bf16 v[92:95], v[168:171], v[218:221], v[92:95]
	v_mfma_f32_16x16x32_bf16 v[88:91], v[176:179], v[218:221], v[88:91]
	v_mfma_f32_16x16x32_bf16 v[76:79], v[168:171], v[226:229], v[76:79]
	v_mfma_f32_16x16x32_bf16 v[72:75], v[176:179], v[226:229], v[72:75]
	v_mfma_f32_16x16x32_bf16 v[116:119], v[180:183], v[198:201], v[116:119]
	v_mfma_f32_16x16x32_bf16 v[112:115], v[188:191], v[198:201], v[112:115]
	v_mfma_f32_16x16x32_bf16 v[100:103], v[180:183], v[206:209], v[100:103]
	v_mfma_f32_16x16x32_bf16 v[96:99], v[188:191], v[206:209], v[96:99]
	v_mfma_f32_16x16x32_bf16 v[84:87], v[180:183], v[214:217], v[84:87]
	v_mfma_f32_16x16x32_bf16 v[80:83], v[188:191], v[214:217], v[80:83]
	v_mfma_f32_16x16x32_bf16 v[68:71], v[180:183], v[222:225], v[68:71]
	v_mfma_f32_16x16x32_bf16 v[64:67], v[188:191], v[222:225], v[64:67]
	v_mfma_f32_16x16x32_bf16 v[116:119], v[184:187], v[202:205], v[116:119]
	v_mfma_f32_16x16x32_bf16 v[112:115], v[192:195], v[202:205], v[112:115]
	v_mfma_f32_16x16x32_bf16 v[100:103], v[184:187], v[210:213], v[100:103]
	v_mfma_f32_16x16x32_bf16 v[96:99], v[192:195], v[210:213], v[96:99]
	v_mfma_f32_16x16x32_bf16 v[84:87], v[184:187], v[218:221], v[84:87]
	v_mfma_f32_16x16x32_bf16 v[80:83], v[192:195], v[218:221], v[80:83]
	v_mfma_f32_16x16x32_bf16 v[68:71], v[184:187], v[226:229], v[68:71]
	v_mfma_f32_16x16x32_bf16 v[64:67], v[192:195], v[226:229], v[64:67]
	s_barrier
; #define PG8_STAGE(bufoff, gbase, voff) do { _Pragma("unroll") for (int _i = 0; _i < 2; ++_i) \
;         __builtin_amdgcn_global_load_lds((const unsigned*)((const char*)(gbase) + (voff)[_i]), (PG8_LAS unsigned*)(lds + (bufoff) + ldsw + _i * 8192), 16, 0, 0); } while (0)
; #define PG8_LDA(dst, b, h) do { _Pragma("unroll") for (int m = 0; m < 4; ++m) _Pragma("unroll") for (int k = 0; k < 2; ++k) dst[m][k] = *(const PG8_LAS bf16x8*)(lds + PG8_SA(b, h) + aoff + m * 2048 + k * 1024); } while (0)
; #define PG8_LDB(dst, b, h) do { _Pragma("unroll") for (int n = 0; n < 2; ++n) _Pragma("unroll") for (int k = 0; k < 2; ++k) dst[n][k] = *(const PG8_LAS bf16x8*)(lds + PG8_SB(b, h) + boff + n * 2048 + k * 1024); } while (0)
; #define PG8_MMA(ai, bj, At, Bt) do { __builtin_amdgcn_s_setprio(1); _Pragma("unroll") for (int m = 0; m < 4; ++m) _Pragma("unroll") for (int n = 0; n < 2; ++n) _Pragma("unroll") for (int k = 0; k < 2; ++k) \
;         acc[ai][bj][m][n] = __builtin_amdgcn_mfma_f32_16x16x32_bf16(Bt[n][k], At[m][k], acc[ai][bj][m][n], 0, 0, 0); __builtin_amdgcn_s_setprio(0); } while (0)
; #define PG8_WAIT_V(n) asm volatile("s_waitcnt vmcnt(" #n ")" ::: "memory")
; #define PG8_WAIT_L(n) asm volatile("s_waitcnt lgkmcnt(" #n ")" ::: "memory")
; #define PG8_BAR __builtin_amdgcn_s_barrier()
; #define PG8_SCHED __builtin_amdgcn_sched_barrier(0)
; template <class Epi, class Sched, bool ALIGN_EPI = false, bool SP2 = false>
; __device__ __forceinline__ void gemm_phase(PG8_LAS unsigned char* lds, const Gemm g, const Sched& S, const Epi& E) {
;     ...
;             PG8_LDA(At, 0, 1); PG8_STAGE(PG8_SB(0, 0), b2, voffB); PG8_STAGE(PG8_SB(0, 1), b2 + hstep, voffB); PG8_STAGE(PG8_SA(0, 0), a2, voffA);
;             PG8_WAIT_V(8); PG8_WAIT_L(0); PG8_BAR; PG8_MMA(1, 0, At, B0); PG8_MMA(1, 1, At, B1); PG8_BAR; PG8_SCHED;
;             PG8_LDB(B0, 1, 0); PG8_LDB(B1, 1, 1); PG8_SCHED; PG8_LDA(At, 1, 0); PG8_STAGE(PG8_SA(0, 1), a2 + hstep, voffA);
;             PG8_WAIT_V(8); PG8_WAIT_L(0); PG8_BAR; PG8_MMA(0, 0, At, B0); PG8_MMA(0, 1, At, B1); PG8_BAR; PG8_SCHED;
	s_add_i32 s89, s77, s70
	s_add_u32 s98, s34, s18
	s_addc_u32 s99, s35, s19
	s_add_u32 s100, s62, s18
	s_addc_u32 s101, s63, s19
	s_mov_b32 m0, s89
	ds_read_b128 v[198:201], v165 offset:16384
	ds_read_b128 v[202:205], v165 offset:17408
	ds_read_b128 v[206:209], v165 offset:18432
	ds_read_b128 v[210:213], v165 offset:19456
	ds_read_b128 v[214:217], v165 offset:20480
	ds_read_b128 v[218:221], v165 offset:21504
	ds_read_b128 v[222:225], v165 offset:22528
	ds_read_b128 v[226:229], v165 offset:23552
	global_load_lds_dwordx4 v146, s[34:35]
	s_add_i32 m0, s89, 0x2000
	s_add_u32 s90, s34, 0x40000
	s_addc_u32 s91, s35, 0
	s_add_i32 s89, s78, s70
	global_load_lds_dwordx4 v150, s[34:35]
	s_mov_b32 m0, s89
	s_nop 0
	global_load_lds_dwordx4 v146, s[90:91]
	s_add_i32 m0, s89, 0x2000
	s_nop 0
	global_load_lds_dwordx4 v150, s[90:91]
	s_mov_b32 m0, s71
	s_nop 0
	global_load_lds_dwordx4 v144, s[62:63]
	s_mov_b32 m0, s72
	s_nop 0
	global_load_lds_dwordx4 v148, s[62:63]
	s_waitcnt vmcnt(8)
	s_waitcnt lgkmcnt(0)
	s_barrier
	s_waitcnt lgkmcnt(0)
	v_mfma_f32_16x16x32_bf16 v[60:63], v[140:143], v[198:201], v[60:63]
	v_mfma_f32_16x16x32_bf16 v[56:59], v[172:175], v[198:201], v[56:59]
	v_mfma_f32_16x16x32_bf16 v[48:51], v[140:143], v[206:209], v[48:51]
	v_mfma_f32_16x16x32_bf16 v[40:43], v[172:175], v[206:209], v[40:43]
	v_mfma_f32_16x16x32_bf16 v[32:35], v[140:143], v[214:217], v[32:35]
	v_mfma_f32_16x16x32_bf16 v[24:27], v[172:175], v[214:217], v[24:27]
	v_mfma_f32_16x16x32_bf16 v[16:19], v[140:143], v[222:225], v[16:19]
	v_mfma_f32_16x16x32_bf16 v[8:11], v[172:175], v[222:225], v[8:11]
	v_mfma_f32_16x16x32_bf16 v[60:63], v[168:171], v[202:205], v[60:63]
	v_mfma_f32_16x16x32_bf16 v[56:59], v[176:179], v[202:205], v[56:59]
	v_mfma_f32_16x16x32_bf16 v[48:51], v[168:171], v[210:213], v[48:51]
	v_mfma_f32_16x16x32_bf16 v[40:43], v[176:179], v[210:213], v[40:43]
	v_mfma_f32_16x16x32_bf16 v[32:35], v[168:171], v[218:221], v[32:35]
	v_mfma_f32_16x16x32_bf16 v[24:27], v[176:179], v[218:221], v[24:27]
	v_mfma_f32_16x16x32_bf16 v[16:19], v[168:171], v[226:229], v[16:19]
	v_mfma_f32_16x16x32_bf16 v[8:11], v[176:179], v[226:229], v[8:11]
	v_mfma_f32_16x16x32_bf16 v[52:55], v[180:183], v[198:201], v[52:55]
	v_mfma_f32_16x16x32_bf16 v[44:47], v[188:191], v[198:201], v[44:47]
	v_mfma_f32_16x16x32_bf16 v[36:39], v[180:183], v[206:209], v[36:39]
	v_mfma_f32_16x16x32_bf16 v[28:31], v[188:191], v[206:209], v[28:31]
	v_mfma_f32_16x16x32_bf16 v[20:23], v[180:183], v[214:217], v[20:23]
	v_mfma_f32_16x16x32_bf16 v[12:15], v[188:191], v[214:217], v[12:15]
	v_mfma_f32_16x16x32_bf16 v[4:7], v[180:183], v[222:225], v[4:7]
	v_mfma_f32_16x16x32_bf16 v[0:3], v[188:191], v[222:225], v[0:3]
	v_mfma_f32_16x16x32_bf16 v[52:55], v[184:187], v[202:205], v[52:55]
	v_mfma_f32_16x16x32_bf16 v[44:47], v[192:195], v[202:205], v[44:47]
	v_mfma_f32_16x16x32_bf16 v[36:39], v[184:187], v[210:213], v[36:39]
	v_mfma_f32_16x16x32_bf16 v[28:31], v[192:195], v[210:213], v[28:31]
	v_mfma_f32_16x16x32_bf16 v[20:23], v[184:187], v[218:221], v[20:23]
	v_mfma_f32_16x16x32_bf16 v[12:15], v[192:195], v[218:221], v[12:15]
	v_mfma_f32_16x16x32_bf16 v[4:7], v[184:187], v[226:229], v[4:7]
	v_mfma_f32_16x16x32_bf16 v[0:3], v[192:195], v[226:229], v[0:3]
	s_barrier
	s_add_i32 s89, 0, 0x18000
	v_add_u32_e32 v128, s89, v161
	s_add_i32 s90, 0, 0x1c000
	ds_read_b128 v[140:143], v128
	ds_read_b128 v[168:171], v128 offset:1024
	ds_read_b128 v[172:175], v128 offset:2048
	ds_read_b128 v[176:179], v128 offset:3072
	v_add_u32_e32 v128, s90, v161
	ds_read_b128 v[180:183], v128
	ds_read_b128 v[184:187], v128 offset:1024
	ds_read_b128 v[188:191], v128 offset:2048
	ds_read_b128 v[192:195], v128 offset:3072
	s_add_u32 s62, s62, 0x40000
	s_addc_u32 s63, s63, 0
	s_mov_b32 m0, s73
	ds_read_b128 v[198:201], v165 offset:32768
	ds_read_b128 v[202:205], v165 offset:33792
	ds_read_b128 v[206:209], v165 offset:34816
	ds_read_b128 v[210:213], v165 offset:35840
	ds_read_b128 v[214:217], v165 offset:36864
	ds_read_b128 v[218:221], v165 offset:37888
	ds_read_b128 v[222:225], v165 offset:38912
	ds_read_b128 v[226:229], v165 offset:39936
	global_load_lds_dwordx4 v144, s[62:63]
	s_mov_b32 m0, s74
	s_nop 0
	global_load_lds_dwordx4 v148, s[62:63]
	s_waitcnt vmcnt(8)
	s_waitcnt lgkmcnt(0)
	s_barrier
; #define PG8_STAGE(bufoff, gbase, voff) do { _Pragma("unroll") for (int _i = 0; _i < 2; ++_i) \
;         __builtin_amdgcn_global_load_lds((const unsigned*)((const char*)(gbase) + (voff)[_i]), (PG8_LAS unsigned*)(lds + (bufoff) + ldsw + _i * 8192), 16, 0, 0); } while (0)
; #define PG8_LDA(dst, b, h) do { _Pragma("unroll") for (int m = 0; m < 4; ++m) _Pragma("unroll") for (int k = 0; k < 2; ++k) dst[m][k] = *(const PG8_LAS bf16x8*)(lds + PG8_SA(b, h) + aoff + m * 2048 + k * 1024); } while (0)
; #define PG8_MMA(ai, bj, At, Bt) do { __builtin_amdgcn_s_setprio(1); _Pragma("unroll") for (int m = 0; m < 4; ++m) _Pragma("unroll") for (int n = 0; n < 2; ++n) _Pragma("unroll") for (int k = 0; k < 2; ++k) \
;         acc[ai][bj][m][n] = __builtin_amdgcn_mfma_f32_16x16x32_bf16(Bt[n][k], At[m][k], acc[ai][bj][m][n], 0, 0, 0); __builtin_amdgcn_s_setprio(0); } while (0)
; #define PG8_WAIT_V(n) asm volatile("s_waitcnt vmcnt(" #n ")" ::: "memory")
; #define PG8_WAIT_L(n) asm volatile("s_waitcnt lgkmcnt(" #n ")" ::: "memory")
; #define PG8_BAR __builtin_amdgcn_s_barrier()
; #define PG8_SCHED __builtin_amdgcn_sched_barrier(0)
; template <class Epi, class Sched, bool ALIGN_EPI = false, bool SP2 = false>
; __device__ __forceinline__ void gemm_phase(PG8_LAS unsigned char* lds, const Gemm g, const Sched& S, const Epi& E) {
;     ...
;             PG8_WAIT_V(8); PG8_WAIT_L(0); PG8_BAR; PG8_MMA(0, 0, At, B0); PG8_MMA(0, 1, At, B1); PG8_BAR; PG8_SCHED;
;             PG8_LDA(At, 1, 1); PG8_STAGE(PG8_SB(1, 0), b3, voffB); PG8_STAGE(PG8_SB(1, 1), b3 + hstep, voffB); PG8_STAGE(PG8_SA(1, 0), a3, voffA);
;             PG8_WAIT_V(8); PG8_WAIT_L(0); PG8_BAR; PG8_MMA(1, 0, At, B0); PG8_MMA(1, 1, At, B1); PG8_BAR; PG8_SCHED;
	s_waitcnt lgkmcnt(0)
	v_mfma_f32_16x16x32_bf16 v[124:127], v[140:143], v[198:201], v[124:127]
	v_mfma_f32_16x16x32_bf16 v[120:123], v[172:175], v[198:201], v[120:123]
	v_mfma_f32_16x16x32_bf16 v[108:111], v[140:143], v[206:209], v[108:111]
	v_mfma_f32_16x16x32_bf16 v[104:107], v[172:175], v[206:209], v[104:107]
	v_mfma_f32_16x16x32_bf16 v[92:95], v[140:143], v[214:217], v[92:95]
	v_mfma_f32_16x16x32_bf16 v[88:91], v[172:175], v[214:217], v[88:91]
	v_mfma_f32_16x16x32_bf16 v[76:79], v[140:143], v[222:225], v[76:79]
	v_mfma_f32_16x16x32_bf16 v[72:75], v[172:175], v[222:225], v[72:75]
	v_mfma_f32_16x16x32_bf16 v[124:127], v[168:171], v[202:205], v[124:127]
	v_mfma_f32_16x16x32_bf16 v[120:123], v[176:179], v[202:205], v[120:123]
	v_mfma_f32_16x16x32_bf16 v[108:111], v[168:171], v[210:213], v[108:111]
	v_mfma_f32_16x16x32_bf16 v[104:107], v[176:179], v[210:213], v[104:107]
	v_mfma_f32_16x16x32_bf16 v[92:95], v[168:171], v[218:221], v[92:95]
	v_mfma_f32_16x16x32_bf16 v[88:91], v[176:179], v[218:221], v[88:91]
	v_mfma_f32_16x16x32_bf16 v[76:79], v[168:171], v[226:229], v[76:79]
	v_mfma_f32_16x16x32_bf16 v[72:75], v[176:179], v[226:229], v[72:75]
	v_mfma_f32_16x16x32_bf16 v[116:119], v[180:183], v[198:201], v[116:119]
	v_mfma_f32_16x16x32_bf16 v[112:115], v[188:191], v[198:201], v[112:115]
	v_mfma_f32_16x16x32_bf16 v[100:103], v[180:183], v[206:209], v[100:103]
	v_mfma_f32_16x16x32_bf16 v[96:99], v[188:191], v[206:209], v[96:99]
	v_mfma_f32_16x16x32_bf16 v[84:87], v[180:183], v[214:217], v[84:87]
	v_mfma_f32_16x16x32_bf16 v[80:83], v[188:191], v[214:217], v[80:83]
	v_mfma_f32_16x16x32_bf16 v[68:71], v[180:183], v[222:225], v[68:71]
	v_mfma_f32_16x16x32_bf16 v[64:67], v[188:191], v[222:225], v[64:67]
	v_mfma_f32_16x16x32_bf16 v[116:119], v[184:187], v[202:205], v[116:119]
	v_mfma_f32_16x16x32_bf16 v[112:115], v[192:195], v[202:205], v[112:115]
	v_mfma_f32_16x16x32_bf16 v[100:103], v[184:187], v[210:213], v[100:103]
	v_mfma_f32_16x16x32_bf16 v[96:99], v[192:195], v[210:213], v[96:99]
	v_mfma_f32_16x16x32_bf16 v[84:87], v[184:187], v[218:221], v[84:87]
	v_mfma_f32_16x16x32_bf16 v[80:83], v[192:195], v[218:221], v[80:83]
	v_mfma_f32_16x16x32_bf16 v[68:71], v[184:187], v[226:229], v[68:71]
	v_mfma_f32_16x16x32_bf16 v[64:67], v[192:195], v[226:229], v[64:67]
	s_barrier
	s_add_i32 s62, s89, s70
	s_mov_b32 m0, s62
	ds_read_b128 v[198:201], v165 offset:49152
	ds_read_b128 v[202:205], v165 offset:50176
	ds_read_b128 v[206:209], v165 offset:51200
	ds_read_b128 v[210:213], v165 offset:52224
	ds_read_b128 v[214:217], v165 offset:53248
	ds_read_b128 v[218:221], v165 offset:54272
	ds_read_b128 v[222:225], v165 offset:55296
	ds_read_b128 v[226:229], v165 offset:56320
	global_load_lds_dwordx4 v146, s[98:99]
	s_add_i32 m0, s62, 0x2000
	s_add_u32 s34, s34, 0x40080
	s_addc_u32 s35, s35, 0
	s_add_i32 s62, s90, s70
	global_load_lds_dwordx4 v150, s[98:99]
	s_mov_b32 m0, s62
	s_nop 0
	global_load_lds_dwordx4 v146, s[34:35]
	s_add_i32 m0, s62, 0x2000
	s_nop 0
	global_load_lds_dwordx4 v150, s[34:35]
	s_mov_b32 m0, s75
	s_nop 0
	global_load_lds_dwordx4 v144, s[100:101]
	s_mov_b32 m0, s76
	s_nop 0
	global_load_lds_dwordx4 v148, s[100:101]
	s_waitcnt vmcnt(8)
	s_waitcnt lgkmcnt(0)
	s_barrier
	s_waitcnt lgkmcnt(0)
	v_mfma_f32_16x16x32_bf16 v[60:63], v[140:143], v[198:201], v[60:63]
	v_mfma_f32_16x16x32_bf16 v[56:59], v[172:175], v[198:201], v[56:59]
	v_mfma_f32_16x16x32_bf16 v[48:51], v[140:143], v[206:209], v[48:51]
	v_mfma_f32_16x16x32_bf16 v[40:43], v[172:175], v[206:209], v[40:43]
	v_mfma_f32_16x16x32_bf16 v[32:35], v[140:143], v[214:217], v[32:35]
	v_mfma_f32_16x16x32_bf16 v[24:27], v[172:175], v[214:217], v[24:27]
	v_mfma_f32_16x16x32_bf16 v[16:19], v[140:143], v[222:225], v[16:19]
	v_mfma_f32_16x16x32_bf16 v[8:11], v[172:175], v[222:225], v[8:11]
	v_mfma_f32_16x16x32_bf16 v[60:63], v[168:171], v[202:205], v[60:63]
	v_mfma_f32_16x16x32_bf16 v[56:59], v[176:179], v[202:205], v[56:59]
	v_mfma_f32_16x16x32_bf16 v[48:51], v[168:171], v[210:213], v[48:51]
	v_mfma_f32_16x16x32_bf16 v[40:43], v[176:179], v[210:213], v[40:43]
	v_mfma_f32_16x16x32_bf16 v[32:35], v[168:171], v[218:221], v[32:35]
	v_mfma_f32_16x16x32_bf16 v[24:27], v[176:179], v[218:221], v[24:27]
	v_mfma_f32_16x16x32_bf16 v[16:19], v[168:171], v[226:229], v[16:19]
	v_mfma_f32_16x16x32_bf16 v[8:11], v[176:179], v[226:229], v[8:11]
	v_mfma_f32_16x16x32_bf16 v[52:55], v[180:183], v[198:201], v[52:55]
	v_mfma_f32_16x16x32_bf16 v[44:47], v[188:191], v[198:201], v[44:47]
	v_mfma_f32_16x16x32_bf16 v[36:39], v[180:183], v[206:209], v[36:39]
	v_mfma_f32_16x16x32_bf16 v[28:31], v[188:191], v[206:209], v[28:31]
	v_mfma_f32_16x16x32_bf16 v[20:23], v[180:183], v[214:217], v[20:23]
	v_mfma_f32_16x16x32_bf16 v[12:15], v[188:191], v[214:217], v[12:15]
	v_mfma_f32_16x16x32_bf16 v[4:7], v[180:183], v[222:225], v[4:7]
	v_mfma_f32_16x16x32_bf16 v[0:3], v[188:191], v[222:225], v[0:3]
	v_mfma_f32_16x16x32_bf16 v[52:55], v[184:187], v[202:205], v[52:55]
	v_mfma_f32_16x16x32_bf16 v[44:47], v[192:195], v[202:205], v[44:47]
	v_mfma_f32_16x16x32_bf16 v[36:39], v[184:187], v[210:213], v[36:39]
	v_mfma_f32_16x16x32_bf16 v[28:31], v[192:195], v[210:213], v[28:31]
	v_mfma_f32_16x16x32_bf16 v[20:23], v[184:187], v[218:221], v[20:23]
	v_mfma_f32_16x16x32_bf16 v[12:15], v[192:195], v[218:221], v[12:15]
	v_mfma_f32_16x16x32_bf16 v[4:7], v[184:187], v[226:229], v[4:7]
	v_mfma_f32_16x16x32_bf16 v[0:3], v[192:195], v[226:229], v[0:3]
	s_barrier
	s_add_i32 s88, s88, 2
	s_add_u32 s20, s20, 0x100
	s_addc_u32 s21, s21, 0
	s_add_u32 s86, s86, 0x100
	s_addc_u32 s87, s87, 0
	s_cmp_gt_u32 s88, 13
	s_cbranch_scc0 .LBB0_1200
	s_and_b64 vcc, exec, s[38:39]
	s_cbranch_vccz .LBB0_1203
	s_barrier

; #define PG8_STAGE(bufoff, gbase, voff) do { _Pragma("unroll") for (int _i = 0; _i < 2; ++_i) \
;         __builtin_amdgcn_global_load_lds((const unsigned*)((const char*)(gbase) + (voff)[_i]), (PG8_LAS unsigned*)(lds + (bufoff) + ldsw + _i * 8192), 16, 0, 0); } while (0)
; #define PG8_LDA(dst, b, h) do { _Pragma("unroll") for (int m = 0; m < 4; ++m) _Pragma("unroll") for (int k = 0; k < 2; ++k) dst[m][k] = *(const PG8_LAS bf16x8*)(lds + PG8_SA(b, h) + aoff + m * 2048 + k * 1024); } while (0)
; #define PG8_LDB(dst, b, h) do { _Pragma("unroll") for (int n = 0; n < 2; ++n) _Pragma("unroll") for (int k = 0; k < 2; ++k) dst[n][k] = *(const PG8_LAS bf16x8*)(lds + PG8_SB(b, h) + boff + n * 2048 + k * 1024); } while (0)
; #define PG8_MMA(ai, bj, At, Bt) do { __builtin_amdgcn_s_setprio(1); _Pragma("unroll") for (int m = 0; m < 4; ++m) _Pragma("unroll") for (int n = 0; n < 2; ++n) _Pragma("unroll") for (int k = 0; k < 2; ++k) \
;         acc[ai][bj][m][n] = __builtin_amdgcn_mfma_f32_16x16x32_bf16(Bt[n][k], At[m][k], acc[ai][bj][m][n], 0, 0, 0); __builtin_amdgcn_s_setprio(0); } while (0)
; #define PG8_BAR __builtin_amdgcn_s_barrier()
; template <class Epi, class Sched, bool ALIGN_EPI = false, bool SP2 = false>
; __device__ __forceinline__ void gemm_phase(PG8_LAS unsigned char* lds, const Gemm g, const Sched& S, const Epi& E) {
;     ...
;         const bool has_next = S.next(ui + 1, nxt);
;         const char* nA = has_next ? (const char*)g.A + (size_t)nxt.pm * tstep : cA; const char* nB = has_next ? (const char*)g.Bt + (size_t)nxt.pn * tstep : cB;
;         for (int t = 0; t < nt; t += 2) {
;             const bool last = (t == nt - 2);
;             const char* a1 = cA + (size_t)(t + 1) * kstep;
;             const char* a2 = last ? nA : cA + (size_t)(t + 2) * kstep; const char* b2 = last ? nB : cB + (size_t)(t + 2) * kstep;
;             const char* a3 = a2 + kstep; const char* b3 = b2 + kstep;
;             if (last && has_next) S.a_ready(nxt);
;             if constexpr (SP2) {
;             PG8_LDB(B0, 0, 0); PG8_LDB(B1, 0, 1); PG8_SCHED; PG8_LDA(At, 0, 0); PG8_STAGE(PG8_SA(1, 1), a1 + hstep, voffA);
;             PG8_WAIT_V(8); PG8_WAIT_L(0); PG8_BAR; PG8_MMA(0, 0, At, B0); PG8_MMA(0, 1, At, B1); PG8_BAR; PG8_SCHED;
;             PG8_LDA(At, 0, 1); PG8_STAGE(PG8_SB(0, 0), b2, voffB); PG8_STAGE(PG8_SB(0, 1), b2 + hstep, voffB); PG8_STAGE(PG8_SA(0, 0), a2, voffA);
.LBB0_1445:
	s_ashr_i32 s15, s14, 31
	s_lshl_b64 s[16:17], s[14:15], 19
	s_add_u32 s16, s49, s16
	s_addc_u32 s17, s50, s17
	s_and_b64 s[18:19], s[4:5], exec
	s_cselect_b32 s15, s17, s21
	s_cselect_b32 s65, s16, s20
	s_ashr_i32 s13, s12, 31
	s_lshl_b64 s[18:19], s[12:13], 19
	s_add_u32 s18, s36, s18
	s_addc_u32 s19, s37, s19
	s_and_b64 s[44:45], s[4:5], exec
	s_cselect_b32 s13, s19, s39
	s_cselect_b32 s66, s18, s38
	s_add_u32 s20, s20, 0x40080
	s_addc_u32 s21, s21, 0
	s_add_u32 s67, s38, 0x100
	s_addc_u32 s68, s39, 0
	s_mov_b32 s69, -2
	ds_read_b128 v[128:131], v153
	ds_read_b128 v[132:135], v153 offset:1024
	ds_read_b128 v[136:139], v153 offset:2048
	ds_read_b128 v[140:143], v153 offset:3072
	ds_read_b128 v[172:175], v155
	ds_read_b128 v[176:179], v155 offset:1024
	ds_read_b128 v[180:183], v155 offset:2048
	ds_read_b128 v[184:187], v155 offset:3072
	s_add_u32 s38, s20, 0xfffc0080
	s_addc_u32 s39, s21, -1
	s_cmp_eq_u32 s69, 12
	s_cselect_b32 s45, s15, s39
	s_cselect_b32 s44, s65, s38
	s_cselect_b32 s39, s13, s68
	s_cselect_b32 s38, s66, s67
	s_add_i32 m0, s35, 0xc000
	ds_read_b128 v[188:191], v157
	ds_read_b128 v[192:195], v157 offset:1024
	ds_read_b128 v[198:201], v157 offset:2048
	ds_read_b128 v[202:205], v157 offset:3072
	ds_read_b128 v[206:209], v157 offset:4096
	ds_read_b128 v[210:213], v157 offset:5120
	ds_read_b128 v[214:217], v157 offset:6144
	ds_read_b128 v[218:221], v157 offset:7168
	global_load_lds_dwordx4 v162, s[20:21]
	s_add_i32 m0, s35, 0xe000
	s_nop 0
	global_load_lds_dwordx4 v164, s[20:21]
	s_waitcnt vmcnt(8)
	s_waitcnt lgkmcnt(0)
	s_barrier
	s_waitcnt lgkmcnt(0)
	v_mfma_f32_16x16x32_bf16 v[124:127], v[128:131], v[188:191], 0
	v_mfma_f32_16x16x32_bf16 v[120:123], v[136:139], v[188:191], 0
	v_mfma_f32_16x16x32_bf16 v[108:111], v[128:131], v[198:201], 0
	v_mfma_f32_16x16x32_bf16 v[104:107], v[136:139], v[198:201], 0
	v_mfma_f32_16x16x32_bf16 v[96:99], v[128:131], v[206:209], 0
	v_mfma_f32_16x16x32_bf16 v[88:91], v[136:139], v[206:209], 0
	v_mfma_f32_16x16x32_bf16 v[80:83], v[128:131], v[214:217], 0
	v_mfma_f32_16x16x32_bf16 v[72:75], v[136:139], v[214:217], 0
	v_mfma_f32_16x16x32_bf16 v[124:127], v[132:135], v[192:195], v[124:127]
	v_mfma_f32_16x16x32_bf16 v[120:123], v[140:143], v[192:195], v[120:123]
	v_mfma_f32_16x16x32_bf16 v[108:111], v[132:135], v[202:205], v[108:111]
	v_mfma_f32_16x16x32_bf16 v[104:107], v[140:143], v[202:205], v[104:107]
	v_mfma_f32_16x16x32_bf16 v[96:99], v[132:135], v[210:213], v[96:99]
	v_mfma_f32_16x16x32_bf16 v[88:91], v[140:143], v[210:213], v[88:91]
	v_mfma_f32_16x16x32_bf16 v[80:83], v[132:135], v[218:221], v[80:83]
	v_mfma_f32_16x16x32_bf16 v[72:75], v[140:143], v[218:221], v[72:75]
	v_mfma_f32_16x16x32_bf16 v[116:119], v[172:175], v[188:191], 0
	v_mfma_f32_16x16x32_bf16 v[112:115], v[180:183], v[188:191], 0
	v_mfma_f32_16x16x32_bf16 v[100:103], v[172:175], v[198:201], 0
	v_mfma_f32_16x16x32_bf16 v[92:95], v[180:183], v[198:201], 0
	v_mfma_f32_16x16x32_bf16 v[84:87], v[172:175], v[206:209], 0
	v_mfma_f32_16x16x32_bf16 v[76:79], v[180:183], v[206:209], 0
	v_mfma_f32_16x16x32_bf16 v[68:71], v[172:175], v[214:217], 0
	v_mfma_f32_16x16x32_bf16 v[64:67], v[180:183], v[214:217], 0
	v_mfma_f32_16x16x32_bf16 v[116:119], v[176:179], v[192:195], v[116:119]
	v_mfma_f32_16x16x32_bf16 v[112:115], v[184:187], v[192:195], v[112:115]
	v_mfma_f32_16x16x32_bf16 v[100:103], v[176:179], v[202:205], v[100:103]
	v_mfma_f32_16x16x32_bf16 v[92:95], v[184:187], v[202:205], v[92:95]
	v_mfma_f32_16x16x32_bf16 v[84:87], v[176:179], v[210:213], v[84:87]
	v_mfma_f32_16x16x32_bf16 v[76:79], v[184:187], v[210:213], v[76:79]
	v_mfma_f32_16x16x32_bf16 v[68:71], v[176:179], v[218:221], v[68:71]
	v_mfma_f32_16x16x32_bf16 v[64:67], v[184:187], v[218:221], v[64:67]
	s_barrier
	s_add_i32 s70, s60, s51
	s_add_u32 s98, s38, s6
	s_addc_u32 s99, s39, s7
	s_add_u32 s100, s44, s6
	s_addc_u32 s101, s45, s7
	s_mov_b32 m0, s70
	ds_read_b128 v[188:191], v157 offset:16384
	ds_read_b128 v[192:195], v157 offset:17408
	ds_read_b128 v[198:201], v157 offset:18432
	ds_read_b128 v[202:205], v157 offset:19456
	ds_read_b128 v[206:209], v157 offset:20480
	ds_read_b128 v[210:213], v157 offset:21504
	ds_read_b128 v[214:217], v157 offset:22528
	ds_read_b128 v[218:221], v157 offset:23552
	global_load_lds_dwordx4 v146, s[38:39]
	s_add_i32 m0, s70, 0x2000
	s_add_u32 s70, s38, 0x40000
	s_addc_u32 s71, s39, 0
	s_add_i32 s72, s61, s51
	global_load_lds_dwordx4 v150, s[38:39]
	s_mov_b32 m0, s72
	s_nop 0
	global_load_lds_dwordx4 v146, s[70:71]
	s_add_i32 m0, s72, 0x2000
	s_nop 0
	global_load_lds_dwordx4 v150, s[70:71]
	s_mov_b32 m0, s35
	s_nop 0
	global_load_lds_dwordx4 v144, s[44:45]
	s_mov_b32 m0, s52
	s_nop 0
	global_load_lds_dwordx4 v148, s[44:45]
	s_waitcnt vmcnt(8)
	s_waitcnt lgkmcnt(0)
	s_barrier
; #define PG8_STAGE(bufoff, gbase, voff) do { _Pragma("unroll") for (int _i = 0; _i < 2; ++_i) \
;         __builtin_amdgcn_global_load_lds((const unsigned*)((const char*)(gbase) + (voff)[_i]), (PG8_LAS unsigned*)(lds + (bufoff) + ldsw + _i * 8192), 16, 0, 0); } while (0)
; #define PG8_LDA(dst, b, h) do { _Pragma("unroll") for (int m = 0; m < 4; ++m) _Pragma("unroll") for (int k = 0; k < 2; ++k) dst[m][k] = *(const PG8_LAS bf16x8*)(lds + PG8_SA(b, h) + aoff + m * 2048 + k * 1024); } while (0)
; #define PG8_LDB(dst, b, h) do { _Pragma("unroll") for (int n = 0; n < 2; ++n) _Pragma("unroll") for (int k = 0; k < 2; ++k) dst[n][k] = *(const PG8_LAS bf16x8*)(lds + PG8_SB(b, h) + boff + n * 2048 + k * 1024); } while (0)
; #define PG8_MMA(ai, bj, At, Bt) do { __builtin_amdgcn_s_setprio(1); _Pragma("unroll") for (int m = 0; m < 4; ++m) _Pragma("unroll") for (int n = 0; n < 2; ++n) _Pragma("unroll") for (int k = 0; k < 2; ++k) \
;         acc[ai][bj][m][n] = __builtin_amdgcn_mfma_f32_16x16x32_bf16(Bt[n][k], At[m][k], acc[ai][bj][m][n], 0, 0, 0); __builtin_amdgcn_s_setprio(0); } while (0)
; #define PG8_WAIT_V(n) asm volatile("s_waitcnt vmcnt(" #n ")" ::: "memory")
; #define PG8_WAIT_L(n) asm volatile("s_waitcnt lgkmcnt(" #n ")" ::: "memory")
; #define PG8_BAR __builtin_amdgcn_s_barrier()
; #define PG8_SCHED __builtin_amdgcn_sched_barrier(0)
; template <class Epi, class Sched, bool ALIGN_EPI = false, bool SP2 = false>
; __device__ __forceinline__ void gemm_phase(PG8_LAS unsigned char* lds, const Gemm g, const Sched& S, const Epi& E) {
;     ...
;             PG8_WAIT_V(8); PG8_WAIT_L(0); PG8_BAR; PG8_MMA(1, 0, At, B0); PG8_MMA(1, 1, At, B1); PG8_BAR; PG8_SCHED;
;             PG8_LDB(B0, 1, 0); PG8_LDB(B1, 1, 1); PG8_SCHED; PG8_LDA(At, 1, 0); PG8_STAGE(PG8_SA(0, 1), a2 + hstep, voffA);
;             PG8_WAIT_V(8); PG8_WAIT_L(0); PG8_BAR; PG8_MMA(0, 0, At, B0); PG8_MMA(0, 1, At, B1); PG8_BAR; PG8_SCHED;
	s_waitcnt lgkmcnt(0)
	v_mfma_f32_16x16x32_bf16 v[60:63], v[128:131], v[188:191], 0
	v_mfma_f32_16x16x32_bf16 v[56:59], v[136:139], v[188:191], 0
	v_mfma_f32_16x16x32_bf16 v[48:51], v[128:131], v[198:201], 0
	v_mfma_f32_16x16x32_bf16 v[40:43], v[136:139], v[198:201], 0
	v_mfma_f32_16x16x32_bf16 v[32:35], v[128:131], v[206:209], 0
	v_mfma_f32_16x16x32_bf16 v[24:27], v[136:139], v[206:209], 0
	v_mfma_f32_16x16x32_bf16 v[16:19], v[128:131], v[214:217], 0
	v_mfma_f32_16x16x32_bf16 v[8:11], v[136:139], v[214:217], 0
	v_mfma_f32_16x16x32_bf16 v[60:63], v[132:135], v[192:195], v[60:63]
	v_mfma_f32_16x16x32_bf16 v[56:59], v[140:143], v[192:195], v[56:59]
	v_mfma_f32_16x16x32_bf16 v[48:51], v[132:135], v[202:205], v[48:51]
	v_mfma_f32_16x16x32_bf16 v[40:43], v[140:143], v[202:205], v[40:43]
	v_mfma_f32_16x16x32_bf16 v[32:35], v[132:135], v[210:213], v[32:35]
	v_mfma_f32_16x16x32_bf16 v[24:27], v[140:143], v[210:213], v[24:27]
	v_mfma_f32_16x16x32_bf16 v[16:19], v[132:135], v[218:221], v[16:19]
	v_mfma_f32_16x16x32_bf16 v[8:11], v[140:143], v[218:221], v[8:11]
	v_mfma_f32_16x16x32_bf16 v[52:55], v[172:175], v[188:191], 0
	v_mfma_f32_16x16x32_bf16 v[44:47], v[180:183], v[188:191], 0
	v_mfma_f32_16x16x32_bf16 v[36:39], v[172:175], v[198:201], 0
	v_mfma_f32_16x16x32_bf16 v[28:31], v[180:183], v[198:201], 0
	v_mfma_f32_16x16x32_bf16 v[20:23], v[172:175], v[206:209], 0
	v_mfma_f32_16x16x32_bf16 v[12:15], v[180:183], v[206:209], 0
	v_mfma_f32_16x16x32_bf16 v[4:7], v[172:175], v[214:217], 0
	v_mfma_f32_16x16x32_bf16 v[0:3], v[180:183], v[214:217], 0
	v_mfma_f32_16x16x32_bf16 v[52:55], v[176:179], v[192:195], v[52:55]
	v_mfma_f32_16x16x32_bf16 v[44:47], v[184:187], v[192:195], v[44:47]
	v_mfma_f32_16x16x32_bf16 v[36:39], v[176:179], v[202:205], v[36:39]
	v_mfma_f32_16x16x32_bf16 v[28:31], v[184:187], v[202:205], v[28:31]
	v_mfma_f32_16x16x32_bf16 v[20:23], v[176:179], v[210:213], v[20:23]
	v_mfma_f32_16x16x32_bf16 v[12:15], v[184:187], v[210:213], v[12:15]
	v_mfma_f32_16x16x32_bf16 v[4:7], v[176:179], v[218:221], v[4:7]
	v_mfma_f32_16x16x32_bf16 v[0:3], v[184:187], v[218:221], v[0:3]
	s_barrier
	s_add_i32 s70, 0, 0x18000
	s_add_i32 s71, 0, 0x1c000
	v_add_u32_e32 v140, s70, v170
	v_add_u32_e32 v159, s71, v170
	ds_read_b128 v[128:131], v140
	ds_read_b128 v[132:135], v140 offset:1024
	ds_read_b128 v[136:139], v140 offset:2048
	ds_read_b128 v[140:143], v140 offset:3072
	ds_read_b128 v[172:175], v159
	ds_read_b128 v[176:179], v159 offset:1024
	ds_read_b128 v[180:183], v159 offset:2048
	ds_read_b128 v[184:187], v159 offset:3072
	s_add_u32 s44, s44, 0x40000
	s_addc_u32 s45, s45, 0
	s_mov_b32 m0, s53
	ds_read_b128 v[188:191], v157 offset:32768
	ds_read_b128 v[192:195], v157 offset:33792
	ds_read_b128 v[198:201], v157 offset:34816
	ds_read_b128 v[202:205], v157 offset:35840
	ds_read_b128 v[206:209], v157 offset:36864
	ds_read_b128 v[210:213], v157 offset:37888
	ds_read_b128 v[214:217], v157 offset:38912
	ds_read_b128 v[218:221], v157 offset:39936
	global_load_lds_dwordx4 v144, s[44:45]
	s_mov_b32 m0, s54
	s_nop 0
	global_load_lds_dwordx4 v148, s[44:45]
	s_waitcnt vmcnt(8)
	s_waitcnt lgkmcnt(0)
	s_barrier
	s_waitcnt lgkmcnt(0)
	v_mfma_f32_16x16x32_bf16 v[124:127], v[128:131], v[188:191], v[124:127]
	v_mfma_f32_16x16x32_bf16 v[120:123], v[136:139], v[188:191], v[120:123]
	v_mfma_f32_16x16x32_bf16 v[108:111], v[128:131], v[198:201], v[108:111]
	v_mfma_f32_16x16x32_bf16 v[104:107], v[136:139], v[198:201], v[104:107]
	v_mfma_f32_16x16x32_bf16 v[96:99], v[128:131], v[206:209], v[96:99]
	v_mfma_f32_16x16x32_bf16 v[88:91], v[136:139], v[206:209], v[88:91]
	v_mfma_f32_16x16x32_bf16 v[80:83], v[128:131], v[214:217], v[80:83]
	v_mfma_f32_16x16x32_bf16 v[72:75], v[136:139], v[214:217], v[72:75]
	v_mfma_f32_16x16x32_bf16 v[124:127], v[132:135], v[192:195], v[124:127]
	v_mfma_f32_16x16x32_bf16 v[120:123], v[140:143], v[192:195], v[120:123]
	v_mfma_f32_16x16x32_bf16 v[108:111], v[132:135], v[202:205], v[108:111]
	v_mfma_f32_16x16x32_bf16 v[104:107], v[140:143], v[202:205], v[104:107]
	v_mfma_f32_16x16x32_bf16 v[96:99], v[132:135], v[210:213], v[96:99]
	v_mfma_f32_16x16x32_bf16 v[88:91], v[140:143], v[210:213], v[88:91]
	v_mfma_f32_16x16x32_bf16 v[80:83], v[132:135], v[218:221], v[80:83]
	v_mfma_f32_16x16x32_bf16 v[72:75], v[140:143], v[218:221], v[72:75]
	v_mfma_f32_16x16x32_bf16 v[116:119], v[172:175], v[188:191], v[116:119]
	v_mfma_f32_16x16x32_bf16 v[112:115], v[180:183], v[188:191], v[112:115]
	v_mfma_f32_16x16x32_bf16 v[100:103], v[172:175], v[198:201], v[100:103]
	v_mfma_f32_16x16x32_bf16 v[92:95], v[180:183], v[198:201], v[92:95]
	v_mfma_f32_16x16x32_bf16 v[84:87], v[172:175], v[206:209], v[84:87]
	v_mfma_f32_16x16x32_bf16 v[76:79], v[180:183], v[206:209], v[76:79]
	v_mfma_f32_16x16x32_bf16 v[68:71], v[172:175], v[214:217], v[68:71]
	v_mfma_f32_16x16x32_bf16 v[64:67], v[180:183], v[214:217], v[64:67]
	v_mfma_f32_16x16x32_bf16 v[116:119], v[176:179], v[192:195], v[116:119]
	v_mfma_f32_16x16x32_bf16 v[112:115], v[184:187], v[192:195], v[112:115]
	v_mfma_f32_16x16x32_bf16 v[100:103], v[176:179], v[202:205], v[100:103]
	v_mfma_f32_16x16x32_bf16 v[92:95], v[184:187], v[202:205], v[92:95]
	v_mfma_f32_16x16x32_bf16 v[84:87], v[176:179], v[210:213], v[84:87]
	v_mfma_f32_16x16x32_bf16 v[76:79], v[184:187], v[210:213], v[76:79]
	v_mfma_f32_16x16x32_bf16 v[68:71], v[176:179], v[218:221], v[68:71]
	v_mfma_f32_16x16x32_bf16 v[64:67], v[184:187], v[218:221], v[64:67]
	s_barrier
; #define PG8_STAGE(bufoff, gbase, voff) do { _Pragma("unroll") for (int _i = 0; _i < 2; ++_i) \
;         __builtin_amdgcn_global_load_lds((const unsigned*)((const char*)(gbase) + (voff)[_i]), (PG8_LAS unsigned*)(lds + (bufoff) + ldsw + _i * 8192), 16, 0, 0); } while (0)
; #define PG8_LDA(dst, b, h) do { _Pragma("unroll") for (int m = 0; m < 4; ++m) _Pragma("unroll") for (int k = 0; k < 2; ++k) dst[m][k] = *(const PG8_LAS bf16x8*)(lds + PG8_SA(b, h) + aoff + m * 2048 + k * 1024); } while (0)
; #define PG8_LDB(dst, b, h) do { _Pragma("unroll") for (int n = 0; n < 2; ++n) _Pragma("unroll") for (int k = 0; k < 2; ++k) dst[n][k] = *(const PG8_LAS bf16x8*)(lds + PG8_SB(b, h) + boff + n * 2048 + k * 1024); } while (0)
; #define PG8_MMA(ai, bj, At, Bt) do { __builtin_amdgcn_s_setprio(1); _Pragma("unroll") for (int m = 0; m < 4; ++m) _Pragma("unroll") for (int n = 0; n < 2; ++n) _Pragma("unroll") for (int k = 0; k < 2; ++k) \
;         acc[ai][bj][m][n] = __builtin_amdgcn_mfma_f32_16x16x32_bf16(Bt[n][k], At[m][k], acc[ai][bj][m][n], 0, 0, 0); __builtin_amdgcn_s_setprio(0); } while (0)
; #define PG8_WAIT_V(n) asm volatile("s_waitcnt vmcnt(" #n ")" ::: "memory")
; template <class Epi, class Sched, bool ALIGN_EPI = false, bool SP2 = false>
; __device__ __forceinline__ void gemm_phase(PG8_LAS unsigned char* lds, const Gemm g, const Sched& S, const Epi& E) {
;     ...
;             PG8_LDB(B0, 0, 0); PG8_LDB(B1, 0, 1); PG8_SCHED; PG8_LDA(At, 0, 0); PG8_STAGE(PG8_SA(1, 1), a1 + hstep, voffA);
;             PG8_WAIT_V(8); PG8_WAIT_L(0); PG8_BAR; PG8_MMA(0, 0, At, B0); PG8_MMA(0, 1, At, B1); PG8_BAR; PG8_SCHED;
;             PG8_LDA(At, 0, 1); PG8_STAGE(PG8_SB(0, 0), b2, voffB); PG8_STAGE(PG8_SB(0, 1), b2 + hstep, voffB); PG8_STAGE(PG8_SA(0, 0), a2, voffA);
;             PG8_WAIT_V(8); PG8_WAIT_L(0); PG8_BAR; PG8_MMA(1, 0, At, B0); PG8_MMA(1, 1, At, B1); PG8_BAR; PG8_SCHED;
;             PG8_LDB(B0, 1, 0); PG8_LDB(B1, 1, 1); PG8_SCHED; PG8_LDA(At, 1, 0); PG8_STAGE(PG8_SA(0, 1), a2 + hstep, voffA);
;             PG8_WAIT_V(8); PG8_WAIT_L(0); PG8_BAR; PG8_MMA(0, 0, At, B0); PG8_MMA(0, 1, At, B1); PG8_BAR; PG8_SCHED;
;             PG8_LDA(At, 1, 1); PG8_STAGE(PG8_SB(1, 0), b3, voffB); PG8_STAGE(PG8_SB(1, 1), b3 + hstep, voffB); PG8_STAGE(PG8_SA(1, 0), a3, voffA);
;             PG8_WAIT_V(8); PG8_WAIT_L(0); PG8_BAR; PG8_MMA(1, 0, At, B0); PG8_MMA(1, 1, At, B1); PG8_BAR; PG8_SCHED;
	s_add_i32 s44, s70, s51
	s_mov_b32 m0, s44
	ds_read_b128 v[188:191], v157 offset:49152
	ds_read_b128 v[192:195], v157 offset:50176
	ds_read_b128 v[198:201], v157 offset:51200
	ds_read_b128 v[202:205], v157 offset:52224
	ds_read_b128 v[206:209], v157 offset:53248
	ds_read_b128 v[210:213], v157 offset:54272
	ds_read_b128 v[214:217], v157 offset:55296
	ds_read_b128 v[218:221], v157 offset:56320
	global_load_lds_dwordx4 v146, s[98:99]
	s_add_i32 m0, s44, 0x2000
	s_add_u32 s38, s38, 0x40080
	s_addc_u32 s39, s39, 0
	s_add_i32 s44, s71, s51
	global_load_lds_dwordx4 v150, s[98:99]
	s_mov_b32 m0, s44
	s_nop 0
	global_load_lds_dwordx4 v146, s[38:39]
	s_add_i32 m0, s44, 0x2000
	s_nop 0
	global_load_lds_dwordx4 v150, s[38:39]
	s_mov_b32 m0, s58
	s_nop 0
	global_load_lds_dwordx4 v144, s[100:101]
	s_mov_b32 m0, s59
	s_nop 0
	global_load_lds_dwordx4 v148, s[100:101]
	s_waitcnt vmcnt(8)
	s_waitcnt lgkmcnt(0)
	s_barrier
	s_waitcnt lgkmcnt(0)
	v_mfma_f32_16x16x32_bf16 v[60:63], v[128:131], v[188:191], v[60:63]
	v_mfma_f32_16x16x32_bf16 v[56:59], v[136:139], v[188:191], v[56:59]
	v_mfma_f32_16x16x32_bf16 v[48:51], v[128:131], v[198:201], v[48:51]
	v_mfma_f32_16x16x32_bf16 v[40:43], v[136:139], v[198:201], v[40:43]
	v_mfma_f32_16x16x32_bf16 v[32:35], v[128:131], v[206:209], v[32:35]
	v_mfma_f32_16x16x32_bf16 v[24:27], v[136:139], v[206:209], v[24:27]
	v_mfma_f32_16x16x32_bf16 v[16:19], v[128:131], v[214:217], v[16:19]
	v_mfma_f32_16x16x32_bf16 v[8:11], v[136:139], v[214:217], v[8:11]
	v_mfma_f32_16x16x32_bf16 v[60:63], v[132:135], v[192:195], v[60:63]
	v_mfma_f32_16x16x32_bf16 v[56:59], v[140:143], v[192:195], v[56:59]
	v_mfma_f32_16x16x32_bf16 v[48:51], v[132:135], v[202:205], v[48:51]
	v_mfma_f32_16x16x32_bf16 v[40:43], v[140:143], v[202:205], v[40:43]
	v_mfma_f32_16x16x32_bf16 v[32:35], v[132:135], v[210:213], v[32:35]
	v_mfma_f32_16x16x32_bf16 v[24:27], v[140:143], v[210:213], v[24:27]
	v_mfma_f32_16x16x32_bf16 v[16:19], v[132:135], v[218:221], v[16:19]
	v_mfma_f32_16x16x32_bf16 v[8:11], v[140:143], v[218:221], v[8:11]
	v_mfma_f32_16x16x32_bf16 v[52:55], v[172:175], v[188:191], v[52:55]
	v_mfma_f32_16x16x32_bf16 v[44:47], v[180:183], v[188:191], v[44:47]
	v_mfma_f32_16x16x32_bf16 v[36:39], v[172:175], v[198:201], v[36:39]
	v_mfma_f32_16x16x32_bf16 v[28:31], v[180:183], v[198:201], v[28:31]
	v_mfma_f32_16x16x32_bf16 v[20:23], v[172:175], v[206:209], v[20:23]
	v_mfma_f32_16x16x32_bf16 v[12:15], v[180:183], v[206:209], v[12:15]
	v_mfma_f32_16x16x32_bf16 v[4:7], v[172:175], v[214:217], v[4:7]
	v_mfma_f32_16x16x32_bf16 v[0:3], v[180:183], v[214:217], v[0:3]
	v_mfma_f32_16x16x32_bf16 v[52:55], v[176:179], v[192:195], v[52:55]
	v_mfma_f32_16x16x32_bf16 v[44:47], v[184:187], v[192:195], v[44:47]
	v_mfma_f32_16x16x32_bf16 v[36:39], v[176:179], v[202:205], v[36:39]
	v_mfma_f32_16x16x32_bf16 v[28:31], v[184:187], v[202:205], v[28:31]
	v_mfma_f32_16x16x32_bf16 v[20:23], v[176:179], v[210:213], v[20:23]
	v_mfma_f32_16x16x32_bf16 v[12:15], v[184:187], v[210:213], v[12:15]
	v_mfma_f32_16x16x32_bf16 v[4:7], v[176:179], v[218:221], v[4:7]
	v_mfma_f32_16x16x32_bf16 v[0:3], v[184:187], v[218:221], v[0:3]
	s_barrier
	s_add_i32 s69, s69, 2
	s_add_u32 s20, s20, 0x100
	s_addc_u32 s21, s21, 0
	s_add_u32 s67, s67, 0x100
	s_addc_u32 s68, s68, 0
	s_cmp_gt_u32 s69, 13
.LBB0_1446:
	ds_read_b128 v[128:131], v153
	ds_read_b128 v[132:135], v153 offset:1024
	ds_read_b128 v[136:139], v153 offset:2048
	ds_read_b128 v[140:143], v153 offset:3072
	ds_read_b128 v[172:175], v155
	ds_read_b128 v[176:179], v155 offset:1024
	ds_read_b128 v[180:183], v155 offset:2048
	ds_read_b128 v[184:187], v155 offset:3072
	s_add_u32 s38, s20, 0xfffc0080
	s_addc_u32 s39, s21, -1
	s_cmp_eq_u32 s69, 12
	s_cselect_b32 s45, s15, s39
	s_cselect_b32 s44, s65, s38
	s_cselect_b32 s39, s13, s68
	s_cselect_b32 s38, s66, s67
	s_add_i32 m0, s35, 0xc000
	ds_read_b128 v[188:191], v157
	ds_read_b128 v[192:195], v157 offset:1024
	ds_read_b128 v[198:201], v157 offset:2048
	ds_read_b128 v[202:205], v157 offset:3072
	ds_read_b128 v[206:209], v157 offset:4096
	ds_read_b128 v[210:213], v157 offset:5120
	ds_read_b128 v[214:217], v157 offset:6144
	ds_read_b128 v[218:221], v157 offset:7168
	global_load_lds_dwordx4 v162, s[20:21]
	s_add_i32 m0, s35, 0xe000
	s_nop 0
	global_load_lds_dwordx4 v164, s[20:21]
	s_waitcnt vmcnt(8)
	s_waitcnt lgkmcnt(0)
	s_barrier
	s_waitcnt lgkmcnt(0)
	v_mfma_f32_16x16x32_bf16 v[124:127], v[128:131], v[188:191], v[124:127]
	v_mfma_f32_16x16x32_bf16 v[120:123], v[136:139], v[188:191], v[120:123]
	v_mfma_f32_16x16x32_bf16 v[108:111], v[128:131], v[198:201], v[108:111]
	v_mfma_f32_16x16x32_bf16 v[104:107], v[136:139], v[198:201], v[104:107]
	v_mfma_f32_16x16x32_bf16 v[96:99], v[128:131], v[206:209], v[96:99]
	v_mfma_f32_16x16x32_bf16 v[88:91], v[136:139], v[206:209], v[88:91]
	v_mfma_f32_16x16x32_bf16 v[80:83], v[128:131], v[214:217], v[80:83]
	v_mfma_f32_16x16x32_bf16 v[72:75], v[136:139], v[214:217], v[72:75]
	v_mfma_f32_16x16x32_bf16 v[124:127], v[132:135], v[192:195], v[124:127]
	v_mfma_f32_16x16x32_bf16 v[120:123], v[140:143], v[192:195], v[120:123]
	v_mfma_f32_16x16x32_bf16 v[108:111], v[132:135], v[202:205], v[108:111]
	v_mfma_f32_16x16x32_bf16 v[104:107], v[140:143], v[202:205], v[104:107]
	v_mfma_f32_16x16x32_bf16 v[96:99], v[132:135], v[210:213], v[96:99]
	v_mfma_f32_16x16x32_bf16 v[88:91], v[140:143], v[210:213], v[88:91]
	v_mfma_f32_16x16x32_bf16 v[80:83], v[132:135], v[218:221], v[80:83]
	v_mfma_f32_16x16x32_bf16 v[72:75], v[140:143], v[218:221], v[72:75]
	v_mfma_f32_16x16x32_bf16 v[116:119], v[172:175], v[188:191], v[116:119]
	v_mfma_f32_16x16x32_bf16 v[112:115], v[180:183], v[188:191], v[112:115]
	v_mfma_f32_16x16x32_bf16 v[100:103], v[172:175], v[198:201], v[100:103]
	v_mfma_f32_16x16x32_bf16 v[92:95], v[180:183], v[198:201], v[92:95]
	v_mfma_f32_16x16x32_bf16 v[84:87], v[172:175], v[206:209], v[84:87]
	v_mfma_f32_16x16x32_bf16 v[76:79], v[180:183], v[206:209], v[76:79]
	v_mfma_f32_16x16x32_bf16 v[68:71], v[172:175], v[214:217], v[68:71]
	v_mfma_f32_16x16x32_bf16 v[64:67], v[180:183], v[214:217], v[64:67]
	v_mfma_f32_16x16x32_bf16 v[116:119], v[176:179], v[192:195], v[116:119]
	v_mfma_f32_16x16x32_bf16 v[112:115], v[184:187], v[192:195], v[112:115]
	v_mfma_f32_16x16x32_bf16 v[100:103], v[176:179], v[202:205], v[100:103]
	v_mfma_f32_16x16x32_bf16 v[92:95], v[184:187], v[202:205], v[92:95]
	v_mfma_f32_16x16x32_bf16 v[84:87], v[176:179], v[210:213], v[84:87]
	v_mfma_f32_16x16x32_bf16 v[76:79], v[184:187], v[210:213], v[76:79]
	v_mfma_f32_16x16x32_bf16 v[68:71], v[176:179], v[218:221], v[68:71]
	v_mfma_f32_16x16x32_bf16 v[64:67], v[184:187], v[218:221], v[64:67]
	s_barrier
; #define PG8_STAGE(bufoff, gbase, voff) do { _Pragma("unroll") for (int _i = 0; _i < 2; ++_i) \
;         __builtin_amdgcn_global_load_lds((const unsigned*)((const char*)(gbase) + (voff)[_i]), (PG8_LAS unsigned*)(lds + (bufoff) + ldsw + _i * 8192), 16, 0, 0); } while (0)
; #define PG8_LDA(dst, b, h) do { _Pragma("unroll") for (int m = 0; m < 4; ++m) _Pragma("unroll") for (int k = 0; k < 2; ++k) dst[m][k] = *(const PG8_LAS bf16x8*)(lds + PG8_SA(b, h) + aoff + m * 2048 + k * 1024); } while (0)
; #define PG8_LDB(dst, b, h) do { _Pragma("unroll") for (int n = 0; n < 2; ++n) _Pragma("unroll") for (int k = 0; k < 2; ++k) dst[n][k] = *(const PG8_LAS bf16x8*)(lds + PG8_SB(b, h) + boff + n * 2048 + k * 1024); } while (0)
; #define PG8_MMA(ai, bj, At, Bt) do { __builtin_amdgcn_s_setprio(1); _Pragma("unroll") for (int m = 0; m < 4; ++m) _Pragma("unroll") for (int n = 0; n < 2; ++n) _Pragma("unroll") for (int k = 0; k < 2; ++k) \
;         acc[ai][bj][m][n] = __builtin_amdgcn_mfma_f32_16x16x32_bf16(Bt[n][k], At[m][k], acc[ai][bj][m][n], 0, 0, 0); __builtin_amdgcn_s_setprio(0); } while (0)
; #define PG8_WAIT_V(n) asm volatile("s_waitcnt vmcnt(" #n ")" ::: "memory")
; #define PG8_WAIT_L(n) asm volatile("s_waitcnt lgkmcnt(" #n ")" ::: "memory")
; #define PG8_BAR __builtin_amdgcn_s_barrier()
; #define PG8_SCHED __builtin_amdgcn_sched_barrier(0)
; template <class Epi, class Sched, bool ALIGN_EPI = false, bool SP2 = false>
; __device__ __forceinline__ void gemm_phase(PG8_LAS unsigned char* lds, const Gemm g, const Sched& S, const Epi& E) {
;     ...
;             PG8_LDA(At, 0, 1); PG8_STAGE(PG8_SB(0, 0), b2, voffB); PG8_STAGE(PG8_SB(0, 1), b2 + hstep, voffB); PG8_STAGE(PG8_SA(0, 0), a2, voffA);
;             PG8_WAIT_V(8); PG8_WAIT_L(0); PG8_BAR; PG8_MMA(1, 0, At, B0); PG8_MMA(1, 1, At, B1); PG8_BAR; PG8_SCHED;
;             PG8_LDB(B0, 1, 0); PG8_LDB(B1, 1, 1); PG8_SCHED; PG8_LDA(At, 1, 0); PG8_STAGE(PG8_SA(0, 1), a2 + hstep, voffA);
;             PG8_WAIT_V(8); PG8_WAIT_L(0); PG8_BAR; PG8_MMA(0, 0, At, B0); PG8_MMA(0, 1, At, B1); PG8_BAR; PG8_SCHED;
	s_add_i32 s70, s60, s51
	s_add_u32 s98, s38, s6
	s_addc_u32 s99, s39, s7
	s_add_u32 s100, s44, s6
	s_addc_u32 s101, s45, s7
	s_mov_b32 m0, s70
	ds_read_b128 v[188:191], v157 offset:16384
	ds_read_b128 v[192:195], v157 offset:17408
	ds_read_b128 v[198:201], v157 offset:18432
	ds_read_b128 v[202:205], v157 offset:19456
	ds_read_b128 v[206:209], v157 offset:20480
	ds_read_b128 v[210:213], v157 offset:21504
	ds_read_b128 v[214:217], v157 offset:22528
	ds_read_b128 v[218:221], v157 offset:23552
	global_load_lds_dwordx4 v146, s[38:39]
	s_add_i32 m0, s70, 0x2000
	s_add_u32 s70, s38, 0x40000
	s_addc_u32 s71, s39, 0
	s_add_i32 s72, s61, s51
	global_load_lds_dwordx4 v150, s[38:39]
	s_mov_b32 m0, s72
	s_nop 0
	global_load_lds_dwordx4 v146, s[70:71]
	s_add_i32 m0, s72, 0x2000
	s_nop 0
	global_load_lds_dwordx4 v150, s[70:71]
	s_mov_b32 m0, s35
	s_nop 0
	global_load_lds_dwordx4 v144, s[44:45]
	s_mov_b32 m0, s52
	s_nop 0
	global_load_lds_dwordx4 v148, s[44:45]
	s_waitcnt vmcnt(8)
	s_waitcnt lgkmcnt(0)
	s_barrier
	s_waitcnt lgkmcnt(0)
	v_mfma_f32_16x16x32_bf16 v[60:63], v[128:131], v[188:191], v[60:63]
	v_mfma_f32_16x16x32_bf16 v[56:59], v[136:139], v[188:191], v[56:59]
	v_mfma_f32_16x16x32_bf16 v[48:51], v[128:131], v[198:201], v[48:51]
	v_mfma_f32_16x16x32_bf16 v[40:43], v[136:139], v[198:201], v[40:43]
	v_mfma_f32_16x16x32_bf16 v[32:35], v[128:131], v[206:209], v[32:35]
	v_mfma_f32_16x16x32_bf16 v[24:27], v[136:139], v[206:209], v[24:27]
	v_mfma_f32_16x16x32_bf16 v[16:19], v[128:131], v[214:217], v[16:19]
	v_mfma_f32_16x16x32_bf16 v[8:11], v[136:139], v[214:217], v[8:11]
	v_mfma_f32_16x16x32_bf16 v[60:63], v[132:135], v[192:195], v[60:63]
	v_mfma_f32_16x16x32_bf16 v[56:59], v[140:143], v[192:195], v[56:59]
	v_mfma_f32_16x16x32_bf16 v[48:51], v[132:135], v[202:205], v[48:51]
	v_mfma_f32_16x16x32_bf16 v[40:43], v[140:143], v[202:205], v[40:43]
	v_mfma_f32_16x16x32_bf16 v[32:35], v[132:135], v[210:213], v[32:35]
	v_mfma_f32_16x16x32_bf16 v[24:27], v[140:143], v[210:213], v[24:27]
	v_mfma_f32_16x16x32_bf16 v[16:19], v[132:135], v[218:221], v[16:19]
	v_mfma_f32_16x16x32_bf16 v[8:11], v[140:143], v[218:221], v[8:11]
	v_mfma_f32_16x16x32_bf16 v[52:55], v[172:175], v[188:191], v[52:55]
	v_mfma_f32_16x16x32_bf16 v[44:47], v[180:183], v[188:191], v[44:47]
	v_mfma_f32_16x16x32_bf16 v[36:39], v[172:175], v[198:201], v[36:39]
	v_mfma_f32_16x16x32_bf16 v[28:31], v[180:183], v[198:201], v[28:31]
	v_mfma_f32_16x16x32_bf16 v[20:23], v[172:175], v[206:209], v[20:23]
	v_mfma_f32_16x16x32_bf16 v[12:15], v[180:183], v[206:209], v[12:15]
	v_mfma_f32_16x16x32_bf16 v[4:7], v[172:175], v[214:217], v[4:7]
	v_mfma_f32_16x16x32_bf16 v[0:3], v[180:183], v[214:217], v[0:3]
	v_mfma_f32_16x16x32_bf16 v[52:55], v[176:179], v[192:195], v[52:55]
	v_mfma_f32_16x16x32_bf16 v[44:47], v[184:187], v[192:195], v[44:47]
	v_mfma_f32_16x16x32_bf16 v[36:39], v[176:179], v[202:205], v[36:39]
	v_mfma_f32_16x16x32_bf16 v[28:31], v[184:187], v[202:205], v[28:31]
	v_mfma_f32_16x16x32_bf16 v[20:23], v[176:179], v[210:213], v[20:23]
	v_mfma_f32_16x16x32_bf16 v[12:15], v[184:187], v[210:213], v[12:15]
	v_mfma_f32_16x16x32_bf16 v[4:7], v[176:179], v[218:221], v[4:7]
	v_mfma_f32_16x16x32_bf16 v[0:3], v[184:187], v[218:221], v[0:3]
	s_barrier
	s_add_i32 s70, 0, 0x18000
	s_add_i32 s71, 0, 0x1c000
	v_add_u32_e32 v140, s70, v170
	v_add_u32_e32 v159, s71, v170
	ds_read_b128 v[128:131], v140
	ds_read_b128 v[132:135], v140 offset:1024
	ds_read_b128 v[136:139], v140 offset:2048
	ds_read_b128 v[140:143], v140 offset:3072
	ds_read_b128 v[172:175], v159
	ds_read_b128 v[176:179], v159 offset:1024
	ds_read_b128 v[180:183], v159 offset:2048
	ds_read_b128 v[184:187], v159 offset:3072
	s_add_u32 s44, s44, 0x40000
	s_addc_u32 s45, s45, 0
	s_mov_b32 m0, s53
	ds_read_b128 v[188:191], v157 offset:32768
	ds_read_b128 v[192:195], v157 offset:33792
	ds_read_b128 v[198:201], v157 offset:34816
	ds_read_b128 v[202:205], v157 offset:35840
	ds_read_b128 v[206:209], v157 offset:36864
	ds_read_b128 v[210:213], v157 offset:37888
	ds_read_b128 v[214:217], v157 offset:38912
	ds_read_b128 v[218:221], v157 offset:39936
	global_load_lds_dwordx4 v144, s[44:45]
	s_mov_b32 m0, s54
	s_nop 0
	global_load_lds_dwordx4 v148, s[44:45]
	s_waitcnt vmcnt(8)
	s_waitcnt lgkmcnt(0)
	s_barrier
; #define PG8_STAGE(bufoff, gbase, voff) do { _Pragma("unroll") for (int _i = 0; _i < 2; ++_i) \
;         __builtin_amdgcn_global_load_lds((const unsigned*)((const char*)(gbase) + (voff)[_i]), (PG8_LAS unsigned*)(lds + (bufoff) + ldsw + _i * 8192), 16, 0, 0); } while (0)
; #define PG8_LDA(dst, b, h) do { _Pragma("unroll") for (int m = 0; m < 4; ++m) _Pragma("unroll") for (int k = 0; k < 2; ++k) dst[m][k] = *(const PG8_LAS bf16x8*)(lds + PG8_SA(b, h) + aoff + m * 2048 + k * 1024); } while (0)
; #define PG8_MMA(ai, bj, At, Bt) do { __builtin_amdgcn_s_setprio(1); _Pragma("unroll") for (int m = 0; m < 4; ++m) _Pragma("unroll") for (int n = 0; n < 2; ++n) _Pragma("unroll") for (int k = 0; k < 2; ++k) \
;         acc[ai][bj][m][n] = __builtin_amdgcn_mfma_f32_16x16x32_bf16(Bt[n][k], At[m][k], acc[ai][bj][m][n], 0, 0, 0); __builtin_amdgcn_s_setprio(0); } while (0)
; #define PG8_WAIT_V(n) asm volatile("s_waitcnt vmcnt(" #n ")" ::: "memory")
; #define PG8_WAIT_L(n) asm volatile("s_waitcnt lgkmcnt(" #n ")" ::: "memory")
; #define PG8_BAR __builtin_amdgcn_s_barrier()
; #define PG8_SCHED __builtin_amdgcn_sched_barrier(0)
; template <class Epi, class Sched, bool ALIGN_EPI = false, bool SP2 = false>
; __device__ __forceinline__ void gemm_phase(PG8_LAS unsigned char* lds, const Gemm g, const Sched& S, const Epi& E) {
;     ...
;             PG8_WAIT_V(8); PG8_WAIT_L(0); PG8_BAR; PG8_MMA(0, 0, At, B0); PG8_MMA(0, 1, At, B1); PG8_BAR; PG8_SCHED;
;             PG8_LDA(At, 1, 1); PG8_STAGE(PG8_SB(1, 0), b3, voffB); PG8_STAGE(PG8_SB(1, 1), b3 + hstep, voffB); PG8_STAGE(PG8_SA(1, 0), a3, voffA);
;             PG8_WAIT_V(8); PG8_WAIT_L(0); PG8_BAR; PG8_MMA(1, 0, At, B0); PG8_MMA(1, 1, At, B1); PG8_BAR; PG8_SCHED;
	s_waitcnt lgkmcnt(0)
	v_mfma_f32_16x16x32_bf16 v[124:127], v[128:131], v[188:191], v[124:127]
	v_mfma_f32_16x16x32_bf16 v[120:123], v[136:139], v[188:191], v[120:123]
	v_mfma_f32_16x16x32_bf16 v[108:111], v[128:131], v[198:201], v[108:111]
	v_mfma_f32_16x16x32_bf16 v[104:107], v[136:139], v[198:201], v[104:107]
	v_mfma_f32_16x16x32_bf16 v[96:99], v[128:131], v[206:209], v[96:99]
	v_mfma_f32_16x16x32_bf16 v[88:91], v[136:139], v[206:209], v[88:91]
	v_mfma_f32_16x16x32_bf16 v[80:83], v[128:131], v[214:217], v[80:83]
	v_mfma_f32_16x16x32_bf16 v[72:75], v[136:139], v[214:217], v[72:75]
	v_mfma_f32_16x16x32_bf16 v[124:127], v[132:135], v[192:195], v[124:127]
	v_mfma_f32_16x16x32_bf16 v[120:123], v[140:143], v[192:195], v[120:123]
	v_mfma_f32_16x16x32_bf16 v[108:111], v[132:135], v[202:205], v[108:111]
	v_mfma_f32_16x16x32_bf16 v[104:107], v[140:143], v[202:205], v[104:107]
	v_mfma_f32_16x16x32_bf16 v[96:99], v[132:135], v[210:213], v[96:99]
	v_mfma_f32_16x16x32_bf16 v[88:91], v[140:143], v[210:213], v[88:91]
	v_mfma_f32_16x16x32_bf16 v[80:83], v[132:135], v[218:221], v[80:83]
	v_mfma_f32_16x16x32_bf16 v[72:75], v[140:143], v[218:221], v[72:75]
	v_mfma_f32_16x16x32_bf16 v[116:119], v[172:175], v[188:191], v[116:119]
	v_mfma_f32_16x16x32_bf16 v[112:115], v[180:183], v[188:191], v[112:115]
	v_mfma_f32_16x16x32_bf16 v[100:103], v[172:175], v[198:201], v[100:103]
	v_mfma_f32_16x16x32_bf16 v[92:95], v[180:183], v[198:201], v[92:95]
	v_mfma_f32_16x16x32_bf16 v[84:87], v[172:175], v[206:209], v[84:87]
	v_mfma_f32_16x16x32_bf16 v[76:79], v[180:183], v[206:209], v[76:79]
	v_mfma_f32_16x16x32_bf16 v[68:71], v[172:175], v[214:217], v[68:71]
	v_mfma_f32_16x16x32_bf16 v[64:67], v[180:183], v[214:217], v[64:67]
	v_mfma_f32_16x16x32_bf16 v[116:119], v[176:179], v[192:195], v[116:119]
	v_mfma_f32_16x16x32_bf16 v[112:115], v[184:187], v[192:195], v[112:115]
	v_mfma_f32_16x16x32_bf16 v[100:103], v[176:179], v[202:205], v[100:103]
	v_mfma_f32_16x16x32_bf16 v[92:95], v[184:187], v[202:205], v[92:95]
	v_mfma_f32_16x16x32_bf16 v[84:87], v[176:179], v[210:213], v[84:87]
	v_mfma_f32_16x16x32_bf16 v[76:79], v[184:187], v[210:213], v[76:79]
	v_mfma_f32_16x16x32_bf16 v[68:71], v[176:179], v[218:221], v[68:71]
	v_mfma_f32_16x16x32_bf16 v[64:67], v[184:187], v[218:221], v[64:67]
	s_barrier
	s_add_i32 s44, s70, s51
	s_mov_b32 m0, s44
	ds_read_b128 v[188:191], v157 offset:49152
	ds_read_b128 v[192:195], v157 offset:50176
	ds_read_b128 v[198:201], v157 offset:51200
	ds_read_b128 v[202:205], v157 offset:52224
	ds_read_b128 v[206:209], v157 offset:53248
	ds_read_b128 v[210:213], v157 offset:54272
	ds_read_b128 v[214:217], v157 offset:55296
	ds_read_b128 v[218:221], v157 offset:56320
	global_load_lds_dwordx4 v146, s[98:99]
	s_add_i32 m0, s44, 0x2000
	s_add_u32 s38, s38, 0x40080
	s_addc_u32 s39, s39, 0
	s_add_i32 s44, s71, s51
	global_load_lds_dwordx4 v150, s[98:99]
	s_mov_b32 m0, s44
	s_nop 0
	global_load_lds_dwordx4 v146, s[38:39]
	s_add_i32 m0, s44, 0x2000
	s_nop 0
	global_load_lds_dwordx4 v150, s[38:39]
	s_mov_b32 m0, s58
	s_nop 0
	global_load_lds_dwordx4 v144, s[100:101]
	s_mov_b32 m0, s59
	s_nop 0
	global_load_lds_dwordx4 v148, s[100:101]
	s_waitcnt vmcnt(8)
	s_waitcnt lgkmcnt(0)
	s_barrier
	s_waitcnt lgkmcnt(0)
	v_mfma_f32_16x16x32_bf16 v[60:63], v[128:131], v[188:191], v[60:63]
	v_mfma_f32_16x16x32_bf16 v[56:59], v[136:139], v[188:191], v[56:59]
	v_mfma_f32_16x16x32_bf16 v[48:51], v[128:131], v[198:201], v[48:51]
	v_mfma_f32_16x16x32_bf16 v[40:43], v[136:139], v[198:201], v[40:43]
	v_mfma_f32_16x16x32_bf16 v[32:35], v[128:131], v[206:209], v[32:35]
	v_mfma_f32_16x16x32_bf16 v[24:27], v[136:139], v[206:209], v[24:27]
	v_mfma_f32_16x16x32_bf16 v[16:19], v[128:131], v[214:217], v[16:19]
	v_mfma_f32_16x16x32_bf16 v[8:11], v[136:139], v[214:217], v[8:11]
	v_mfma_f32_16x16x32_bf16 v[60:63], v[132:135], v[192:195], v[60:63]
	v_mfma_f32_16x16x32_bf16 v[56:59], v[140:143], v[192:195], v[56:59]
	v_mfma_f32_16x16x32_bf16 v[48:51], v[132:135], v[202:205], v[48:51]
	v_mfma_f32_16x16x32_bf16 v[40:43], v[140:143], v[202:205], v[40:43]
	v_mfma_f32_16x16x32_bf16 v[32:35], v[132:135], v[210:213], v[32:35]
	v_mfma_f32_16x16x32_bf16 v[24:27], v[140:143], v[210:213], v[24:27]
	v_mfma_f32_16x16x32_bf16 v[16:19], v[132:135], v[218:221], v[16:19]
	v_mfma_f32_16x16x32_bf16 v[8:11], v[140:143], v[218:221], v[8:11]
	v_mfma_f32_16x16x32_bf16 v[52:55], v[172:175], v[188:191], v[52:55]
	v_mfma_f32_16x16x32_bf16 v[44:47], v[180:183], v[188:191], v[44:47]
	v_mfma_f32_16x16x32_bf16 v[36:39], v[172:175], v[198:201], v[36:39]
	v_mfma_f32_16x16x32_bf16 v[28:31], v[180:183], v[198:201], v[28:31]
	v_mfma_f32_16x16x32_bf16 v[20:23], v[172:175], v[206:209], v[20:23]
	v_mfma_f32_16x16x32_bf16 v[12:15], v[180:183], v[206:209], v[12:15]
	v_mfma_f32_16x16x32_bf16 v[4:7], v[172:175], v[214:217], v[4:7]
	v_mfma_f32_16x16x32_bf16 v[0:3], v[180:183], v[214:217], v[0:3]
	v_mfma_f32_16x16x32_bf16 v[52:55], v[176:179], v[192:195], v[52:55]
	v_mfma_f32_16x16x32_bf16 v[44:47], v[184:187], v[192:195], v[44:47]
	v_mfma_f32_16x16x32_bf16 v[36:39], v[176:179], v[202:205], v[36:39]
	v_mfma_f32_16x16x32_bf16 v[28:31], v[184:187], v[202:205], v[28:31]
	v_mfma_f32_16x16x32_bf16 v[20:23], v[176:179], v[210:213], v[20:23]
	v_mfma_f32_16x16x32_bf16 v[12:15], v[184:187], v[210:213], v[12:15]
	v_mfma_f32_16x16x32_bf16 v[4:7], v[176:179], v[218:221], v[4:7]
	v_mfma_f32_16x16x32_bf16 v[0:3], v[184:187], v[218:221], v[0:3]
	s_barrier
	s_add_i32 s69, s69, 2
	s_add_u32 s20, s20, 0x100
	s_addc_u32 s21, s21, 0
	s_add_u32 s67, s67, 0x100
	s_addc_u32 s68, s68, 0
	s_cmp_gt_u32 s69, 13
	s_cbranch_scc0 .LBB0_1446
	s_and_b64 vcc, exec, s[8:9]
	s_cbranch_vccz .LBB0_1449
	s_barrier

; #define PG8_STAGE(bufoff, gbase, voff) do { _Pragma("unroll") for (int _i = 0; _i < 2; ++_i) \
;         __builtin_amdgcn_global_load_lds((const unsigned*)((const char*)(gbase) + (voff)[_i]), (PG8_LAS unsigned*)(lds + (bufoff) + ldsw + _i * 8192), 16, 0, 0); } while (0)
; #define PG8_LDA(dst, b, h) do { _Pragma("unroll") for (int m = 0; m < 4; ++m) _Pragma("unroll") for (int k = 0; k < 2; ++k) dst[m][k] = *(const PG8_LAS bf16x8*)(lds + PG8_SA(b, h) + aoff + m * 2048 + k * 1024); } while (0)
; #define PG8_LDB(dst, b, h) do { _Pragma("unroll") for (int n = 0; n < 2; ++n) _Pragma("unroll") for (int k = 0; k < 2; ++k) dst[n][k] = *(const PG8_LAS bf16x8*)(lds + PG8_SB(b, h) + boff + n * 2048 + k * 1024); } while (0)
; #define PG8_MMA(ai, bj, At, Bt) do { __builtin_amdgcn_s_setprio(1); _Pragma("unroll") for (int m = 0; m < 4; ++m) _Pragma("unroll") for (int n = 0; n < 2; ++n) _Pragma("unroll") for (int k = 0; k < 2; ++k) \
;         acc[ai][bj][m][n] = __builtin_amdgcn_mfma_f32_16x16x32_bf16(Bt[n][k], At[m][k], acc[ai][bj][m][n], 0, 0, 0); __builtin_amdgcn_s_setprio(0); } while (0)
; #define PG8_BAR __builtin_amdgcn_s_barrier()
; template <class Epi, class Sched, bool ALIGN_EPI = false, bool SP2 = false>
; __device__ __forceinline__ void gemm_phase(PG8_LAS unsigned char* lds, const Gemm g, const Sched& S, const Epi& E) {
;     ...
;         const bool has_next = S.next(ui + 1, nxt);
;         const char* nA = has_next ? (const char*)g.A + (size_t)nxt.pm * tstep : cA; const char* nB = has_next ? (const char*)g.Bt + (size_t)nxt.pn * tstep : cB;
;         for (int t = 0; t < nt; t += 2) {
;             const bool last = (t == nt - 2);
;             const char* a1 = cA + (size_t)(t + 1) * kstep;
;             const char* a2 = last ? nA : cA + (size_t)(t + 2) * kstep; const char* b2 = last ? nB : cB + (size_t)(t + 2) * kstep;
;             const char* a3 = a2 + kstep; const char* b3 = b2 + kstep;
;             if (last && has_next) S.a_ready(nxt);
;             if constexpr (SP2) {
;             PG8_LDB(B0, 0, 0); PG8_LDB(B1, 0, 1); PG8_SCHED; PG8_LDA(At, 0, 0); PG8_STAGE(PG8_SA(1, 1), a1 + hstep, voffA);
;             PG8_WAIT_V(8); PG8_WAIT_L(0); PG8_BAR; PG8_MMA(0, 0, At, B0); PG8_MMA(0, 1, At, B1); PG8_BAR; PG8_SCHED;
;             PG8_LDA(At, 0, 1); PG8_STAGE(PG8_SB(0, 0), b2, voffB); PG8_STAGE(PG8_SB(0, 1), b2 + hstep, voffB); PG8_STAGE(PG8_SA(0, 0), a2, voffA);
.LBB0_1634:
	s_ashr_i32 s47, s46, 31
	s_lshl_b64 s[48:49], s[46:47], 19
	s_add_u32 s48, s18, s48
	s_addc_u32 s49, s19, s49
	s_and_b64 s[50:51], s[6:7], exec
	s_cselect_b32 s35, s49, s21
	s_cselect_b32 s47, s48, s20
	s_ashr_i32 s45, s44, 31
	s_lshl_b64 s[50:51], s[44:45], 19
	s_add_u32 s50, s3, s50
	s_addc_u32 s51, s33, s51
	s_and_b64 s[56:57], s[6:7], exec
	s_cselect_b32 s45, s51, s55
	s_cselect_b32 s73, s50, s54
	s_add_u32 s20, s20, 0x40080
	s_addc_u32 s21, s21, 0
	s_add_u32 s74, s54, 0x100
	s_addc_u32 s75, s55, 0
	s_mov_b32 s76, -2
	s_waitcnt lgkmcnt(0)
	ds_read_b128 v[96:99], v223
	ds_read_b128 v[108:111], v223 offset:1024
	ds_read_b128 v[120:123], v223 offset:2048
	ds_read_b128 v[128:131], v223 offset:3072
	ds_read_b128 v[144:147], v224
	ds_read_b128 v[148:151], v224 offset:1024
	ds_read_b128 v[152:155], v224 offset:2048
	ds_read_b128 v[156:159], v224 offset:3072
	s_add_u32 s54, s20, 0xfffc0080
	s_addc_u32 s55, s21, -1
	s_cmp_eq_u32 s76, 12
	s_cselect_b32 s57, s35, s55
	s_cselect_b32 s56, s47, s54
	s_cselect_b32 s55, s45, s75
	s_cselect_b32 s54, s73, s74
	s_add_i32 m0, s53, 0xc000
	ds_read_b128 v[160:163], v225
	ds_read_b128 v[164:167], v225 offset:1024
	ds_read_b128 v[168:171], v225 offset:2048
	ds_read_b128 v[172:175], v225 offset:3072
	ds_read_b128 v[176:179], v225 offset:4096
	ds_read_b128 v[180:183], v225 offset:5120
	ds_read_b128 v[202:205], v225 offset:6144
	ds_read_b128 v[206:209], v225 offset:7168
	global_load_lds_dwordx4 v192, s[20:21]
	s_add_i32 m0, s53, 0xe000
	s_nop 0
	global_load_lds_dwordx4 v194, s[20:21]
	s_waitcnt vmcnt(8)
	s_waitcnt lgkmcnt(0)
	s_barrier
	s_waitcnt lgkmcnt(0)
	v_mfma_f32_16x16x32_bf16 v[140:143], v[96:99], v[160:163], 0
	v_mfma_f32_16x16x32_bf16 v[136:139], v[120:123], v[160:163], 0
	v_mfma_f32_16x16x32_bf16 v[116:119], v[96:99], v[168:171], 0
	v_mfma_f32_16x16x32_bf16 v[112:115], v[120:123], v[168:171], 0
	v_mfma_f32_16x16x32_bf16 v[92:95], v[96:99], v[176:179], 0
	v_mfma_f32_16x16x32_bf16 v[88:91], v[120:123], v[176:179], 0
	v_mfma_f32_16x16x32_bf16 v[76:79], v[96:99], v[202:205], 0
	v_mfma_f32_16x16x32_bf16 v[72:75], v[120:123], v[202:205], 0
	v_mfma_f32_16x16x32_bf16 v[140:143], v[108:111], v[164:167], v[140:143]
	v_mfma_f32_16x16x32_bf16 v[136:139], v[128:131], v[164:167], v[136:139]
	v_mfma_f32_16x16x32_bf16 v[116:119], v[108:111], v[172:175], v[116:119]
	v_mfma_f32_16x16x32_bf16 v[112:115], v[128:131], v[172:175], v[112:115]
	v_mfma_f32_16x16x32_bf16 v[92:95], v[108:111], v[180:183], v[92:95]
	v_mfma_f32_16x16x32_bf16 v[88:91], v[128:131], v[180:183], v[88:91]
	v_mfma_f32_16x16x32_bf16 v[76:79], v[108:111], v[206:209], v[76:79]
	v_mfma_f32_16x16x32_bf16 v[72:75], v[128:131], v[206:209], v[72:75]
	v_mfma_f32_16x16x32_bf16 v[132:135], v[144:147], v[160:163], 0
	v_mfma_f32_16x16x32_bf16 v[124:127], v[152:155], v[160:163], 0
	v_mfma_f32_16x16x32_bf16 v[104:107], v[144:147], v[168:171], 0
	v_mfma_f32_16x16x32_bf16 v[100:103], v[152:155], v[168:171], 0
	v_mfma_f32_16x16x32_bf16 v[84:87], v[144:147], v[176:179], 0
	v_mfma_f32_16x16x32_bf16 v[80:83], v[152:155], v[176:179], 0
	v_mfma_f32_16x16x32_bf16 v[68:71], v[144:147], v[202:205], 0
	v_mfma_f32_16x16x32_bf16 v[64:67], v[152:155], v[202:205], 0
	v_mfma_f32_16x16x32_bf16 v[132:135], v[148:151], v[164:167], v[132:135]
	v_mfma_f32_16x16x32_bf16 v[124:127], v[156:159], v[164:167], v[124:127]
	v_mfma_f32_16x16x32_bf16 v[104:107], v[148:151], v[172:175], v[104:107]
	v_mfma_f32_16x16x32_bf16 v[100:103], v[156:159], v[172:175], v[100:103]
	v_mfma_f32_16x16x32_bf16 v[84:87], v[148:151], v[180:183], v[84:87]
	v_mfma_f32_16x16x32_bf16 v[80:83], v[156:159], v[180:183], v[80:83]
	v_mfma_f32_16x16x32_bf16 v[68:71], v[148:151], v[206:209], v[68:71]
	v_mfma_f32_16x16x32_bf16 v[64:67], v[156:159], v[206:209], v[64:67]
	s_barrier
	s_add_i32 s77, s71, s58
	s_add_u32 s98, s54, s12
	s_addc_u32 s99, s55, s13
	s_add_u32 s100, s56, s12
	s_addc_u32 s101, s57, s13
	s_mov_b32 m0, s77
	ds_read_b128 v[160:163], v225 offset:16384
	ds_read_b128 v[164:167], v225 offset:17408
	ds_read_b128 v[168:171], v225 offset:18432
	ds_read_b128 v[172:175], v225 offset:19456
	ds_read_b128 v[176:179], v225 offset:20480
	ds_read_b128 v[180:183], v225 offset:21504
	ds_read_b128 v[202:205], v225 offset:22528
	ds_read_b128 v[206:209], v225 offset:23552
	global_load_lds_dwordx4 v186, s[54:55]
	s_add_i32 m0, s77, 0x2000
	s_add_u32 s78, s54, 0x40000
	s_addc_u32 s79, s55, 0
	s_add_i32 s77, s72, s58
	global_load_lds_dwordx4 v190, s[54:55]
	s_mov_b32 m0, s77
	s_nop 0
	global_load_lds_dwordx4 v186, s[78:79]
	s_add_i32 m0, s77, 0x2000
	s_nop 0
	global_load_lds_dwordx4 v190, s[78:79]
	s_mov_b32 m0, s53
	s_nop 0
	global_load_lds_dwordx4 v184, s[56:57]
	s_mov_b32 m0, s59
	s_nop 0
	global_load_lds_dwordx4 v188, s[56:57]
	s_waitcnt vmcnt(8)
	s_waitcnt lgkmcnt(0)
	s_barrier
; #define PG8_STAGE(bufoff, gbase, voff) do { _Pragma("unroll") for (int _i = 0; _i < 2; ++_i) \
;         __builtin_amdgcn_global_load_lds((const unsigned*)((const char*)(gbase) + (voff)[_i]), (PG8_LAS unsigned*)(lds + (bufoff) + ldsw + _i * 8192), 16, 0, 0); } while (0)
; #define PG8_LDA(dst, b, h) do { _Pragma("unroll") for (int m = 0; m < 4; ++m) _Pragma("unroll") for (int k = 0; k < 2; ++k) dst[m][k] = *(const PG8_LAS bf16x8*)(lds + PG8_SA(b, h) + aoff + m * 2048 + k * 1024); } while (0)
; #define PG8_LDB(dst, b, h) do { _Pragma("unroll") for (int n = 0; n < 2; ++n) _Pragma("unroll") for (int k = 0; k < 2; ++k) dst[n][k] = *(const PG8_LAS bf16x8*)(lds + PG8_SB(b, h) + boff + n * 2048 + k * 1024); } while (0)
; #define PG8_MMA(ai, bj, At, Bt) do { __builtin_amdgcn_s_setprio(1); _Pragma("unroll") for (int m = 0; m < 4; ++m) _Pragma("unroll") for (int n = 0; n < 2; ++n) _Pragma("unroll") for (int k = 0; k < 2; ++k) \
;         acc[ai][bj][m][n] = __builtin_amdgcn_mfma_f32_16x16x32_bf16(Bt[n][k], At[m][k], acc[ai][bj][m][n], 0, 0, 0); __builtin_amdgcn_s_setprio(0); } while (0)
; #define PG8_WAIT_V(n) asm volatile("s_waitcnt vmcnt(" #n ")" ::: "memory")
; #define PG8_WAIT_L(n) asm volatile("s_waitcnt lgkmcnt(" #n ")" ::: "memory")
; #define PG8_BAR __builtin_amdgcn_s_barrier()
; #define PG8_SCHED __builtin_amdgcn_sched_barrier(0)
; template <class Epi, class Sched, bool ALIGN_EPI = false, bool SP2 = false>
; __device__ __forceinline__ void gemm_phase(PG8_LAS unsigned char* lds, const Gemm g, const Sched& S, const Epi& E) {
;     ...
;             PG8_WAIT_V(8); PG8_WAIT_L(0); PG8_BAR; PG8_MMA(1, 0, At, B0); PG8_MMA(1, 1, At, B1); PG8_BAR; PG8_SCHED;
;             PG8_LDB(B0, 1, 0); PG8_LDB(B1, 1, 1); PG8_SCHED; PG8_LDA(At, 1, 0); PG8_STAGE(PG8_SA(0, 1), a2 + hstep, voffA);
;             PG8_WAIT_V(8); PG8_WAIT_L(0); PG8_BAR; PG8_MMA(0, 0, At, B0); PG8_MMA(0, 1, At, B1); PG8_BAR; PG8_SCHED;
	s_waitcnt lgkmcnt(0)
	v_mfma_f32_16x16x32_bf16 v[60:63], v[96:99], v[160:163], 0
	v_mfma_f32_16x16x32_bf16 v[56:59], v[120:123], v[160:163], 0
	v_mfma_f32_16x16x32_bf16 v[44:47], v[96:99], v[168:171], 0
	v_mfma_f32_16x16x32_bf16 v[40:43], v[120:123], v[168:171], 0
	v_mfma_f32_16x16x32_bf16 v[28:31], v[96:99], v[176:179], 0
	v_mfma_f32_16x16x32_bf16 v[24:27], v[120:123], v[176:179], 0
	v_mfma_f32_16x16x32_bf16 v[12:15], v[96:99], v[202:205], 0
	v_mfma_f32_16x16x32_bf16 v[8:11], v[120:123], v[202:205], 0
	v_mfma_f32_16x16x32_bf16 v[60:63], v[108:111], v[164:167], v[60:63]
	v_mfma_f32_16x16x32_bf16 v[56:59], v[128:131], v[164:167], v[56:59]
	v_mfma_f32_16x16x32_bf16 v[44:47], v[108:111], v[172:175], v[44:47]
	v_mfma_f32_16x16x32_bf16 v[40:43], v[128:131], v[172:175], v[40:43]
	v_mfma_f32_16x16x32_bf16 v[28:31], v[108:111], v[180:183], v[28:31]
	v_mfma_f32_16x16x32_bf16 v[24:27], v[128:131], v[180:183], v[24:27]
	v_mfma_f32_16x16x32_bf16 v[12:15], v[108:111], v[206:209], v[12:15]
	v_mfma_f32_16x16x32_bf16 v[8:11], v[128:131], v[206:209], v[8:11]
	v_mfma_f32_16x16x32_bf16 v[52:55], v[144:147], v[160:163], 0
	v_mfma_f32_16x16x32_bf16 v[48:51], v[152:155], v[160:163], 0
	v_mfma_f32_16x16x32_bf16 v[36:39], v[144:147], v[168:171], 0
	v_mfma_f32_16x16x32_bf16 v[32:35], v[152:155], v[168:171], 0
	v_mfma_f32_16x16x32_bf16 v[20:23], v[144:147], v[176:179], 0
	v_mfma_f32_16x16x32_bf16 v[16:19], v[152:155], v[176:179], 0
	v_mfma_f32_16x16x32_bf16 v[4:7], v[144:147], v[202:205], 0
	v_mfma_f32_16x16x32_bf16 v[0:3], v[152:155], v[202:205], 0
	v_mfma_f32_16x16x32_bf16 v[52:55], v[148:151], v[164:167], v[52:55]
	v_mfma_f32_16x16x32_bf16 v[48:51], v[156:159], v[164:167], v[48:51]
	v_mfma_f32_16x16x32_bf16 v[36:39], v[148:151], v[172:175], v[36:39]
	v_mfma_f32_16x16x32_bf16 v[32:35], v[156:159], v[172:175], v[32:35]
	v_mfma_f32_16x16x32_bf16 v[20:23], v[148:151], v[180:183], v[20:23]
	v_mfma_f32_16x16x32_bf16 v[16:19], v[156:159], v[180:183], v[16:19]
	v_mfma_f32_16x16x32_bf16 v[4:7], v[148:151], v[206:209], v[4:7]
	v_mfma_f32_16x16x32_bf16 v[0:3], v[156:159], v[206:209], v[0:3]
	s_barrier
	s_add_i32 s77, 0, 0x18000
	s_add_i32 s78, 0, 0x1c000
	v_add_u32_e32 v128, s77, v221
	v_add_u32_e32 v156, s78, v221
	ds_read_b128 v[96:99], v128
	ds_read_b128 v[108:111], v128 offset:1024
	ds_read_b128 v[120:123], v128 offset:2048
	ds_read_b128 v[128:131], v128 offset:3072
	ds_read_b128 v[144:147], v156
	ds_read_b128 v[148:151], v156 offset:1024
	ds_read_b128 v[152:155], v156 offset:2048
	ds_read_b128 v[156:159], v156 offset:3072
	s_add_u32 s56, s56, 0x40000
	s_addc_u32 s57, s57, 0
	s_mov_b32 m0, s60
	ds_read_b128 v[160:163], v225 offset:32768
	ds_read_b128 v[164:167], v225 offset:33792
	ds_read_b128 v[168:171], v225 offset:34816
	ds_read_b128 v[172:175], v225 offset:35840
	ds_read_b128 v[176:179], v225 offset:36864
	ds_read_b128 v[180:183], v225 offset:37888
	ds_read_b128 v[202:205], v225 offset:38912
	ds_read_b128 v[206:209], v225 offset:39936
	global_load_lds_dwordx4 v184, s[56:57]
	s_mov_b32 m0, s61
	s_nop 0
	global_load_lds_dwordx4 v188, s[56:57]
	s_waitcnt vmcnt(8)
	s_waitcnt lgkmcnt(0)
	s_barrier
	s_waitcnt lgkmcnt(0)
	v_mfma_f32_16x16x32_bf16 v[140:143], v[96:99], v[160:163], v[140:143]
	v_mfma_f32_16x16x32_bf16 v[136:139], v[120:123], v[160:163], v[136:139]
	v_mfma_f32_16x16x32_bf16 v[116:119], v[96:99], v[168:171], v[116:119]
	v_mfma_f32_16x16x32_bf16 v[112:115], v[120:123], v[168:171], v[112:115]
	v_mfma_f32_16x16x32_bf16 v[92:95], v[96:99], v[176:179], v[92:95]
	v_mfma_f32_16x16x32_bf16 v[88:91], v[120:123], v[176:179], v[88:91]
	v_mfma_f32_16x16x32_bf16 v[76:79], v[96:99], v[202:205], v[76:79]
	v_mfma_f32_16x16x32_bf16 v[72:75], v[120:123], v[202:205], v[72:75]
	v_mfma_f32_16x16x32_bf16 v[140:143], v[108:111], v[164:167], v[140:143]
	v_mfma_f32_16x16x32_bf16 v[136:139], v[128:131], v[164:167], v[136:139]
	v_mfma_f32_16x16x32_bf16 v[116:119], v[108:111], v[172:175], v[116:119]
	v_mfma_f32_16x16x32_bf16 v[112:115], v[128:131], v[172:175], v[112:115]
	v_mfma_f32_16x16x32_bf16 v[92:95], v[108:111], v[180:183], v[92:95]
	v_mfma_f32_16x16x32_bf16 v[88:91], v[128:131], v[180:183], v[88:91]
	v_mfma_f32_16x16x32_bf16 v[76:79], v[108:111], v[206:209], v[76:79]
	v_mfma_f32_16x16x32_bf16 v[72:75], v[128:131], v[206:209], v[72:75]
	v_mfma_f32_16x16x32_bf16 v[132:135], v[144:147], v[160:163], v[132:135]
	v_mfma_f32_16x16x32_bf16 v[124:127], v[152:155], v[160:163], v[124:127]
	v_mfma_f32_16x16x32_bf16 v[104:107], v[144:147], v[168:171], v[104:107]
	v_mfma_f32_16x16x32_bf16 v[100:103], v[152:155], v[168:171], v[100:103]
	v_mfma_f32_16x16x32_bf16 v[84:87], v[144:147], v[176:179], v[84:87]
	v_mfma_f32_16x16x32_bf16 v[80:83], v[152:155], v[176:179], v[80:83]
	v_mfma_f32_16x16x32_bf16 v[68:71], v[144:147], v[202:205], v[68:71]
	v_mfma_f32_16x16x32_bf16 v[64:67], v[152:155], v[202:205], v[64:67]
	v_mfma_f32_16x16x32_bf16 v[132:135], v[148:151], v[164:167], v[132:135]
	v_mfma_f32_16x16x32_bf16 v[124:127], v[156:159], v[164:167], v[124:127]
	v_mfma_f32_16x16x32_bf16 v[104:107], v[148:151], v[172:175], v[104:107]
	v_mfma_f32_16x16x32_bf16 v[100:103], v[156:159], v[172:175], v[100:103]
	v_mfma_f32_16x16x32_bf16 v[84:87], v[148:151], v[180:183], v[84:87]
	v_mfma_f32_16x16x32_bf16 v[80:83], v[156:159], v[180:183], v[80:83]
	v_mfma_f32_16x16x32_bf16 v[68:71], v[148:151], v[206:209], v[68:71]
	v_mfma_f32_16x16x32_bf16 v[64:67], v[156:159], v[206:209], v[64:67]
	s_barrier
; #define PG8_STAGE(bufoff, gbase, voff) do { _Pragma("unroll") for (int _i = 0; _i < 2; ++_i) \
;         __builtin_amdgcn_global_load_lds((const unsigned*)((const char*)(gbase) + (voff)[_i]), (PG8_LAS unsigned*)(lds + (bufoff) + ldsw + _i * 8192), 16, 0, 0); } while (0)
; #define PG8_LDA(dst, b, h) do { _Pragma("unroll") for (int m = 0; m < 4; ++m) _Pragma("unroll") for (int k = 0; k < 2; ++k) dst[m][k] = *(const PG8_LAS bf16x8*)(lds + PG8_SA(b, h) + aoff + m * 2048 + k * 1024); } while (0)
; #define PG8_MMA(ai, bj, At, Bt) do { __builtin_amdgcn_s_setprio(1); _Pragma("unroll") for (int m = 0; m < 4; ++m) _Pragma("unroll") for (int n = 0; n < 2; ++n) _Pragma("unroll") for (int k = 0; k < 2; ++k) \
;         acc[ai][bj][m][n] = __builtin_amdgcn_mfma_f32_16x16x32_bf16(Bt[n][k], At[m][k], acc[ai][bj][m][n], 0, 0, 0); __builtin_amdgcn_s_setprio(0); } while (0)
; #define PG8_WAIT_V(n) asm volatile("s_waitcnt vmcnt(" #n ")" ::: "memory")
; #define PG8_WAIT_L(n) asm volatile("s_waitcnt lgkmcnt(" #n ")" ::: "memory")
; #define PG8_BAR __builtin_amdgcn_s_barrier()
; #define PG8_SCHED __builtin_amdgcn_sched_barrier(0)
; template <class Epi, class Sched, bool ALIGN_EPI = false, bool SP2 = false>
; __device__ __forceinline__ void gemm_phase(PG8_LAS unsigned char* lds, const Gemm g, const Sched& S, const Epi& E) {
;     ...
;             PG8_LDA(At, 1, 1); PG8_STAGE(PG8_SB(1, 0), b3, voffB); PG8_STAGE(PG8_SB(1, 1), b3 + hstep, voffB); PG8_STAGE(PG8_SA(1, 0), a3, voffA);
;             PG8_WAIT_V(8); PG8_WAIT_L(0); PG8_BAR; PG8_MMA(1, 0, At, B0); PG8_MMA(1, 1, At, B1); PG8_BAR; PG8_SCHED;
	s_add_i32 s56, s77, s58
	s_mov_b32 m0, s56
	ds_read_b128 v[160:163], v225 offset:49152
	ds_read_b128 v[164:167], v225 offset:50176
	ds_read_b128 v[168:171], v225 offset:51200
	ds_read_b128 v[172:175], v225 offset:52224
	ds_read_b128 v[176:179], v225 offset:53248
	ds_read_b128 v[180:183], v225 offset:54272
	ds_read_b128 v[202:205], v225 offset:55296
	ds_read_b128 v[206:209], v225 offset:56320
	global_load_lds_dwordx4 v186, s[98:99]
	s_add_i32 m0, s56, 0x2000
	s_add_u32 s54, s54, 0x40080
	s_addc_u32 s55, s55, 0
	s_add_i32 s56, s78, s58
	global_load_lds_dwordx4 v190, s[98:99]
	s_mov_b32 m0, s56
	s_nop 0
	global_load_lds_dwordx4 v186, s[54:55]
	s_add_i32 m0, s56, 0x2000
	s_nop 0
	global_load_lds_dwordx4 v190, s[54:55]
	s_mov_b32 m0, s66
	s_nop 0
	global_load_lds_dwordx4 v184, s[100:101]
	s_mov_b32 m0, s67
	s_nop 0
	global_load_lds_dwordx4 v188, s[100:101]
	s_waitcnt vmcnt(8)
	s_waitcnt lgkmcnt(0)
	s_barrier
	s_waitcnt lgkmcnt(0)
	v_mfma_f32_16x16x32_bf16 v[60:63], v[96:99], v[160:163], v[60:63]
	v_mfma_f32_16x16x32_bf16 v[56:59], v[120:123], v[160:163], v[56:59]
	v_mfma_f32_16x16x32_bf16 v[44:47], v[96:99], v[168:171], v[44:47]
	v_mfma_f32_16x16x32_bf16 v[40:43], v[120:123], v[168:171], v[40:43]
	v_mfma_f32_16x16x32_bf16 v[28:31], v[96:99], v[176:179], v[28:31]
	v_mfma_f32_16x16x32_bf16 v[24:27], v[120:123], v[176:179], v[24:27]
	v_mfma_f32_16x16x32_bf16 v[12:15], v[96:99], v[202:205], v[12:15]
	v_mfma_f32_16x16x32_bf16 v[8:11], v[120:123], v[202:205], v[8:11]
	v_mfma_f32_16x16x32_bf16 v[60:63], v[108:111], v[164:167], v[60:63]
	v_mfma_f32_16x16x32_bf16 v[56:59], v[128:131], v[164:167], v[56:59]
	v_mfma_f32_16x16x32_bf16 v[44:47], v[108:111], v[172:175], v[44:47]
	v_mfma_f32_16x16x32_bf16 v[40:43], v[128:131], v[172:175], v[40:43]
	v_mfma_f32_16x16x32_bf16 v[28:31], v[108:111], v[180:183], v[28:31]
	v_mfma_f32_16x16x32_bf16 v[24:27], v[128:131], v[180:183], v[24:27]
	v_mfma_f32_16x16x32_bf16 v[12:15], v[108:111], v[206:209], v[12:15]
	v_mfma_f32_16x16x32_bf16 v[8:11], v[128:131], v[206:209], v[8:11]
	v_mfma_f32_16x16x32_bf16 v[52:55], v[144:147], v[160:163], v[52:55]
	v_mfma_f32_16x16x32_bf16 v[48:51], v[152:155], v[160:163], v[48:51]
	v_mfma_f32_16x16x32_bf16 v[36:39], v[144:147], v[168:171], v[36:39]
	v_mfma_f32_16x16x32_bf16 v[32:35], v[152:155], v[168:171], v[32:35]
	v_mfma_f32_16x16x32_bf16 v[20:23], v[144:147], v[176:179], v[20:23]
	v_mfma_f32_16x16x32_bf16 v[16:19], v[152:155], v[176:179], v[16:19]
	v_mfma_f32_16x16x32_bf16 v[4:7], v[144:147], v[202:205], v[4:7]
	v_mfma_f32_16x16x32_bf16 v[0:3], v[152:155], v[202:205], v[0:3]
	v_mfma_f32_16x16x32_bf16 v[52:55], v[148:151], v[164:167], v[52:55]
	v_mfma_f32_16x16x32_bf16 v[48:51], v[156:159], v[164:167], v[48:51]
	v_mfma_f32_16x16x32_bf16 v[36:39], v[148:151], v[172:175], v[36:39]
	v_mfma_f32_16x16x32_bf16 v[32:35], v[156:159], v[172:175], v[32:35]
	v_mfma_f32_16x16x32_bf16 v[20:23], v[148:151], v[180:183], v[20:23]
	v_mfma_f32_16x16x32_bf16 v[16:19], v[156:159], v[180:183], v[16:19]
	v_mfma_f32_16x16x32_bf16 v[4:7], v[148:151], v[206:209], v[4:7]
	v_mfma_f32_16x16x32_bf16 v[0:3], v[156:159], v[206:209], v[0:3]
	s_barrier
	s_add_i32 s76, s76, 2
	s_add_u32 s20, s20, 0x100
	s_addc_u32 s21, s21, 0
	s_add_u32 s74, s74, 0x100
	s_addc_u32 s75, s75, 0
	s_cmp_gt_u32 s76, 13

; #define PG8_STAGE(bufoff, gbase, voff) do { _Pragma("unroll") for (int _i = 0; _i < 2; ++_i) \
;         __builtin_amdgcn_global_load_lds((const unsigned*)((const char*)(gbase) + (voff)[_i]), (PG8_LAS unsigned*)(lds + (bufoff) + ldsw + _i * 8192), 16, 0, 0); } while (0)
; #define PG8_LDA(dst, b, h) do { _Pragma("unroll") for (int m = 0; m < 4; ++m) _Pragma("unroll") for (int k = 0; k < 2; ++k) dst[m][k] = *(const PG8_LAS bf16x8*)(lds + PG8_SA(b, h) + aoff + m * 2048 + k * 1024); } while (0)
; #define PG8_LDB(dst, b, h) do { _Pragma("unroll") for (int n = 0; n < 2; ++n) _Pragma("unroll") for (int k = 0; k < 2; ++k) dst[n][k] = *(const PG8_LAS bf16x8*)(lds + PG8_SB(b, h) + boff + n * 2048 + k * 1024); } while (0)
; #define PG8_WAIT_V(n) asm volatile("s_waitcnt vmcnt(" #n ")" ::: "memory")
; #define PG8_WAIT_L(n) asm volatile("s_waitcnt lgkmcnt(" #n ")" ::: "memory")
; #define PG8_BAR __builtin_amdgcn_s_barrier()
; #define PG8_SCHED __builtin_amdgcn_sched_barrier(0)
; template <class Epi, class Sched, bool ALIGN_EPI = false, bool SP2 = false>
; __device__ __forceinline__ void gemm_phase(PG8_LAS unsigned char* lds, const Gemm g, const Sched& S, const Epi& E) {
;     ...
;         const char* nA = has_next ? (const char*)g.A + (size_t)nxt.pm * tstep : cA; const char* nB = has_next ? (const char*)g.Bt + (size_t)nxt.pn * tstep : cB;
;         for (int t = 0; t < nt; t += 2) {
;             const bool last = (t == nt - 2);
;             const char* a1 = cA + (size_t)(t + 1) * kstep;
;             const char* a2 = last ? nA : cA + (size_t)(t + 2) * kstep; const char* b2 = last ? nB : cB + (size_t)(t + 2) * kstep;
;             const char* a3 = a2 + kstep; const char* b3 = b2 + kstep;
;             if (last && has_next) S.a_ready(nxt);
;             if constexpr (SP2) {
;             PG8_LDB(B0, 0, 0); PG8_LDB(B1, 0, 1); PG8_SCHED; PG8_LDA(At, 0, 0); PG8_STAGE(PG8_SA(1, 1), a1 + hstep, voffA);
;             PG8_WAIT_V(8); PG8_WAIT_L(0); PG8_BAR; PG8_MMA(0, 0, At, B0); PG8_MMA(0, 1, At, B1); PG8_BAR; PG8_SCHED;
;             PG8_LDA(At, 0, 1); PG8_STAGE(PG8_SB(0, 0), b2, voffB); PG8_STAGE(PG8_SB(0, 1), b2 + hstep, voffB); PG8_STAGE(PG8_SA(0, 0), a2, voffA);
;             PG8_WAIT_V(8); PG8_WAIT_L(0); PG8_BAR; PG8_MMA(1, 0, At, B0); PG8_MMA(1, 1, At, B1); PG8_BAR; PG8_SCHED;
.LBB0_1739:
	s_ashr_i32 s15, s14, 31
	s_lshl_b64 s[16:17], s[14:15], 19
	s_add_u32 s16, s36, s16
	s_addc_u32 s17, s37, s17
	s_and_b64 s[18:19], s[4:5], exec
	s_cselect_b32 s15, s17, s21
	s_cselect_b32 s63, s16, s20
	s_ashr_i32 s13, s12, 31
	s_lshl_b64 s[18:19], s[12:13], 19
	s_add_u32 s18, s48, s18
	s_addc_u32 s19, s49, s19
	s_and_b64 s[42:43], s[4:5], exec
	s_cselect_b32 s13, s19, s39
	s_cselect_b32 s64, s18, s38
	s_add_u32 s20, s20, 0x40080
	s_addc_u32 s21, s21, 0
	s_add_u32 s65, s38, 0x100
	s_addc_u32 s66, s39, 0
	s_mov_b32 s67, -2
	ds_read_b128 v[154:157], v150
	ds_read_b128 v[158:161], v150 offset:1024
	ds_read_b128 v[162:165], v150 offset:2048
	ds_read_b128 v[166:169], v150 offset:3072
	ds_read_b128 v[170:173], v151
	ds_read_b128 v[174:177], v151 offset:1024
	ds_read_b128 v[178:181], v151 offset:2048
	ds_read_b128 v[182:185], v151 offset:3072
	s_add_u32 s38, s20, 0xfffc0080
	s_addc_u32 s39, s21, -1
	s_cmp_eq_u32 s67, 12
	s_cselect_b32 s43, s15, s39
	s_cselect_b32 s42, s63, s38
	s_cselect_b32 s39, s13, s66
	s_cselect_b32 s38, s64, s65
	s_add_i32 m0, s35, 0xc000
	ds_read_b128 v[186:189], v152
	ds_read_b128 v[190:193], v152 offset:1024
	ds_read_b128 v[198:201], v152 offset:2048
	ds_read_b128 v[202:205], v152 offset:3072
	ds_read_b128 v[206:209], v152 offset:4096
	ds_read_b128 v[210:213], v152 offset:5120
	ds_read_b128 v[214:217], v152 offset:6144
	ds_read_b128 v[218:221], v152 offset:7168
	global_load_lds_dwordx4 v136, s[20:21]
	s_add_i32 m0, s35, 0xe000
	s_nop 0
	global_load_lds_dwordx4 v138, s[20:21]
	s_waitcnt vmcnt(8)
	s_waitcnt lgkmcnt(0)
	s_barrier
	s_waitcnt lgkmcnt(0)
	v_mfma_f32_16x16x32_bf16 v[124:127], v[154:157], v[186:189], 0
	v_mfma_f32_16x16x32_bf16 v[116:119], v[162:165], v[186:189], 0
	v_mfma_f32_16x16x32_bf16 v[108:111], v[154:157], v[198:201], 0
	v_mfma_f32_16x16x32_bf16 v[100:103], v[162:165], v[198:201], 0
	v_mfma_f32_16x16x32_bf16 v[92:95], v[154:157], v[206:209], 0
	v_mfma_f32_16x16x32_bf16 v[84:87], v[162:165], v[206:209], 0
	v_mfma_f32_16x16x32_bf16 v[76:79], v[154:157], v[214:217], 0
	v_mfma_f32_16x16x32_bf16 v[68:71], v[162:165], v[214:217], 0
	v_mfma_f32_16x16x32_bf16 v[124:127], v[158:161], v[190:193], v[124:127]
	v_mfma_f32_16x16x32_bf16 v[116:119], v[166:169], v[190:193], v[116:119]
	v_mfma_f32_16x16x32_bf16 v[108:111], v[158:161], v[202:205], v[108:111]
	v_mfma_f32_16x16x32_bf16 v[100:103], v[166:169], v[202:205], v[100:103]
	v_mfma_f32_16x16x32_bf16 v[92:95], v[158:161], v[210:213], v[92:95]
	v_mfma_f32_16x16x32_bf16 v[84:87], v[166:169], v[210:213], v[84:87]
	v_mfma_f32_16x16x32_bf16 v[76:79], v[158:161], v[218:221], v[76:79]
	v_mfma_f32_16x16x32_bf16 v[68:71], v[166:169], v[218:221], v[68:71]
	v_mfma_f32_16x16x32_bf16 v[120:123], v[170:173], v[186:189], 0
	v_mfma_f32_16x16x32_bf16 v[112:115], v[178:181], v[186:189], 0
	v_mfma_f32_16x16x32_bf16 v[104:107], v[170:173], v[198:201], 0
	v_mfma_f32_16x16x32_bf16 v[96:99], v[178:181], v[198:201], 0
	v_mfma_f32_16x16x32_bf16 v[88:91], v[170:173], v[206:209], 0
	v_mfma_f32_16x16x32_bf16 v[80:83], v[178:181], v[206:209], 0
	v_mfma_f32_16x16x32_bf16 v[72:75], v[170:173], v[214:217], 0
	v_mfma_f32_16x16x32_bf16 v[64:67], v[178:181], v[214:217], 0
	v_mfma_f32_16x16x32_bf16 v[120:123], v[174:177], v[190:193], v[120:123]
	v_mfma_f32_16x16x32_bf16 v[112:115], v[182:185], v[190:193], v[112:115]
	v_mfma_f32_16x16x32_bf16 v[104:107], v[174:177], v[202:205], v[104:107]
	v_mfma_f32_16x16x32_bf16 v[96:99], v[182:185], v[202:205], v[96:99]
	v_mfma_f32_16x16x32_bf16 v[88:91], v[174:177], v[210:213], v[88:91]
	v_mfma_f32_16x16x32_bf16 v[80:83], v[182:185], v[210:213], v[80:83]
	v_mfma_f32_16x16x32_bf16 v[72:75], v[174:177], v[218:221], v[72:75]
	v_mfma_f32_16x16x32_bf16 v[64:67], v[182:185], v[218:221], v[64:67]
	s_barrier
	s_add_i32 s68, s58, s50
	s_add_u32 s98, s38, s8
	s_addc_u32 s99, s39, s9
	s_add_u32 s100, s42, s8
	s_addc_u32 s101, s43, s9
	s_mov_b32 m0, s68
	ds_read_b128 v[186:189], v152 offset:16384
	ds_read_b128 v[190:193], v152 offset:17408
	ds_read_b128 v[198:201], v152 offset:18432
	ds_read_b128 v[202:205], v152 offset:19456
	ds_read_b128 v[206:209], v152 offset:20480
	ds_read_b128 v[210:213], v152 offset:21504
	ds_read_b128 v[214:217], v152 offset:22528
	ds_read_b128 v[218:221], v152 offset:23552
	global_load_lds_dwordx4 v132, s[38:39]
	s_add_i32 m0, s68, 0x2000
	s_add_u32 s68, s38, 0x40000
	s_addc_u32 s69, s39, 0
	s_add_i32 s70, s59, s50
	global_load_lds_dwordx4 v128, s[38:39]
	s_mov_b32 m0, s70
	s_nop 0
	global_load_lds_dwordx4 v132, s[68:69]
	s_add_i32 m0, s70, 0x2000
	s_nop 0
	global_load_lds_dwordx4 v128, s[68:69]
	s_mov_b32 m0, s35
	s_nop 0
	global_load_lds_dwordx4 v134, s[42:43]
	s_mov_b32 m0, s52
	s_nop 0
	global_load_lds_dwordx4 v130, s[42:43]
	s_waitcnt vmcnt(8)
	s_waitcnt lgkmcnt(0)
	s_barrier
; #define PG8_STAGE(bufoff, gbase, voff) do { _Pragma("unroll") for (int _i = 0; _i < 2; ++_i) \
;         __builtin_amdgcn_global_load_lds((const unsigned*)((const char*)(gbase) + (voff)[_i]), (PG8_LAS unsigned*)(lds + (bufoff) + ldsw + _i * 8192), 16, 0, 0); } while (0)
; #define PG8_LDA(dst, b, h) do { _Pragma("unroll") for (int m = 0; m < 4; ++m) _Pragma("unroll") for (int k = 0; k < 2; ++k) dst[m][k] = *(const PG8_LAS bf16x8*)(lds + PG8_SA(b, h) + aoff + m * 2048 + k * 1024); } while (0)
; #define PG8_LDB(dst, b, h) do { _Pragma("unroll") for (int n = 0; n < 2; ++n) _Pragma("unroll") for (int k = 0; k < 2; ++k) dst[n][k] = *(const PG8_LAS bf16x8*)(lds + PG8_SB(b, h) + boff + n * 2048 + k * 1024); } while (0)
; #define PG8_MMA(ai, bj, At, Bt) do { __builtin_amdgcn_s_setprio(1); _Pragma("unroll") for (int m = 0; m < 4; ++m) _Pragma("unroll") for (int n = 0; n < 2; ++n) _Pragma("unroll") for (int k = 0; k < 2; ++k) \
;         acc[ai][bj][m][n] = __builtin_amdgcn_mfma_f32_16x16x32_bf16(Bt[n][k], At[m][k], acc[ai][bj][m][n], 0, 0, 0); __builtin_amdgcn_s_setprio(0); } while (0)
; #define PG8_WAIT_V(n) asm volatile("s_waitcnt vmcnt(" #n ")" ::: "memory")
; #define PG8_WAIT_L(n) asm volatile("s_waitcnt lgkmcnt(" #n ")" ::: "memory")
; #define PG8_BAR __builtin_amdgcn_s_barrier()
; #define PG8_SCHED __builtin_amdgcn_sched_barrier(0)
; template <class Epi, class Sched, bool ALIGN_EPI = false, bool SP2 = false>
; __device__ __forceinline__ void gemm_phase(PG8_LAS unsigned char* lds, const Gemm g, const Sched& S, const Epi& E) {
;     ...
;             PG8_WAIT_V(8); PG8_WAIT_L(0); PG8_BAR; PG8_MMA(1, 0, At, B0); PG8_MMA(1, 1, At, B1); PG8_BAR; PG8_SCHED;
;             PG8_LDB(B0, 1, 0); PG8_LDB(B1, 1, 1); PG8_SCHED; PG8_LDA(At, 1, 0); PG8_STAGE(PG8_SA(0, 1), a2 + hstep, voffA);
;             PG8_WAIT_V(8); PG8_WAIT_L(0); PG8_BAR; PG8_MMA(0, 0, At, B0); PG8_MMA(0, 1, At, B1); PG8_BAR; PG8_SCHED;
	s_waitcnt lgkmcnt(0)
	v_mfma_f32_16x16x32_bf16 v[60:63], v[154:157], v[186:189], 0
	v_mfma_f32_16x16x32_bf16 v[52:55], v[162:165], v[186:189], 0
	v_mfma_f32_16x16x32_bf16 v[44:47], v[154:157], v[198:201], 0
	v_mfma_f32_16x16x32_bf16 v[36:39], v[162:165], v[198:201], 0
	v_mfma_f32_16x16x32_bf16 v[28:31], v[154:157], v[206:209], 0
	v_mfma_f32_16x16x32_bf16 v[20:23], v[162:165], v[206:209], 0
	v_mfma_f32_16x16x32_bf16 v[12:15], v[154:157], v[214:217], 0
	v_mfma_f32_16x16x32_bf16 v[4:7], v[162:165], v[214:217], 0
	v_mfma_f32_16x16x32_bf16 v[60:63], v[158:161], v[190:193], v[60:63]
	v_mfma_f32_16x16x32_bf16 v[52:55], v[166:169], v[190:193], v[52:55]
	v_mfma_f32_16x16x32_bf16 v[44:47], v[158:161], v[202:205], v[44:47]
	v_mfma_f32_16x16x32_bf16 v[36:39], v[166:169], v[202:205], v[36:39]
	v_mfma_f32_16x16x32_bf16 v[28:31], v[158:161], v[210:213], v[28:31]
	v_mfma_f32_16x16x32_bf16 v[20:23], v[166:169], v[210:213], v[20:23]
	v_mfma_f32_16x16x32_bf16 v[12:15], v[158:161], v[218:221], v[12:15]
	v_mfma_f32_16x16x32_bf16 v[4:7], v[166:169], v[218:221], v[4:7]
	v_mfma_f32_16x16x32_bf16 v[56:59], v[170:173], v[186:189], 0
	v_mfma_f32_16x16x32_bf16 v[48:51], v[178:181], v[186:189], 0
	v_mfma_f32_16x16x32_bf16 v[40:43], v[170:173], v[198:201], 0
	v_mfma_f32_16x16x32_bf16 v[32:35], v[178:181], v[198:201], 0
	v_mfma_f32_16x16x32_bf16 v[24:27], v[170:173], v[206:209], 0
	v_mfma_f32_16x16x32_bf16 v[16:19], v[178:181], v[206:209], 0
	v_mfma_f32_16x16x32_bf16 v[8:11], v[170:173], v[214:217], 0
	v_mfma_f32_16x16x32_bf16 v[0:3], v[178:181], v[214:217], 0
	v_mfma_f32_16x16x32_bf16 v[56:59], v[174:177], v[190:193], v[56:59]
	v_mfma_f32_16x16x32_bf16 v[48:51], v[182:185], v[190:193], v[48:51]
	v_mfma_f32_16x16x32_bf16 v[40:43], v[174:177], v[202:205], v[40:43]
	v_mfma_f32_16x16x32_bf16 v[32:35], v[182:185], v[202:205], v[32:35]
	v_mfma_f32_16x16x32_bf16 v[24:27], v[174:177], v[210:213], v[24:27]
	v_mfma_f32_16x16x32_bf16 v[16:19], v[182:185], v[210:213], v[16:19]
	v_mfma_f32_16x16x32_bf16 v[8:11], v[174:177], v[218:221], v[8:11]
	v_mfma_f32_16x16x32_bf16 v[0:3], v[182:185], v[218:221], v[0:3]
	s_barrier
	s_add_i32 s68, 0, 0x18000
	v_add_u32_e32 v153, s68, v147
	s_add_i32 s69, 0, 0x1c000
	ds_read_b128 v[154:157], v153
	ds_read_b128 v[158:161], v153 offset:1024
	ds_read_b128 v[162:165], v153 offset:2048
	ds_read_b128 v[166:169], v153 offset:3072
	v_add_u32_e32 v153, s69, v147
	ds_read_b128 v[170:173], v153
	ds_read_b128 v[174:177], v153 offset:1024
	ds_read_b128 v[178:181], v153 offset:2048
	ds_read_b128 v[182:185], v153 offset:3072
	s_add_u32 s42, s42, 0x40000
	s_addc_u32 s43, s43, 0
	s_mov_b32 m0, s53
	ds_read_b128 v[186:189], v152 offset:32768
	ds_read_b128 v[190:193], v152 offset:33792
	ds_read_b128 v[198:201], v152 offset:34816
	ds_read_b128 v[202:205], v152 offset:35840
	ds_read_b128 v[206:209], v152 offset:36864
	ds_read_b128 v[210:213], v152 offset:37888
	ds_read_b128 v[214:217], v152 offset:38912
	ds_read_b128 v[218:221], v152 offset:39936
	global_load_lds_dwordx4 v134, s[42:43]
	s_mov_b32 m0, s54
	s_nop 0
	global_load_lds_dwordx4 v130, s[42:43]
	s_waitcnt vmcnt(8)
	s_waitcnt lgkmcnt(0)
	s_barrier
	s_waitcnt lgkmcnt(0)
	v_mfma_f32_16x16x32_bf16 v[124:127], v[154:157], v[186:189], v[124:127]
	v_mfma_f32_16x16x32_bf16 v[116:119], v[162:165], v[186:189], v[116:119]
	v_mfma_f32_16x16x32_bf16 v[108:111], v[154:157], v[198:201], v[108:111]
	v_mfma_f32_16x16x32_bf16 v[100:103], v[162:165], v[198:201], v[100:103]
	v_mfma_f32_16x16x32_bf16 v[92:95], v[154:157], v[206:209], v[92:95]
	v_mfma_f32_16x16x32_bf16 v[84:87], v[162:165], v[206:209], v[84:87]
	v_mfma_f32_16x16x32_bf16 v[76:79], v[154:157], v[214:217], v[76:79]
	v_mfma_f32_16x16x32_bf16 v[68:71], v[162:165], v[214:217], v[68:71]
	v_mfma_f32_16x16x32_bf16 v[124:127], v[158:161], v[190:193], v[124:127]
	v_mfma_f32_16x16x32_bf16 v[116:119], v[166:169], v[190:193], v[116:119]
	v_mfma_f32_16x16x32_bf16 v[108:111], v[158:161], v[202:205], v[108:111]
	v_mfma_f32_16x16x32_bf16 v[100:103], v[166:169], v[202:205], v[100:103]
	v_mfma_f32_16x16x32_bf16 v[92:95], v[158:161], v[210:213], v[92:95]
	v_mfma_f32_16x16x32_bf16 v[84:87], v[166:169], v[210:213], v[84:87]
	v_mfma_f32_16x16x32_bf16 v[76:79], v[158:161], v[218:221], v[76:79]
	v_mfma_f32_16x16x32_bf16 v[68:71], v[166:169], v[218:221], v[68:71]
	v_mfma_f32_16x16x32_bf16 v[120:123], v[170:173], v[186:189], v[120:123]
	v_mfma_f32_16x16x32_bf16 v[112:115], v[178:181], v[186:189], v[112:115]
	v_mfma_f32_16x16x32_bf16 v[104:107], v[170:173], v[198:201], v[104:107]
	v_mfma_f32_16x16x32_bf16 v[96:99], v[178:181], v[198:201], v[96:99]
	v_mfma_f32_16x16x32_bf16 v[88:91], v[170:173], v[206:209], v[88:91]
	v_mfma_f32_16x16x32_bf16 v[80:83], v[178:181], v[206:209], v[80:83]
	v_mfma_f32_16x16x32_bf16 v[72:75], v[170:173], v[214:217], v[72:75]
	v_mfma_f32_16x16x32_bf16 v[64:67], v[178:181], v[214:217], v[64:67]
	v_mfma_f32_16x16x32_bf16 v[120:123], v[174:177], v[190:193], v[120:123]
	v_mfma_f32_16x16x32_bf16 v[112:115], v[182:185], v[190:193], v[112:115]
	v_mfma_f32_16x16x32_bf16 v[104:107], v[174:177], v[202:205], v[104:107]
	v_mfma_f32_16x16x32_bf16 v[96:99], v[182:185], v[202:205], v[96:99]
	v_mfma_f32_16x16x32_bf16 v[88:91], v[174:177], v[210:213], v[88:91]
	v_mfma_f32_16x16x32_bf16 v[80:83], v[182:185], v[210:213], v[80:83]
	v_mfma_f32_16x16x32_bf16 v[72:75], v[174:177], v[218:221], v[72:75]
	v_mfma_f32_16x16x32_bf16 v[64:67], v[182:185], v[218:221], v[64:67]
	s_barrier
; #define PG8_STAGE(bufoff, gbase, voff) do { _Pragma("unroll") for (int _i = 0; _i < 2; ++_i) \
;         __builtin_amdgcn_global_load_lds((const unsigned*)((const char*)(gbase) + (voff)[_i]), (PG8_LAS unsigned*)(lds + (bufoff) + ldsw + _i * 8192), 16, 0, 0); } while (0)
; #define PG8_LDA(dst, b, h) do { _Pragma("unroll") for (int m = 0; m < 4; ++m) _Pragma("unroll") for (int k = 0; k < 2; ++k) dst[m][k] = *(const PG8_LAS bf16x8*)(lds + PG8_SA(b, h) + aoff + m * 2048 + k * 1024); } while (0)
; #define PG8_LDB(dst, b, h) do { _Pragma("unroll") for (int n = 0; n < 2; ++n) _Pragma("unroll") for (int k = 0; k < 2; ++k) dst[n][k] = *(const PG8_LAS bf16x8*)(lds + PG8_SB(b, h) + boff + n * 2048 + k * 1024); } while (0)
; #define PG8_MMA(ai, bj, At, Bt) do { __builtin_amdgcn_s_setprio(1); _Pragma("unroll") for (int m = 0; m < 4; ++m) _Pragma("unroll") for (int n = 0; n < 2; ++n) _Pragma("unroll") for (int k = 0; k < 2; ++k) \
;         acc[ai][bj][m][n] = __builtin_amdgcn_mfma_f32_16x16x32_bf16(Bt[n][k], At[m][k], acc[ai][bj][m][n], 0, 0, 0); __builtin_amdgcn_s_setprio(0); } while (0)
; #define PG8_WAIT_V(n) asm volatile("s_waitcnt vmcnt(" #n ")" ::: "memory")
; template <class Epi, class Sched, bool ALIGN_EPI = false, bool SP2 = false>
; __device__ __forceinline__ void gemm_phase(PG8_LAS unsigned char* lds, const Gemm g, const Sched& S, const Epi& E) {
;     ...
;             PG8_LDB(B0, 0, 0); PG8_LDB(B1, 0, 1); PG8_SCHED; PG8_LDA(At, 0, 0); PG8_STAGE(PG8_SA(1, 1), a1 + hstep, voffA);
;             PG8_WAIT_V(8); PG8_WAIT_L(0); PG8_BAR; PG8_MMA(0, 0, At, B0); PG8_MMA(0, 1, At, B1); PG8_BAR; PG8_SCHED;
;             PG8_LDA(At, 0, 1); PG8_STAGE(PG8_SB(0, 0), b2, voffB); PG8_STAGE(PG8_SB(0, 1), b2 + hstep, voffB); PG8_STAGE(PG8_SA(0, 0), a2, voffA);
;             PG8_WAIT_V(8); PG8_WAIT_L(0); PG8_BAR; PG8_MMA(1, 0, At, B0); PG8_MMA(1, 1, At, B1); PG8_BAR; PG8_SCHED;
;             PG8_LDB(B0, 1, 0); PG8_LDB(B1, 1, 1); PG8_SCHED; PG8_LDA(At, 1, 0); PG8_STAGE(PG8_SA(0, 1), a2 + hstep, voffA);
;             PG8_WAIT_V(8); PG8_WAIT_L(0); PG8_BAR; PG8_MMA(0, 0, At, B0); PG8_MMA(0, 1, At, B1); PG8_BAR; PG8_SCHED;
;             PG8_LDA(At, 1, 1); PG8_STAGE(PG8_SB(1, 0), b3, voffB); PG8_STAGE(PG8_SB(1, 1), b3 + hstep, voffB); PG8_STAGE(PG8_SA(1, 0), a3, voffA);
;             PG8_WAIT_V(8); PG8_WAIT_L(0); PG8_BAR; PG8_MMA(1, 0, At, B0); PG8_MMA(1, 1, At, B1); PG8_BAR; PG8_SCHED;
	s_add_i32 s42, s68, s50
	s_mov_b32 m0, s42
	ds_read_b128 v[186:189], v152 offset:49152
	ds_read_b128 v[190:193], v152 offset:50176
	ds_read_b128 v[198:201], v152 offset:51200
	ds_read_b128 v[202:205], v152 offset:52224
	ds_read_b128 v[206:209], v152 offset:53248
	ds_read_b128 v[210:213], v152 offset:54272
	ds_read_b128 v[214:217], v152 offset:55296
	ds_read_b128 v[218:221], v152 offset:56320
	global_load_lds_dwordx4 v132, s[98:99]
	s_add_i32 m0, s42, 0x2000
	s_add_u32 s38, s38, 0x40080
	s_addc_u32 s39, s39, 0
	s_add_i32 s42, s69, s50
	global_load_lds_dwordx4 v128, s[98:99]
	s_mov_b32 m0, s42
	s_nop 0
	global_load_lds_dwordx4 v132, s[38:39]
	s_add_i32 m0, s42, 0x2000
	s_nop 0
	global_load_lds_dwordx4 v128, s[38:39]
	s_mov_b32 m0, s56
	s_nop 0
	global_load_lds_dwordx4 v134, s[100:101]
	s_mov_b32 m0, s57
	s_nop 0
	global_load_lds_dwordx4 v130, s[100:101]
	s_waitcnt vmcnt(8)
	s_waitcnt lgkmcnt(0)
	s_barrier
	s_waitcnt lgkmcnt(0)
	v_mfma_f32_16x16x32_bf16 v[60:63], v[154:157], v[186:189], v[60:63]
	v_mfma_f32_16x16x32_bf16 v[52:55], v[162:165], v[186:189], v[52:55]
	v_mfma_f32_16x16x32_bf16 v[44:47], v[154:157], v[198:201], v[44:47]
	v_mfma_f32_16x16x32_bf16 v[36:39], v[162:165], v[198:201], v[36:39]
	v_mfma_f32_16x16x32_bf16 v[28:31], v[154:157], v[206:209], v[28:31]
	v_mfma_f32_16x16x32_bf16 v[20:23], v[162:165], v[206:209], v[20:23]
	v_mfma_f32_16x16x32_bf16 v[12:15], v[154:157], v[214:217], v[12:15]
	v_mfma_f32_16x16x32_bf16 v[4:7], v[162:165], v[214:217], v[4:7]
	v_mfma_f32_16x16x32_bf16 v[60:63], v[158:161], v[190:193], v[60:63]
	v_mfma_f32_16x16x32_bf16 v[52:55], v[166:169], v[190:193], v[52:55]
	v_mfma_f32_16x16x32_bf16 v[44:47], v[158:161], v[202:205], v[44:47]
	v_mfma_f32_16x16x32_bf16 v[36:39], v[166:169], v[202:205], v[36:39]
	v_mfma_f32_16x16x32_bf16 v[28:31], v[158:161], v[210:213], v[28:31]
	v_mfma_f32_16x16x32_bf16 v[20:23], v[166:169], v[210:213], v[20:23]
	v_mfma_f32_16x16x32_bf16 v[12:15], v[158:161], v[218:221], v[12:15]
	v_mfma_f32_16x16x32_bf16 v[4:7], v[166:169], v[218:221], v[4:7]
	v_mfma_f32_16x16x32_bf16 v[56:59], v[170:173], v[186:189], v[56:59]
	v_mfma_f32_16x16x32_bf16 v[48:51], v[178:181], v[186:189], v[48:51]
	v_mfma_f32_16x16x32_bf16 v[40:43], v[170:173], v[198:201], v[40:43]
	v_mfma_f32_16x16x32_bf16 v[32:35], v[178:181], v[198:201], v[32:35]
	v_mfma_f32_16x16x32_bf16 v[24:27], v[170:173], v[206:209], v[24:27]
	v_mfma_f32_16x16x32_bf16 v[16:19], v[178:181], v[206:209], v[16:19]
	v_mfma_f32_16x16x32_bf16 v[8:11], v[170:173], v[214:217], v[8:11]
	v_mfma_f32_16x16x32_bf16 v[0:3], v[178:181], v[214:217], v[0:3]
	v_mfma_f32_16x16x32_bf16 v[56:59], v[174:177], v[190:193], v[56:59]
	v_mfma_f32_16x16x32_bf16 v[48:51], v[182:185], v[190:193], v[48:51]
	v_mfma_f32_16x16x32_bf16 v[40:43], v[174:177], v[202:205], v[40:43]
	v_mfma_f32_16x16x32_bf16 v[32:35], v[182:185], v[202:205], v[32:35]
	v_mfma_f32_16x16x32_bf16 v[24:27], v[174:177], v[210:213], v[24:27]
	v_mfma_f32_16x16x32_bf16 v[16:19], v[182:185], v[210:213], v[16:19]
	v_mfma_f32_16x16x32_bf16 v[8:11], v[174:177], v[218:221], v[8:11]
	v_mfma_f32_16x16x32_bf16 v[0:3], v[182:185], v[218:221], v[0:3]
	s_barrier
	s_add_i32 s67, s67, 2
	s_add_u32 s20, s20, 0x100
	s_addc_u32 s21, s21, 0
	s_add_u32 s65, s65, 0x100
	s_addc_u32 s66, s66, 0
	s_cmp_gt_u32 s67, 13
.LBB0_1740:
	ds_read_b128 v[154:157], v150
	ds_read_b128 v[158:161], v150 offset:1024
	ds_read_b128 v[162:165], v150 offset:2048
	ds_read_b128 v[166:169], v150 offset:3072
	ds_read_b128 v[170:173], v151
	ds_read_b128 v[174:177], v151 offset:1024
	ds_read_b128 v[178:181], v151 offset:2048
	ds_read_b128 v[182:185], v151 offset:3072
	s_add_u32 s38, s20, 0xfffc0080
	s_addc_u32 s39, s21, -1
	s_cmp_eq_u32 s67, 12
	s_cselect_b32 s43, s15, s39
	s_cselect_b32 s42, s63, s38
	s_cselect_b32 s39, s13, s66
	s_cselect_b32 s38, s64, s65
	s_add_i32 m0, s35, 0xc000
	ds_read_b128 v[186:189], v152
	ds_read_b128 v[190:193], v152 offset:1024
	ds_read_b128 v[198:201], v152 offset:2048
	ds_read_b128 v[202:205], v152 offset:3072
	ds_read_b128 v[206:209], v152 offset:4096
	ds_read_b128 v[210:213], v152 offset:5120
	ds_read_b128 v[214:217], v152 offset:6144
	ds_read_b128 v[218:221], v152 offset:7168
	global_load_lds_dwordx4 v136, s[20:21]
	s_add_i32 m0, s35, 0xe000
	s_nop 0
	global_load_lds_dwordx4 v138, s[20:21]
	s_waitcnt vmcnt(8)
	s_waitcnt lgkmcnt(0)
	s_barrier
	s_waitcnt lgkmcnt(0)
	v_mfma_f32_16x16x32_bf16 v[124:127], v[154:157], v[186:189], v[124:127]
	v_mfma_f32_16x16x32_bf16 v[116:119], v[162:165], v[186:189], v[116:119]
	v_mfma_f32_16x16x32_bf16 v[108:111], v[154:157], v[198:201], v[108:111]
	v_mfma_f32_16x16x32_bf16 v[100:103], v[162:165], v[198:201], v[100:103]
	v_mfma_f32_16x16x32_bf16 v[92:95], v[154:157], v[206:209], v[92:95]
	v_mfma_f32_16x16x32_bf16 v[84:87], v[162:165], v[206:209], v[84:87]
	v_mfma_f32_16x16x32_bf16 v[76:79], v[154:157], v[214:217], v[76:79]
	v_mfma_f32_16x16x32_bf16 v[68:71], v[162:165], v[214:217], v[68:71]
	v_mfma_f32_16x16x32_bf16 v[124:127], v[158:161], v[190:193], v[124:127]
	v_mfma_f32_16x16x32_bf16 v[116:119], v[166:169], v[190:193], v[116:119]
	v_mfma_f32_16x16x32_bf16 v[108:111], v[158:161], v[202:205], v[108:111]
	v_mfma_f32_16x16x32_bf16 v[100:103], v[166:169], v[202:205], v[100:103]
	v_mfma_f32_16x16x32_bf16 v[92:95], v[158:161], v[210:213], v[92:95]
	v_mfma_f32_16x16x32_bf16 v[84:87], v[166:169], v[210:213], v[84:87]
	v_mfma_f32_16x16x32_bf16 v[76:79], v[158:161], v[218:221], v[76:79]
	v_mfma_f32_16x16x32_bf16 v[68:71], v[166:169], v[218:221], v[68:71]
	v_mfma_f32_16x16x32_bf16 v[120:123], v[170:173], v[186:189], v[120:123]
	v_mfma_f32_16x16x32_bf16 v[112:115], v[178:181], v[186:189], v[112:115]
	v_mfma_f32_16x16x32_bf16 v[104:107], v[170:173], v[198:201], v[104:107]
	v_mfma_f32_16x16x32_bf16 v[96:99], v[178:181], v[198:201], v[96:99]
	v_mfma_f32_16x16x32_bf16 v[88:91], v[170:173], v[206:209], v[88:91]
	v_mfma_f32_16x16x32_bf16 v[80:83], v[178:181], v[206:209], v[80:83]
	v_mfma_f32_16x16x32_bf16 v[72:75], v[170:173], v[214:217], v[72:75]
	v_mfma_f32_16x16x32_bf16 v[64:67], v[178:181], v[214:217], v[64:67]
	v_mfma_f32_16x16x32_bf16 v[120:123], v[174:177], v[190:193], v[120:123]
	v_mfma_f32_16x16x32_bf16 v[112:115], v[182:185], v[190:193], v[112:115]
	v_mfma_f32_16x16x32_bf16 v[104:107], v[174:177], v[202:205], v[104:107]
	v_mfma_f32_16x16x32_bf16 v[96:99], v[182:185], v[202:205], v[96:99]
	v_mfma_f32_16x16x32_bf16 v[88:91], v[174:177], v[210:213], v[88:91]
	v_mfma_f32_16x16x32_bf16 v[80:83], v[182:185], v[210:213], v[80:83]
	v_mfma_f32_16x16x32_bf16 v[72:75], v[174:177], v[218:221], v[72:75]
	v_mfma_f32_16x16x32_bf16 v[64:67], v[182:185], v[218:221], v[64:67]
	s_barrier
; #define PG8_STAGE(bufoff, gbase, voff) do { _Pragma("unroll") for (int _i = 0; _i < 2; ++_i) \
;         __builtin_amdgcn_global_load_lds((const unsigned*)((const char*)(gbase) + (voff)[_i]), (PG8_LAS unsigned*)(lds + (bufoff) + ldsw + _i * 8192), 16, 0, 0); } while (0)
; #define PG8_LDA(dst, b, h) do { _Pragma("unroll") for (int m = 0; m < 4; ++m) _Pragma("unroll") for (int k = 0; k < 2; ++k) dst[m][k] = *(const PG8_LAS bf16x8*)(lds + PG8_SA(b, h) + aoff + m * 2048 + k * 1024); } while (0)
; #define PG8_LDB(dst, b, h) do { _Pragma("unroll") for (int n = 0; n < 2; ++n) _Pragma("unroll") for (int k = 0; k < 2; ++k) dst[n][k] = *(const PG8_LAS bf16x8*)(lds + PG8_SB(b, h) + boff + n * 2048 + k * 1024); } while (0)
; #define PG8_MMA(ai, bj, At, Bt) do { __builtin_amdgcn_s_setprio(1); _Pragma("unroll") for (int m = 0; m < 4; ++m) _Pragma("unroll") for (int n = 0; n < 2; ++n) _Pragma("unroll") for (int k = 0; k < 2; ++k) \
;         acc[ai][bj][m][n] = __builtin_amdgcn_mfma_f32_16x16x32_bf16(Bt[n][k], At[m][k], acc[ai][bj][m][n], 0, 0, 0); __builtin_amdgcn_s_setprio(0); } while (0)
; #define PG8_WAIT_V(n) asm volatile("s_waitcnt vmcnt(" #n ")" ::: "memory")
; #define PG8_WAIT_L(n) asm volatile("s_waitcnt lgkmcnt(" #n ")" ::: "memory")
; #define PG8_BAR __builtin_amdgcn_s_barrier()
; #define PG8_SCHED __builtin_amdgcn_sched_barrier(0)
; template <class Epi, class Sched, bool ALIGN_EPI = false, bool SP2 = false>
; __device__ __forceinline__ void gemm_phase(PG8_LAS unsigned char* lds, const Gemm g, const Sched& S, const Epi& E) {
;     ...
;             PG8_LDA(At, 0, 1); PG8_STAGE(PG8_SB(0, 0), b2, voffB); PG8_STAGE(PG8_SB(0, 1), b2 + hstep, voffB); PG8_STAGE(PG8_SA(0, 0), a2, voffA);
;             PG8_WAIT_V(8); PG8_WAIT_L(0); PG8_BAR; PG8_MMA(1, 0, At, B0); PG8_MMA(1, 1, At, B1); PG8_BAR; PG8_SCHED;
;             PG8_LDB(B0, 1, 0); PG8_LDB(B1, 1, 1); PG8_SCHED; PG8_LDA(At, 1, 0); PG8_STAGE(PG8_SA(0, 1), a2 + hstep, voffA);
	s_add_i32 s68, s58, s50
	s_add_u32 s98, s38, s8
	s_addc_u32 s99, s39, s9
	s_add_u32 s100, s42, s8
	s_addc_u32 s101, s43, s9
	s_mov_b32 m0, s68
	ds_read_b128 v[186:189], v152 offset:16384
	ds_read_b128 v[190:193], v152 offset:17408
	ds_read_b128 v[198:201], v152 offset:18432
	ds_read_b128 v[202:205], v152 offset:19456
	ds_read_b128 v[206:209], v152 offset:20480
	ds_read_b128 v[210:213], v152 offset:21504
	ds_read_b128 v[214:217], v152 offset:22528
	ds_read_b128 v[218:221], v152 offset:23552
	global_load_lds_dwordx4 v132, s[38:39]
	s_add_i32 m0, s68, 0x2000
	s_add_u32 s68, s38, 0x40000
	s_addc_u32 s69, s39, 0
	s_add_i32 s70, s59, s50
	global_load_lds_dwordx4 v128, s[38:39]
	s_mov_b32 m0, s70
	s_nop 0
	global_load_lds_dwordx4 v132, s[68:69]
	s_add_i32 m0, s70, 0x2000
	s_nop 0
	global_load_lds_dwordx4 v128, s[68:69]
	s_mov_b32 m0, s35
	s_nop 0
	global_load_lds_dwordx4 v134, s[42:43]
	s_mov_b32 m0, s52
	s_nop 0
	global_load_lds_dwordx4 v130, s[42:43]
	s_waitcnt vmcnt(8)
	s_waitcnt lgkmcnt(0)
	s_barrier
	s_waitcnt lgkmcnt(0)
	v_mfma_f32_16x16x32_bf16 v[60:63], v[154:157], v[186:189], v[60:63]
	v_mfma_f32_16x16x32_bf16 v[52:55], v[162:165], v[186:189], v[52:55]
	v_mfma_f32_16x16x32_bf16 v[44:47], v[154:157], v[198:201], v[44:47]
	v_mfma_f32_16x16x32_bf16 v[36:39], v[162:165], v[198:201], v[36:39]
	v_mfma_f32_16x16x32_bf16 v[28:31], v[154:157], v[206:209], v[28:31]
	v_mfma_f32_16x16x32_bf16 v[20:23], v[162:165], v[206:209], v[20:23]
	v_mfma_f32_16x16x32_bf16 v[12:15], v[154:157], v[214:217], v[12:15]
	v_mfma_f32_16x16x32_bf16 v[4:7], v[162:165], v[214:217], v[4:7]
	v_mfma_f32_16x16x32_bf16 v[60:63], v[158:161], v[190:193], v[60:63]
	v_mfma_f32_16x16x32_bf16 v[52:55], v[166:169], v[190:193], v[52:55]
	v_mfma_f32_16x16x32_bf16 v[44:47], v[158:161], v[202:205], v[44:47]
	v_mfma_f32_16x16x32_bf16 v[36:39], v[166:169], v[202:205], v[36:39]
	v_mfma_f32_16x16x32_bf16 v[28:31], v[158:161], v[210:213], v[28:31]
	v_mfma_f32_16x16x32_bf16 v[20:23], v[166:169], v[210:213], v[20:23]
	v_mfma_f32_16x16x32_bf16 v[12:15], v[158:161], v[218:221], v[12:15]
	v_mfma_f32_16x16x32_bf16 v[4:7], v[166:169], v[218:221], v[4:7]
	v_mfma_f32_16x16x32_bf16 v[56:59], v[170:173], v[186:189], v[56:59]
	v_mfma_f32_16x16x32_bf16 v[48:51], v[178:181], v[186:189], v[48:51]
	v_mfma_f32_16x16x32_bf16 v[40:43], v[170:173], v[198:201], v[40:43]
	v_mfma_f32_16x16x32_bf16 v[32:35], v[178:181], v[198:201], v[32:35]
	v_mfma_f32_16x16x32_bf16 v[24:27], v[170:173], v[206:209], v[24:27]
	v_mfma_f32_16x16x32_bf16 v[16:19], v[178:181], v[206:209], v[16:19]
	v_mfma_f32_16x16x32_bf16 v[8:11], v[170:173], v[214:217], v[8:11]
	v_mfma_f32_16x16x32_bf16 v[0:3], v[178:181], v[214:217], v[0:3]
	v_mfma_f32_16x16x32_bf16 v[56:59], v[174:177], v[190:193], v[56:59]
	v_mfma_f32_16x16x32_bf16 v[48:51], v[182:185], v[190:193], v[48:51]
	v_mfma_f32_16x16x32_bf16 v[40:43], v[174:177], v[202:205], v[40:43]
	v_mfma_f32_16x16x32_bf16 v[32:35], v[182:185], v[202:205], v[32:35]
	v_mfma_f32_16x16x32_bf16 v[24:27], v[174:177], v[210:213], v[24:27]
	v_mfma_f32_16x16x32_bf16 v[16:19], v[182:185], v[210:213], v[16:19]
	v_mfma_f32_16x16x32_bf16 v[8:11], v[174:177], v[218:221], v[8:11]
	v_mfma_f32_16x16x32_bf16 v[0:3], v[182:185], v[218:221], v[0:3]
	s_barrier
	s_add_i32 s68, 0, 0x18000
	v_add_u32_e32 v153, s68, v147
	s_add_i32 s69, 0, 0x1c000
	ds_read_b128 v[154:157], v153
	ds_read_b128 v[158:161], v153 offset:1024
	ds_read_b128 v[162:165], v153 offset:2048
	ds_read_b128 v[166:169], v153 offset:3072
	v_add_u32_e32 v153, s69, v147
	ds_read_b128 v[170:173], v153
	ds_read_b128 v[174:177], v153 offset:1024
	ds_read_b128 v[178:181], v153 offset:2048
	ds_read_b128 v[182:185], v153 offset:3072
	s_add_u32 s42, s42, 0x40000
	s_addc_u32 s43, s43, 0
	s_mov_b32 m0, s53
	ds_read_b128 v[186:189], v152 offset:32768
	ds_read_b128 v[190:193], v152 offset:33792
	ds_read_b128 v[198:201], v152 offset:34816
	ds_read_b128 v[202:205], v152 offset:35840
	ds_read_b128 v[206:209], v152 offset:36864
	ds_read_b128 v[210:213], v152 offset:37888
	ds_read_b128 v[214:217], v152 offset:38912
	ds_read_b128 v[218:221], v152 offset:39936
	global_load_lds_dwordx4 v134, s[42:43]
	s_mov_b32 m0, s54
	s_nop 0
	global_load_lds_dwordx4 v130, s[42:43]
	s_waitcnt vmcnt(8)
	s_waitcnt lgkmcnt(0)
	s_barrier
; #define PG8_STAGE(bufoff, gbase, voff) do { _Pragma("unroll") for (int _i = 0; _i < 2; ++_i) \
;         __builtin_amdgcn_global_load_lds((const unsigned*)((const char*)(gbase) + (voff)[_i]), (PG8_LAS unsigned*)(lds + (bufoff) + ldsw + _i * 8192), 16, 0, 0); } while (0)
; #define PG8_LDA(dst, b, h) do { _Pragma("unroll") for (int m = 0; m < 4; ++m) _Pragma("unroll") for (int k = 0; k < 2; ++k) dst[m][k] = *(const PG8_LAS bf16x8*)(lds + PG8_SA(b, h) + aoff + m * 2048 + k * 1024); } while (0)
; #define PG8_LDB(dst, b, h) do { _Pragma("unroll") for (int n = 0; n < 2; ++n) _Pragma("unroll") for (int k = 0; k < 2; ++k) dst[n][k] = *(const PG8_LAS bf16x8*)(lds + PG8_SB(b, h) + boff + n * 2048 + k * 1024); } while (0)
; #define PG8_MMA(ai, bj, At, Bt) do { __builtin_amdgcn_s_setprio(1); _Pragma("unroll") for (int m = 0; m < 4; ++m) _Pragma("unroll") for (int n = 0; n < 2; ++n) _Pragma("unroll") for (int k = 0; k < 2; ++k) \
;         acc[ai][bj][m][n] = __builtin_amdgcn_mfma_f32_16x16x32_bf16(Bt[n][k], At[m][k], acc[ai][bj][m][n], 0, 0, 0); __builtin_amdgcn_s_setprio(0); } while (0)
; #define PG8_WAIT_V(n) asm volatile("s_waitcnt vmcnt(" #n ")" ::: "memory")
; #define PG8_WAIT_L(n) asm volatile("s_waitcnt lgkmcnt(" #n ")" ::: "memory")
; #define PG8_BAR __builtin_amdgcn_s_barrier()
; #define PG8_SCHED __builtin_amdgcn_sched_barrier(0)
; template <class Epi, class Sched, bool ALIGN_EPI = false, bool SP2 = false>
; __device__ __forceinline__ void gemm_phase(PG8_LAS unsigned char* lds, const Gemm g, const Sched& S, const Epi& E) {
;     ...
;             PG8_LDB(B0, 1, 0); PG8_LDB(B1, 1, 1); PG8_SCHED; PG8_LDA(At, 1, 0); PG8_STAGE(PG8_SA(0, 1), a2 + hstep, voffA);
;             PG8_WAIT_V(8); PG8_WAIT_L(0); PG8_BAR; PG8_MMA(0, 0, At, B0); PG8_MMA(0, 1, At, B1); PG8_BAR; PG8_SCHED;
;             PG8_LDA(At, 1, 1); PG8_STAGE(PG8_SB(1, 0), b3, voffB); PG8_STAGE(PG8_SB(1, 1), b3 + hstep, voffB); PG8_STAGE(PG8_SA(1, 0), a3, voffA);
;             PG8_WAIT_V(8); PG8_WAIT_L(0); PG8_BAR; PG8_MMA(1, 0, At, B0); PG8_MMA(1, 1, At, B1); PG8_BAR; PG8_SCHED;
;     ...
;         if constexpr (ALIGN_EPI) { if (wr == 0) PG8_BAR; }
	s_waitcnt lgkmcnt(0)
	v_mfma_f32_16x16x32_bf16 v[124:127], v[154:157], v[186:189], v[124:127]
	v_mfma_f32_16x16x32_bf16 v[116:119], v[162:165], v[186:189], v[116:119]
	v_mfma_f32_16x16x32_bf16 v[108:111], v[154:157], v[198:201], v[108:111]
	v_mfma_f32_16x16x32_bf16 v[100:103], v[162:165], v[198:201], v[100:103]
	v_mfma_f32_16x16x32_bf16 v[92:95], v[154:157], v[206:209], v[92:95]
	v_mfma_f32_16x16x32_bf16 v[84:87], v[162:165], v[206:209], v[84:87]
	v_mfma_f32_16x16x32_bf16 v[76:79], v[154:157], v[214:217], v[76:79]
	v_mfma_f32_16x16x32_bf16 v[68:71], v[162:165], v[214:217], v[68:71]
	v_mfma_f32_16x16x32_bf16 v[124:127], v[158:161], v[190:193], v[124:127]
	v_mfma_f32_16x16x32_bf16 v[116:119], v[166:169], v[190:193], v[116:119]
	v_mfma_f32_16x16x32_bf16 v[108:111], v[158:161], v[202:205], v[108:111]
	v_mfma_f32_16x16x32_bf16 v[100:103], v[166:169], v[202:205], v[100:103]
	v_mfma_f32_16x16x32_bf16 v[92:95], v[158:161], v[210:213], v[92:95]
	v_mfma_f32_16x16x32_bf16 v[84:87], v[166:169], v[210:213], v[84:87]
	v_mfma_f32_16x16x32_bf16 v[76:79], v[158:161], v[218:221], v[76:79]
	v_mfma_f32_16x16x32_bf16 v[68:71], v[166:169], v[218:221], v[68:71]
	v_mfma_f32_16x16x32_bf16 v[120:123], v[170:173], v[186:189], v[120:123]
	v_mfma_f32_16x16x32_bf16 v[112:115], v[178:181], v[186:189], v[112:115]
	v_mfma_f32_16x16x32_bf16 v[104:107], v[170:173], v[198:201], v[104:107]
	v_mfma_f32_16x16x32_bf16 v[96:99], v[178:181], v[198:201], v[96:99]
	v_mfma_f32_16x16x32_bf16 v[88:91], v[170:173], v[206:209], v[88:91]
	v_mfma_f32_16x16x32_bf16 v[80:83], v[178:181], v[206:209], v[80:83]
	v_mfma_f32_16x16x32_bf16 v[72:75], v[170:173], v[214:217], v[72:75]
	v_mfma_f32_16x16x32_bf16 v[64:67], v[178:181], v[214:217], v[64:67]
	v_mfma_f32_16x16x32_bf16 v[120:123], v[174:177], v[190:193], v[120:123]
	v_mfma_f32_16x16x32_bf16 v[112:115], v[182:185], v[190:193], v[112:115]
	v_mfma_f32_16x16x32_bf16 v[104:107], v[174:177], v[202:205], v[104:107]
	v_mfma_f32_16x16x32_bf16 v[96:99], v[182:185], v[202:205], v[96:99]
	v_mfma_f32_16x16x32_bf16 v[88:91], v[174:177], v[210:213], v[88:91]
	v_mfma_f32_16x16x32_bf16 v[80:83], v[182:185], v[210:213], v[80:83]
	v_mfma_f32_16x16x32_bf16 v[72:75], v[174:177], v[218:221], v[72:75]
	v_mfma_f32_16x16x32_bf16 v[64:67], v[182:185], v[218:221], v[64:67]
	s_barrier
	s_add_i32 s42, s68, s50
	s_mov_b32 m0, s42
	ds_read_b128 v[186:189], v152 offset:49152
	ds_read_b128 v[190:193], v152 offset:50176
	ds_read_b128 v[198:201], v152 offset:51200
	ds_read_b128 v[202:205], v152 offset:52224
	ds_read_b128 v[206:209], v152 offset:53248
	ds_read_b128 v[210:213], v152 offset:54272
	ds_read_b128 v[214:217], v152 offset:55296
	ds_read_b128 v[218:221], v152 offset:56320
	global_load_lds_dwordx4 v132, s[98:99]
	s_add_i32 m0, s42, 0x2000
	s_add_u32 s38, s38, 0x40080
	s_addc_u32 s39, s39, 0
	s_add_i32 s42, s69, s50
	global_load_lds_dwordx4 v128, s[98:99]
	s_mov_b32 m0, s42
	s_nop 0
	global_load_lds_dwordx4 v132, s[38:39]
	s_add_i32 m0, s42, 0x2000
	s_nop 0
	global_load_lds_dwordx4 v128, s[38:39]
	s_mov_b32 m0, s56
	s_nop 0
	global_load_lds_dwordx4 v134, s[100:101]
	s_mov_b32 m0, s57
	s_nop 0
	global_load_lds_dwordx4 v130, s[100:101]
	s_waitcnt vmcnt(8)
	s_waitcnt lgkmcnt(0)
	s_barrier
	s_waitcnt lgkmcnt(0)
	v_mfma_f32_16x16x32_bf16 v[60:63], v[154:157], v[186:189], v[60:63]
	v_mfma_f32_16x16x32_bf16 v[52:55], v[162:165], v[186:189], v[52:55]
	v_mfma_f32_16x16x32_bf16 v[44:47], v[154:157], v[198:201], v[44:47]
	v_mfma_f32_16x16x32_bf16 v[36:39], v[162:165], v[198:201], v[36:39]
	v_mfma_f32_16x16x32_bf16 v[28:31], v[154:157], v[206:209], v[28:31]
	v_mfma_f32_16x16x32_bf16 v[20:23], v[162:165], v[206:209], v[20:23]
	v_mfma_f32_16x16x32_bf16 v[12:15], v[154:157], v[214:217], v[12:15]
	v_mfma_f32_16x16x32_bf16 v[4:7], v[162:165], v[214:217], v[4:7]
	v_mfma_f32_16x16x32_bf16 v[60:63], v[158:161], v[190:193], v[60:63]
	v_mfma_f32_16x16x32_bf16 v[52:55], v[166:169], v[190:193], v[52:55]
	v_mfma_f32_16x16x32_bf16 v[44:47], v[158:161], v[202:205], v[44:47]
	v_mfma_f32_16x16x32_bf16 v[36:39], v[166:169], v[202:205], v[36:39]
	v_mfma_f32_16x16x32_bf16 v[28:31], v[158:161], v[210:213], v[28:31]
	v_mfma_f32_16x16x32_bf16 v[20:23], v[166:169], v[210:213], v[20:23]
	v_mfma_f32_16x16x32_bf16 v[12:15], v[158:161], v[218:221], v[12:15]
	v_mfma_f32_16x16x32_bf16 v[4:7], v[166:169], v[218:221], v[4:7]
	v_mfma_f32_16x16x32_bf16 v[56:59], v[170:173], v[186:189], v[56:59]
	v_mfma_f32_16x16x32_bf16 v[48:51], v[178:181], v[186:189], v[48:51]
	v_mfma_f32_16x16x32_bf16 v[40:43], v[170:173], v[198:201], v[40:43]
	v_mfma_f32_16x16x32_bf16 v[32:35], v[178:181], v[198:201], v[32:35]
	v_mfma_f32_16x16x32_bf16 v[24:27], v[170:173], v[206:209], v[24:27]
	v_mfma_f32_16x16x32_bf16 v[16:19], v[178:181], v[206:209], v[16:19]
	v_mfma_f32_16x16x32_bf16 v[8:11], v[170:173], v[214:217], v[8:11]
	v_mfma_f32_16x16x32_bf16 v[0:3], v[178:181], v[214:217], v[0:3]
	v_mfma_f32_16x16x32_bf16 v[56:59], v[174:177], v[190:193], v[56:59]
	v_mfma_f32_16x16x32_bf16 v[48:51], v[182:185], v[190:193], v[48:51]
	v_mfma_f32_16x16x32_bf16 v[40:43], v[174:177], v[202:205], v[40:43]
	v_mfma_f32_16x16x32_bf16 v[32:35], v[182:185], v[202:205], v[32:35]
	v_mfma_f32_16x16x32_bf16 v[24:27], v[174:177], v[210:213], v[24:27]
	v_mfma_f32_16x16x32_bf16 v[16:19], v[182:185], v[210:213], v[16:19]
	v_mfma_f32_16x16x32_bf16 v[8:11], v[174:177], v[218:221], v[8:11]
	v_mfma_f32_16x16x32_bf16 v[0:3], v[182:185], v[218:221], v[0:3]
	s_barrier
	s_add_i32 s67, s67, 2
	s_add_u32 s20, s20, 0x100
	s_addc_u32 s21, s21, 0
	s_add_u32 s65, s65, 0x100
	s_addc_u32 s66, s66, 0
	s_cmp_gt_u32 s67, 13
	s_cbranch_scc0 .LBB0_1740
	s_and_b64 vcc, exec, s[10:11]
	s_cbranch_vccz .LBB0_1743
	s_barrier

; #define PG8_STAGE(bufoff, gbase, voff) do { _Pragma("unroll") for (int _i = 0; _i < 2; ++_i) \
;         __builtin_amdgcn_global_load_lds((const unsigned*)((const char*)(gbase) + (voff)[_i]), (PG8_LAS unsigned*)(lds + (bufoff) + ldsw + _i * 8192), 16, 0, 0); } while (0)
; #define PG8_LDA(dst, b, h) do { _Pragma("unroll") for (int m = 0; m < 4; ++m) _Pragma("unroll") for (int k = 0; k < 2; ++k) dst[m][k] = *(const PG8_LAS bf16x8*)(lds + PG8_SA(b, h) + aoff + m * 2048 + k * 1024); } while (0)
; #define PG8_LDB(dst, b, h) do { _Pragma("unroll") for (int n = 0; n < 2; ++n) _Pragma("unroll") for (int k = 0; k < 2; ++k) dst[n][k] = *(const PG8_LAS bf16x8*)(lds + PG8_SB(b, h) + boff + n * 2048 + k * 1024); } while (0)
; #define PG8_WAIT_V(n) asm volatile("s_waitcnt vmcnt(" #n ")" ::: "memory")
; #define PG8_WAIT_L(n) asm volatile("s_waitcnt lgkmcnt(" #n ")" ::: "memory")
; #define PG8_BAR __builtin_amdgcn_s_barrier()
; #define PG8_SCHED __builtin_amdgcn_sched_barrier(0)
; template <class Epi, class Sched, bool ALIGN_EPI = false, bool SP2 = false>
; __device__ __forceinline__ void gemm_phase(PG8_LAS unsigned char* lds, const Gemm g, const Sched& S, const Epi& E) {
;     ...
;         const char* nA = has_next ? (const char*)g.A + (size_t)nxt.pm * tstep : cA; const char* nB = has_next ? (const char*)g.Bt + (size_t)nxt.pn * tstep : cB;
;         for (int t = 0; t < nt; t += 2) {
;             const bool last = (t == nt - 2);
;             const char* a1 = cA + (size_t)(t + 1) * kstep;
;             const char* a2 = last ? nA : cA + (size_t)(t + 2) * kstep; const char* b2 = last ? nB : cB + (size_t)(t + 2) * kstep;
;             const char* a3 = a2 + kstep; const char* b3 = b2 + kstep;
;             if (last && has_next) S.a_ready(nxt);
;             if constexpr (SP2) {
;             PG8_LDB(B0, 0, 0); PG8_LDB(B1, 0, 1); PG8_SCHED; PG8_LDA(At, 0, 0); PG8_STAGE(PG8_SA(1, 1), a1 + hstep, voffA);
;             PG8_WAIT_V(8); PG8_WAIT_L(0); PG8_BAR; PG8_MMA(0, 0, At, B0); PG8_MMA(0, 1, At, B1); PG8_BAR; PG8_SCHED;
;             PG8_LDA(At, 0, 1); PG8_STAGE(PG8_SB(0, 0), b2, voffB); PG8_STAGE(PG8_SB(0, 1), b2 + hstep, voffB); PG8_STAGE(PG8_SA(0, 0), a2, voffA);
;             PG8_WAIT_V(8); PG8_WAIT_L(0); PG8_BAR; PG8_MMA(1, 0, At, B0); PG8_MMA(1, 1, At, B1); PG8_BAR; PG8_SCHED;
.LBB0_1824:
	s_add_u32 s20, s20, 0xb0080
	s_addc_u32 s21, s21, 0
	s_add_u32 s68, s34, 0x100
	s_addc_u32 s69, s35, 0
	s_mov_b32 s70, -2
	s_waitcnt lgkmcnt(0)
	ds_read_b128 v[96:99], v222
	ds_read_b128 v[108:111], v222 offset:1024
	ds_read_b128 v[120:123], v222 offset:2048
	ds_read_b128 v[128:131], v222 offset:3072
	ds_read_b128 v[144:147], v223
	ds_read_b128 v[148:151], v223 offset:1024
	ds_read_b128 v[152:155], v223 offset:2048
	ds_read_b128 v[156:159], v223 offset:3072
	s_add_u32 s34, s20, 0xfff50080
	s_addc_u32 s35, s21, -1
	s_cmp_eq_u32 s70, 40
	s_cselect_b32 s47, s1, s35
	s_cselect_b32 s46, s0, s34
	s_cselect_b32 s35, s45, s69
	s_cselect_b32 s34, s44, s68
	s_add_i32 m0, s49, 0xc000
	ds_read_b128 v[160:163], v224
	ds_read_b128 v[164:167], v224 offset:1024
	ds_read_b128 v[168:171], v224 offset:2048
	ds_read_b128 v[172:175], v224 offset:3072
	ds_read_b128 v[176:179], v224 offset:4096
	ds_read_b128 v[180:183], v224 offset:5120
	ds_read_b128 v[202:205], v224 offset:6144
	ds_read_b128 v[206:209], v224 offset:7168
	global_load_lds_dwordx4 v192, s[20:21]
	s_add_i32 m0, s49, 0xe000
	s_nop 0
	global_load_lds_dwordx4 v194, s[20:21]
	s_waitcnt vmcnt(8)
	s_waitcnt lgkmcnt(0)
	s_barrier
	s_waitcnt lgkmcnt(0)
	v_mfma_f32_16x16x32_bf16 v[140:143], v[96:99], v[160:163], 0
	v_mfma_f32_16x16x32_bf16 v[136:139], v[120:123], v[160:163], 0
	v_mfma_f32_16x16x32_bf16 v[116:119], v[96:99], v[168:171], 0
	v_mfma_f32_16x16x32_bf16 v[112:115], v[120:123], v[168:171], 0
	v_mfma_f32_16x16x32_bf16 v[92:95], v[96:99], v[176:179], 0
	v_mfma_f32_16x16x32_bf16 v[88:91], v[120:123], v[176:179], 0
	v_mfma_f32_16x16x32_bf16 v[76:79], v[96:99], v[202:205], 0
	v_mfma_f32_16x16x32_bf16 v[72:75], v[120:123], v[202:205], 0
	v_mfma_f32_16x16x32_bf16 v[140:143], v[108:111], v[164:167], v[140:143]
	v_mfma_f32_16x16x32_bf16 v[136:139], v[128:131], v[164:167], v[136:139]
	v_mfma_f32_16x16x32_bf16 v[116:119], v[108:111], v[172:175], v[116:119]
	v_mfma_f32_16x16x32_bf16 v[112:115], v[128:131], v[172:175], v[112:115]
	v_mfma_f32_16x16x32_bf16 v[92:95], v[108:111], v[180:183], v[92:95]
	v_mfma_f32_16x16x32_bf16 v[88:91], v[128:131], v[180:183], v[88:91]
	v_mfma_f32_16x16x32_bf16 v[76:79], v[108:111], v[206:209], v[76:79]
	v_mfma_f32_16x16x32_bf16 v[72:75], v[128:131], v[206:209], v[72:75]
	v_mfma_f32_16x16x32_bf16 v[132:135], v[144:147], v[160:163], 0
	v_mfma_f32_16x16x32_bf16 v[124:127], v[152:155], v[160:163], 0
	v_mfma_f32_16x16x32_bf16 v[104:107], v[144:147], v[168:171], 0
	v_mfma_f32_16x16x32_bf16 v[100:103], v[152:155], v[168:171], 0
	v_mfma_f32_16x16x32_bf16 v[84:87], v[144:147], v[176:179], 0
	v_mfma_f32_16x16x32_bf16 v[80:83], v[152:155], v[176:179], 0
	v_mfma_f32_16x16x32_bf16 v[68:71], v[144:147], v[202:205], 0
	v_mfma_f32_16x16x32_bf16 v[64:67], v[152:155], v[202:205], 0
	v_mfma_f32_16x16x32_bf16 v[132:135], v[148:151], v[164:167], v[132:135]
	v_mfma_f32_16x16x32_bf16 v[124:127], v[156:159], v[164:167], v[124:127]
	v_mfma_f32_16x16x32_bf16 v[104:107], v[148:151], v[172:175], v[104:107]
	v_mfma_f32_16x16x32_bf16 v[100:103], v[156:159], v[172:175], v[100:103]
	v_mfma_f32_16x16x32_bf16 v[84:87], v[148:151], v[180:183], v[84:87]
	v_mfma_f32_16x16x32_bf16 v[80:83], v[156:159], v[180:183], v[80:83]
	v_mfma_f32_16x16x32_bf16 v[68:71], v[148:151], v[206:209], v[68:71]
	v_mfma_f32_16x16x32_bf16 v[64:67], v[156:159], v[206:209], v[64:67]
	s_barrier
	s_add_i32 s71, s62, s48
	s_add_u32 s98, s34, s12
	s_addc_u32 s99, s35, s13
	s_add_u32 s100, s46, s12
	s_addc_u32 s101, s47, s13
	s_mov_b32 m0, s71
	ds_read_b128 v[160:163], v224 offset:16384
	ds_read_b128 v[164:167], v224 offset:17408
	ds_read_b128 v[168:171], v224 offset:18432
	ds_read_b128 v[172:175], v224 offset:19456
	ds_read_b128 v[176:179], v224 offset:20480
	ds_read_b128 v[180:183], v224 offset:21504
	ds_read_b128 v[202:205], v224 offset:22528
	ds_read_b128 v[206:209], v224 offset:23552
	global_load_lds_dwordx4 v186, s[34:35]
	s_add_i32 m0, s71, 0x2000
	s_add_u32 s72, s34, 0xb0000
	s_addc_u32 s73, s35, 0
	s_add_i32 s71, s63, s48
	global_load_lds_dwordx4 v190, s[34:35]
	s_mov_b32 m0, s71
	s_nop 0
	global_load_lds_dwordx4 v186, s[72:73]
	s_add_i32 m0, s71, 0x2000
	s_nop 0
	global_load_lds_dwordx4 v190, s[72:73]
	s_mov_b32 m0, s49
	s_nop 0
	global_load_lds_dwordx4 v184, s[46:47]
	s_mov_b32 m0, s50
	s_nop 0
	global_load_lds_dwordx4 v188, s[46:47]
	s_waitcnt vmcnt(8)
	s_waitcnt lgkmcnt(0)
	s_barrier
	s_waitcnt lgkmcnt(0)
	v_mfma_f32_16x16x32_bf16 v[60:63], v[96:99], v[160:163], 0
	v_mfma_f32_16x16x32_bf16 v[56:59], v[120:123], v[160:163], 0
	v_mfma_f32_16x16x32_bf16 v[44:47], v[96:99], v[168:171], 0
	v_mfma_f32_16x16x32_bf16 v[40:43], v[120:123], v[168:171], 0
	v_mfma_f32_16x16x32_bf16 v[28:31], v[96:99], v[176:179], 0
	v_mfma_f32_16x16x32_bf16 v[24:27], v[120:123], v[176:179], 0
	v_mfma_f32_16x16x32_bf16 v[12:15], v[96:99], v[202:205], 0
	v_mfma_f32_16x16x32_bf16 v[8:11], v[120:123], v[202:205], 0
	v_mfma_f32_16x16x32_bf16 v[60:63], v[108:111], v[164:167], v[60:63]
	v_mfma_f32_16x16x32_bf16 v[56:59], v[128:131], v[164:167], v[56:59]
	v_mfma_f32_16x16x32_bf16 v[44:47], v[108:111], v[172:175], v[44:47]
	v_mfma_f32_16x16x32_bf16 v[40:43], v[128:131], v[172:175], v[40:43]
	v_mfma_f32_16x16x32_bf16 v[28:31], v[108:111], v[180:183], v[28:31]
	v_mfma_f32_16x16x32_bf16 v[24:27], v[128:131], v[180:183], v[24:27]
	v_mfma_f32_16x16x32_bf16 v[12:15], v[108:111], v[206:209], v[12:15]
	v_mfma_f32_16x16x32_bf16 v[8:11], v[128:131], v[206:209], v[8:11]
	v_mfma_f32_16x16x32_bf16 v[52:55], v[144:147], v[160:163], 0
	v_mfma_f32_16x16x32_bf16 v[48:51], v[152:155], v[160:163], 0
	v_mfma_f32_16x16x32_bf16 v[36:39], v[144:147], v[168:171], 0
	v_mfma_f32_16x16x32_bf16 v[32:35], v[152:155], v[168:171], 0
	v_mfma_f32_16x16x32_bf16 v[20:23], v[144:147], v[176:179], 0
	v_mfma_f32_16x16x32_bf16 v[16:19], v[152:155], v[176:179], 0
	v_mfma_f32_16x16x32_bf16 v[4:7], v[144:147], v[202:205], 0
	v_mfma_f32_16x16x32_bf16 v[0:3], v[152:155], v[202:205], 0
	v_mfma_f32_16x16x32_bf16 v[52:55], v[148:151], v[164:167], v[52:55]
	v_mfma_f32_16x16x32_bf16 v[48:51], v[156:159], v[164:167], v[48:51]
	v_mfma_f32_16x16x32_bf16 v[36:39], v[148:151], v[172:175], v[36:39]
	v_mfma_f32_16x16x32_bf16 v[32:35], v[156:159], v[172:175], v[32:35]
	v_mfma_f32_16x16x32_bf16 v[20:23], v[148:151], v[180:183], v[20:23]
	v_mfma_f32_16x16x32_bf16 v[16:19], v[156:159], v[180:183], v[16:19]
	v_mfma_f32_16x16x32_bf16 v[4:7], v[148:151], v[206:209], v[4:7]
	v_mfma_f32_16x16x32_bf16 v[0:3], v[156:159], v[206:209], v[0:3]
	s_barrier
; #define PG8_STAGE(bufoff, gbase, voff) do { _Pragma("unroll") for (int _i = 0; _i < 2; ++_i) \
;         __builtin_amdgcn_global_load_lds((const unsigned*)((const char*)(gbase) + (voff)[_i]), (PG8_LAS unsigned*)(lds + (bufoff) + ldsw + _i * 8192), 16, 0, 0); } while (0)
; #define PG8_LDA(dst, b, h) do { _Pragma("unroll") for (int m = 0; m < 4; ++m) _Pragma("unroll") for (int k = 0; k < 2; ++k) dst[m][k] = *(const PG8_LAS bf16x8*)(lds + PG8_SA(b, h) + aoff + m * 2048 + k * 1024); } while (0)
; #define PG8_LDB(dst, b, h) do { _Pragma("unroll") for (int n = 0; n < 2; ++n) _Pragma("unroll") for (int k = 0; k < 2; ++k) dst[n][k] = *(const PG8_LAS bf16x8*)(lds + PG8_SB(b, h) + boff + n * 2048 + k * 1024); } while (0)
; #define PG8_MMA(ai, bj, At, Bt) do { __builtin_amdgcn_s_setprio(1); _Pragma("unroll") for (int m = 0; m < 4; ++m) _Pragma("unroll") for (int n = 0; n < 2; ++n) _Pragma("unroll") for (int k = 0; k < 2; ++k) \
;         acc[ai][bj][m][n] = __builtin_amdgcn_mfma_f32_16x16x32_bf16(Bt[n][k], At[m][k], acc[ai][bj][m][n], 0, 0, 0); __builtin_amdgcn_s_setprio(0); } while (0)
; #define PG8_WAIT_V(n) asm volatile("s_waitcnt vmcnt(" #n ")" ::: "memory")
; #define PG8_WAIT_L(n) asm volatile("s_waitcnt lgkmcnt(" #n ")" ::: "memory")
; #define PG8_BAR __builtin_amdgcn_s_barrier()
; #define PG8_SCHED __builtin_amdgcn_sched_barrier(0)
; template <class Epi, class Sched, bool ALIGN_EPI = false, bool SP2 = false>
; __device__ __forceinline__ void gemm_phase(PG8_LAS unsigned char* lds, const Gemm g, const Sched& S, const Epi& E) {
;     ...
;             PG8_LDB(B0, 1, 0); PG8_LDB(B1, 1, 1); PG8_SCHED; PG8_LDA(At, 1, 0); PG8_STAGE(PG8_SA(0, 1), a2 + hstep, voffA);
;             PG8_WAIT_V(8); PG8_WAIT_L(0); PG8_BAR; PG8_MMA(0, 0, At, B0); PG8_MMA(0, 1, At, B1); PG8_BAR; PG8_SCHED;
;             PG8_LDA(At, 1, 1); PG8_STAGE(PG8_SB(1, 0), b3, voffB); PG8_STAGE(PG8_SB(1, 1), b3 + hstep, voffB); PG8_STAGE(PG8_SA(1, 0), a3, voffA);
;             PG8_WAIT_V(8); PG8_WAIT_L(0); PG8_BAR; PG8_MMA(1, 0, At, B0); PG8_MMA(1, 1, At, B1); PG8_BAR; PG8_SCHED;
	s_add_i32 s71, 0, 0x18000
	s_add_i32 s72, 0, 0x1c000
	v_add_u32_e32 v128, s71, v197
	v_add_u32_e32 v156, s72, v197
	ds_read_b128 v[96:99], v128
	ds_read_b128 v[108:111], v128 offset:1024
	ds_read_b128 v[120:123], v128 offset:2048
	ds_read_b128 v[128:131], v128 offset:3072
	ds_read_b128 v[144:147], v156
	ds_read_b128 v[148:151], v156 offset:1024
	ds_read_b128 v[152:155], v156 offset:2048
	ds_read_b128 v[156:159], v156 offset:3072
	s_add_u32 s46, s46, 0xb0000
	s_addc_u32 s47, s47, 0
	s_mov_b32 m0, s51
	ds_read_b128 v[160:163], v224 offset:32768
	ds_read_b128 v[164:167], v224 offset:33792
	ds_read_b128 v[168:171], v224 offset:34816
	ds_read_b128 v[172:175], v224 offset:35840
	ds_read_b128 v[176:179], v224 offset:36864
	ds_read_b128 v[180:183], v224 offset:37888
	ds_read_b128 v[202:205], v224 offset:38912
	ds_read_b128 v[206:209], v224 offset:39936
	global_load_lds_dwordx4 v184, s[46:47]
	s_mov_b32 m0, s52
	s_nop 0
	global_load_lds_dwordx4 v188, s[46:47]
	s_waitcnt vmcnt(8)
	s_waitcnt lgkmcnt(0)
	s_barrier
	s_waitcnt lgkmcnt(0)
	v_mfma_f32_16x16x32_bf16 v[140:143], v[96:99], v[160:163], v[140:143]
	v_mfma_f32_16x16x32_bf16 v[136:139], v[120:123], v[160:163], v[136:139]
	v_mfma_f32_16x16x32_bf16 v[116:119], v[96:99], v[168:171], v[116:119]
	v_mfma_f32_16x16x32_bf16 v[112:115], v[120:123], v[168:171], v[112:115]
	v_mfma_f32_16x16x32_bf16 v[92:95], v[96:99], v[176:179], v[92:95]
	v_mfma_f32_16x16x32_bf16 v[88:91], v[120:123], v[176:179], v[88:91]
	v_mfma_f32_16x16x32_bf16 v[76:79], v[96:99], v[202:205], v[76:79]
	v_mfma_f32_16x16x32_bf16 v[72:75], v[120:123], v[202:205], v[72:75]
	v_mfma_f32_16x16x32_bf16 v[140:143], v[108:111], v[164:167], v[140:143]
	v_mfma_f32_16x16x32_bf16 v[136:139], v[128:131], v[164:167], v[136:139]
	v_mfma_f32_16x16x32_bf16 v[116:119], v[108:111], v[172:175], v[116:119]
	v_mfma_f32_16x16x32_bf16 v[112:115], v[128:131], v[172:175], v[112:115]
	v_mfma_f32_16x16x32_bf16 v[92:95], v[108:111], v[180:183], v[92:95]
	v_mfma_f32_16x16x32_bf16 v[88:91], v[128:131], v[180:183], v[88:91]
	v_mfma_f32_16x16x32_bf16 v[76:79], v[108:111], v[206:209], v[76:79]
	v_mfma_f32_16x16x32_bf16 v[72:75], v[128:131], v[206:209], v[72:75]
	v_mfma_f32_16x16x32_bf16 v[132:135], v[144:147], v[160:163], v[132:135]
	v_mfma_f32_16x16x32_bf16 v[124:127], v[152:155], v[160:163], v[124:127]
	v_mfma_f32_16x16x32_bf16 v[104:107], v[144:147], v[168:171], v[104:107]
	v_mfma_f32_16x16x32_bf16 v[100:103], v[152:155], v[168:171], v[100:103]
	v_mfma_f32_16x16x32_bf16 v[84:87], v[144:147], v[176:179], v[84:87]
	v_mfma_f32_16x16x32_bf16 v[80:83], v[152:155], v[176:179], v[80:83]
	v_mfma_f32_16x16x32_bf16 v[68:71], v[144:147], v[202:205], v[68:71]
	v_mfma_f32_16x16x32_bf16 v[64:67], v[152:155], v[202:205], v[64:67]
	v_mfma_f32_16x16x32_bf16 v[132:135], v[148:151], v[164:167], v[132:135]
	v_mfma_f32_16x16x32_bf16 v[124:127], v[156:159], v[164:167], v[124:127]
	v_mfma_f32_16x16x32_bf16 v[104:107], v[148:151], v[172:175], v[104:107]
	v_mfma_f32_16x16x32_bf16 v[100:103], v[156:159], v[172:175], v[100:103]
	v_mfma_f32_16x16x32_bf16 v[84:87], v[148:151], v[180:183], v[84:87]
	v_mfma_f32_16x16x32_bf16 v[80:83], v[156:159], v[180:183], v[80:83]
	v_mfma_f32_16x16x32_bf16 v[68:71], v[148:151], v[206:209], v[68:71]
	v_mfma_f32_16x16x32_bf16 v[64:67], v[156:159], v[206:209], v[64:67]
	s_barrier
	s_add_i32 s46, s71, s48
	s_mov_b32 m0, s46
	ds_read_b128 v[160:163], v224 offset:49152
	ds_read_b128 v[164:167], v224 offset:50176
	ds_read_b128 v[168:171], v224 offset:51200
	ds_read_b128 v[172:175], v224 offset:52224
	ds_read_b128 v[176:179], v224 offset:53248
	ds_read_b128 v[180:183], v224 offset:54272
	ds_read_b128 v[202:205], v224 offset:55296
	ds_read_b128 v[206:209], v224 offset:56320
	global_load_lds_dwordx4 v186, s[98:99]
	s_add_i32 m0, s46, 0x2000
	s_add_u32 s34, s34, 0xb0080
	s_addc_u32 s35, s35, 0
	s_add_i32 s46, s72, s48
	global_load_lds_dwordx4 v190, s[98:99]
	s_mov_b32 m0, s46
	s_nop 0
	global_load_lds_dwordx4 v186, s[34:35]
	s_add_i32 m0, s46, 0x2000
	s_nop 0
	global_load_lds_dwordx4 v190, s[34:35]
	s_mov_b32 m0, s57
	s_nop 0
	global_load_lds_dwordx4 v184, s[100:101]
	s_mov_b32 m0, s58
	s_nop 0
	global_load_lds_dwordx4 v188, s[100:101]
	s_waitcnt vmcnt(8)
	s_waitcnt lgkmcnt(0)
	s_barrier
	s_waitcnt lgkmcnt(0)
	v_mfma_f32_16x16x32_bf16 v[60:63], v[96:99], v[160:163], v[60:63]
	v_mfma_f32_16x16x32_bf16 v[56:59], v[120:123], v[160:163], v[56:59]
	v_mfma_f32_16x16x32_bf16 v[44:47], v[96:99], v[168:171], v[44:47]
	v_mfma_f32_16x16x32_bf16 v[40:43], v[120:123], v[168:171], v[40:43]
	v_mfma_f32_16x16x32_bf16 v[28:31], v[96:99], v[176:179], v[28:31]
	v_mfma_f32_16x16x32_bf16 v[24:27], v[120:123], v[176:179], v[24:27]
	v_mfma_f32_16x16x32_bf16 v[12:15], v[96:99], v[202:205], v[12:15]
	v_mfma_f32_16x16x32_bf16 v[8:11], v[120:123], v[202:205], v[8:11]
	v_mfma_f32_16x16x32_bf16 v[60:63], v[108:111], v[164:167], v[60:63]
	v_mfma_f32_16x16x32_bf16 v[56:59], v[128:131], v[164:167], v[56:59]
	v_mfma_f32_16x16x32_bf16 v[44:47], v[108:111], v[172:175], v[44:47]
	v_mfma_f32_16x16x32_bf16 v[40:43], v[128:131], v[172:175], v[40:43]
	v_mfma_f32_16x16x32_bf16 v[28:31], v[108:111], v[180:183], v[28:31]
	v_mfma_f32_16x16x32_bf16 v[24:27], v[128:131], v[180:183], v[24:27]
	v_mfma_f32_16x16x32_bf16 v[12:15], v[108:111], v[206:209], v[12:15]
	v_mfma_f32_16x16x32_bf16 v[8:11], v[128:131], v[206:209], v[8:11]
	v_mfma_f32_16x16x32_bf16 v[52:55], v[144:147], v[160:163], v[52:55]
	v_mfma_f32_16x16x32_bf16 v[48:51], v[152:155], v[160:163], v[48:51]
	v_mfma_f32_16x16x32_bf16 v[36:39], v[144:147], v[168:171], v[36:39]
	v_mfma_f32_16x16x32_bf16 v[32:35], v[152:155], v[168:171], v[32:35]
	v_mfma_f32_16x16x32_bf16 v[20:23], v[144:147], v[176:179], v[20:23]
	v_mfma_f32_16x16x32_bf16 v[16:19], v[152:155], v[176:179], v[16:19]
	v_mfma_f32_16x16x32_bf16 v[4:7], v[144:147], v[202:205], v[4:7]
	v_mfma_f32_16x16x32_bf16 v[0:3], v[152:155], v[202:205], v[0:3]
	v_mfma_f32_16x16x32_bf16 v[52:55], v[148:151], v[164:167], v[52:55]
	v_mfma_f32_16x16x32_bf16 v[48:51], v[156:159], v[164:167], v[48:51]
	v_mfma_f32_16x16x32_bf16 v[36:39], v[148:151], v[172:175], v[36:39]
	v_mfma_f32_16x16x32_bf16 v[32:35], v[156:159], v[172:175], v[32:35]
	v_mfma_f32_16x16x32_bf16 v[20:23], v[148:151], v[180:183], v[20:23]
	v_mfma_f32_16x16x32_bf16 v[16:19], v[156:159], v[180:183], v[16:19]
	v_mfma_f32_16x16x32_bf16 v[4:7], v[148:151], v[206:209], v[4:7]
	v_mfma_f32_16x16x32_bf16 v[0:3], v[156:159], v[206:209], v[0:3]
	s_barrier
	s_add_i32 s70, s70, 2
	s_add_u32 s20, s20, 0x100
	s_addc_u32 s21, s21, 0
	s_add_u32 s68, s68, 0x100
	s_addc_u32 s69, s69, 0
	s_cmp_gt_u32 s70, 41
; #define PG8_STAGE(bufoff, gbase, voff) do { _Pragma("unroll") for (int _i = 0; _i < 2; ++_i) \
;         __builtin_amdgcn_global_load_lds((const unsigned*)((const char*)(gbase) + (voff)[_i]), (PG8_LAS unsigned*)(lds + (bufoff) + ldsw + _i * 8192), 16, 0, 0); } while (0)
; #define PG8_LDA(dst, b, h) do { _Pragma("unroll") for (int m = 0; m < 4; ++m) _Pragma("unroll") for (int k = 0; k < 2; ++k) dst[m][k] = *(const PG8_LAS bf16x8*)(lds + PG8_SA(b, h) + aoff + m * 2048 + k * 1024); } while (0)
; #define PG8_LDB(dst, b, h) do { _Pragma("unroll") for (int n = 0; n < 2; ++n) _Pragma("unroll") for (int k = 0; k < 2; ++k) dst[n][k] = *(const PG8_LAS bf16x8*)(lds + PG8_SB(b, h) + boff + n * 2048 + k * 1024); } while (0)
; #define PG8_MMA(ai, bj, At, Bt) do { __builtin_amdgcn_s_setprio(1); _Pragma("unroll") for (int m = 0; m < 4; ++m) _Pragma("unroll") for (int n = 0; n < 2; ++n) _Pragma("unroll") for (int k = 0; k < 2; ++k) \
;         acc[ai][bj][m][n] = __builtin_amdgcn_mfma_f32_16x16x32_bf16(Bt[n][k], At[m][k], acc[ai][bj][m][n], 0, 0, 0); __builtin_amdgcn_s_setprio(0); } while (0)
; #define PG8_WAIT_V(n) asm volatile("s_waitcnt vmcnt(" #n ")" ::: "memory")
; #define PG8_WAIT_L(n) asm volatile("s_waitcnt lgkmcnt(" #n ")" ::: "memory")
; #define PG8_BAR __builtin_amdgcn_s_barrier()
; #define PG8_SCHED __builtin_amdgcn_sched_barrier(0)
; template <class Epi, class Sched, bool ALIGN_EPI = false, bool SP2 = false>
; __device__ __forceinline__ void gemm_phase(PG8_LAS unsigned char* lds, const Gemm g, const Sched& S, const Epi& E) {
;     ...
;             PG8_LDB(B0, 0, 0); PG8_LDB(B1, 0, 1); PG8_SCHED; PG8_LDA(At, 0, 0); PG8_STAGE(PG8_SA(1, 1), a1 + hstep, voffA);
;             PG8_WAIT_V(8); PG8_WAIT_L(0); PG8_BAR; PG8_MMA(0, 0, At, B0); PG8_MMA(0, 1, At, B1); PG8_BAR; PG8_SCHED;
;             PG8_LDA(At, 0, 1); PG8_STAGE(PG8_SB(0, 0), b2, voffB); PG8_STAGE(PG8_SB(0, 1), b2 + hstep, voffB); PG8_STAGE(PG8_SA(0, 0), a2, voffA);
;             PG8_WAIT_V(8); PG8_WAIT_L(0); PG8_BAR; PG8_MMA(1, 0, At, B0); PG8_MMA(1, 1, At, B1); PG8_BAR; PG8_SCHED;
.LBB0_1825:
	ds_read_b128 v[96:99], v222
	ds_read_b128 v[108:111], v222 offset:1024
	ds_read_b128 v[120:123], v222 offset:2048
	ds_read_b128 v[128:131], v222 offset:3072
	ds_read_b128 v[144:147], v223
	ds_read_b128 v[148:151], v223 offset:1024
	ds_read_b128 v[152:155], v223 offset:2048
	ds_read_b128 v[156:159], v223 offset:3072
	s_add_u32 s34, s20, 0xfff50080
	s_addc_u32 s35, s21, -1
	s_cmp_eq_u32 s70, 40
	s_cselect_b32 s47, s1, s35
	s_cselect_b32 s46, s0, s34
	s_cselect_b32 s35, s45, s69
	s_cselect_b32 s34, s44, s68
	s_add_i32 m0, s49, 0xc000
	ds_read_b128 v[160:163], v224
	ds_read_b128 v[164:167], v224 offset:1024
	ds_read_b128 v[168:171], v224 offset:2048
	ds_read_b128 v[172:175], v224 offset:3072
	ds_read_b128 v[176:179], v224 offset:4096
	ds_read_b128 v[180:183], v224 offset:5120
	ds_read_b128 v[202:205], v224 offset:6144
	ds_read_b128 v[206:209], v224 offset:7168
	global_load_lds_dwordx4 v192, s[20:21]
	s_add_i32 m0, s49, 0xe000
	s_nop 0
	global_load_lds_dwordx4 v194, s[20:21]
	s_waitcnt vmcnt(8)
	s_waitcnt lgkmcnt(0)
	s_barrier
	s_waitcnt lgkmcnt(0)
	v_mfma_f32_16x16x32_bf16 v[140:143], v[96:99], v[160:163], v[140:143]
	v_mfma_f32_16x16x32_bf16 v[136:139], v[120:123], v[160:163], v[136:139]
	v_mfma_f32_16x16x32_bf16 v[116:119], v[96:99], v[168:171], v[116:119]
	v_mfma_f32_16x16x32_bf16 v[112:115], v[120:123], v[168:171], v[112:115]
	v_mfma_f32_16x16x32_bf16 v[92:95], v[96:99], v[176:179], v[92:95]
	v_mfma_f32_16x16x32_bf16 v[88:91], v[120:123], v[176:179], v[88:91]
	v_mfma_f32_16x16x32_bf16 v[76:79], v[96:99], v[202:205], v[76:79]
	v_mfma_f32_16x16x32_bf16 v[72:75], v[120:123], v[202:205], v[72:75]
	v_mfma_f32_16x16x32_bf16 v[140:143], v[108:111], v[164:167], v[140:143]
	v_mfma_f32_16x16x32_bf16 v[136:139], v[128:131], v[164:167], v[136:139]
	v_mfma_f32_16x16x32_bf16 v[116:119], v[108:111], v[172:175], v[116:119]
	v_mfma_f32_16x16x32_bf16 v[112:115], v[128:131], v[172:175], v[112:115]
	v_mfma_f32_16x16x32_bf16 v[92:95], v[108:111], v[180:183], v[92:95]
	v_mfma_f32_16x16x32_bf16 v[88:91], v[128:131], v[180:183], v[88:91]
	v_mfma_f32_16x16x32_bf16 v[76:79], v[108:111], v[206:209], v[76:79]
	v_mfma_f32_16x16x32_bf16 v[72:75], v[128:131], v[206:209], v[72:75]
	v_mfma_f32_16x16x32_bf16 v[132:135], v[144:147], v[160:163], v[132:135]
	v_mfma_f32_16x16x32_bf16 v[124:127], v[152:155], v[160:163], v[124:127]
	v_mfma_f32_16x16x32_bf16 v[104:107], v[144:147], v[168:171], v[104:107]
	v_mfma_f32_16x16x32_bf16 v[100:103], v[152:155], v[168:171], v[100:103]
	v_mfma_f32_16x16x32_bf16 v[84:87], v[144:147], v[176:179], v[84:87]
	v_mfma_f32_16x16x32_bf16 v[80:83], v[152:155], v[176:179], v[80:83]
	v_mfma_f32_16x16x32_bf16 v[68:71], v[144:147], v[202:205], v[68:71]
	v_mfma_f32_16x16x32_bf16 v[64:67], v[152:155], v[202:205], v[64:67]
	v_mfma_f32_16x16x32_bf16 v[132:135], v[148:151], v[164:167], v[132:135]
	v_mfma_f32_16x16x32_bf16 v[124:127], v[156:159], v[164:167], v[124:127]
	v_mfma_f32_16x16x32_bf16 v[104:107], v[148:151], v[172:175], v[104:107]
	v_mfma_f32_16x16x32_bf16 v[100:103], v[156:159], v[172:175], v[100:103]
	v_mfma_f32_16x16x32_bf16 v[84:87], v[148:151], v[180:183], v[84:87]
	v_mfma_f32_16x16x32_bf16 v[80:83], v[156:159], v[180:183], v[80:83]
	v_mfma_f32_16x16x32_bf16 v[68:71], v[148:151], v[206:209], v[68:71]
	v_mfma_f32_16x16x32_bf16 v[64:67], v[156:159], v[206:209], v[64:67]
	s_barrier
	s_add_i32 s71, s62, s48
	s_add_u32 s98, s34, s12
	s_addc_u32 s99, s35, s13
	s_add_u32 s100, s46, s12
	s_addc_u32 s101, s47, s13
	s_mov_b32 m0, s71
	ds_read_b128 v[160:163], v224 offset:16384
	ds_read_b128 v[164:167], v224 offset:17408
	ds_read_b128 v[168:171], v224 offset:18432
	ds_read_b128 v[172:175], v224 offset:19456
	ds_read_b128 v[176:179], v224 offset:20480
	ds_read_b128 v[180:183], v224 offset:21504
	ds_read_b128 v[202:205], v224 offset:22528
	ds_read_b128 v[206:209], v224 offset:23552
	global_load_lds_dwordx4 v186, s[34:35]
	s_add_i32 m0, s71, 0x2000
	s_add_u32 s72, s34, 0xb0000
	s_addc_u32 s73, s35, 0
	s_add_i32 s71, s63, s48
	global_load_lds_dwordx4 v190, s[34:35]
	s_mov_b32 m0, s71
	s_nop 0
	global_load_lds_dwordx4 v186, s[72:73]
	s_add_i32 m0, s71, 0x2000
	s_nop 0
	global_load_lds_dwordx4 v190, s[72:73]
	s_mov_b32 m0, s49
	s_nop 0
	global_load_lds_dwordx4 v184, s[46:47]
	s_mov_b32 m0, s50
	s_nop 0
	global_load_lds_dwordx4 v188, s[46:47]
	s_waitcnt vmcnt(8)
	s_waitcnt lgkmcnt(0)
	s_barrier
	s_waitcnt lgkmcnt(0)
	v_mfma_f32_16x16x32_bf16 v[60:63], v[96:99], v[160:163], v[60:63]
	v_mfma_f32_16x16x32_bf16 v[56:59], v[120:123], v[160:163], v[56:59]
	v_mfma_f32_16x16x32_bf16 v[44:47], v[96:99], v[168:171], v[44:47]
	v_mfma_f32_16x16x32_bf16 v[40:43], v[120:123], v[168:171], v[40:43]
	v_mfma_f32_16x16x32_bf16 v[28:31], v[96:99], v[176:179], v[28:31]
	v_mfma_f32_16x16x32_bf16 v[24:27], v[120:123], v[176:179], v[24:27]
	v_mfma_f32_16x16x32_bf16 v[12:15], v[96:99], v[202:205], v[12:15]
	v_mfma_f32_16x16x32_bf16 v[8:11], v[120:123], v[202:205], v[8:11]
	v_mfma_f32_16x16x32_bf16 v[60:63], v[108:111], v[164:167], v[60:63]
	v_mfma_f32_16x16x32_bf16 v[56:59], v[128:131], v[164:167], v[56:59]
	v_mfma_f32_16x16x32_bf16 v[44:47], v[108:111], v[172:175], v[44:47]
	v_mfma_f32_16x16x32_bf16 v[40:43], v[128:131], v[172:175], v[40:43]
	v_mfma_f32_16x16x32_bf16 v[28:31], v[108:111], v[180:183], v[28:31]
	v_mfma_f32_16x16x32_bf16 v[24:27], v[128:131], v[180:183], v[24:27]
	v_mfma_f32_16x16x32_bf16 v[12:15], v[108:111], v[206:209], v[12:15]
	v_mfma_f32_16x16x32_bf16 v[8:11], v[128:131], v[206:209], v[8:11]
	v_mfma_f32_16x16x32_bf16 v[52:55], v[144:147], v[160:163], v[52:55]
	v_mfma_f32_16x16x32_bf16 v[48:51], v[152:155], v[160:163], v[48:51]
	v_mfma_f32_16x16x32_bf16 v[36:39], v[144:147], v[168:171], v[36:39]
	v_mfma_f32_16x16x32_bf16 v[32:35], v[152:155], v[168:171], v[32:35]
	v_mfma_f32_16x16x32_bf16 v[20:23], v[144:147], v[176:179], v[20:23]
	v_mfma_f32_16x16x32_bf16 v[16:19], v[152:155], v[176:179], v[16:19]
	v_mfma_f32_16x16x32_bf16 v[4:7], v[144:147], v[202:205], v[4:7]
	v_mfma_f32_16x16x32_bf16 v[0:3], v[152:155], v[202:205], v[0:3]
	v_mfma_f32_16x16x32_bf16 v[52:55], v[148:151], v[164:167], v[52:55]
	v_mfma_f32_16x16x32_bf16 v[48:51], v[156:159], v[164:167], v[48:51]
	v_mfma_f32_16x16x32_bf16 v[36:39], v[148:151], v[172:175], v[36:39]
	v_mfma_f32_16x16x32_bf16 v[32:35], v[156:159], v[172:175], v[32:35]
	v_mfma_f32_16x16x32_bf16 v[20:23], v[148:151], v[180:183], v[20:23]
	v_mfma_f32_16x16x32_bf16 v[16:19], v[156:159], v[180:183], v[16:19]
	v_mfma_f32_16x16x32_bf16 v[4:7], v[148:151], v[206:209], v[4:7]
	v_mfma_f32_16x16x32_bf16 v[0:3], v[156:159], v[206:209], v[0:3]
	s_barrier
; #define PG8_STAGE(bufoff, gbase, voff) do { _Pragma("unroll") for (int _i = 0; _i < 2; ++_i) \
;         __builtin_amdgcn_global_load_lds((const unsigned*)((const char*)(gbase) + (voff)[_i]), (PG8_LAS unsigned*)(lds + (bufoff) + ldsw + _i * 8192), 16, 0, 0); } while (0)
; #define PG8_LDA(dst, b, h) do { _Pragma("unroll") for (int m = 0; m < 4; ++m) _Pragma("unroll") for (int k = 0; k < 2; ++k) dst[m][k] = *(const PG8_LAS bf16x8*)(lds + PG8_SA(b, h) + aoff + m * 2048 + k * 1024); } while (0)
; #define PG8_LDB(dst, b, h) do { _Pragma("unroll") for (int n = 0; n < 2; ++n) _Pragma("unroll") for (int k = 0; k < 2; ++k) dst[n][k] = *(const PG8_LAS bf16x8*)(lds + PG8_SB(b, h) + boff + n * 2048 + k * 1024); } while (0)
; #define PG8_MMA(ai, bj, At, Bt) do { __builtin_amdgcn_s_setprio(1); _Pragma("unroll") for (int m = 0; m < 4; ++m) _Pragma("unroll") for (int n = 0; n < 2; ++n) _Pragma("unroll") for (int k = 0; k < 2; ++k) \
;         acc[ai][bj][m][n] = __builtin_amdgcn_mfma_f32_16x16x32_bf16(Bt[n][k], At[m][k], acc[ai][bj][m][n], 0, 0, 0); __builtin_amdgcn_s_setprio(0); } while (0)
; #define PG8_WAIT_V(n) asm volatile("s_waitcnt vmcnt(" #n ")" ::: "memory")
; #define PG8_WAIT_L(n) asm volatile("s_waitcnt lgkmcnt(" #n ")" ::: "memory")
; #define PG8_BAR __builtin_amdgcn_s_barrier()
; #define PG8_SCHED __builtin_amdgcn_sched_barrier(0)
; template <class Epi, class Sched, bool ALIGN_EPI = false, bool SP2 = false>
; __device__ __forceinline__ void gemm_phase(PG8_LAS unsigned char* lds, const Gemm g, const Sched& S, const Epi& E) {
;     ...
;             PG8_LDB(B0, 1, 0); PG8_LDB(B1, 1, 1); PG8_SCHED; PG8_LDA(At, 1, 0); PG8_STAGE(PG8_SA(0, 1), a2 + hstep, voffA);
;             PG8_WAIT_V(8); PG8_WAIT_L(0); PG8_BAR; PG8_MMA(0, 0, At, B0); PG8_MMA(0, 1, At, B1); PG8_BAR; PG8_SCHED;
;             PG8_LDA(At, 1, 1); PG8_STAGE(PG8_SB(1, 0), b3, voffB); PG8_STAGE(PG8_SB(1, 1), b3 + hstep, voffB); PG8_STAGE(PG8_SA(1, 0), a3, voffA);
;             PG8_WAIT_V(8); PG8_WAIT_L(0); PG8_BAR; PG8_MMA(1, 0, At, B0); PG8_MMA(1, 1, At, B1); PG8_BAR; PG8_SCHED;
;     ...
;         if constexpr (ALIGN_EPI) { if (wr == 0) PG8_BAR; }
	s_add_i32 s71, 0, 0x18000
	s_add_i32 s72, 0, 0x1c000
	v_add_u32_e32 v128, s71, v197
	v_add_u32_e32 v156, s72, v197
	ds_read_b128 v[96:99], v128
	ds_read_b128 v[108:111], v128 offset:1024
	ds_read_b128 v[120:123], v128 offset:2048
	ds_read_b128 v[128:131], v128 offset:3072
	ds_read_b128 v[144:147], v156
	ds_read_b128 v[148:151], v156 offset:1024
	ds_read_b128 v[152:155], v156 offset:2048
	ds_read_b128 v[156:159], v156 offset:3072
	s_add_u32 s46, s46, 0xb0000
	s_addc_u32 s47, s47, 0
	s_mov_b32 m0, s51
	ds_read_b128 v[160:163], v224 offset:32768
	ds_read_b128 v[164:167], v224 offset:33792
	ds_read_b128 v[168:171], v224 offset:34816
	ds_read_b128 v[172:175], v224 offset:35840
	ds_read_b128 v[176:179], v224 offset:36864
	ds_read_b128 v[180:183], v224 offset:37888
	ds_read_b128 v[202:205], v224 offset:38912
	ds_read_b128 v[206:209], v224 offset:39936
	global_load_lds_dwordx4 v184, s[46:47]
	s_mov_b32 m0, s52
	s_nop 0
	global_load_lds_dwordx4 v188, s[46:47]
	s_waitcnt vmcnt(8)
	s_waitcnt lgkmcnt(0)
	s_barrier
	s_waitcnt lgkmcnt(0)
	v_mfma_f32_16x16x32_bf16 v[140:143], v[96:99], v[160:163], v[140:143]
	v_mfma_f32_16x16x32_bf16 v[136:139], v[120:123], v[160:163], v[136:139]
	v_mfma_f32_16x16x32_bf16 v[116:119], v[96:99], v[168:171], v[116:119]
	v_mfma_f32_16x16x32_bf16 v[112:115], v[120:123], v[168:171], v[112:115]
	v_mfma_f32_16x16x32_bf16 v[92:95], v[96:99], v[176:179], v[92:95]
	v_mfma_f32_16x16x32_bf16 v[88:91], v[120:123], v[176:179], v[88:91]
	v_mfma_f32_16x16x32_bf16 v[76:79], v[96:99], v[202:205], v[76:79]
	v_mfma_f32_16x16x32_bf16 v[72:75], v[120:123], v[202:205], v[72:75]
	v_mfma_f32_16x16x32_bf16 v[140:143], v[108:111], v[164:167], v[140:143]
	v_mfma_f32_16x16x32_bf16 v[136:139], v[128:131], v[164:167], v[136:139]
	v_mfma_f32_16x16x32_bf16 v[116:119], v[108:111], v[172:175], v[116:119]
	v_mfma_f32_16x16x32_bf16 v[112:115], v[128:131], v[172:175], v[112:115]
	v_mfma_f32_16x16x32_bf16 v[92:95], v[108:111], v[180:183], v[92:95]
	v_mfma_f32_16x16x32_bf16 v[88:91], v[128:131], v[180:183], v[88:91]
	v_mfma_f32_16x16x32_bf16 v[76:79], v[108:111], v[206:209], v[76:79]
	v_mfma_f32_16x16x32_bf16 v[72:75], v[128:131], v[206:209], v[72:75]
	v_mfma_f32_16x16x32_bf16 v[132:135], v[144:147], v[160:163], v[132:135]
	v_mfma_f32_16x16x32_bf16 v[124:127], v[152:155], v[160:163], v[124:127]
	v_mfma_f32_16x16x32_bf16 v[104:107], v[144:147], v[168:171], v[104:107]
	v_mfma_f32_16x16x32_bf16 v[100:103], v[152:155], v[168:171], v[100:103]
	v_mfma_f32_16x16x32_bf16 v[84:87], v[144:147], v[176:179], v[84:87]
	v_mfma_f32_16x16x32_bf16 v[80:83], v[152:155], v[176:179], v[80:83]
	v_mfma_f32_16x16x32_bf16 v[68:71], v[144:147], v[202:205], v[68:71]
	v_mfma_f32_16x16x32_bf16 v[64:67], v[152:155], v[202:205], v[64:67]
	v_mfma_f32_16x16x32_bf16 v[132:135], v[148:151], v[164:167], v[132:135]
	v_mfma_f32_16x16x32_bf16 v[124:127], v[156:159], v[164:167], v[124:127]
	v_mfma_f32_16x16x32_bf16 v[104:107], v[148:151], v[172:175], v[104:107]
	v_mfma_f32_16x16x32_bf16 v[100:103], v[156:159], v[172:175], v[100:103]
	v_mfma_f32_16x16x32_bf16 v[84:87], v[148:151], v[180:183], v[84:87]
	v_mfma_f32_16x16x32_bf16 v[80:83], v[156:159], v[180:183], v[80:83]
	v_mfma_f32_16x16x32_bf16 v[68:71], v[148:151], v[206:209], v[68:71]
	v_mfma_f32_16x16x32_bf16 v[64:67], v[156:159], v[206:209], v[64:67]
	s_barrier
	s_add_i32 s46, s71, s48
	s_mov_b32 m0, s46
	ds_read_b128 v[160:163], v224 offset:49152
	ds_read_b128 v[164:167], v224 offset:50176
	ds_read_b128 v[168:171], v224 offset:51200
	ds_read_b128 v[172:175], v224 offset:52224
	ds_read_b128 v[176:179], v224 offset:53248
	ds_read_b128 v[180:183], v224 offset:54272
	ds_read_b128 v[202:205], v224 offset:55296
	ds_read_b128 v[206:209], v224 offset:56320
	global_load_lds_dwordx4 v186, s[98:99]
	s_add_i32 m0, s46, 0x2000
	s_add_u32 s34, s34, 0xb0080
	s_addc_u32 s35, s35, 0
	s_add_i32 s46, s72, s48
	global_load_lds_dwordx4 v190, s[98:99]
	s_mov_b32 m0, s46
	s_nop 0
	global_load_lds_dwordx4 v186, s[34:35]
	s_add_i32 m0, s46, 0x2000
	s_nop 0
	global_load_lds_dwordx4 v190, s[34:35]
	s_mov_b32 m0, s57
	s_nop 0
	global_load_lds_dwordx4 v184, s[100:101]
	s_mov_b32 m0, s58
	s_nop 0
	global_load_lds_dwordx4 v188, s[100:101]
	s_waitcnt vmcnt(8)
	s_waitcnt lgkmcnt(0)
	s_barrier
	s_waitcnt lgkmcnt(0)
	v_mfma_f32_16x16x32_bf16 v[60:63], v[96:99], v[160:163], v[60:63]
	v_mfma_f32_16x16x32_bf16 v[56:59], v[120:123], v[160:163], v[56:59]
	v_mfma_f32_16x16x32_bf16 v[44:47], v[96:99], v[168:171], v[44:47]
	v_mfma_f32_16x16x32_bf16 v[40:43], v[120:123], v[168:171], v[40:43]
	v_mfma_f32_16x16x32_bf16 v[28:31], v[96:99], v[176:179], v[28:31]
	v_mfma_f32_16x16x32_bf16 v[24:27], v[120:123], v[176:179], v[24:27]
	v_mfma_f32_16x16x32_bf16 v[12:15], v[96:99], v[202:205], v[12:15]
	v_mfma_f32_16x16x32_bf16 v[8:11], v[120:123], v[202:205], v[8:11]
	v_mfma_f32_16x16x32_bf16 v[60:63], v[108:111], v[164:167], v[60:63]
	v_mfma_f32_16x16x32_bf16 v[56:59], v[128:131], v[164:167], v[56:59]
	v_mfma_f32_16x16x32_bf16 v[44:47], v[108:111], v[172:175], v[44:47]
	v_mfma_f32_16x16x32_bf16 v[40:43], v[128:131], v[172:175], v[40:43]
	v_mfma_f32_16x16x32_bf16 v[28:31], v[108:111], v[180:183], v[28:31]
	v_mfma_f32_16x16x32_bf16 v[24:27], v[128:131], v[180:183], v[24:27]
	v_mfma_f32_16x16x32_bf16 v[12:15], v[108:111], v[206:209], v[12:15]
	v_mfma_f32_16x16x32_bf16 v[8:11], v[128:131], v[206:209], v[8:11]
	v_mfma_f32_16x16x32_bf16 v[52:55], v[144:147], v[160:163], v[52:55]
	v_mfma_f32_16x16x32_bf16 v[48:51], v[152:155], v[160:163], v[48:51]
	v_mfma_f32_16x16x32_bf16 v[36:39], v[144:147], v[168:171], v[36:39]
	v_mfma_f32_16x16x32_bf16 v[32:35], v[152:155], v[168:171], v[32:35]
	v_mfma_f32_16x16x32_bf16 v[20:23], v[144:147], v[176:179], v[20:23]
	v_mfma_f32_16x16x32_bf16 v[16:19], v[152:155], v[176:179], v[16:19]
	v_mfma_f32_16x16x32_bf16 v[4:7], v[144:147], v[202:205], v[4:7]
	v_mfma_f32_16x16x32_bf16 v[0:3], v[152:155], v[202:205], v[0:3]
	v_mfma_f32_16x16x32_bf16 v[52:55], v[148:151], v[164:167], v[52:55]
	v_mfma_f32_16x16x32_bf16 v[48:51], v[156:159], v[164:167], v[48:51]
	v_mfma_f32_16x16x32_bf16 v[36:39], v[148:151], v[172:175], v[36:39]
	v_mfma_f32_16x16x32_bf16 v[32:35], v[156:159], v[172:175], v[32:35]
	v_mfma_f32_16x16x32_bf16 v[20:23], v[148:151], v[180:183], v[20:23]
	v_mfma_f32_16x16x32_bf16 v[16:19], v[156:159], v[180:183], v[16:19]
	v_mfma_f32_16x16x32_bf16 v[4:7], v[148:151], v[206:209], v[4:7]
	v_mfma_f32_16x16x32_bf16 v[0:3], v[156:159], v[206:209], v[0:3]
	s_barrier
	s_add_i32 s70, s70, 2
	s_add_u32 s20, s20, 0x100
	s_addc_u32 s21, s21, 0
	s_add_u32 s68, s68, 0x100
	s_addc_u32 s69, s69, 0
	s_cmp_gt_u32 s70, 41
	s_cbranch_scc0 .LBB0_1825
	s_and_b64 vcc, exec, s[14:15]
	s_cbranch_vccz .LBB0_1828
	s_barrier
